# v55 + GEMM K-loops: the 56 redundant post-barrier lgkmcnt(0) waits at the head of the MFMA blocks deleted (the same wait already sits before the barrier)
# baseline (speedup 1.0000x reference)
; #define PG8_STAGE(bufoff, gbase, voff) do { _Pragma("unroll") for (int _i = 0; _i < 2; ++_i) \
;         __builtin_amdgcn_global_load_lds((const unsigned*)((const char*)(gbase) + (voff)[_i]), (PG8_LAS unsigned*)(lds + (bufoff) + ldsw + _i * 8192), 16, 0, 0); } while (0)
; #define PG8_LDA(dst, b, h) do { _Pragma("unroll") for (int m = 0; m < 4; ++m) _Pragma("unroll") for (int k = 0; k < 2; ++k) dst[m][k] = *(const PG8_LAS bf16x8*)(lds + PG8_SA(b, h) + aoff + m * 2048 + k * 1024); } while (0)
; #define PG8_LDB(dst, b, h) do { _Pragma("unroll") for (int n = 0; n < 2; ++n) _Pragma("unroll") for (int k = 0; k < 2; ++k) dst[n][k] = *(const PG8_LAS bf16x8*)(lds + PG8_SB(b, h) + boff + n * 2048 + k * 1024); } while (0)
; #define PG8_MMA(ai, bj, At, Bt) do { __builtin_amdgcn_s_setprio(1); _Pragma("unroll") for (int m = 0; m < 4; ++m) _Pragma("unroll") for (int n = 0; n < 2; ++n) _Pragma("unroll") for (int k = 0; k < 2; ++k) \
;         acc[ai][bj][m][n] = __builtin_amdgcn_mfma_f32_16x16x32_bf16(Bt[n][k], At[m][k], acc[ai][bj][m][n], 0, 0, 0); __builtin_amdgcn_s_setprio(0); } while (0)
; template <class Epi, class Sched, bool ALIGN_EPI = false, bool SP2 = false>
; __device__ __forceinline__ void gemm_phase(PG8_LAS unsigned char* lds, const Gemm g, const Sched& S, const Epi& E) {
;     ...
;             if constexpr (SP2) {
;             PG8_LDB(B0, 0, 0); PG8_LDB(B1, 0, 1); PG8_SCHED; PG8_LDA(At, 0, 0); PG8_STAGE(PG8_SA(1, 1), a1 + hstepA, voffA);
;             PG8_WAIT_V(8); PG8_WAIT_L(0); PG8_BAR; PG8_MMA(0, 0, At, B0); PG8_MMA(0, 1, At, B1); PG8_BAR; PG8_SCHED;
;             PG8_LDA(At, 0, 1); PG8_STAGE(PG8_SB(0, 0), b2, voffB); PG8_STAGE(PG8_SB(0, 1), b2 + hstepB, voffB); PG8_STAGE(PG8_SA(0, 0), a2, voffA);
;             PG8_WAIT_V(8); PG8_WAIT_L(0); PG8_BAR; PG8_MMA(1, 0, At, B0); PG8_MMA(1, 1, At, B1); PG8_BAR; PG8_SCHED;
;             PG8_LDB(B0, 1, 0); PG8_LDB(B1, 1, 1); PG8_SCHED; PG8_LDA(At, 1, 0); PG8_STAGE(PG8_SA(0, 1), a2 + hstepA, voffA);
;             PG8_WAIT_V(8); PG8_WAIT_L(0); PG8_BAR; PG8_MMA(0, 0, At, B0); PG8_MMA(0, 1, At, B1); PG8_BAR; PG8_SCHED;
;             PG8_LDA(At, 1, 1); PG8_STAGE(PG8_SB(1, 0), b3, voffB); PG8_STAGE(PG8_SB(1, 1), b3 + hstepB, voffB); PG8_STAGE(PG8_SA(1, 0), a3, voffA);
;             PG8_WAIT_V(8); PG8_WAIT_L(0); PG8_BAR; PG8_MMA(1, 0, At, B0); PG8_MMA(1, 1, At, B1); PG8_BAR; PG8_SCHED;
.LBB0_275:
	s_add_u32 s28, s26, 0xfffc0080
	s_addc_u32 s29, s27, -1
	s_add_i32 s51, 0, 0x10000
	s_cmp_eq_u32 s50, 12
	s_cselect_b32 s31, s9, s29
	s_cselect_b32 s30, s21, s28
	s_cselect_b32 s29, s19, s47
	s_cselect_b32 s28, s45, s46
	s_add_i32 s56, 0, 0x14000
	v_add_u32_e32 v44, s51, v163
	v_add_u32_e32 v158, s56, v163
	ds_read_b128 v[24:27], v44
	ds_read_b128 v[28:31], v44 offset:1024
	ds_read_b128 v[36:39], v44 offset:2048
	ds_read_b128 v[44:47], v44 offset:3072
	ds_read_b128 v[154:157], v158
	ds_read_b128 v[166:169], v158 offset:1024
	ds_read_b128 v[174:177], v158 offset:2048
	ds_read_b128 v[178:181], v158 offset:3072
	s_add_i32 m0, s3, 0xc000
	ds_read_b128 v[182:185], v165
	ds_read_b128 v[192:195], v165 offset:1024
	ds_read_b128 v[196:199], v165 offset:2048
	ds_read_b128 v[200:203], v165 offset:3072
	ds_read_b128 v[204:207], v165 offset:4096
	ds_read_b128 v[208:211], v165 offset:5120
	ds_read_b128 v[212:215], v165 offset:6144
	ds_read_b128 v[216:219], v165 offset:7168
	global_load_lds_dwordx4 v150, s[26:27]
	s_add_i32 m0, s3, 0xe000
	s_nop 0
	global_load_lds_dwordx4 v152, s[26:27]
	s_waitcnt vmcnt(8)
	s_waitcnt lgkmcnt(0)
	s_barrier
	s_setprio 1
	v_mfma_f32_16x16x32_bf16 v[140:143], v[24:27], v[182:185], v[140:143]
	v_mfma_f32_16x16x32_bf16 v[136:139], v[36:39], v[182:185], v[136:139]
	v_mfma_f32_16x16x32_bf16 v[124:127], v[24:27], v[196:199], v[124:127]
	v_mfma_f32_16x16x32_bf16 v[120:123], v[36:39], v[196:199], v[120:123]
	v_mfma_f32_16x16x32_bf16 v[108:111], v[24:27], v[204:207], v[108:111]
	v_mfma_f32_16x16x32_bf16 v[104:107], v[36:39], v[204:207], v[104:107]
	v_mfma_f32_16x16x32_bf16 v[92:95], v[24:27], v[212:215], v[92:95]
	v_mfma_f32_16x16x32_bf16 v[88:91], v[36:39], v[212:215], v[88:91]
	v_mfma_f32_16x16x32_bf16 v[140:143], v[28:31], v[192:195], v[140:143]
	v_mfma_f32_16x16x32_bf16 v[136:139], v[44:47], v[192:195], v[136:139]
	v_mfma_f32_16x16x32_bf16 v[124:127], v[28:31], v[200:203], v[124:127]
	v_mfma_f32_16x16x32_bf16 v[120:123], v[44:47], v[200:203], v[120:123]
	v_mfma_f32_16x16x32_bf16 v[108:111], v[28:31], v[208:211], v[108:111]
	v_mfma_f32_16x16x32_bf16 v[104:107], v[44:47], v[208:211], v[104:107]
	v_mfma_f32_16x16x32_bf16 v[92:95], v[28:31], v[216:219], v[92:95]
	v_mfma_f32_16x16x32_bf16 v[88:91], v[44:47], v[216:219], v[88:91]
	s_setprio 0
	s_setprio 1
	v_mfma_f32_16x16x32_bf16 v[132:135], v[154:157], v[182:185], v[132:135]
	v_mfma_f32_16x16x32_bf16 v[128:131], v[174:177], v[182:185], v[128:131]
	v_mfma_f32_16x16x32_bf16 v[116:119], v[154:157], v[196:199], v[116:119]
	v_mfma_f32_16x16x32_bf16 v[112:115], v[174:177], v[196:199], v[112:115]
	v_mfma_f32_16x16x32_bf16 v[100:103], v[154:157], v[204:207], v[100:103]
	v_mfma_f32_16x16x32_bf16 v[96:99], v[174:177], v[204:207], v[96:99]
	v_mfma_f32_16x16x32_bf16 v[84:87], v[154:157], v[212:215], v[84:87]
	v_mfma_f32_16x16x32_bf16 v[80:83], v[174:177], v[212:215], v[80:83]
	v_mfma_f32_16x16x32_bf16 v[132:135], v[166:169], v[192:195], v[132:135]
	v_mfma_f32_16x16x32_bf16 v[128:131], v[178:181], v[192:195], v[128:131]
	v_mfma_f32_16x16x32_bf16 v[116:119], v[166:169], v[200:203], v[116:119]
	v_mfma_f32_16x16x32_bf16 v[112:115], v[178:181], v[200:203], v[112:115]
	v_mfma_f32_16x16x32_bf16 v[100:103], v[166:169], v[208:211], v[100:103]
	v_mfma_f32_16x16x32_bf16 v[96:99], v[178:181], v[208:211], v[96:99]
	v_mfma_f32_16x16x32_bf16 v[84:87], v[166:169], v[216:219], v[84:87]
	v_mfma_f32_16x16x32_bf16 v[80:83], v[178:181], v[216:219], v[80:83]
	s_setprio 0
	s_barrier
	s_add_i32 s51, s51, s2
	v_lshl_add_u64 v[160:161], s[28:29], 0, v[172:173]
	s_mov_b32 m0, s51
	ds_read_b128 v[182:185], v165 offset:16384
	ds_read_b128 v[192:195], v165 offset:17408
	ds_read_b128 v[196:199], v165 offset:18432
	ds_read_b128 v[200:203], v165 offset:19456
	ds_read_b128 v[204:207], v165 offset:20480
	ds_read_b128 v[208:211], v165 offset:21504
	ds_read_b128 v[212:215], v165 offset:22528
	ds_read_b128 v[216:219], v165 offset:23552
	global_load_lds_dwordx4 v[160:161], off
	s_add_i32 m0, s51, 0x2000
	s_add_u32 s52, s28, 0x10000
	v_lshl_add_u64 v[170:171], s[28:29], 0, v[148:149]
	s_addc_u32 s53, s29, 0
	s_add_i32 s51, s56, s2
	global_load_lds_dwordx4 v[170:171], off
	s_mov_b32 m0, s51
	v_lshl_add_u64 v[220:221], s[30:31], 0, v[146:147]
	global_load_lds_dwordx4 v172, s[52:53]
	s_add_i32 m0, s51, 0x2000
	s_nop 0
	global_load_lds_dwordx4 v148, s[52:53]
	v_lshl_add_u64 v[186:187], s[30:31], 0, v[144:145]
	s_mov_b32 m0, s3
	s_nop 0
	global_load_lds_dwordx4 v[186:187], off
	s_mov_b32 m0, s25
	s_nop 0
	global_load_lds_dwordx4 v[220:221], off
	s_waitcnt vmcnt(8)
	s_waitcnt lgkmcnt(0)
	s_barrier
; #define PG8_STAGE(bufoff, gbase, voff) do { _Pragma("unroll") for (int _i = 0; _i < 2; ++_i) \
;         __builtin_amdgcn_global_load_lds((const unsigned*)((const char*)(gbase) + (voff)[_i]), (PG8_LAS unsigned*)(lds + (bufoff) + ldsw + _i * 8192), 16, 0, 0); } while (0)
; #define PG8_LDA(dst, b, h) do { _Pragma("unroll") for (int m = 0; m < 4; ++m) _Pragma("unroll") for (int k = 0; k < 2; ++k) dst[m][k] = *(const PG8_LAS bf16x8*)(lds + PG8_SA(b, h) + aoff + m * 2048 + k * 1024); } while (0)
; #define PG8_LDB(dst, b, h) do { _Pragma("unroll") for (int n = 0; n < 2; ++n) _Pragma("unroll") for (int k = 0; k < 2; ++k) dst[n][k] = *(const PG8_LAS bf16x8*)(lds + PG8_SB(b, h) + boff + n * 2048 + k * 1024); } while (0)
; #define PG8_MMA(ai, bj, At, Bt) do { __builtin_amdgcn_s_setprio(1); _Pragma("unroll") for (int m = 0; m < 4; ++m) _Pragma("unroll") for (int n = 0; n < 2; ++n) _Pragma("unroll") for (int k = 0; k < 2; ++k) \
;         acc[ai][bj][m][n] = __builtin_amdgcn_mfma_f32_16x16x32_bf16(Bt[n][k], At[m][k], acc[ai][bj][m][n], 0, 0, 0); __builtin_amdgcn_s_setprio(0); } while (0)
; template <class Epi, class Sched, bool ALIGN_EPI = false, bool SP2 = false>
; __device__ __forceinline__ void gemm_phase(PG8_LAS unsigned char* lds, const Gemm g, const Sched& S, const Epi& E) {
;     ...
;             if constexpr (SP2) {
;             PG8_LDB(B0, 0, 0); PG8_LDB(B1, 0, 1); PG8_SCHED; PG8_LDA(At, 0, 0); PG8_STAGE(PG8_SA(1, 1), a1 + hstepA, voffA);
;             PG8_WAIT_V(8); PG8_WAIT_L(0); PG8_BAR; PG8_MMA(0, 0, At, B0); PG8_MMA(0, 1, At, B1); PG8_BAR; PG8_SCHED;
;             PG8_LDA(At, 0, 1); PG8_STAGE(PG8_SB(0, 0), b2, voffB); PG8_STAGE(PG8_SB(0, 1), b2 + hstepB, voffB); PG8_STAGE(PG8_SA(0, 0), a2, voffA);
;             PG8_WAIT_V(8); PG8_WAIT_L(0); PG8_BAR; PG8_MMA(1, 0, At, B0); PG8_MMA(1, 1, At, B1); PG8_BAR; PG8_SCHED;
;             PG8_LDB(B0, 1, 0); PG8_LDB(B1, 1, 1); PG8_SCHED; PG8_LDA(At, 1, 0); PG8_STAGE(PG8_SA(0, 1), a2 + hstepA, voffA);
;             PG8_WAIT_V(8); PG8_WAIT_L(0); PG8_BAR; PG8_MMA(0, 0, At, B0); PG8_MMA(0, 1, At, B1); PG8_BAR; PG8_SCHED;
;             PG8_LDA(At, 1, 1); PG8_STAGE(PG8_SB(1, 0), b3, voffB); PG8_STAGE(PG8_SB(1, 1), b3 + hstepB, voffB); PG8_STAGE(PG8_SA(1, 0), a3, voffA);
;             PG8_WAIT_V(8); PG8_WAIT_L(0); PG8_BAR; PG8_MMA(1, 0, At, B0); PG8_MMA(1, 1, At, B1); PG8_BAR; PG8_SCHED;
	s_setprio 1
	v_mfma_f32_16x16x32_bf16 v[76:79], v[24:27], v[182:185], v[76:79]
	v_mfma_f32_16x16x32_bf16 v[72:75], v[36:39], v[182:185], v[72:75]
	v_mfma_f32_16x16x32_bf16 v[60:63], v[24:27], v[196:199], v[60:63]
	v_mfma_f32_16x16x32_bf16 v[56:59], v[36:39], v[196:199], v[56:59]
	v_mfma_f32_16x16x32_bf16 v[40:43], v[24:27], v[204:207], v[40:43]
	v_mfma_f32_16x16x32_bf16 v[32:35], v[36:39], v[204:207], v[32:35]
	v_mfma_f32_16x16x32_bf16 v[12:15], v[24:27], v[212:215], v[12:15]
	v_mfma_f32_16x16x32_bf16 v[8:11], v[36:39], v[212:215], v[8:11]
	v_mfma_f32_16x16x32_bf16 v[76:79], v[28:31], v[192:195], v[76:79]
	v_mfma_f32_16x16x32_bf16 v[72:75], v[44:47], v[192:195], v[72:75]
	v_mfma_f32_16x16x32_bf16 v[60:63], v[28:31], v[200:203], v[60:63]
	v_mfma_f32_16x16x32_bf16 v[56:59], v[44:47], v[200:203], v[56:59]
	v_mfma_f32_16x16x32_bf16 v[40:43], v[28:31], v[208:211], v[40:43]
	v_mfma_f32_16x16x32_bf16 v[32:35], v[44:47], v[208:211], v[32:35]
	v_mfma_f32_16x16x32_bf16 v[12:15], v[28:31], v[216:219], v[12:15]
	v_mfma_f32_16x16x32_bf16 v[8:11], v[44:47], v[216:219], v[8:11]
	s_setprio 0
	s_setprio 1
	v_mfma_f32_16x16x32_bf16 v[20:23], v[154:157], v[204:207], v[20:23]
	v_mfma_f32_16x16x32_bf16 v[16:19], v[174:177], v[204:207], v[16:19]
	v_mfma_f32_16x16x32_bf16 v[4:7], v[154:157], v[212:215], v[4:7]
	v_mfma_f32_16x16x32_bf16 v[0:3], v[174:177], v[212:215], v[0:3]
	v_mfma_f32_16x16x32_bf16 v[24:27], v[154:157], v[182:185], v[68:71]
	v_mfma_f32_16x16x32_bf16 v[28:31], v[174:177], v[182:185], v[64:67]
	v_mfma_f32_16x16x32_bf16 v[36:39], v[154:157], v[196:199], v[52:55]
	v_mfma_f32_16x16x32_bf16 v[44:47], v[174:177], v[196:199], v[48:51]
	v_mfma_f32_16x16x32_bf16 v[20:23], v[166:169], v[208:211], v[20:23]
	v_mfma_f32_16x16x32_bf16 v[16:19], v[178:181], v[208:211], v[16:19]
	v_mfma_f32_16x16x32_bf16 v[4:7], v[166:169], v[216:219], v[4:7]
	v_mfma_f32_16x16x32_bf16 v[0:3], v[178:181], v[216:219], v[0:3]
	v_mfma_f32_16x16x32_bf16 v[24:27], v[166:169], v[192:195], v[24:27]
	v_mfma_f32_16x16x32_bf16 v[28:31], v[178:181], v[192:195], v[28:31]
	v_mfma_f32_16x16x32_bf16 v[36:39], v[166:169], v[200:203], v[36:39]
	v_mfma_f32_16x16x32_bf16 v[44:47], v[178:181], v[200:203], v[44:47]
	s_setprio 0
	s_barrier
	s_add_i32 s51, 0, 0x18000
	s_add_i32 s52, 0, 0x1c000
	v_add_u32_e32 v68, s51, v163
	v_add_u32_e32 v158, s52, v163
	ds_read_b128 v[48:51], v68
	ds_read_b128 v[52:55], v68 offset:1024
	ds_read_b128 v[64:67], v68 offset:2048
	ds_read_b128 v[68:71], v68 offset:3072
	ds_read_b128 v[154:157], v158
	ds_read_b128 v[166:169], v158 offset:1024
	ds_read_b128 v[174:177], v158 offset:2048
	ds_read_b128 v[178:181], v158 offset:3072
	s_add_u32 s30, s30, 0x40000
	s_addc_u32 s31, s31, 0
	s_mov_b32 m0, s40
	ds_read_b128 v[182:185], v165 offset:32768
	ds_read_b128 v[192:195], v165 offset:33792
	ds_read_b128 v[196:199], v165 offset:34816
	ds_read_b128 v[200:203], v165 offset:35840
	ds_read_b128 v[204:207], v165 offset:36864
	ds_read_b128 v[208:211], v165 offset:37888
	ds_read_b128 v[212:215], v165 offset:38912
	ds_read_b128 v[216:219], v165 offset:39936
	global_load_lds_dwordx4 v144, s[30:31]
	v_lshl_add_u64 v[222:223], s[30:31], 0, v[146:147]
	s_mov_b32 m0, s41
	s_nop 0
	global_load_lds_dwordx4 v[222:223], off
	s_waitcnt vmcnt(8)
	s_waitcnt lgkmcnt(0)
	s_barrier
	s_setprio 1
	v_mfma_f32_16x16x32_bf16 v[140:143], v[48:51], v[182:185], v[140:143]
	v_mfma_f32_16x16x32_bf16 v[136:139], v[64:67], v[182:185], v[136:139]
	v_mfma_f32_16x16x32_bf16 v[124:127], v[48:51], v[196:199], v[124:127]
	v_mfma_f32_16x16x32_bf16 v[120:123], v[64:67], v[196:199], v[120:123]
	v_mfma_f32_16x16x32_bf16 v[108:111], v[48:51], v[204:207], v[108:111]
	v_mfma_f32_16x16x32_bf16 v[104:107], v[64:67], v[204:207], v[104:107]
	v_mfma_f32_16x16x32_bf16 v[92:95], v[48:51], v[212:215], v[92:95]
	v_mfma_f32_16x16x32_bf16 v[88:91], v[64:67], v[212:215], v[88:91]
	v_mfma_f32_16x16x32_bf16 v[140:143], v[52:55], v[192:195], v[140:143]
	v_mfma_f32_16x16x32_bf16 v[136:139], v[68:71], v[192:195], v[136:139]
	v_mfma_f32_16x16x32_bf16 v[124:127], v[52:55], v[200:203], v[124:127]
	v_mfma_f32_16x16x32_bf16 v[120:123], v[68:71], v[200:203], v[120:123]
	v_mfma_f32_16x16x32_bf16 v[108:111], v[52:55], v[208:211], v[108:111]
	v_mfma_f32_16x16x32_bf16 v[104:107], v[68:71], v[208:211], v[104:107]
	v_mfma_f32_16x16x32_bf16 v[92:95], v[52:55], v[216:219], v[92:95]
	v_mfma_f32_16x16x32_bf16 v[88:91], v[68:71], v[216:219], v[88:91]
	s_setprio 0
	s_setprio 1
	v_mfma_f32_16x16x32_bf16 v[132:135], v[154:157], v[182:185], v[132:135]
	v_mfma_f32_16x16x32_bf16 v[128:131], v[174:177], v[182:185], v[128:131]
	v_mfma_f32_16x16x32_bf16 v[116:119], v[154:157], v[196:199], v[116:119]
	v_mfma_f32_16x16x32_bf16 v[112:115], v[174:177], v[196:199], v[112:115]
	v_mfma_f32_16x16x32_bf16 v[100:103], v[154:157], v[204:207], v[100:103]
	v_mfma_f32_16x16x32_bf16 v[96:99], v[174:177], v[204:207], v[96:99]
	v_mfma_f32_16x16x32_bf16 v[84:87], v[154:157], v[212:215], v[84:87]
	v_mfma_f32_16x16x32_bf16 v[80:83], v[174:177], v[212:215], v[80:83]
	v_mfma_f32_16x16x32_bf16 v[132:135], v[166:169], v[192:195], v[132:135]
	v_mfma_f32_16x16x32_bf16 v[128:131], v[178:181], v[192:195], v[128:131]
	v_mfma_f32_16x16x32_bf16 v[116:119], v[166:169], v[200:203], v[116:119]
	v_mfma_f32_16x16x32_bf16 v[112:115], v[178:181], v[200:203], v[112:115]
	v_mfma_f32_16x16x32_bf16 v[100:103], v[166:169], v[208:211], v[100:103]
	v_mfma_f32_16x16x32_bf16 v[96:99], v[178:181], v[208:211], v[96:99]
	v_mfma_f32_16x16x32_bf16 v[84:87], v[166:169], v[216:219], v[84:87]
	v_mfma_f32_16x16x32_bf16 v[80:83], v[178:181], v[216:219], v[80:83]
	s_setprio 0
	s_barrier
; #define PG8_STAGE(bufoff, gbase, voff) do { _Pragma("unroll") for (int _i = 0; _i < 2; ++_i) \
;         __builtin_amdgcn_global_load_lds((const unsigned*)((const char*)(gbase) + (voff)[_i]), (PG8_LAS unsigned*)(lds + (bufoff) + ldsw + _i * 8192), 16, 0, 0); } while (0)
; #define PG8_LDA(dst, b, h) do { _Pragma("unroll") for (int m = 0; m < 4; ++m) _Pragma("unroll") for (int k = 0; k < 2; ++k) dst[m][k] = *(const PG8_LAS bf16x8*)(lds + PG8_SA(b, h) + aoff + m * 2048 + k * 1024); } while (0)
; #define PG8_LDB(dst, b, h) do { _Pragma("unroll") for (int n = 0; n < 2; ++n) _Pragma("unroll") for (int k = 0; k < 2; ++k) dst[n][k] = *(const PG8_LAS bf16x8*)(lds + PG8_SB(b, h) + boff + n * 2048 + k * 1024); } while (0)
; template <class Epi, class Sched, bool ALIGN_EPI = false, bool SP2 = false>
; __device__ __forceinline__ void gemm_phase(PG8_LAS unsigned char* lds, const Gemm g, const Sched& S, const Epi& E) {
;     ...
;         for (int t = 0; t < nt; t += 2) {
;             const bool last = (t == nt - 2);
;             const char* a1 = cA + (size_t)(t + 1) * kstep;
;             const char* a2 = last ? nA : cA + (size_t)(t + 2) * kstep; const char* b2 = last ? nB : cB + (size_t)(t + 2) * kstep;
;             const char* a3 = a2 + kstep; const char* b3 = b2 + kstep;
;             if (last && has_next) S.a_ready(nxt);
;             if constexpr (SP2) {
;             PG8_LDB(B0, 0, 0); PG8_LDB(B1, 0, 1); PG8_SCHED; PG8_LDA(At, 0, 0); PG8_STAGE(PG8_SA(1, 1), a1 + hstepA, voffA);
;             PG8_WAIT_V(8); PG8_WAIT_L(0); PG8_BAR; PG8_MMA(0, 0, At, B0); PG8_MMA(0, 1, At, B1); PG8_BAR; PG8_SCHED;
;             PG8_LDA(At, 0, 1); PG8_STAGE(PG8_SB(0, 0), b2, voffB); PG8_STAGE(PG8_SB(0, 1), b2 + hstepB, voffB); PG8_STAGE(PG8_SA(0, 0), a2, voffA);
;             PG8_WAIT_V(8); PG8_WAIT_L(0); PG8_BAR; PG8_MMA(1, 0, At, B0); PG8_MMA(1, 1, At, B1); PG8_BAR; PG8_SCHED;
;             PG8_LDB(B0, 1, 0); PG8_LDB(B1, 1, 1); PG8_SCHED; PG8_LDA(At, 1, 0); PG8_STAGE(PG8_SA(0, 1), a2 + hstepA, voffA);
;             PG8_WAIT_V(8); PG8_WAIT_L(0); PG8_BAR; PG8_MMA(0, 0, At, B0); PG8_MMA(0, 1, At, B1); PG8_BAR; PG8_SCHED;
;             PG8_LDA(At, 1, 1); PG8_STAGE(PG8_SB(1, 0), b3, voffB); PG8_STAGE(PG8_SB(1, 1), b3 + hstepB, voffB); PG8_STAGE(PG8_SA(1, 0), a3, voffA);
;             PG8_WAIT_V(8); PG8_WAIT_L(0); PG8_BAR; PG8_MMA(1, 0, At, B0); PG8_MMA(1, 1, At, B1); PG8_BAR; PG8_SCHED;
	s_add_i32 s30, s51, s2
	v_lshl_add_u64 v[160:161], v[160:161], 0, s[80:81]
	s_mov_b32 m0, s30
	ds_read_b128 v[182:185], v165 offset:49152
	ds_read_b128 v[192:195], v165 offset:50176
	ds_read_b128 v[196:199], v165 offset:51200
	ds_read_b128 v[200:203], v165 offset:52224
	ds_read_b128 v[204:207], v165 offset:53248
	ds_read_b128 v[208:211], v165 offset:54272
	ds_read_b128 v[212:215], v165 offset:55296
	ds_read_b128 v[216:219], v165 offset:56320
	global_load_lds_dwordx4 v[160:161], off
	s_add_i32 m0, s30, 0x2000
	s_add_u32 s28, s28, 0x10080
	v_lshl_add_u64 v[160:161], v[170:171], 0, s[80:81]
	s_addc_u32 s29, s29, 0
	s_add_i32 s30, s52, s2
	global_load_lds_dwordx4 v[160:161], off
	s_mov_b32 m0, s30
	s_nop 0
	global_load_lds_dwordx4 v172, s[28:29]
	s_add_i32 m0, s30, 0x2000
	s_nop 0
	global_load_lds_dwordx4 v148, s[28:29]
	v_lshl_add_u64 v[160:161], v[186:187], 0, s[80:81]
	s_mov_b32 m0, s42
	s_nop 0
	global_load_lds_dwordx4 v[160:161], off
	v_lshl_add_u64 v[160:161], v[220:221], 0, s[80:81]
	s_mov_b32 m0, s43
	s_nop 0
	global_load_lds_dwordx4 v[160:161], off
	s_waitcnt vmcnt(8)
	s_waitcnt lgkmcnt(0)
	s_barrier
	s_setprio 1
	v_mfma_f32_16x16x32_bf16 v[76:79], v[48:51], v[182:185], v[76:79]
	v_mfma_f32_16x16x32_bf16 v[72:75], v[64:67], v[182:185], v[72:75]
	v_mfma_f32_16x16x32_bf16 v[60:63], v[48:51], v[196:199], v[60:63]
	v_mfma_f32_16x16x32_bf16 v[56:59], v[64:67], v[196:199], v[56:59]
	v_mfma_f32_16x16x32_bf16 v[40:43], v[48:51], v[204:207], v[40:43]
	v_mfma_f32_16x16x32_bf16 v[32:35], v[64:67], v[204:207], v[32:35]
	v_mfma_f32_16x16x32_bf16 v[12:15], v[48:51], v[212:215], v[12:15]
	v_mfma_f32_16x16x32_bf16 v[8:11], v[64:67], v[212:215], v[8:11]
	v_mfma_f32_16x16x32_bf16 v[76:79], v[52:55], v[192:195], v[76:79]
	v_mfma_f32_16x16x32_bf16 v[72:75], v[68:71], v[192:195], v[72:75]
	v_mfma_f32_16x16x32_bf16 v[60:63], v[52:55], v[200:203], v[60:63]
	v_mfma_f32_16x16x32_bf16 v[56:59], v[68:71], v[200:203], v[56:59]
	v_mfma_f32_16x16x32_bf16 v[40:43], v[52:55], v[208:211], v[40:43]
	v_mfma_f32_16x16x32_bf16 v[32:35], v[68:71], v[208:211], v[32:35]
	v_mfma_f32_16x16x32_bf16 v[12:15], v[52:55], v[216:219], v[12:15]
	v_mfma_f32_16x16x32_bf16 v[8:11], v[68:71], v[216:219], v[8:11]
	s_setprio 0
	s_setprio 1
	v_mfma_f32_16x16x32_bf16 v[24:27], v[154:157], v[182:185], v[24:27]
	v_mfma_f32_16x16x32_bf16 v[68:71], v[166:169], v[192:195], v[24:27]
	v_mfma_f32_16x16x32_bf16 v[24:27], v[174:177], v[182:185], v[28:31]
	v_mfma_f32_16x16x32_bf16 v[64:67], v[178:181], v[192:195], v[24:27]
	v_mfma_f32_16x16x32_bf16 v[24:27], v[154:157], v[196:199], v[36:39]
	v_mfma_f32_16x16x32_bf16 v[52:55], v[166:169], v[200:203], v[24:27]
	v_mfma_f32_16x16x32_bf16 v[24:27], v[174:177], v[196:199], v[44:47]
	v_mfma_f32_16x16x32_bf16 v[20:23], v[154:157], v[204:207], v[20:23]
	v_mfma_f32_16x16x32_bf16 v[16:19], v[174:177], v[204:207], v[16:19]
	v_mfma_f32_16x16x32_bf16 v[4:7], v[154:157], v[212:215], v[4:7]
	v_mfma_f32_16x16x32_bf16 v[0:3], v[174:177], v[212:215], v[0:3]
	v_mfma_f32_16x16x32_bf16 v[48:51], v[178:181], v[200:203], v[24:27]
	v_mfma_f32_16x16x32_bf16 v[20:23], v[166:169], v[208:211], v[20:23]
	v_mfma_f32_16x16x32_bf16 v[16:19], v[178:181], v[208:211], v[16:19]
	v_mfma_f32_16x16x32_bf16 v[4:7], v[166:169], v[216:219], v[4:7]
	v_mfma_f32_16x16x32_bf16 v[0:3], v[178:181], v[216:219], v[0:3]
	s_setprio 0
	s_barrier
	s_add_i32 s50, s50, 2
	s_add_u32 s26, s26, 0x100
	s_addc_u32 s27, s27, 0
	s_add_u32 s46, s46, 0x100
	s_addc_u32 s47, s47, 0
	s_cmp_gt_u32 s50, 13
	s_cbranch_scc0 .LBB0_275
	s_and_b64 vcc, exec, s[16:17]
	s_cbranch_vccz .LBB0_278
	s_barrier

; #define PG8_STAGE(bufoff, gbase, voff) do { _Pragma("unroll") for (int _i = 0; _i < 2; ++_i) \
;         __builtin_amdgcn_global_load_lds((const unsigned*)((const char*)(gbase) + (voff)[_i]), (PG8_LAS unsigned*)(lds + (bufoff) + ldsw + _i * 8192), 16, 0, 0); } while (0)
; #define PG8_LDA(dst, b, h) do { _Pragma("unroll") for (int m = 0; m < 4; ++m) _Pragma("unroll") for (int k = 0; k < 2; ++k) dst[m][k] = *(const PG8_LAS bf16x8*)(lds + PG8_SA(b, h) + aoff + m * 2048 + k * 1024); } while (0)
; #define PG8_LDB(dst, b, h) do { _Pragma("unroll") for (int n = 0; n < 2; ++n) _Pragma("unroll") for (int k = 0; k < 2; ++k) dst[n][k] = *(const PG8_LAS bf16x8*)(lds + PG8_SB(b, h) + boff + n * 2048 + k * 1024); } while (0)
; #define PG8_MMA(ai, bj, At, Bt) do { __builtin_amdgcn_s_setprio(1); _Pragma("unroll") for (int m = 0; m < 4; ++m) _Pragma("unroll") for (int n = 0; n < 2; ++n) _Pragma("unroll") for (int k = 0; k < 2; ++k) \
;         acc[ai][bj][m][n] = __builtin_amdgcn_mfma_f32_16x16x32_bf16(Bt[n][k], At[m][k], acc[ai][bj][m][n], 0, 0, 0); __builtin_amdgcn_s_setprio(0); } while (0)
; template <class Epi, class Sched, bool ALIGN_EPI = false, bool SP2 = false>
; __device__ __forceinline__ void gemm_phase(PG8_LAS unsigned char* lds, const Gemm g, const Sched& S, const Epi& E) {
;     ...
;             if constexpr (SP2) {
;             PG8_LDB(B0, 0, 0); PG8_LDB(B1, 0, 1); PG8_SCHED; PG8_LDA(At, 0, 0); PG8_STAGE(PG8_SA(1, 1), a1 + hstepA, voffA);
;             PG8_WAIT_V(8); PG8_WAIT_L(0); PG8_BAR; PG8_MMA(0, 0, At, B0); PG8_MMA(0, 1, At, B1); PG8_BAR; PG8_SCHED;
;             PG8_LDA(At, 0, 1); PG8_STAGE(PG8_SB(0, 0), b2, voffB); PG8_STAGE(PG8_SB(0, 1), b2 + hstepB, voffB); PG8_STAGE(PG8_SA(0, 0), a2, voffA);
;             PG8_WAIT_V(8); PG8_WAIT_L(0); PG8_BAR; PG8_MMA(1, 0, At, B0); PG8_MMA(1, 1, At, B1); PG8_BAR; PG8_SCHED;
;             PG8_LDB(B0, 1, 0); PG8_LDB(B1, 1, 1); PG8_SCHED; PG8_LDA(At, 1, 0); PG8_STAGE(PG8_SA(0, 1), a2 + hstepA, voffA);
;             PG8_WAIT_V(8); PG8_WAIT_L(0); PG8_BAR; PG8_MMA(0, 0, At, B0); PG8_MMA(0, 1, At, B1); PG8_BAR; PG8_SCHED;
;             PG8_LDA(At, 1, 1); PG8_STAGE(PG8_SB(1, 0), b3, voffB); PG8_STAGE(PG8_SB(1, 1), b3 + hstepB, voffB); PG8_STAGE(PG8_SA(1, 0), a3, voffA);
;             PG8_WAIT_V(8); PG8_WAIT_L(0); PG8_BAR; PG8_MMA(1, 0, At, B0); PG8_MMA(1, 1, At, B1); PG8_BAR; PG8_SCHED;
.LBB0_330:
	s_add_u32 s56, s42, 0xfffc0080
	s_addc_u32 s57, s43, -1
	s_add_i32 s64, 0, 0x10000
	s_cmp_eq_u32 s87, 12
	s_cselect_b32 vcc_hi, s73, s57
	s_cselect_b32 vcc_lo, s75, s56
	s_cselect_b32 s71, s47, s89
	s_cselect_b32 s70, s86, s85
	s_add_i32 s52, 0, 0x14000
	v_add_u32_e32 v150, s64, v171
	v_add_u32_e32 v166, s52, v171
	ds_read_b128 v[138:141], v150
	ds_read_b128 v[142:145], v150 offset:1024
	ds_read_b128 v[146:149], v150 offset:2048
	ds_read_b128 v[150:153], v150 offset:3072
	ds_read_b128 v[154:157], v166
	ds_read_b128 v[158:161], v166 offset:1024
	ds_read_b128 v[162:165], v166 offset:2048
	ds_read_b128 v[166:169], v166 offset:3072
	s_add_i32 m0, s45, 0xc000
	ds_read_b128 v[174:177], v180
	ds_read_b128 v[182:185], v180 offset:1024
	ds_read_b128 v[192:195], v180 offset:2048
	ds_read_b128 v[196:199], v180 offset:3072
	ds_read_b128 v[200:203], v180 offset:4096
	ds_read_b128 v[204:207], v180 offset:5120
	ds_read_b128 v[208:211], v180 offset:6144
	ds_read_b128 v[212:215], v180 offset:7168
	global_load_lds_dwordx4 v134, s[42:43]
	s_add_i32 m0, s45, 0xe000
	s_nop 0
	global_load_lds_dwordx4 v136, s[42:43]
	s_waitcnt vmcnt(8)
	s_waitcnt lgkmcnt(0)
	s_barrier
	s_setprio 1
	v_mfma_f32_16x16x32_bf16 v[124:127], v[138:141], v[174:177], v[124:127]
	v_mfma_f32_16x16x32_bf16 v[120:123], v[146:149], v[174:177], v[120:123]
	v_mfma_f32_16x16x32_bf16 v[108:111], v[138:141], v[192:195], v[108:111]
	v_mfma_f32_16x16x32_bf16 v[104:107], v[146:149], v[192:195], v[104:107]
	v_mfma_f32_16x16x32_bf16 v[92:95], v[138:141], v[200:203], v[92:95]
	v_mfma_f32_16x16x32_bf16 v[88:91], v[146:149], v[200:203], v[88:91]
	v_mfma_f32_16x16x32_bf16 v[76:79], v[138:141], v[208:211], v[76:79]
	v_mfma_f32_16x16x32_bf16 v[72:75], v[146:149], v[208:211], v[72:75]
	v_mfma_f32_16x16x32_bf16 v[124:127], v[142:145], v[182:185], v[124:127]
	v_mfma_f32_16x16x32_bf16 v[120:123], v[150:153], v[182:185], v[120:123]
	v_mfma_f32_16x16x32_bf16 v[108:111], v[142:145], v[196:199], v[108:111]
	v_mfma_f32_16x16x32_bf16 v[104:107], v[150:153], v[196:199], v[104:107]
	v_mfma_f32_16x16x32_bf16 v[92:95], v[142:145], v[204:207], v[92:95]
	v_mfma_f32_16x16x32_bf16 v[88:91], v[150:153], v[204:207], v[88:91]
	v_mfma_f32_16x16x32_bf16 v[76:79], v[142:145], v[212:215], v[76:79]
	v_mfma_f32_16x16x32_bf16 v[72:75], v[150:153], v[212:215], v[72:75]
	s_setprio 0
	s_setprio 1
	v_mfma_f32_16x16x32_bf16 v[116:119], v[154:157], v[174:177], v[116:119]
	v_mfma_f32_16x16x32_bf16 v[112:115], v[162:165], v[174:177], v[112:115]
	v_mfma_f32_16x16x32_bf16 v[100:103], v[154:157], v[192:195], v[100:103]
	v_mfma_f32_16x16x32_bf16 v[96:99], v[162:165], v[192:195], v[96:99]
	v_mfma_f32_16x16x32_bf16 v[84:87], v[154:157], v[200:203], v[84:87]
	v_mfma_f32_16x16x32_bf16 v[80:83], v[162:165], v[200:203], v[80:83]
	v_mfma_f32_16x16x32_bf16 v[68:71], v[154:157], v[208:211], v[68:71]
	v_mfma_f32_16x16x32_bf16 v[64:67], v[162:165], v[208:211], v[64:67]
	v_mfma_f32_16x16x32_bf16 v[116:119], v[158:161], v[182:185], v[116:119]
	v_mfma_f32_16x16x32_bf16 v[112:115], v[166:169], v[182:185], v[112:115]
	v_mfma_f32_16x16x32_bf16 v[100:103], v[158:161], v[196:199], v[100:103]
	v_mfma_f32_16x16x32_bf16 v[96:99], v[166:169], v[196:199], v[96:99]
	v_mfma_f32_16x16x32_bf16 v[84:87], v[158:161], v[204:207], v[84:87]
	v_mfma_f32_16x16x32_bf16 v[80:83], v[166:169], v[204:207], v[80:83]
	v_mfma_f32_16x16x32_bf16 v[68:71], v[158:161], v[212:215], v[68:71]
	v_mfma_f32_16x16x32_bf16 v[64:67], v[166:169], v[212:215], v[64:67]
	s_setprio 0
	s_barrier
	s_add_i32 s56, s64, s66
	v_lshl_add_u64 v[186:187], s[70:71], 0, v[172:173]
	s_mov_b32 m0, s56
	ds_read_b128 v[174:177], v180 offset:16384
	ds_read_b128 v[182:185], v180 offset:17408
	ds_read_b128 v[192:195], v180 offset:18432
	ds_read_b128 v[196:199], v180 offset:19456
	ds_read_b128 v[200:203], v180 offset:20480
	ds_read_b128 v[204:207], v180 offset:21504
	ds_read_b128 v[208:211], v180 offset:22528
	ds_read_b128 v[212:215], v180 offset:23552
	global_load_lds_dwordx4 v[186:187], off
	s_add_i32 m0, s56, 0x2000
	s_add_u32 s56, s70, 0x40000
	v_lshl_add_u64 v[216:217], s[70:71], 0, v[132:133]
	s_addc_u32 s57, s71, 0
	s_add_i32 s52, s52, s66
	global_load_lds_dwordx4 v[216:217], off
	s_mov_b32 m0, s52
	v_lshl_add_u64 v[220:221], vcc, 0, v[130:131]
	global_load_lds_dwordx4 v172, s[56:57]
	s_add_i32 m0, s52, 0x2000
	s_nop 0
	global_load_lds_dwordx4 v132, s[56:57]
	v_lshl_add_u64 v[218:219], vcc, 0, v[128:129]
	s_mov_b32 m0, s45
	s_nop 0
	global_load_lds_dwordx4 v[218:219], off
	s_mov_b32 m0, s93
	s_nop 0
	global_load_lds_dwordx4 v[220:221], off
	s_waitcnt vmcnt(8)
	s_waitcnt lgkmcnt(0)
	s_barrier
; #define PG8_STAGE(bufoff, gbase, voff) do { _Pragma("unroll") for (int _i = 0; _i < 2; ++_i) \
;         __builtin_amdgcn_global_load_lds((const unsigned*)((const char*)(gbase) + (voff)[_i]), (PG8_LAS unsigned*)(lds + (bufoff) + ldsw + _i * 8192), 16, 0, 0); } while (0)
; #define PG8_LDA(dst, b, h) do { _Pragma("unroll") for (int m = 0; m < 4; ++m) _Pragma("unroll") for (int k = 0; k < 2; ++k) dst[m][k] = *(const PG8_LAS bf16x8*)(lds + PG8_SA(b, h) + aoff + m * 2048 + k * 1024); } while (0)
; #define PG8_LDB(dst, b, h) do { _Pragma("unroll") for (int n = 0; n < 2; ++n) _Pragma("unroll") for (int k = 0; k < 2; ++k) dst[n][k] = *(const PG8_LAS bf16x8*)(lds + PG8_SB(b, h) + boff + n * 2048 + k * 1024); } while (0)
; #define PG8_MMA(ai, bj, At, Bt) do { __builtin_amdgcn_s_setprio(1); _Pragma("unroll") for (int m = 0; m < 4; ++m) _Pragma("unroll") for (int n = 0; n < 2; ++n) _Pragma("unroll") for (int k = 0; k < 2; ++k) \
;         acc[ai][bj][m][n] = __builtin_amdgcn_mfma_f32_16x16x32_bf16(Bt[n][k], At[m][k], acc[ai][bj][m][n], 0, 0, 0); __builtin_amdgcn_s_setprio(0); } while (0)
; template <class Epi, class Sched, bool ALIGN_EPI = false, bool SP2 = false>
; __device__ __forceinline__ void gemm_phase(PG8_LAS unsigned char* lds, const Gemm g, const Sched& S, const Epi& E) {
;     ...
;             if constexpr (SP2) {
;             PG8_LDB(B0, 0, 0); PG8_LDB(B1, 0, 1); PG8_SCHED; PG8_LDA(At, 0, 0); PG8_STAGE(PG8_SA(1, 1), a1 + hstepA, voffA);
;             PG8_WAIT_V(8); PG8_WAIT_L(0); PG8_BAR; PG8_MMA(0, 0, At, B0); PG8_MMA(0, 1, At, B1); PG8_BAR; PG8_SCHED;
;             PG8_LDA(At, 0, 1); PG8_STAGE(PG8_SB(0, 0), b2, voffB); PG8_STAGE(PG8_SB(0, 1), b2 + hstepB, voffB); PG8_STAGE(PG8_SA(0, 0), a2, voffA);
;             PG8_WAIT_V(8); PG8_WAIT_L(0); PG8_BAR; PG8_MMA(1, 0, At, B0); PG8_MMA(1, 1, At, B1); PG8_BAR; PG8_SCHED;
;             PG8_LDB(B0, 1, 0); PG8_LDB(B1, 1, 1); PG8_SCHED; PG8_LDA(At, 1, 0); PG8_STAGE(PG8_SA(0, 1), a2 + hstepA, voffA);
;             PG8_WAIT_V(8); PG8_WAIT_L(0); PG8_BAR; PG8_MMA(0, 0, At, B0); PG8_MMA(0, 1, At, B1); PG8_BAR; PG8_SCHED;
;             PG8_LDA(At, 1, 1); PG8_STAGE(PG8_SB(1, 0), b3, voffB); PG8_STAGE(PG8_SB(1, 1), b3 + hstepB, voffB); PG8_STAGE(PG8_SA(1, 0), a3, voffA);
;             PG8_WAIT_V(8); PG8_WAIT_L(0); PG8_BAR; PG8_MMA(1, 0, At, B0); PG8_MMA(1, 1, At, B1); PG8_BAR; PG8_SCHED;
	s_setprio 1
	v_mfma_f32_16x16x32_bf16 v[60:63], v[138:141], v[174:177], v[60:63]
	v_mfma_f32_16x16x32_bf16 v[56:59], v[146:149], v[174:177], v[56:59]
	v_mfma_f32_16x16x32_bf16 v[44:47], v[138:141], v[192:195], v[44:47]
	v_mfma_f32_16x16x32_bf16 v[40:43], v[146:149], v[192:195], v[40:43]
	v_mfma_f32_16x16x32_bf16 v[28:31], v[138:141], v[200:203], v[28:31]
	v_mfma_f32_16x16x32_bf16 v[24:27], v[146:149], v[200:203], v[24:27]
	v_mfma_f32_16x16x32_bf16 v[12:15], v[138:141], v[208:211], v[12:15]
	v_mfma_f32_16x16x32_bf16 v[8:11], v[146:149], v[208:211], v[8:11]
	v_mfma_f32_16x16x32_bf16 v[60:63], v[142:145], v[182:185], v[60:63]
	v_mfma_f32_16x16x32_bf16 v[56:59], v[150:153], v[182:185], v[56:59]
	v_mfma_f32_16x16x32_bf16 v[44:47], v[142:145], v[196:199], v[44:47]
	v_mfma_f32_16x16x32_bf16 v[40:43], v[150:153], v[196:199], v[40:43]
	v_mfma_f32_16x16x32_bf16 v[28:31], v[142:145], v[204:207], v[28:31]
	v_mfma_f32_16x16x32_bf16 v[24:27], v[150:153], v[204:207], v[24:27]
	v_mfma_f32_16x16x32_bf16 v[12:15], v[142:145], v[212:215], v[12:15]
	v_mfma_f32_16x16x32_bf16 v[8:11], v[150:153], v[212:215], v[8:11]
	s_setprio 0
	s_setprio 1
	v_mfma_f32_16x16x32_bf16 v[52:55], v[154:157], v[174:177], v[52:55]
	v_mfma_f32_16x16x32_bf16 v[48:51], v[162:165], v[174:177], v[48:51]
	v_mfma_f32_16x16x32_bf16 v[36:39], v[154:157], v[192:195], v[36:39]
	v_mfma_f32_16x16x32_bf16 v[32:35], v[162:165], v[192:195], v[32:35]
	v_mfma_f32_16x16x32_bf16 v[20:23], v[154:157], v[200:203], v[20:23]
	v_mfma_f32_16x16x32_bf16 v[16:19], v[162:165], v[200:203], v[16:19]
	v_mfma_f32_16x16x32_bf16 v[4:7], v[154:157], v[208:211], v[4:7]
	v_mfma_f32_16x16x32_bf16 v[0:3], v[162:165], v[208:211], v[0:3]
	v_mfma_f32_16x16x32_bf16 v[52:55], v[158:161], v[182:185], v[52:55]
	v_mfma_f32_16x16x32_bf16 v[48:51], v[166:169], v[182:185], v[48:51]
	v_mfma_f32_16x16x32_bf16 v[36:39], v[158:161], v[196:199], v[36:39]
	v_mfma_f32_16x16x32_bf16 v[32:35], v[166:169], v[196:199], v[32:35]
	v_mfma_f32_16x16x32_bf16 v[20:23], v[158:161], v[204:207], v[20:23]
	v_mfma_f32_16x16x32_bf16 v[16:19], v[166:169], v[204:207], v[16:19]
	v_mfma_f32_16x16x32_bf16 v[4:7], v[158:161], v[212:215], v[4:7]
	v_mfma_f32_16x16x32_bf16 v[0:3], v[166:169], v[212:215], v[0:3]
	s_setprio 0
	s_barrier
	s_add_i32 s52, 0, 0x18000
	s_add_i32 s64, 0, 0x1c000
	v_add_u32_e32 v150, s52, v171
	v_add_u32_e32 v166, s64, v171
	ds_read_b128 v[138:141], v150
	ds_read_b128 v[142:145], v150 offset:1024
	ds_read_b128 v[146:149], v150 offset:2048
	ds_read_b128 v[150:153], v150 offset:3072
	ds_read_b128 v[154:157], v166
	ds_read_b128 v[158:161], v166 offset:1024
	ds_read_b128 v[162:165], v166 offset:2048
	ds_read_b128 v[166:169], v166 offset:3072
	s_add_u32 s56, vcc_lo, 0x40000
	s_addc_u32 s57, vcc_hi, 0
	s_mov_b32 m0, s95
	ds_read_b128 v[174:177], v180 offset:32768
	ds_read_b128 v[182:185], v180 offset:33792
	ds_read_b128 v[192:195], v180 offset:34816
	ds_read_b128 v[196:199], v180 offset:35840
	ds_read_b128 v[200:203], v180 offset:36864
	ds_read_b128 v[204:207], v180 offset:37888
	ds_read_b128 v[208:211], v180 offset:38912
	ds_read_b128 v[212:215], v180 offset:39936
	global_load_lds_dwordx4 v128, s[56:57]
	v_lshl_add_u64 v[222:223], s[56:57], 0, v[130:131]
	s_mov_b32 m0, s96
	s_nop 0
	global_load_lds_dwordx4 v[222:223], off
	s_waitcnt vmcnt(8)
	s_waitcnt lgkmcnt(0)
	s_barrier
	s_setprio 1
	v_mfma_f32_16x16x32_bf16 v[124:127], v[138:141], v[174:177], v[124:127]
	v_mfma_f32_16x16x32_bf16 v[120:123], v[146:149], v[174:177], v[120:123]
	v_mfma_f32_16x16x32_bf16 v[108:111], v[138:141], v[192:195], v[108:111]
	v_mfma_f32_16x16x32_bf16 v[104:107], v[146:149], v[192:195], v[104:107]
	v_mfma_f32_16x16x32_bf16 v[92:95], v[138:141], v[200:203], v[92:95]
	v_mfma_f32_16x16x32_bf16 v[88:91], v[146:149], v[200:203], v[88:91]
	v_mfma_f32_16x16x32_bf16 v[76:79], v[138:141], v[208:211], v[76:79]
	v_mfma_f32_16x16x32_bf16 v[72:75], v[146:149], v[208:211], v[72:75]
	v_mfma_f32_16x16x32_bf16 v[124:127], v[142:145], v[182:185], v[124:127]
	v_mfma_f32_16x16x32_bf16 v[120:123], v[150:153], v[182:185], v[120:123]
	v_mfma_f32_16x16x32_bf16 v[108:111], v[142:145], v[196:199], v[108:111]
	v_mfma_f32_16x16x32_bf16 v[104:107], v[150:153], v[196:199], v[104:107]
	v_mfma_f32_16x16x32_bf16 v[92:95], v[142:145], v[204:207], v[92:95]
	v_mfma_f32_16x16x32_bf16 v[88:91], v[150:153], v[204:207], v[88:91]
	v_mfma_f32_16x16x32_bf16 v[76:79], v[142:145], v[212:215], v[76:79]
	v_mfma_f32_16x16x32_bf16 v[72:75], v[150:153], v[212:215], v[72:75]
	s_setprio 0
	s_setprio 1
	v_mfma_f32_16x16x32_bf16 v[116:119], v[154:157], v[174:177], v[116:119]
	v_mfma_f32_16x16x32_bf16 v[112:115], v[162:165], v[174:177], v[112:115]
	v_mfma_f32_16x16x32_bf16 v[100:103], v[154:157], v[192:195], v[100:103]
	v_mfma_f32_16x16x32_bf16 v[96:99], v[162:165], v[192:195], v[96:99]
	v_mfma_f32_16x16x32_bf16 v[84:87], v[154:157], v[200:203], v[84:87]
	v_mfma_f32_16x16x32_bf16 v[80:83], v[162:165], v[200:203], v[80:83]
	v_mfma_f32_16x16x32_bf16 v[68:71], v[154:157], v[208:211], v[68:71]
	v_mfma_f32_16x16x32_bf16 v[64:67], v[162:165], v[208:211], v[64:67]
	v_mfma_f32_16x16x32_bf16 v[116:119], v[158:161], v[182:185], v[116:119]
	v_mfma_f32_16x16x32_bf16 v[112:115], v[166:169], v[182:185], v[112:115]
	v_mfma_f32_16x16x32_bf16 v[100:103], v[158:161], v[196:199], v[100:103]
	v_mfma_f32_16x16x32_bf16 v[96:99], v[166:169], v[196:199], v[96:99]
	v_mfma_f32_16x16x32_bf16 v[84:87], v[158:161], v[204:207], v[84:87]
	v_mfma_f32_16x16x32_bf16 v[80:83], v[166:169], v[204:207], v[80:83]
	v_mfma_f32_16x16x32_bf16 v[68:71], v[158:161], v[212:215], v[68:71]
	v_mfma_f32_16x16x32_bf16 v[64:67], v[166:169], v[212:215], v[64:67]
	s_setprio 0
	s_barrier
; #define PG8_STAGE(bufoff, gbase, voff) do { _Pragma("unroll") for (int _i = 0; _i < 2; ++_i) \
;         __builtin_amdgcn_global_load_lds((const unsigned*)((const char*)(gbase) + (voff)[_i]), (PG8_LAS unsigned*)(lds + (bufoff) + ldsw + _i * 8192), 16, 0, 0); } while (0)
; #define PG8_LDA(dst, b, h) do { _Pragma("unroll") for (int m = 0; m < 4; ++m) _Pragma("unroll") for (int k = 0; k < 2; ++k) dst[m][k] = *(const PG8_LAS bf16x8*)(lds + PG8_SA(b, h) + aoff + m * 2048 + k * 1024); } while (0)
; #define PG8_LDB(dst, b, h) do { _Pragma("unroll") for (int n = 0; n < 2; ++n) _Pragma("unroll") for (int k = 0; k < 2; ++k) dst[n][k] = *(const PG8_LAS bf16x8*)(lds + PG8_SB(b, h) + boff + n * 2048 + k * 1024); } while (0)
; template <class Epi, class Sched, bool ALIGN_EPI = false, bool SP2 = false>
; __device__ __forceinline__ void gemm_phase(PG8_LAS unsigned char* lds, const Gemm g, const Sched& S, const Epi& E) {
;     ...
;         for (int t = 0; t < nt; t += 2) {
;             const bool last = (t == nt - 2);
;             const char* a1 = cA + (size_t)(t + 1) * kstep;
;             const char* a2 = last ? nA : cA + (size_t)(t + 2) * kstep; const char* b2 = last ? nB : cB + (size_t)(t + 2) * kstep;
;             const char* a3 = a2 + kstep; const char* b3 = b2 + kstep;
;             if (last && has_next) S.a_ready(nxt);
;             if constexpr (SP2) {
;             PG8_LDB(B0, 0, 0); PG8_LDB(B1, 0, 1); PG8_SCHED; PG8_LDA(At, 0, 0); PG8_STAGE(PG8_SA(1, 1), a1 + hstepA, voffA);
;             PG8_WAIT_V(8); PG8_WAIT_L(0); PG8_BAR; PG8_MMA(0, 0, At, B0); PG8_MMA(0, 1, At, B1); PG8_BAR; PG8_SCHED;
;             PG8_LDA(At, 0, 1); PG8_STAGE(PG8_SB(0, 0), b2, voffB); PG8_STAGE(PG8_SB(0, 1), b2 + hstepB, voffB); PG8_STAGE(PG8_SA(0, 0), a2, voffA);
;             PG8_WAIT_V(8); PG8_WAIT_L(0); PG8_BAR; PG8_MMA(1, 0, At, B0); PG8_MMA(1, 1, At, B1); PG8_BAR; PG8_SCHED;
;             PG8_LDB(B0, 1, 0); PG8_LDB(B1, 1, 1); PG8_SCHED; PG8_LDA(At, 1, 0); PG8_STAGE(PG8_SA(0, 1), a2 + hstepA, voffA);
;             PG8_WAIT_V(8); PG8_WAIT_L(0); PG8_BAR; PG8_MMA(0, 0, At, B0); PG8_MMA(0, 1, At, B1); PG8_BAR; PG8_SCHED;
;             PG8_LDA(At, 1, 1); PG8_STAGE(PG8_SB(1, 0), b3, voffB); PG8_STAGE(PG8_SB(1, 1), b3 + hstepB, voffB); PG8_STAGE(PG8_SA(1, 0), a3, voffA);
;             PG8_WAIT_V(8); PG8_WAIT_L(0); PG8_BAR; PG8_MMA(1, 0, At, B0); PG8_MMA(1, 1, At, B1); PG8_BAR; PG8_SCHED;
	s_add_i32 s52, s52, s66
	v_lshl_add_u64 v[186:187], v[186:187], 0, s[80:81]
	s_mov_b32 m0, s52
	ds_read_b128 v[174:177], v180 offset:49152
	ds_read_b128 v[182:185], v180 offset:50176
	ds_read_b128 v[192:195], v180 offset:51200
	ds_read_b128 v[196:199], v180 offset:52224
	ds_read_b128 v[200:203], v180 offset:53248
	ds_read_b128 v[204:207], v180 offset:54272
	ds_read_b128 v[208:211], v180 offset:55296
	ds_read_b128 v[212:215], v180 offset:56320
	global_load_lds_dwordx4 v[186:187], off
	s_add_i32 m0, s52, 0x2000
	s_add_u32 s56, s70, 0x40080
	v_lshl_add_u64 v[186:187], v[216:217], 0, s[80:81]
	s_addc_u32 s57, s71, 0
	s_add_i32 s52, s64, s66
	global_load_lds_dwordx4 v[186:187], off
	s_mov_b32 m0, s52
	s_nop 0
	global_load_lds_dwordx4 v172, s[56:57]
	s_add_i32 m0, s52, 0x2000
	s_nop 0
	global_load_lds_dwordx4 v132, s[56:57]
	v_lshl_add_u64 v[186:187], v[218:219], 0, s[80:81]
	s_mov_b32 m0, s53
	s_nop 0
	global_load_lds_dwordx4 v[186:187], off
	v_lshl_add_u64 v[186:187], v[220:221], 0, s[80:81]
	s_mov_b32 m0, s58
	s_nop 0
	global_load_lds_dwordx4 v[186:187], off
	s_waitcnt vmcnt(8)
	s_waitcnt lgkmcnt(0)
	s_barrier
	s_setprio 1
	v_mfma_f32_16x16x32_bf16 v[60:63], v[138:141], v[174:177], v[60:63]
	v_mfma_f32_16x16x32_bf16 v[56:59], v[146:149], v[174:177], v[56:59]
	v_mfma_f32_16x16x32_bf16 v[44:47], v[138:141], v[192:195], v[44:47]
	v_mfma_f32_16x16x32_bf16 v[40:43], v[146:149], v[192:195], v[40:43]
	v_mfma_f32_16x16x32_bf16 v[28:31], v[138:141], v[200:203], v[28:31]
	v_mfma_f32_16x16x32_bf16 v[24:27], v[146:149], v[200:203], v[24:27]
	v_mfma_f32_16x16x32_bf16 v[12:15], v[138:141], v[208:211], v[12:15]
	v_mfma_f32_16x16x32_bf16 v[8:11], v[146:149], v[208:211], v[8:11]
	v_mfma_f32_16x16x32_bf16 v[60:63], v[142:145], v[182:185], v[60:63]
	v_mfma_f32_16x16x32_bf16 v[56:59], v[150:153], v[182:185], v[56:59]
	v_mfma_f32_16x16x32_bf16 v[44:47], v[142:145], v[196:199], v[44:47]
	v_mfma_f32_16x16x32_bf16 v[40:43], v[150:153], v[196:199], v[40:43]
	v_mfma_f32_16x16x32_bf16 v[28:31], v[142:145], v[204:207], v[28:31]
	v_mfma_f32_16x16x32_bf16 v[24:27], v[150:153], v[204:207], v[24:27]
	v_mfma_f32_16x16x32_bf16 v[12:15], v[142:145], v[212:215], v[12:15]
	v_mfma_f32_16x16x32_bf16 v[8:11], v[150:153], v[212:215], v[8:11]
	s_setprio 0
	s_setprio 1
	v_mfma_f32_16x16x32_bf16 v[52:55], v[154:157], v[174:177], v[52:55]
	v_mfma_f32_16x16x32_bf16 v[48:51], v[162:165], v[174:177], v[48:51]
	v_mfma_f32_16x16x32_bf16 v[36:39], v[154:157], v[192:195], v[36:39]
	v_mfma_f32_16x16x32_bf16 v[32:35], v[162:165], v[192:195], v[32:35]
	v_mfma_f32_16x16x32_bf16 v[20:23], v[154:157], v[200:203], v[20:23]
	v_mfma_f32_16x16x32_bf16 v[16:19], v[162:165], v[200:203], v[16:19]
	v_mfma_f32_16x16x32_bf16 v[4:7], v[154:157], v[208:211], v[4:7]
	v_mfma_f32_16x16x32_bf16 v[0:3], v[162:165], v[208:211], v[0:3]
	v_mfma_f32_16x16x32_bf16 v[52:55], v[158:161], v[182:185], v[52:55]
	v_mfma_f32_16x16x32_bf16 v[48:51], v[166:169], v[182:185], v[48:51]
	v_mfma_f32_16x16x32_bf16 v[36:39], v[158:161], v[196:199], v[36:39]
	v_mfma_f32_16x16x32_bf16 v[32:35], v[166:169], v[196:199], v[32:35]
	v_mfma_f32_16x16x32_bf16 v[20:23], v[158:161], v[204:207], v[20:23]
	v_mfma_f32_16x16x32_bf16 v[16:19], v[166:169], v[204:207], v[16:19]
	v_mfma_f32_16x16x32_bf16 v[4:7], v[158:161], v[212:215], v[4:7]
	v_mfma_f32_16x16x32_bf16 v[0:3], v[166:169], v[212:215], v[0:3]
	s_setprio 0
	s_barrier
	s_add_i32 s87, s87, 2
	s_add_u32 s42, s42, 0x100
	s_addc_u32 s43, s43, 0
	s_add_u32 s85, s85, 0x100
	s_addc_u32 s89, s89, 0
	s_cmp_gt_u32 s87, 13
	s_cbranch_scc0 .LBB0_330
	s_and_b64 vcc, exec, s[76:77]
	s_cbranch_vccz .LBB0_333
	s_barrier

;     __device__ __forceinline__ bool next(int i, Unit& u) const { const int L = i * G + c; if (L >= nsub) return false; u.pk = L >> 4; u.pm = MLAT / BM + (L & 3); u.pn = (L >> 2) & 3; return true; }
; #define PG8_STAGE(bufoff, gbase, voff) do { _Pragma("unroll") for (int _i = 0; _i < 2; ++_i) \
;         __builtin_amdgcn_global_load_lds((const unsigned*)((const char*)(gbase) + (voff)[_i]), (PG8_LAS unsigned*)(lds + (bufoff) + ldsw + _i * 8192), 16, 0, 0); } while (0)
; #define PG8_LDA(dst, b, h) do { _Pragma("unroll") for (int m = 0; m < 4; ++m) _Pragma("unroll") for (int k = 0; k < 2; ++k) dst[m][k] = *(const PG8_LAS bf16x8*)(lds + PG8_SA(b, h) + aoff + m * 2048 + k * 1024); } while (0)
; #define PG8_LDB(dst, b, h) do { _Pragma("unroll") for (int n = 0; n < 2; ++n) _Pragma("unroll") for (int k = 0; k < 2; ++k) dst[n][k] = *(const PG8_LAS bf16x8*)(lds + PG8_SB(b, h) + boff + n * 2048 + k * 1024); } while (0)
; #define PG8_WAIT_V(n) asm volatile("s_waitcnt vmcnt(" #n ")" ::: "memory")
; #define PG8_WAIT_L(n) asm volatile("s_waitcnt lgkmcnt(" #n ")" ::: "memory")
; template <class Epi, class Sched, bool ALIGN_EPI = false, bool SP2 = false>
; __device__ __forceinline__ void gemm_phase(PG8_LAS unsigned char* lds, const Gemm g, const Sched& S, const Epi& E) {
;     ...
;         const bool has_next = S.next(ui + 1, nxt);
;         const char* nA = has_next ? g.a_of(nxt) : cA; const char* nB = has_next ? g.b_of(nxt) : cB;
;         for (int t = 0; t < nt; t += 2) {
;             const bool last = (t == nt - 2);
;             const char* a1 = cA + (size_t)(t + 1) * kstep;
;             const char* a2 = last ? nA : cA + (size_t)(t + 2) * kstep; const char* b2 = last ? nB : cB + (size_t)(t + 2) * kstep;
;             const char* a3 = a2 + kstep; const char* b3 = b2 + kstep;
;             if (last && has_next) S.a_ready(nxt);
;             if constexpr (SP2) {
;             PG8_LDB(B0, 0, 0); PG8_LDB(B1, 0, 1); PG8_SCHED; PG8_LDA(At, 0, 0); PG8_STAGE(PG8_SA(1, 1), a1 + hstepA, voffA);
;             PG8_WAIT_V(8); PG8_WAIT_L(0); PG8_BAR; PG8_MMA(0, 0, At, B0); PG8_MMA(0, 1, At, B1); PG8_BAR; PG8_SCHED;
;             PG8_LDA(At, 0, 1); PG8_STAGE(PG8_SB(0, 0), b2, voffB); PG8_STAGE(PG8_SB(0, 1), b2 + hstepB, voffB); PG8_STAGE(PG8_SA(0, 0), a2, voffA);
;             PG8_WAIT_V(8); PG8_WAIT_L(0); PG8_BAR; PG8_MMA(1, 0, At, B0); PG8_MMA(1, 1, At, B1); PG8_BAR; PG8_SCHED;
.LBB0_436:
	s_add_u32 s43, s38, s42
	s_addc_u32 s50, s39, 0
	s_add_u32 s46, s43, 0x100
	s_addc_u32 s47, s50, 0
	s_and_b64 s[44:45], s[40:41], exec
	s_cselect_b32 s45, s23, s47
	s_cselect_b32 s44, s25, s46
	s_add_u32 s42, s36, s42
	s_addc_u32 s46, s37, 0
	s_add_u32 s42, s42, 0x100
	s_addc_u32 s46, s46, 0
	s_add_i32 s74, 0, 0x10000
	s_and_b64 s[40:41], s[40:41], exec
	s_cselect_b32 s47, s27, s46
	s_cselect_b32 s46, s26, s42
	s_add_i32 s41, 0, 0x14000
	s_add_u32 s52, s43, 0x10080
	s_addc_u32 s53, s50, 0
	s_add_i32 s73, s74, s2
	s_add_i32 m0, s31, 0xc000
	s_add_i32 s76, s31, 0xe000
	s_add_i32 s70, s73, 0x2000
	v_add_u32_e32 v147, s74, v143
	s_add_u32 s50, s46, 0x440000
	ds_read_b128 v[134:137], v147
	ds_read_b128 v[138:141], v147 offset:1024
	ds_read_b128 v[148:151], v147 offset:2048
	ds_read_b128 v[152:155], v147 offset:3072
	v_add_u32_e32 v147, s41, v143
	s_addc_u32 s51, s47, 0
	s_add_i32 s72, s41, s2
	ds_read_b128 v[156:159], v147
	ds_read_b128 v[160:163], v147 offset:1024
	ds_read_b128 v[164:167], v147 offset:2048
	ds_read_b128 v[168:171], v147 offset:3072
	s_add_i32 s71, s72, 0x2000
	s_add_i32 s67, 0, 0x18000
	s_add_i32 s66, 0, 0x1c000
	s_add_u32 s42, s44, 0x10000
	s_addc_u32 s43, s45, 0
	s_add_i32 s65, s67, s2
	s_add_i32 s64, s65, 0x2000
	s_add_u32 s40, s46, 0x440080
	s_addc_u32 s41, s47, 0
	s_add_i32 s75, s66, s2
	s_add_i32 s74, s75, 0x2000
	v_lshl_add_u64 v[186:187], s[52:53], 0, v[132:133]
	ds_read_b128 v[174:177], v146
	ds_read_b128 v[178:181], v146 offset:1024
	ds_read_b128 v[182:185], v146 offset:2048
	ds_read_b128 v[192:195], v146 offset:3072
	ds_read_b128 v[196:199], v146 offset:4096
	ds_read_b128 v[200:203], v146 offset:5120
	ds_read_b128 v[204:207], v146 offset:6144
	ds_read_b128 v[208:211], v146 offset:7168
	global_load_lds_dwordx4 v[186:187], off
	v_lshl_add_u64 v[186:187], s[52:53], 0, v[130:131]
	s_mov_b32 m0, s76
	s_nop 0
	global_load_lds_dwordx4 v[186:187], off
	s_waitcnt vmcnt(8)
	s_waitcnt lgkmcnt(0)
	s_barrier
	s_setprio 1
	v_mfma_f32_16x16x32_bf16 v[124:127], v[134:137], v[174:177], v[124:127]
	v_mfma_f32_16x16x32_bf16 v[120:123], v[148:151], v[174:177], v[120:123]
	v_mfma_f32_16x16x32_bf16 v[108:111], v[134:137], v[182:185], v[108:111]
	v_mfma_f32_16x16x32_bf16 v[104:107], v[148:151], v[182:185], v[104:107]
	v_mfma_f32_16x16x32_bf16 v[92:95], v[134:137], v[196:199], v[92:95]
	v_mfma_f32_16x16x32_bf16 v[88:91], v[148:151], v[196:199], v[88:91]
	v_mfma_f32_16x16x32_bf16 v[76:79], v[134:137], v[204:207], v[76:79]
	v_mfma_f32_16x16x32_bf16 v[72:75], v[148:151], v[204:207], v[72:75]
	v_mfma_f32_16x16x32_bf16 v[124:127], v[138:141], v[178:181], v[124:127]
	v_mfma_f32_16x16x32_bf16 v[120:123], v[152:155], v[178:181], v[120:123]
	v_mfma_f32_16x16x32_bf16 v[108:111], v[138:141], v[192:195], v[108:111]
	v_mfma_f32_16x16x32_bf16 v[104:107], v[152:155], v[192:195], v[104:107]
	v_mfma_f32_16x16x32_bf16 v[92:95], v[138:141], v[200:203], v[92:95]
	v_mfma_f32_16x16x32_bf16 v[88:91], v[152:155], v[200:203], v[88:91]
	v_mfma_f32_16x16x32_bf16 v[76:79], v[138:141], v[208:211], v[76:79]
	v_mfma_f32_16x16x32_bf16 v[72:75], v[152:155], v[208:211], v[72:75]
	s_setprio 0
	s_setprio 1
	v_mfma_f32_16x16x32_bf16 v[116:119], v[156:159], v[174:177], v[116:119]
	v_mfma_f32_16x16x32_bf16 v[112:115], v[164:167], v[174:177], v[112:115]
	v_mfma_f32_16x16x32_bf16 v[100:103], v[156:159], v[182:185], v[100:103]
	v_mfma_f32_16x16x32_bf16 v[96:99], v[164:167], v[182:185], v[96:99]
	v_mfma_f32_16x16x32_bf16 v[84:87], v[156:159], v[196:199], v[84:87]
	v_mfma_f32_16x16x32_bf16 v[80:83], v[164:167], v[196:199], v[80:83]
	v_mfma_f32_16x16x32_bf16 v[68:71], v[156:159], v[204:207], v[68:71]
	v_mfma_f32_16x16x32_bf16 v[64:67], v[164:167], v[204:207], v[64:67]
	v_mfma_f32_16x16x32_bf16 v[116:119], v[160:163], v[178:181], v[116:119]
	v_mfma_f32_16x16x32_bf16 v[112:115], v[168:171], v[178:181], v[112:115]
	v_mfma_f32_16x16x32_bf16 v[100:103], v[160:163], v[192:195], v[100:103]
	v_mfma_f32_16x16x32_bf16 v[96:99], v[168:171], v[192:195], v[96:99]
	v_mfma_f32_16x16x32_bf16 v[84:87], v[160:163], v[200:203], v[84:87]
	v_mfma_f32_16x16x32_bf16 v[80:83], v[168:171], v[200:203], v[80:83]
	v_mfma_f32_16x16x32_bf16 v[68:71], v[160:163], v[208:211], v[68:71]
	v_mfma_f32_16x16x32_bf16 v[64:67], v[168:171], v[208:211], v[64:67]
	s_setprio 0
	s_barrier
	s_mov_b32 m0, s73
	v_lshl_add_u64 v[186:187], s[46:47], 0, v[172:173]
	ds_read_b128 v[174:177], v146 offset:16384
	ds_read_b128 v[178:181], v146 offset:17408
	ds_read_b128 v[182:185], v146 offset:18432
	ds_read_b128 v[192:195], v146 offset:19456
	ds_read_b128 v[196:199], v146 offset:20480
	ds_read_b128 v[200:203], v146 offset:21504
	ds_read_b128 v[204:207], v146 offset:22528
	ds_read_b128 v[208:211], v146 offset:23552
	global_load_lds_dwordx4 v[186:187], off
	v_lshl_add_u64 v[212:213], s[46:47], 0, v[128:129]
	s_mov_b32 m0, s70
	v_lshl_add_u64 v[214:215], s[50:51], 0, v[172:173]
	global_load_lds_dwordx4 v[212:213], off
	s_mov_b32 m0, s72
	v_lshl_add_u64 v[216:217], s[44:45], 0, v[130:131]
	global_load_lds_dwordx4 v[214:215], off
	v_lshl_add_u64 v[214:215], s[50:51], 0, v[128:129]
	s_mov_b32 m0, s71
	s_nop 0
	global_load_lds_dwordx4 v[214:215], off
	v_lshl_add_u64 v[214:215], s[44:45], 0, v[132:133]
	s_mov_b32 m0, s31
	s_nop 0
	global_load_lds_dwordx4 v[214:215], off
	s_mov_b32 m0, s35
	s_nop 0
	global_load_lds_dwordx4 v[216:217], off
	s_waitcnt vmcnt(8)
	s_waitcnt lgkmcnt(0)
	s_barrier
; #define PG8_STAGE(bufoff, gbase, voff) do { _Pragma("unroll") for (int _i = 0; _i < 2; ++_i) \
;         __builtin_amdgcn_global_load_lds((const unsigned*)((const char*)(gbase) + (voff)[_i]), (PG8_LAS unsigned*)(lds + (bufoff) + ldsw + _i * 8192), 16, 0, 0); } while (0)
; #define PG8_LDA(dst, b, h) do { _Pragma("unroll") for (int m = 0; m < 4; ++m) _Pragma("unroll") for (int k = 0; k < 2; ++k) dst[m][k] = *(const PG8_LAS bf16x8*)(lds + PG8_SA(b, h) + aoff + m * 2048 + k * 1024); } while (0)
; #define PG8_LDB(dst, b, h) do { _Pragma("unroll") for (int n = 0; n < 2; ++n) _Pragma("unroll") for (int k = 0; k < 2; ++k) dst[n][k] = *(const PG8_LAS bf16x8*)(lds + PG8_SB(b, h) + boff + n * 2048 + k * 1024); } while (0)
; #define PG8_MMA(ai, bj, At, Bt) do { __builtin_amdgcn_s_setprio(1); _Pragma("unroll") for (int m = 0; m < 4; ++m) _Pragma("unroll") for (int n = 0; n < 2; ++n) _Pragma("unroll") for (int k = 0; k < 2; ++k) \
;         acc[ai][bj][m][n] = __builtin_amdgcn_mfma_f32_16x16x32_bf16(Bt[n][k], At[m][k], acc[ai][bj][m][n], 0, 0, 0); __builtin_amdgcn_s_setprio(0); } while (0)
; #define PG8_WAIT_V(n) asm volatile("s_waitcnt vmcnt(" #n ")" ::: "memory")
; #define PG8_WAIT_L(n) asm volatile("s_waitcnt lgkmcnt(" #n ")" ::: "memory")
; #define PG8_BAR __builtin_amdgcn_s_barrier()
; #define PG8_SCHED __builtin_amdgcn_sched_barrier(0)
; template <class Epi, class Sched, bool ALIGN_EPI = false, bool SP2 = false>
; __device__ __forceinline__ void gemm_phase(PG8_LAS unsigned char* lds, const Gemm g, const Sched& S, const Epi& E) {
;     ...
;             if constexpr (SP2) {
;             PG8_LDB(B0, 0, 0); PG8_LDB(B1, 0, 1); PG8_SCHED; PG8_LDA(At, 0, 0); PG8_STAGE(PG8_SA(1, 1), a1 + hstepA, voffA);
;             PG8_WAIT_V(8); PG8_WAIT_L(0); PG8_BAR; PG8_MMA(0, 0, At, B0); PG8_MMA(0, 1, At, B1); PG8_BAR; PG8_SCHED;
;             PG8_LDA(At, 0, 1); PG8_STAGE(PG8_SB(0, 0), b2, voffB); PG8_STAGE(PG8_SB(0, 1), b2 + hstepB, voffB); PG8_STAGE(PG8_SA(0, 0), a2, voffA);
;             PG8_WAIT_V(8); PG8_WAIT_L(0); PG8_BAR; PG8_MMA(1, 0, At, B0); PG8_MMA(1, 1, At, B1); PG8_BAR; PG8_SCHED;
;             PG8_LDB(B0, 1, 0); PG8_LDB(B1, 1, 1); PG8_SCHED; PG8_LDA(At, 1, 0); PG8_STAGE(PG8_SA(0, 1), a2 + hstepA, voffA);
;             PG8_WAIT_V(8); PG8_WAIT_L(0); PG8_BAR; PG8_MMA(0, 0, At, B0); PG8_MMA(0, 1, At, B1); PG8_BAR; PG8_SCHED;
	s_setprio 1
	v_mfma_f32_16x16x32_bf16 v[60:63], v[134:137], v[174:177], v[60:63]
	v_mfma_f32_16x16x32_bf16 v[56:59], v[148:151], v[174:177], v[56:59]
	v_mfma_f32_16x16x32_bf16 v[44:47], v[134:137], v[182:185], v[44:47]
	v_mfma_f32_16x16x32_bf16 v[40:43], v[148:151], v[182:185], v[40:43]
	v_mfma_f32_16x16x32_bf16 v[28:31], v[134:137], v[196:199], v[28:31]
	v_mfma_f32_16x16x32_bf16 v[24:27], v[148:151], v[196:199], v[24:27]
	v_mfma_f32_16x16x32_bf16 v[12:15], v[134:137], v[204:207], v[12:15]
	v_mfma_f32_16x16x32_bf16 v[8:11], v[148:151], v[204:207], v[8:11]
	v_mfma_f32_16x16x32_bf16 v[60:63], v[138:141], v[178:181], v[60:63]
	v_mfma_f32_16x16x32_bf16 v[56:59], v[152:155], v[178:181], v[56:59]
	v_mfma_f32_16x16x32_bf16 v[44:47], v[138:141], v[192:195], v[44:47]
	v_mfma_f32_16x16x32_bf16 v[40:43], v[152:155], v[192:195], v[40:43]
	v_mfma_f32_16x16x32_bf16 v[28:31], v[138:141], v[200:203], v[28:31]
	v_mfma_f32_16x16x32_bf16 v[24:27], v[152:155], v[200:203], v[24:27]
	v_mfma_f32_16x16x32_bf16 v[12:15], v[138:141], v[208:211], v[12:15]
	v_mfma_f32_16x16x32_bf16 v[8:11], v[152:155], v[208:211], v[8:11]
	s_setprio 0
	s_setprio 1
	v_mfma_f32_16x16x32_bf16 v[52:55], v[156:159], v[174:177], v[52:55]
	v_mfma_f32_16x16x32_bf16 v[48:51], v[164:167], v[174:177], v[48:51]
	v_mfma_f32_16x16x32_bf16 v[36:39], v[156:159], v[182:185], v[36:39]
	v_mfma_f32_16x16x32_bf16 v[32:35], v[164:167], v[182:185], v[32:35]
	v_mfma_f32_16x16x32_bf16 v[20:23], v[156:159], v[196:199], v[20:23]
	v_mfma_f32_16x16x32_bf16 v[16:19], v[164:167], v[196:199], v[16:19]
	v_mfma_f32_16x16x32_bf16 v[4:7], v[156:159], v[204:207], v[4:7]
	v_mfma_f32_16x16x32_bf16 v[0:3], v[164:167], v[204:207], v[0:3]
	v_mfma_f32_16x16x32_bf16 v[52:55], v[160:163], v[178:181], v[52:55]
	v_mfma_f32_16x16x32_bf16 v[48:51], v[168:171], v[178:181], v[48:51]
	v_mfma_f32_16x16x32_bf16 v[36:39], v[160:163], v[192:195], v[36:39]
	v_mfma_f32_16x16x32_bf16 v[32:35], v[168:171], v[192:195], v[32:35]
	v_mfma_f32_16x16x32_bf16 v[20:23], v[160:163], v[200:203], v[20:23]
	v_mfma_f32_16x16x32_bf16 v[16:19], v[168:171], v[200:203], v[16:19]
	v_mfma_f32_16x16x32_bf16 v[4:7], v[160:163], v[208:211], v[4:7]
	v_mfma_f32_16x16x32_bf16 v[0:3], v[168:171], v[208:211], v[0:3]
	s_setprio 0
	s_barrier
	v_add_u32_e32 v147, s67, v143
	ds_read_b128 v[134:137], v147
	ds_read_b128 v[138:141], v147 offset:1024
	ds_read_b128 v[148:151], v147 offset:2048
	ds_read_b128 v[152:155], v147 offset:3072
	v_add_u32_e32 v147, s66, v143
	ds_read_b128 v[156:159], v147
	ds_read_b128 v[160:163], v147 offset:1024
	ds_read_b128 v[164:167], v147 offset:2048
	ds_read_b128 v[168:171], v147 offset:3072
	s_mov_b32 m0, s59
	v_lshl_add_u64 v[218:219], s[42:43], 0, v[132:133]
	ds_read_b128 v[174:177], v146 offset:32768
	ds_read_b128 v[178:181], v146 offset:33792
	ds_read_b128 v[182:185], v146 offset:34816
	ds_read_b128 v[192:195], v146 offset:35840
	ds_read_b128 v[196:199], v146 offset:36864
	ds_read_b128 v[200:203], v146 offset:37888
	ds_read_b128 v[204:207], v146 offset:38912
	ds_read_b128 v[208:211], v146 offset:39936
	global_load_lds_dwordx4 v[218:219], off
	v_lshl_add_u64 v[218:219], s[42:43], 0, v[130:131]
	s_mov_b32 m0, s60
	s_nop 0
	global_load_lds_dwordx4 v[218:219], off
	s_waitcnt vmcnt(8)
	s_waitcnt lgkmcnt(0)
	s_barrier
	s_setprio 1
	v_mfma_f32_16x16x32_bf16 v[124:127], v[134:137], v[174:177], v[124:127]
	v_mfma_f32_16x16x32_bf16 v[120:123], v[148:151], v[174:177], v[120:123]
	v_mfma_f32_16x16x32_bf16 v[108:111], v[134:137], v[182:185], v[108:111]
	v_mfma_f32_16x16x32_bf16 v[104:107], v[148:151], v[182:185], v[104:107]
	v_mfma_f32_16x16x32_bf16 v[92:95], v[134:137], v[196:199], v[92:95]
	v_mfma_f32_16x16x32_bf16 v[88:91], v[148:151], v[196:199], v[88:91]
	v_mfma_f32_16x16x32_bf16 v[76:79], v[134:137], v[204:207], v[76:79]
	v_mfma_f32_16x16x32_bf16 v[72:75], v[148:151], v[204:207], v[72:75]
	v_mfma_f32_16x16x32_bf16 v[124:127], v[138:141], v[178:181], v[124:127]
	v_mfma_f32_16x16x32_bf16 v[120:123], v[152:155], v[178:181], v[120:123]
	v_mfma_f32_16x16x32_bf16 v[108:111], v[138:141], v[192:195], v[108:111]
	v_mfma_f32_16x16x32_bf16 v[104:107], v[152:155], v[192:195], v[104:107]
	v_mfma_f32_16x16x32_bf16 v[92:95], v[138:141], v[200:203], v[92:95]
	v_mfma_f32_16x16x32_bf16 v[88:91], v[152:155], v[200:203], v[88:91]
	v_mfma_f32_16x16x32_bf16 v[76:79], v[138:141], v[208:211], v[76:79]
	v_mfma_f32_16x16x32_bf16 v[72:75], v[152:155], v[208:211], v[72:75]
	s_setprio 0
	s_setprio 1
	v_mfma_f32_16x16x32_bf16 v[116:119], v[156:159], v[174:177], v[116:119]
	v_mfma_f32_16x16x32_bf16 v[112:115], v[164:167], v[174:177], v[112:115]
	v_mfma_f32_16x16x32_bf16 v[100:103], v[156:159], v[182:185], v[100:103]
	v_mfma_f32_16x16x32_bf16 v[96:99], v[164:167], v[182:185], v[96:99]
	v_mfma_f32_16x16x32_bf16 v[84:87], v[156:159], v[196:199], v[84:87]
	v_mfma_f32_16x16x32_bf16 v[80:83], v[164:167], v[196:199], v[80:83]
	v_mfma_f32_16x16x32_bf16 v[68:71], v[156:159], v[204:207], v[68:71]
	v_mfma_f32_16x16x32_bf16 v[64:67], v[164:167], v[204:207], v[64:67]
	v_mfma_f32_16x16x32_bf16 v[116:119], v[160:163], v[178:181], v[116:119]
	v_mfma_f32_16x16x32_bf16 v[112:115], v[168:171], v[178:181], v[112:115]
	v_mfma_f32_16x16x32_bf16 v[100:103], v[160:163], v[192:195], v[100:103]
	v_mfma_f32_16x16x32_bf16 v[96:99], v[168:171], v[192:195], v[96:99]
	v_mfma_f32_16x16x32_bf16 v[84:87], v[160:163], v[200:203], v[84:87]
	v_mfma_f32_16x16x32_bf16 v[80:83], v[168:171], v[200:203], v[80:83]
	v_mfma_f32_16x16x32_bf16 v[68:71], v[160:163], v[208:211], v[68:71]
	v_mfma_f32_16x16x32_bf16 v[64:67], v[168:171], v[208:211], v[64:67]
	s_setprio 0
	s_barrier
; #define PG8_STAGE(bufoff, gbase, voff) do { _Pragma("unroll") for (int _i = 0; _i < 2; ++_i) \
;         __builtin_amdgcn_global_load_lds((const unsigned*)((const char*)(gbase) + (voff)[_i]), (PG8_LAS unsigned*)(lds + (bufoff) + ldsw + _i * 8192), 16, 0, 0); } while (0)
; #define PG8_LDA(dst, b, h) do { _Pragma("unroll") for (int m = 0; m < 4; ++m) _Pragma("unroll") for (int k = 0; k < 2; ++k) dst[m][k] = *(const PG8_LAS bf16x8*)(lds + PG8_SA(b, h) + aoff + m * 2048 + k * 1024); } while (0)
; #define PG8_MMA(ai, bj, At, Bt) do { __builtin_amdgcn_s_setprio(1); _Pragma("unroll") for (int m = 0; m < 4; ++m) _Pragma("unroll") for (int n = 0; n < 2; ++n) _Pragma("unroll") for (int k = 0; k < 2; ++k) \
;         acc[ai][bj][m][n] = __builtin_amdgcn_mfma_f32_16x16x32_bf16(Bt[n][k], At[m][k], acc[ai][bj][m][n], 0, 0, 0); __builtin_amdgcn_s_setprio(0); } while (0)
; #define PG8_WAIT_V(n) asm volatile("s_waitcnt vmcnt(" #n ")" ::: "memory")
; #define PG8_WAIT_L(n) asm volatile("s_waitcnt lgkmcnt(" #n ")" ::: "memory")
; #define PG8_BAR __builtin_amdgcn_s_barrier()
; #define PG8_SCHED __builtin_amdgcn_sched_barrier(0)
; template <class Epi, class Sched, bool ALIGN_EPI = false, bool SP2 = false>
; __device__ __forceinline__ void gemm_phase(PG8_LAS unsigned char* lds, const Gemm g, const Sched& S, const Epi& E) {
;     ...
;             PG8_LDA(At, 1, 1); PG8_STAGE(PG8_SB(1, 0), b3, voffB); PG8_STAGE(PG8_SB(1, 1), b3 + hstepB, voffB); PG8_STAGE(PG8_SA(1, 0), a3, voffA);
;             PG8_WAIT_V(8); PG8_WAIT_L(0); PG8_BAR; PG8_MMA(1, 0, At, B0); PG8_MMA(1, 1, At, B1); PG8_BAR; PG8_SCHED;
;     ...
;         if constexpr (ALIGN_EPI) { if (wr == 0) PG8_BAR; }
	s_mov_b32 m0, s65
	v_lshl_add_u64 v[186:187], v[186:187], 0, s[80:81]
	ds_read_b128 v[174:177], v146 offset:49152
	ds_read_b128 v[178:181], v146 offset:50176
	ds_read_b128 v[182:185], v146 offset:51200
	ds_read_b128 v[192:195], v146 offset:52224
	ds_read_b128 v[196:199], v146 offset:53248
	ds_read_b128 v[200:203], v146 offset:54272
	ds_read_b128 v[204:207], v146 offset:55296
	ds_read_b128 v[208:211], v146 offset:56320
	global_load_lds_dwordx4 v[186:187], off
	v_lshl_add_u64 v[186:187], v[212:213], 0, s[80:81]
	s_mov_b32 m0, s64
	s_nop 0
	global_load_lds_dwordx4 v[186:187], off
	v_lshl_add_u64 v[186:187], s[40:41], 0, v[172:173]
	s_mov_b32 m0, s75
	s_nop 0
	global_load_lds_dwordx4 v[186:187], off
	v_lshl_add_u64 v[186:187], s[40:41], 0, v[128:129]
	s_mov_b32 m0, s74
	s_nop 0
	global_load_lds_dwordx4 v[186:187], off
	v_lshl_add_u64 v[186:187], v[214:215], 0, s[80:81]
	s_mov_b32 m0, s61
	s_nop 0
	global_load_lds_dwordx4 v[186:187], off
	v_lshl_add_u64 v[186:187], v[216:217], 0, s[80:81]
	s_mov_b32 m0, s62
	s_nop 0
	global_load_lds_dwordx4 v[186:187], off
	s_waitcnt vmcnt(8)
	s_waitcnt lgkmcnt(0)
	s_barrier
	s_setprio 1
	v_mfma_f32_16x16x32_bf16 v[60:63], v[134:137], v[174:177], v[60:63]
	v_mfma_f32_16x16x32_bf16 v[56:59], v[148:151], v[174:177], v[56:59]
	v_mfma_f32_16x16x32_bf16 v[44:47], v[134:137], v[182:185], v[44:47]
	v_mfma_f32_16x16x32_bf16 v[40:43], v[148:151], v[182:185], v[40:43]
	v_mfma_f32_16x16x32_bf16 v[28:31], v[134:137], v[196:199], v[28:31]
	v_mfma_f32_16x16x32_bf16 v[24:27], v[148:151], v[196:199], v[24:27]
	v_mfma_f32_16x16x32_bf16 v[12:15], v[134:137], v[204:207], v[12:15]
	v_mfma_f32_16x16x32_bf16 v[8:11], v[148:151], v[204:207], v[8:11]
	v_mfma_f32_16x16x32_bf16 v[60:63], v[138:141], v[178:181], v[60:63]
	v_mfma_f32_16x16x32_bf16 v[56:59], v[152:155], v[178:181], v[56:59]
	v_mfma_f32_16x16x32_bf16 v[44:47], v[138:141], v[192:195], v[44:47]
	v_mfma_f32_16x16x32_bf16 v[40:43], v[152:155], v[192:195], v[40:43]
	v_mfma_f32_16x16x32_bf16 v[28:31], v[138:141], v[200:203], v[28:31]
	v_mfma_f32_16x16x32_bf16 v[24:27], v[152:155], v[200:203], v[24:27]
	v_mfma_f32_16x16x32_bf16 v[12:15], v[138:141], v[208:211], v[12:15]
	v_mfma_f32_16x16x32_bf16 v[8:11], v[152:155], v[208:211], v[8:11]
	s_setprio 0
	s_setprio 1
	v_mfma_f32_16x16x32_bf16 v[52:55], v[156:159], v[174:177], v[52:55]
	v_mfma_f32_16x16x32_bf16 v[48:51], v[164:167], v[174:177], v[48:51]
	v_mfma_f32_16x16x32_bf16 v[36:39], v[156:159], v[182:185], v[36:39]
	v_mfma_f32_16x16x32_bf16 v[32:35], v[164:167], v[182:185], v[32:35]
	v_mfma_f32_16x16x32_bf16 v[20:23], v[156:159], v[196:199], v[20:23]
	v_mfma_f32_16x16x32_bf16 v[16:19], v[164:167], v[196:199], v[16:19]
	v_mfma_f32_16x16x32_bf16 v[4:7], v[156:159], v[204:207], v[4:7]
	v_mfma_f32_16x16x32_bf16 v[0:3], v[164:167], v[204:207], v[0:3]
	v_mfma_f32_16x16x32_bf16 v[52:55], v[160:163], v[178:181], v[52:55]
	v_mfma_f32_16x16x32_bf16 v[48:51], v[168:171], v[178:181], v[48:51]
	v_mfma_f32_16x16x32_bf16 v[36:39], v[160:163], v[192:195], v[36:39]
	v_mfma_f32_16x16x32_bf16 v[32:35], v[168:171], v[192:195], v[32:35]
	v_mfma_f32_16x16x32_bf16 v[20:23], v[160:163], v[200:203], v[20:23]
	v_mfma_f32_16x16x32_bf16 v[16:19], v[168:171], v[200:203], v[16:19]
	v_mfma_f32_16x16x32_bf16 v[4:7], v[160:163], v[208:211], v[4:7]
	v_mfma_f32_16x16x32_bf16 v[0:3], v[168:171], v[208:211], v[0:3]
	s_setprio 0
	s_barrier
	s_movk_i32 s42, 0x100
	s_andn2_b64 vcc, exec, s[8:9]
	s_mov_b64 s[40:41], -1
	s_mov_b64 s[8:9], 0
	s_cbranch_vccz .LBB0_436
	s_and_b64 vcc, exec, s[20:21]
	s_cbranch_vccz .LBB0_439
	s_barrier

;     __device__ __forceinline__ bool next(int i, Unit& u) const { const int L = i * G + c; if (L >= nsub) return false; u.pk = L >> 4; u.pm = MLAT / BM + (L & 3); u.pn = (L >> 2) & 3; return true; }
; #define PG8_STAGE(bufoff, gbase, voff) do { _Pragma("unroll") for (int _i = 0; _i < 2; ++_i) \
;         __builtin_amdgcn_global_load_lds((const unsigned*)((const char*)(gbase) + (voff)[_i]), (PG8_LAS unsigned*)(lds + (bufoff) + ldsw + _i * 8192), 16, 0, 0); } while (0)
; #define PG8_LDA(dst, b, h) do { _Pragma("unroll") for (int m = 0; m < 4; ++m) _Pragma("unroll") for (int k = 0; k < 2; ++k) dst[m][k] = *(const PG8_LAS bf16x8*)(lds + PG8_SA(b, h) + aoff + m * 2048 + k * 1024); } while (0)
; #define PG8_LDB(dst, b, h) do { _Pragma("unroll") for (int n = 0; n < 2; ++n) _Pragma("unroll") for (int k = 0; k < 2; ++k) dst[n][k] = *(const PG8_LAS bf16x8*)(lds + PG8_SB(b, h) + boff + n * 2048 + k * 1024); } while (0)
; #define PG8_WAIT_V(n) asm volatile("s_waitcnt vmcnt(" #n ")" ::: "memory")
; #define PG8_WAIT_L(n) asm volatile("s_waitcnt lgkmcnt(" #n ")" ::: "memory")
; template <class Epi, class Sched, bool ALIGN_EPI = false, bool SP2 = false>
; __device__ __forceinline__ void gemm_phase(PG8_LAS unsigned char* lds, const Gemm g, const Sched& S, const Epi& E) {
;     ...
;         const bool has_next = S.next(ui + 1, nxt);
;         const char* nA = has_next ? g.a_of(nxt) : cA; const char* nB = has_next ? g.b_of(nxt) : cB;
;         for (int t = 0; t < nt; t += 2) {
;             const bool last = (t == nt - 2);
;             const char* a1 = cA + (size_t)(t + 1) * kstep;
;             const char* a2 = last ? nA : cA + (size_t)(t + 2) * kstep; const char* b2 = last ? nB : cB + (size_t)(t + 2) * kstep;
;             const char* a3 = a2 + kstep; const char* b3 = b2 + kstep;
;             if (last && has_next) S.a_ready(nxt);
;             if constexpr (SP2) {
;             PG8_LDB(B0, 0, 0); PG8_LDB(B1, 0, 1); PG8_SCHED; PG8_LDA(At, 0, 0); PG8_STAGE(PG8_SA(1, 1), a1 + hstepA, voffA);
;             PG8_WAIT_V(8); PG8_WAIT_L(0); PG8_BAR; PG8_MMA(0, 0, At, B0); PG8_MMA(0, 1, At, B1); PG8_BAR; PG8_SCHED;
;             PG8_LDA(At, 0, 1); PG8_STAGE(PG8_SB(0, 0), b2, voffB); PG8_STAGE(PG8_SB(0, 1), b2 + hstepB, voffB); PG8_STAGE(PG8_SA(0, 0), a2, voffA);
;             PG8_WAIT_V(8); PG8_WAIT_L(0); PG8_BAR; PG8_MMA(1, 0, At, B0); PG8_MMA(1, 1, At, B1); PG8_BAR; PG8_SCHED;
.LBB0_533:
	s_add_u32 s40, s38, 0xfff80080
	s_addc_u32 s41, s39, -1
	s_add_i32 s70, 0, 0x10000
	s_cmp_eq_u32 s68, 28
	s_cselect_b32 s43, s27, s41
	s_cselect_b32 s42, s35, s40
	s_cselect_b32 s41, s25, s67
	s_cselect_b32 s40, s37, s66
	s_add_i32 s72, 0, 0x14000
	v_add_u32_e32 v92, s70, v181
	v_add_u32_e32 v164, s72, v181
	ds_read_b128 v[72:75], v92
	ds_read_b128 v[76:79], v92 offset:1024
	ds_read_b128 v[88:91], v92 offset:2048
	ds_read_b128 v[92:95], v92 offset:3072
	ds_read_b128 v[152:155], v164
	ds_read_b128 v[156:159], v164 offset:1024
	ds_read_b128 v[160:163], v164 offset:2048
	ds_read_b128 v[164:167], v164 offset:3072
	s_add_i32 m0, s51, 0xc000
	ds_read_b128 v[168:171], v186
	ds_read_b128 v[174:177], v186 offset:1024
	ds_read_b128 v[192:195], v186 offset:2048
	ds_read_b128 v[196:199], v186 offset:3072
	ds_read_b128 v[200:203], v186 offset:4096
	ds_read_b128 v[204:207], v186 offset:5120
	ds_read_b128 v[208:211], v186 offset:6144
	ds_read_b128 v[212:215], v186 offset:7168
	global_load_lds_dwordx4 v148, s[38:39]
	s_add_i32 m0, s51, 0xe000
	s_nop 0
	global_load_lds_dwordx4 v150, s[38:39]
	s_waitcnt vmcnt(8)
	s_waitcnt lgkmcnt(0)
	s_barrier
	s_setprio 1
	v_mfma_f32_16x16x32_bf16 v[140:143], v[72:75], v[168:171], v[140:143]
	v_mfma_f32_16x16x32_bf16 v[136:139], v[88:91], v[168:171], v[136:139]
	v_mfma_f32_16x16x32_bf16 v[124:127], v[72:75], v[192:195], v[124:127]
	v_mfma_f32_16x16x32_bf16 v[120:123], v[88:91], v[192:195], v[120:123]
	v_mfma_f32_16x16x32_bf16 v[108:111], v[72:75], v[200:203], v[108:111]
	v_mfma_f32_16x16x32_bf16 v[104:107], v[88:91], v[200:203], v[104:107]
	v_mfma_f32_16x16x32_bf16 v[84:87], v[72:75], v[208:211], v[84:87]
	v_mfma_f32_16x16x32_bf16 v[80:83], v[88:91], v[208:211], v[80:83]
	v_mfma_f32_16x16x32_bf16 v[140:143], v[76:79], v[174:177], v[140:143]
	v_mfma_f32_16x16x32_bf16 v[136:139], v[92:95], v[174:177], v[136:139]
	v_mfma_f32_16x16x32_bf16 v[124:127], v[76:79], v[196:199], v[124:127]
	v_mfma_f32_16x16x32_bf16 v[120:123], v[92:95], v[196:199], v[120:123]
	v_mfma_f32_16x16x32_bf16 v[108:111], v[76:79], v[204:207], v[108:111]
	v_mfma_f32_16x16x32_bf16 v[104:107], v[92:95], v[204:207], v[104:107]
	v_mfma_f32_16x16x32_bf16 v[84:87], v[76:79], v[212:215], v[84:87]
	v_mfma_f32_16x16x32_bf16 v[80:83], v[92:95], v[212:215], v[80:83]
	s_setprio 0
	s_setprio 1
	v_mfma_f32_16x16x32_bf16 v[132:135], v[152:155], v[168:171], v[132:135]
	v_mfma_f32_16x16x32_bf16 v[128:131], v[160:163], v[168:171], v[128:131]
	v_mfma_f32_16x16x32_bf16 v[116:119], v[152:155], v[192:195], v[116:119]
	v_mfma_f32_16x16x32_bf16 v[112:115], v[160:163], v[192:195], v[112:115]
	v_mfma_f32_16x16x32_bf16 v[100:103], v[152:155], v[200:203], v[100:103]
	v_mfma_f32_16x16x32_bf16 v[96:99], v[160:163], v[200:203], v[96:99]
	v_mfma_f32_16x16x32_bf16 v[68:71], v[152:155], v[208:211], v[68:71]
	v_mfma_f32_16x16x32_bf16 v[64:67], v[160:163], v[208:211], v[64:67]
	v_mfma_f32_16x16x32_bf16 v[132:135], v[156:159], v[174:177], v[132:135]
	v_mfma_f32_16x16x32_bf16 v[128:131], v[164:167], v[174:177], v[128:131]
	v_mfma_f32_16x16x32_bf16 v[116:119], v[156:159], v[196:199], v[116:119]
	v_mfma_f32_16x16x32_bf16 v[112:115], v[164:167], v[196:199], v[112:115]
	v_mfma_f32_16x16x32_bf16 v[100:103], v[156:159], v[204:207], v[100:103]
	v_mfma_f32_16x16x32_bf16 v[96:99], v[164:167], v[204:207], v[96:99]
	v_mfma_f32_16x16x32_bf16 v[68:71], v[156:159], v[212:215], v[68:71]
	v_mfma_f32_16x16x32_bf16 v[64:67], v[164:167], v[212:215], v[64:67]
	s_setprio 0
	s_barrier
	s_add_i32 s70, s70, s50
	v_lshl_add_u64 v[178:179], s[40:41], 0, v[172:173]
	s_mov_b32 m0, s70
	ds_read_b128 v[168:171], v186 offset:16384
	ds_read_b128 v[174:177], v186 offset:17408
	ds_read_b128 v[192:195], v186 offset:18432
	ds_read_b128 v[196:199], v186 offset:19456
	ds_read_b128 v[200:203], v186 offset:20480
	ds_read_b128 v[204:207], v186 offset:21504
	ds_read_b128 v[208:211], v186 offset:22528
	ds_read_b128 v[212:215], v186 offset:23552
	global_load_lds_dwordx4 v[178:179], off
	s_add_i32 m0, s70, 0x2000
	s_add_u32 s70, s40, 0x80000
	v_lshl_add_u64 v[216:217], s[40:41], 0, v[144:145]
	s_addc_u32 s71, s41, 0
	s_add_i32 s72, s72, s50
	global_load_lds_dwordx4 v[216:217], off
	s_mov_b32 m0, s72
	v_lshl_add_u64 v[220:221], s[42:43], 0, v[144:145]
	global_load_lds_dwordx4 v172, s[70:71]
	s_add_i32 m0, s72, 0x2000
	s_nop 0
	global_load_lds_dwordx4 v144, s[70:71]
	v_lshl_add_u64 v[218:219], s[42:43], 0, v[172:173]
	s_mov_b32 m0, s51
	s_nop 0
	global_load_lds_dwordx4 v[218:219], off
	s_mov_b32 m0, s52
	s_nop 0
	global_load_lds_dwordx4 v[220:221], off
	s_waitcnt vmcnt(8)
	s_waitcnt lgkmcnt(0)
	s_barrier
; #define PG8_STAGE(bufoff, gbase, voff) do { _Pragma("unroll") for (int _i = 0; _i < 2; ++_i) \
;         __builtin_amdgcn_global_load_lds((const unsigned*)((const char*)(gbase) + (voff)[_i]), (PG8_LAS unsigned*)(lds + (bufoff) + ldsw + _i * 8192), 16, 0, 0); } while (0)
; #define PG8_LDA(dst, b, h) do { _Pragma("unroll") for (int m = 0; m < 4; ++m) _Pragma("unroll") for (int k = 0; k < 2; ++k) dst[m][k] = *(const PG8_LAS bf16x8*)(lds + PG8_SA(b, h) + aoff + m * 2048 + k * 1024); } while (0)
; #define PG8_LDB(dst, b, h) do { _Pragma("unroll") for (int n = 0; n < 2; ++n) _Pragma("unroll") for (int k = 0; k < 2; ++k) dst[n][k] = *(const PG8_LAS bf16x8*)(lds + PG8_SB(b, h) + boff + n * 2048 + k * 1024); } while (0)
; #define PG8_MMA(ai, bj, At, Bt) do { __builtin_amdgcn_s_setprio(1); _Pragma("unroll") for (int m = 0; m < 4; ++m) _Pragma("unroll") for (int n = 0; n < 2; ++n) _Pragma("unroll") for (int k = 0; k < 2; ++k) \
;         acc[ai][bj][m][n] = __builtin_amdgcn_mfma_f32_16x16x32_bf16(Bt[n][k], At[m][k], acc[ai][bj][m][n], 0, 0, 0); __builtin_amdgcn_s_setprio(0); } while (0)
; #define PG8_WAIT_V(n) asm volatile("s_waitcnt vmcnt(" #n ")" ::: "memory")
; #define PG8_WAIT_L(n) asm volatile("s_waitcnt lgkmcnt(" #n ")" ::: "memory")
; #define PG8_BAR __builtin_amdgcn_s_barrier()
; #define PG8_SCHED __builtin_amdgcn_sched_barrier(0)
; template <class Epi, class Sched, bool ALIGN_EPI = false, bool SP2 = false>
; __device__ __forceinline__ void gemm_phase(PG8_LAS unsigned char* lds, const Gemm g, const Sched& S, const Epi& E) {
;     ...
;             if constexpr (SP2) {
;             PG8_LDB(B0, 0, 0); PG8_LDB(B1, 0, 1); PG8_SCHED; PG8_LDA(At, 0, 0); PG8_STAGE(PG8_SA(1, 1), a1 + hstepA, voffA);
;             PG8_WAIT_V(8); PG8_WAIT_L(0); PG8_BAR; PG8_MMA(0, 0, At, B0); PG8_MMA(0, 1, At, B1); PG8_BAR; PG8_SCHED;
;             PG8_LDA(At, 0, 1); PG8_STAGE(PG8_SB(0, 0), b2, voffB); PG8_STAGE(PG8_SB(0, 1), b2 + hstepB, voffB); PG8_STAGE(PG8_SA(0, 0), a2, voffA);
;             PG8_WAIT_V(8); PG8_WAIT_L(0); PG8_BAR; PG8_MMA(1, 0, At, B0); PG8_MMA(1, 1, At, B1); PG8_BAR; PG8_SCHED;
;             PG8_LDB(B0, 1, 0); PG8_LDB(B1, 1, 1); PG8_SCHED; PG8_LDA(At, 1, 0); PG8_STAGE(PG8_SA(0, 1), a2 + hstepA, voffA);
;             PG8_WAIT_V(8); PG8_WAIT_L(0); PG8_BAR; PG8_MMA(0, 0, At, B0); PG8_MMA(0, 1, At, B1); PG8_BAR; PG8_SCHED;
	s_setprio 1
	v_mfma_f32_16x16x32_bf16 v[60:63], v[72:75], v[168:171], v[60:63]
	v_mfma_f32_16x16x32_bf16 v[56:59], v[88:91], v[168:171], v[56:59]
	v_mfma_f32_16x16x32_bf16 v[44:47], v[72:75], v[192:195], v[44:47]
	v_mfma_f32_16x16x32_bf16 v[40:43], v[88:91], v[192:195], v[40:43]
	v_mfma_f32_16x16x32_bf16 v[28:31], v[72:75], v[200:203], v[28:31]
	v_mfma_f32_16x16x32_bf16 v[24:27], v[88:91], v[200:203], v[24:27]
	v_mfma_f32_16x16x32_bf16 v[12:15], v[72:75], v[208:211], v[12:15]
	v_mfma_f32_16x16x32_bf16 v[8:11], v[88:91], v[208:211], v[8:11]
	v_mfma_f32_16x16x32_bf16 v[60:63], v[76:79], v[174:177], v[60:63]
	v_mfma_f32_16x16x32_bf16 v[56:59], v[92:95], v[174:177], v[56:59]
	v_mfma_f32_16x16x32_bf16 v[44:47], v[76:79], v[196:199], v[44:47]
	v_mfma_f32_16x16x32_bf16 v[40:43], v[92:95], v[196:199], v[40:43]
	v_mfma_f32_16x16x32_bf16 v[28:31], v[76:79], v[204:207], v[28:31]
	v_mfma_f32_16x16x32_bf16 v[24:27], v[92:95], v[204:207], v[24:27]
	v_mfma_f32_16x16x32_bf16 v[12:15], v[76:79], v[212:215], v[12:15]
	v_mfma_f32_16x16x32_bf16 v[8:11], v[92:95], v[212:215], v[8:11]
	s_setprio 0
	s_setprio 1
	v_mfma_f32_16x16x32_bf16 v[52:55], v[152:155], v[168:171], v[52:55]
	v_mfma_f32_16x16x32_bf16 v[48:51], v[160:163], v[168:171], v[48:51]
	v_mfma_f32_16x16x32_bf16 v[36:39], v[152:155], v[192:195], v[36:39]
	v_mfma_f32_16x16x32_bf16 v[32:35], v[160:163], v[192:195], v[32:35]
	v_mfma_f32_16x16x32_bf16 v[20:23], v[152:155], v[200:203], v[20:23]
	v_mfma_f32_16x16x32_bf16 v[16:19], v[160:163], v[200:203], v[16:19]
	v_mfma_f32_16x16x32_bf16 v[4:7], v[152:155], v[208:211], v[4:7]
	v_mfma_f32_16x16x32_bf16 v[0:3], v[160:163], v[208:211], v[0:3]
	v_mfma_f32_16x16x32_bf16 v[52:55], v[156:159], v[174:177], v[52:55]
	v_mfma_f32_16x16x32_bf16 v[48:51], v[164:167], v[174:177], v[48:51]
	v_mfma_f32_16x16x32_bf16 v[36:39], v[156:159], v[196:199], v[36:39]
	v_mfma_f32_16x16x32_bf16 v[32:35], v[164:167], v[196:199], v[32:35]
	v_mfma_f32_16x16x32_bf16 v[20:23], v[156:159], v[204:207], v[20:23]
	v_mfma_f32_16x16x32_bf16 v[16:19], v[164:167], v[204:207], v[16:19]
	v_mfma_f32_16x16x32_bf16 v[4:7], v[156:159], v[212:215], v[4:7]
	v_mfma_f32_16x16x32_bf16 v[0:3], v[164:167], v[212:215], v[0:3]
	s_setprio 0
	s_barrier
	s_add_i32 s70, 0, 0x18000
	s_add_i32 s71, 0, 0x1c000
	v_add_u32_e32 v92, s70, v181
	v_add_u32_e32 v164, s71, v181
	ds_read_b128 v[72:75], v92
	ds_read_b128 v[76:79], v92 offset:1024
	ds_read_b128 v[88:91], v92 offset:2048
	ds_read_b128 v[92:95], v92 offset:3072
	ds_read_b128 v[152:155], v164
	ds_read_b128 v[156:159], v164 offset:1024
	ds_read_b128 v[160:163], v164 offset:2048
	ds_read_b128 v[164:167], v164 offset:3072
	s_add_u32 s42, s42, 0x80000
	s_addc_u32 s43, s43, 0
	s_mov_b32 m0, s53
	ds_read_b128 v[168:171], v186 offset:32768
	ds_read_b128 v[174:177], v186 offset:33792
	ds_read_b128 v[192:195], v186 offset:34816
	ds_read_b128 v[196:199], v186 offset:35840
	ds_read_b128 v[200:203], v186 offset:36864
	ds_read_b128 v[204:207], v186 offset:37888
	ds_read_b128 v[208:211], v186 offset:38912
	ds_read_b128 v[212:215], v186 offset:39936
	global_load_lds_dwordx4 v172, s[42:43]
	v_lshl_add_u64 v[222:223], s[42:43], 0, v[144:145]
	s_mov_b32 m0, s56
	s_nop 0
	global_load_lds_dwordx4 v[222:223], off
	s_waitcnt vmcnt(8)
	s_waitcnt lgkmcnt(0)
	s_barrier
	s_setprio 1
	v_mfma_f32_16x16x32_bf16 v[140:143], v[72:75], v[168:171], v[140:143]
	v_mfma_f32_16x16x32_bf16 v[136:139], v[88:91], v[168:171], v[136:139]
	v_mfma_f32_16x16x32_bf16 v[124:127], v[72:75], v[192:195], v[124:127]
	v_mfma_f32_16x16x32_bf16 v[120:123], v[88:91], v[192:195], v[120:123]
	v_mfma_f32_16x16x32_bf16 v[108:111], v[72:75], v[200:203], v[108:111]
	v_mfma_f32_16x16x32_bf16 v[104:107], v[88:91], v[200:203], v[104:107]
	v_mfma_f32_16x16x32_bf16 v[84:87], v[72:75], v[208:211], v[84:87]
	v_mfma_f32_16x16x32_bf16 v[80:83], v[88:91], v[208:211], v[80:83]
	v_mfma_f32_16x16x32_bf16 v[140:143], v[76:79], v[174:177], v[140:143]
	v_mfma_f32_16x16x32_bf16 v[136:139], v[92:95], v[174:177], v[136:139]
	v_mfma_f32_16x16x32_bf16 v[124:127], v[76:79], v[196:199], v[124:127]
	v_mfma_f32_16x16x32_bf16 v[120:123], v[92:95], v[196:199], v[120:123]
	v_mfma_f32_16x16x32_bf16 v[108:111], v[76:79], v[204:207], v[108:111]
	v_mfma_f32_16x16x32_bf16 v[104:107], v[92:95], v[204:207], v[104:107]
	v_mfma_f32_16x16x32_bf16 v[84:87], v[76:79], v[212:215], v[84:87]
	v_mfma_f32_16x16x32_bf16 v[80:83], v[92:95], v[212:215], v[80:83]
	s_setprio 0
	s_setprio 1
	v_mfma_f32_16x16x32_bf16 v[132:135], v[152:155], v[168:171], v[132:135]
	v_mfma_f32_16x16x32_bf16 v[128:131], v[160:163], v[168:171], v[128:131]
	v_mfma_f32_16x16x32_bf16 v[116:119], v[152:155], v[192:195], v[116:119]
	v_mfma_f32_16x16x32_bf16 v[112:115], v[160:163], v[192:195], v[112:115]
	v_mfma_f32_16x16x32_bf16 v[100:103], v[152:155], v[200:203], v[100:103]
	v_mfma_f32_16x16x32_bf16 v[96:99], v[160:163], v[200:203], v[96:99]
	v_mfma_f32_16x16x32_bf16 v[68:71], v[152:155], v[208:211], v[68:71]
	v_mfma_f32_16x16x32_bf16 v[64:67], v[160:163], v[208:211], v[64:67]
	v_mfma_f32_16x16x32_bf16 v[132:135], v[156:159], v[174:177], v[132:135]
	v_mfma_f32_16x16x32_bf16 v[128:131], v[164:167], v[174:177], v[128:131]
	v_mfma_f32_16x16x32_bf16 v[116:119], v[156:159], v[196:199], v[116:119]
	v_mfma_f32_16x16x32_bf16 v[112:115], v[164:167], v[196:199], v[112:115]
	v_mfma_f32_16x16x32_bf16 v[100:103], v[156:159], v[204:207], v[100:103]
	v_mfma_f32_16x16x32_bf16 v[96:99], v[164:167], v[204:207], v[96:99]
	v_mfma_f32_16x16x32_bf16 v[68:71], v[156:159], v[212:215], v[68:71]
	v_mfma_f32_16x16x32_bf16 v[64:67], v[164:167], v[212:215], v[64:67]
	s_setprio 0
	s_barrier
; #define PG8_STAGE(bufoff, gbase, voff) do { _Pragma("unroll") for (int _i = 0; _i < 2; ++_i) \
;         __builtin_amdgcn_global_load_lds((const unsigned*)((const char*)(gbase) + (voff)[_i]), (PG8_LAS unsigned*)(lds + (bufoff) + ldsw + _i * 8192), 16, 0, 0); } while (0)
; #define PG8_LDA(dst, b, h) do { _Pragma("unroll") for (int m = 0; m < 4; ++m) _Pragma("unroll") for (int k = 0; k < 2; ++k) dst[m][k] = *(const PG8_LAS bf16x8*)(lds + PG8_SA(b, h) + aoff + m * 2048 + k * 1024); } while (0)
; #define PG8_MMA(ai, bj, At, Bt) do { __builtin_amdgcn_s_setprio(1); _Pragma("unroll") for (int m = 0; m < 4; ++m) _Pragma("unroll") for (int n = 0; n < 2; ++n) _Pragma("unroll") for (int k = 0; k < 2; ++k) \
;         acc[ai][bj][m][n] = __builtin_amdgcn_mfma_f32_16x16x32_bf16(Bt[n][k], At[m][k], acc[ai][bj][m][n], 0, 0, 0); __builtin_amdgcn_s_setprio(0); } while (0)
; #define PG8_WAIT_V(n) asm volatile("s_waitcnt vmcnt(" #n ")" ::: "memory")
; #define PG8_WAIT_L(n) asm volatile("s_waitcnt lgkmcnt(" #n ")" ::: "memory")
; #define PG8_BAR __builtin_amdgcn_s_barrier()
; #define PG8_SCHED __builtin_amdgcn_sched_barrier(0)
; template <class Epi, class Sched, bool ALIGN_EPI = false, bool SP2 = false>
; __device__ __forceinline__ void gemm_phase(PG8_LAS unsigned char* lds, const Gemm g, const Sched& S, const Epi& E) {
;     ...
;             PG8_LDA(At, 1, 1); PG8_STAGE(PG8_SB(1, 0), b3, voffB); PG8_STAGE(PG8_SB(1, 1), b3 + hstepB, voffB); PG8_STAGE(PG8_SA(1, 0), a3, voffA);
;             PG8_WAIT_V(8); PG8_WAIT_L(0); PG8_BAR; PG8_MMA(1, 0, At, B0); PG8_MMA(1, 1, At, B1); PG8_BAR; PG8_SCHED;
;     ...
;         if constexpr (ALIGN_EPI) { if (wr == 0) PG8_BAR; }
	s_add_i32 s42, s70, s50
	v_lshl_add_u64 v[178:179], v[178:179], 0, s[80:81]
	s_mov_b32 m0, s42
	ds_read_b128 v[168:171], v186 offset:49152
	ds_read_b128 v[174:177], v186 offset:50176
	ds_read_b128 v[192:195], v186 offset:51200
	ds_read_b128 v[196:199], v186 offset:52224
	ds_read_b128 v[200:203], v186 offset:53248
	ds_read_b128 v[204:207], v186 offset:54272
	ds_read_b128 v[208:211], v186 offset:55296
	ds_read_b128 v[212:215], v186 offset:56320
	global_load_lds_dwordx4 v[178:179], off
	s_add_i32 m0, s42, 0x2000
	s_add_u32 s40, s40, 0x80080
	v_lshl_add_u64 v[178:179], v[216:217], 0, s[80:81]
	s_addc_u32 s41, s41, 0
	s_add_i32 s42, s71, s50
	global_load_lds_dwordx4 v[178:179], off
	s_mov_b32 m0, s42
	s_nop 0
	global_load_lds_dwordx4 v172, s[40:41]
	s_add_i32 m0, s42, 0x2000
	s_nop 0
	global_load_lds_dwordx4 v144, s[40:41]
	v_lshl_add_u64 v[178:179], v[218:219], 0, s[80:81]
	s_mov_b32 m0, s61
	s_nop 0
	global_load_lds_dwordx4 v[178:179], off
	v_lshl_add_u64 v[178:179], v[220:221], 0, s[80:81]
	s_mov_b32 m0, s62
	s_nop 0
	global_load_lds_dwordx4 v[178:179], off
	s_waitcnt vmcnt(8)
	s_waitcnt lgkmcnt(0)
	s_barrier
	s_setprio 1
	v_mfma_f32_16x16x32_bf16 v[60:63], v[72:75], v[168:171], v[60:63]
	v_mfma_f32_16x16x32_bf16 v[56:59], v[88:91], v[168:171], v[56:59]
	v_mfma_f32_16x16x32_bf16 v[44:47], v[72:75], v[192:195], v[44:47]
	v_mfma_f32_16x16x32_bf16 v[40:43], v[88:91], v[192:195], v[40:43]
	v_mfma_f32_16x16x32_bf16 v[28:31], v[72:75], v[200:203], v[28:31]
	v_mfma_f32_16x16x32_bf16 v[24:27], v[88:91], v[200:203], v[24:27]
	v_mfma_f32_16x16x32_bf16 v[12:15], v[72:75], v[208:211], v[12:15]
	v_mfma_f32_16x16x32_bf16 v[8:11], v[88:91], v[208:211], v[8:11]
	v_mfma_f32_16x16x32_bf16 v[60:63], v[76:79], v[174:177], v[60:63]
	v_mfma_f32_16x16x32_bf16 v[56:59], v[92:95], v[174:177], v[56:59]
	v_mfma_f32_16x16x32_bf16 v[44:47], v[76:79], v[196:199], v[44:47]
	v_mfma_f32_16x16x32_bf16 v[40:43], v[92:95], v[196:199], v[40:43]
	v_mfma_f32_16x16x32_bf16 v[28:31], v[76:79], v[204:207], v[28:31]
	v_mfma_f32_16x16x32_bf16 v[24:27], v[92:95], v[204:207], v[24:27]
	v_mfma_f32_16x16x32_bf16 v[12:15], v[76:79], v[212:215], v[12:15]
	v_mfma_f32_16x16x32_bf16 v[8:11], v[92:95], v[212:215], v[8:11]
	s_setprio 0
	s_setprio 1
	v_mfma_f32_16x16x32_bf16 v[52:55], v[152:155], v[168:171], v[52:55]
	v_mfma_f32_16x16x32_bf16 v[48:51], v[160:163], v[168:171], v[48:51]
	v_mfma_f32_16x16x32_bf16 v[36:39], v[152:155], v[192:195], v[36:39]
	v_mfma_f32_16x16x32_bf16 v[32:35], v[160:163], v[192:195], v[32:35]
	v_mfma_f32_16x16x32_bf16 v[20:23], v[152:155], v[200:203], v[20:23]
	v_mfma_f32_16x16x32_bf16 v[16:19], v[160:163], v[200:203], v[16:19]
	v_mfma_f32_16x16x32_bf16 v[4:7], v[152:155], v[208:211], v[4:7]
	v_mfma_f32_16x16x32_bf16 v[0:3], v[160:163], v[208:211], v[0:3]
	v_mfma_f32_16x16x32_bf16 v[52:55], v[156:159], v[174:177], v[52:55]
	v_mfma_f32_16x16x32_bf16 v[48:51], v[164:167], v[174:177], v[48:51]
	v_mfma_f32_16x16x32_bf16 v[36:39], v[156:159], v[196:199], v[36:39]
	v_mfma_f32_16x16x32_bf16 v[32:35], v[164:167], v[196:199], v[32:35]
	v_mfma_f32_16x16x32_bf16 v[20:23], v[156:159], v[204:207], v[20:23]
	v_mfma_f32_16x16x32_bf16 v[16:19], v[164:167], v[204:207], v[16:19]
	v_mfma_f32_16x16x32_bf16 v[4:7], v[156:159], v[212:215], v[4:7]
	v_mfma_f32_16x16x32_bf16 v[0:3], v[164:167], v[212:215], v[0:3]
	s_setprio 0
	s_barrier
	s_add_i32 s68, s68, 2
	s_add_u32 s38, s38, 0x100
	s_addc_u32 s39, s39, 0
	s_add_u32 s66, s66, 0x100
	s_addc_u32 s67, s67, 0
	s_cmp_gt_u32 s68, 29
	s_cbranch_scc0 .LBB0_533
	s_and_b64 vcc, exec, s[22:23]
	s_cbranch_vccz .LBB0_536
	s_barrier

;     __device__ __forceinline__ bool next(int i, Unit& u) const { const int L = i * G + c; if (L >= nsub) return false; u.pk = L >> 4; u.pm = MLAT / BM + (L & 3); u.pn = (L >> 2) & 3; return true; }
; #define PG8_STAGE(bufoff, gbase, voff) do { _Pragma("unroll") for (int _i = 0; _i < 2; ++_i) \
;         __builtin_amdgcn_global_load_lds((const unsigned*)((const char*)(gbase) + (voff)[_i]), (PG8_LAS unsigned*)(lds + (bufoff) + ldsw + _i * 8192), 16, 0, 0); } while (0)
; #define PG8_LDA(dst, b, h) do { _Pragma("unroll") for (int m = 0; m < 4; ++m) _Pragma("unroll") for (int k = 0; k < 2; ++k) dst[m][k] = *(const PG8_LAS bf16x8*)(lds + PG8_SA(b, h) + aoff + m * 2048 + k * 1024); } while (0)
; #define PG8_LDB(dst, b, h) do { _Pragma("unroll") for (int n = 0; n < 2; ++n) _Pragma("unroll") for (int k = 0; k < 2; ++k) dst[n][k] = *(const PG8_LAS bf16x8*)(lds + PG8_SB(b, h) + boff + n * 2048 + k * 1024); } while (0)
; #define PG8_WAIT_V(n) asm volatile("s_waitcnt vmcnt(" #n ")" ::: "memory")
; #define PG8_WAIT_L(n) asm volatile("s_waitcnt lgkmcnt(" #n ")" ::: "memory")
; template <class Epi, class Sched, bool ALIGN_EPI = false, bool SP2 = false>
; __device__ __forceinline__ void gemm_phase(PG8_LAS unsigned char* lds, const Gemm g, const Sched& S, const Epi& E) {
;     ...
;         const bool has_next = S.next(ui + 1, nxt);
;         const char* nA = has_next ? g.a_of(nxt) : cA; const char* nB = has_next ? g.b_of(nxt) : cB;
;         for (int t = 0; t < nt; t += 2) {
;             const bool last = (t == nt - 2);
;             const char* a1 = cA + (size_t)(t + 1) * kstep;
;             const char* a2 = last ? nA : cA + (size_t)(t + 2) * kstep; const char* b2 = last ? nB : cB + (size_t)(t + 2) * kstep;
;             const char* a3 = a2 + kstep; const char* b3 = b2 + kstep;
;             if (last && has_next) S.a_ready(nxt);
;             if constexpr (SP2) {
;             PG8_LDB(B0, 0, 0); PG8_LDB(B1, 0, 1); PG8_SCHED; PG8_LDA(At, 0, 0); PG8_STAGE(PG8_SA(1, 1), a1 + hstepA, voffA);
;             PG8_WAIT_V(8); PG8_WAIT_L(0); PG8_BAR; PG8_MMA(0, 0, At, B0); PG8_MMA(0, 1, At, B1); PG8_BAR; PG8_SCHED;
;             PG8_LDA(At, 0, 1); PG8_STAGE(PG8_SB(0, 0), b2, voffB); PG8_STAGE(PG8_SB(0, 1), b2 + hstepB, voffB); PG8_STAGE(PG8_SA(0, 0), a2, voffA);
;             PG8_WAIT_V(8); PG8_WAIT_L(0); PG8_BAR; PG8_MMA(1, 0, At, B0); PG8_MMA(1, 1, At, B1); PG8_BAR; PG8_SCHED;
.LBB0_570:
	s_add_u32 s23, s26, s19
	s_addc_u32 s40, s27, 0
	s_add_u32 s36, s23, 0x100
	s_addc_u32 s37, s40, 0
	s_and_b64 s[34:35], s[30:31], exec
	s_cselect_b32 s37, s17, s37
	s_cselect_b32 s36, s16, s36
	s_add_u32 s19, s24, s19
	s_addc_u32 s34, s25, 0
	s_add_u32 s19, s19, 0x100
	s_addc_u32 s34, s34, 0
	s_add_i32 s68, 0, 0x10000
	s_and_b64 s[30:31], s[30:31], exec
	s_cselect_b32 s39, s21, s34
	s_cselect_b32 s38, s20, s19
	s_add_i32 s31, 0, 0x14000
	s_add_u32 s42, s23, 0x80080
	s_addc_u32 s43, s40, 0
	s_add_i32 s67, s68, s50
	s_add_i32 m0, s51, 0xc000
	s_add_i32 s71, s51, 0xe000
	s_add_i32 s64, s67, 0x2000
	s_add_u32 s40, s38, 0x80000
	v_add_u32_e32 v124, s68, v154
	v_add_u32_e32 v152, s31, v154
	s_addc_u32 s41, s39, 0
	s_add_i32 s66, s31, s50
	ds_read_b128 v[112:115], v124
	ds_read_b128 v[116:119], v124 offset:1024
	ds_read_b128 v[120:123], v124 offset:2048
	ds_read_b128 v[124:127], v124 offset:3072
	ds_read_b128 v[148:151], v152
	ds_read_b128 v[158:161], v152 offset:1024
	ds_read_b128 v[162:165], v152 offset:2048
	ds_read_b128 v[166:169], v152 offset:3072
	s_add_i32 s65, s66, 0x2000
	s_add_i32 s63, 0, 0x18000
	s_add_i32 s62, 0, 0x1c000
	s_add_u32 s34, s36, 0x80000
	s_addc_u32 s35, s37, 0
	s_add_i32 s23, s63, s50
	s_add_i32 s19, s23, 0x2000
	s_add_u32 s30, s38, 0x80080
	s_addc_u32 s31, s39, 0
	s_add_i32 s70, s62, s50
	s_add_i32 s68, s70, 0x2000
	v_lshl_add_u64 v[152:153], s[42:43], 0, v[146:147]
	ds_read_b128 v[174:177], v157
	ds_read_b128 v[178:181], v157 offset:1024
	ds_read_b128 v[182:185], v157 offset:2048
	ds_read_b128 v[192:195], v157 offset:3072
	ds_read_b128 v[196:199], v157 offset:4096
	ds_read_b128 v[200:203], v157 offset:5120
	ds_read_b128 v[204:207], v157 offset:6144
	ds_read_b128 v[208:211], v157 offset:7168
	global_load_lds_dwordx4 v[152:153], off
	v_lshl_add_u64 v[152:153], s[42:43], 0, v[144:145]
	s_mov_b32 m0, s71
	s_nop 0
	global_load_lds_dwordx4 v[152:153], off
	s_waitcnt vmcnt(8)
	s_waitcnt lgkmcnt(0)
	s_barrier
	s_setprio 1
	v_mfma_f32_16x16x32_bf16 v[140:143], v[112:115], v[174:177], v[140:143]
	v_mfma_f32_16x16x32_bf16 v[136:139], v[120:123], v[174:177], v[136:139]
	v_mfma_f32_16x16x32_bf16 v[108:111], v[112:115], v[182:185], v[108:111]
	v_mfma_f32_16x16x32_bf16 v[104:107], v[120:123], v[182:185], v[104:107]
	v_mfma_f32_16x16x32_bf16 v[92:95], v[112:115], v[196:199], v[92:95]
	v_mfma_f32_16x16x32_bf16 v[88:91], v[120:123], v[196:199], v[88:91]
	v_mfma_f32_16x16x32_bf16 v[76:79], v[112:115], v[204:207], v[76:79]
	v_mfma_f32_16x16x32_bf16 v[72:75], v[120:123], v[204:207], v[72:75]
	v_mfma_f32_16x16x32_bf16 v[140:143], v[116:119], v[178:181], v[140:143]
	v_mfma_f32_16x16x32_bf16 v[136:139], v[124:127], v[178:181], v[136:139]
	v_mfma_f32_16x16x32_bf16 v[108:111], v[116:119], v[192:195], v[108:111]
	v_mfma_f32_16x16x32_bf16 v[104:107], v[124:127], v[192:195], v[104:107]
	v_mfma_f32_16x16x32_bf16 v[92:95], v[116:119], v[200:203], v[92:95]
	v_mfma_f32_16x16x32_bf16 v[88:91], v[124:127], v[200:203], v[88:91]
	v_mfma_f32_16x16x32_bf16 v[76:79], v[116:119], v[208:211], v[76:79]
	v_mfma_f32_16x16x32_bf16 v[72:75], v[124:127], v[208:211], v[72:75]
	s_setprio 0
	s_setprio 1
	v_mfma_f32_16x16x32_bf16 v[132:135], v[148:151], v[174:177], v[132:135]
	v_mfma_f32_16x16x32_bf16 v[128:131], v[162:165], v[174:177], v[128:131]
	v_mfma_f32_16x16x32_bf16 v[100:103], v[148:151], v[182:185], v[100:103]
	v_mfma_f32_16x16x32_bf16 v[96:99], v[162:165], v[182:185], v[96:99]
	v_mfma_f32_16x16x32_bf16 v[84:87], v[148:151], v[196:199], v[84:87]
	v_mfma_f32_16x16x32_bf16 v[80:83], v[162:165], v[196:199], v[80:83]
	v_mfma_f32_16x16x32_bf16 v[68:71], v[148:151], v[204:207], v[68:71]
	v_mfma_f32_16x16x32_bf16 v[64:67], v[162:165], v[204:207], v[64:67]
	v_mfma_f32_16x16x32_bf16 v[132:135], v[158:161], v[178:181], v[132:135]
	v_mfma_f32_16x16x32_bf16 v[128:131], v[166:169], v[178:181], v[128:131]
	v_mfma_f32_16x16x32_bf16 v[100:103], v[158:161], v[192:195], v[100:103]
	v_mfma_f32_16x16x32_bf16 v[96:99], v[166:169], v[192:195], v[96:99]
	v_mfma_f32_16x16x32_bf16 v[84:87], v[158:161], v[200:203], v[84:87]
	v_mfma_f32_16x16x32_bf16 v[80:83], v[166:169], v[200:203], v[80:83]
	v_mfma_f32_16x16x32_bf16 v[68:71], v[158:161], v[208:211], v[68:71]
	v_mfma_f32_16x16x32_bf16 v[64:67], v[166:169], v[208:211], v[64:67]
	s_setprio 0
	s_barrier
	s_mov_b32 m0, s67
	v_lshl_add_u64 v[152:153], s[38:39], 0, v[146:147]
	ds_read_b128 v[174:177], v157 offset:16384
	ds_read_b128 v[178:181], v157 offset:17408
	ds_read_b128 v[182:185], v157 offset:18432
	ds_read_b128 v[192:195], v157 offset:19456
	ds_read_b128 v[196:199], v157 offset:20480
	ds_read_b128 v[200:203], v157 offset:21504
	ds_read_b128 v[204:207], v157 offset:22528
	ds_read_b128 v[208:211], v157 offset:23552
	global_load_lds_dwordx4 v[152:153], off
	v_lshl_add_u64 v[170:171], s[38:39], 0, v[144:145]
	s_mov_b32 m0, s64
	v_lshl_add_u64 v[186:187], s[40:41], 0, v[146:147]
	global_load_lds_dwordx4 v[170:171], off
	s_mov_b32 m0, s66
	v_lshl_add_u64 v[212:213], s[36:37], 0, v[144:145]
	global_load_lds_dwordx4 v[186:187], off
	v_lshl_add_u64 v[186:187], s[40:41], 0, v[144:145]
	s_mov_b32 m0, s65
	s_nop 0
	global_load_lds_dwordx4 v[186:187], off
	v_lshl_add_u64 v[186:187], s[36:37], 0, v[146:147]
	s_mov_b32 m0, s51
	s_nop 0
	global_load_lds_dwordx4 v[186:187], off
	s_mov_b32 m0, s52
	s_nop 0
	global_load_lds_dwordx4 v[212:213], off
	s_waitcnt vmcnt(8)
	s_waitcnt lgkmcnt(0)
	s_barrier
; #define PG8_STAGE(bufoff, gbase, voff) do { _Pragma("unroll") for (int _i = 0; _i < 2; ++_i) \
;         __builtin_amdgcn_global_load_lds((const unsigned*)((const char*)(gbase) + (voff)[_i]), (PG8_LAS unsigned*)(lds + (bufoff) + ldsw + _i * 8192), 16, 0, 0); } while (0)
; #define PG8_LDA(dst, b, h) do { _Pragma("unroll") for (int m = 0; m < 4; ++m) _Pragma("unroll") for (int k = 0; k < 2; ++k) dst[m][k] = *(const PG8_LAS bf16x8*)(lds + PG8_SA(b, h) + aoff + m * 2048 + k * 1024); } while (0)
; #define PG8_LDB(dst, b, h) do { _Pragma("unroll") for (int n = 0; n < 2; ++n) _Pragma("unroll") for (int k = 0; k < 2; ++k) dst[n][k] = *(const PG8_LAS bf16x8*)(lds + PG8_SB(b, h) + boff + n * 2048 + k * 1024); } while (0)
; #define PG8_MMA(ai, bj, At, Bt) do { __builtin_amdgcn_s_setprio(1); _Pragma("unroll") for (int m = 0; m < 4; ++m) _Pragma("unroll") for (int n = 0; n < 2; ++n) _Pragma("unroll") for (int k = 0; k < 2; ++k) \
;         acc[ai][bj][m][n] = __builtin_amdgcn_mfma_f32_16x16x32_bf16(Bt[n][k], At[m][k], acc[ai][bj][m][n], 0, 0, 0); __builtin_amdgcn_s_setprio(0); } while (0)
; #define PG8_WAIT_V(n) asm volatile("s_waitcnt vmcnt(" #n ")" ::: "memory")
; #define PG8_WAIT_L(n) asm volatile("s_waitcnt lgkmcnt(" #n ")" ::: "memory")
; #define PG8_BAR __builtin_amdgcn_s_barrier()
; #define PG8_SCHED __builtin_amdgcn_sched_barrier(0)
; template <class Epi, class Sched, bool ALIGN_EPI = false, bool SP2 = false>
; __device__ __forceinline__ void gemm_phase(PG8_LAS unsigned char* lds, const Gemm g, const Sched& S, const Epi& E) {
;     ...
;             if constexpr (SP2) {
;             PG8_LDB(B0, 0, 0); PG8_LDB(B1, 0, 1); PG8_SCHED; PG8_LDA(At, 0, 0); PG8_STAGE(PG8_SA(1, 1), a1 + hstepA, voffA);
;             PG8_WAIT_V(8); PG8_WAIT_L(0); PG8_BAR; PG8_MMA(0, 0, At, B0); PG8_MMA(0, 1, At, B1); PG8_BAR; PG8_SCHED;
;             PG8_LDA(At, 0, 1); PG8_STAGE(PG8_SB(0, 0), b2, voffB); PG8_STAGE(PG8_SB(0, 1), b2 + hstepB, voffB); PG8_STAGE(PG8_SA(0, 0), a2, voffA);
;             PG8_WAIT_V(8); PG8_WAIT_L(0); PG8_BAR; PG8_MMA(1, 0, At, B0); PG8_MMA(1, 1, At, B1); PG8_BAR; PG8_SCHED;
;             PG8_LDB(B0, 1, 0); PG8_LDB(B1, 1, 1); PG8_SCHED; PG8_LDA(At, 1, 0); PG8_STAGE(PG8_SA(0, 1), a2 + hstepA, voffA);
;             PG8_WAIT_V(8); PG8_WAIT_L(0); PG8_BAR; PG8_MMA(0, 0, At, B0); PG8_MMA(0, 1, At, B1); PG8_BAR; PG8_SCHED;
	s_setprio 1
	v_mfma_f32_16x16x32_bf16 v[60:63], v[112:115], v[174:177], v[60:63]
	v_mfma_f32_16x16x32_bf16 v[56:59], v[120:123], v[174:177], v[56:59]
	v_mfma_f32_16x16x32_bf16 v[52:55], v[112:115], v[182:185], v[52:55]
	v_mfma_f32_16x16x32_bf16 v[40:43], v[120:123], v[182:185], v[40:43]
	v_mfma_f32_16x16x32_bf16 v[36:39], v[112:115], v[196:199], v[36:39]
	v_mfma_f32_16x16x32_bf16 v[24:27], v[120:123], v[196:199], v[24:27]
	v_mfma_f32_16x16x32_bf16 v[20:23], v[112:115], v[204:207], v[20:23]
	v_mfma_f32_16x16x32_bf16 v[8:11], v[120:123], v[204:207], v[8:11]
	v_mfma_f32_16x16x32_bf16 v[60:63], v[116:119], v[178:181], v[60:63]
	v_mfma_f32_16x16x32_bf16 v[56:59], v[124:127], v[178:181], v[56:59]
	v_mfma_f32_16x16x32_bf16 v[52:55], v[116:119], v[192:195], v[52:55]
	v_mfma_f32_16x16x32_bf16 v[40:43], v[124:127], v[192:195], v[40:43]
	v_mfma_f32_16x16x32_bf16 v[36:39], v[116:119], v[200:203], v[36:39]
	v_mfma_f32_16x16x32_bf16 v[24:27], v[124:127], v[200:203], v[24:27]
	v_mfma_f32_16x16x32_bf16 v[20:23], v[116:119], v[208:211], v[20:23]
	v_mfma_f32_16x16x32_bf16 v[8:11], v[124:127], v[208:211], v[8:11]
	s_setprio 0
	s_setprio 1
	v_mfma_f32_16x16x32_bf16 v[48:51], v[148:151], v[174:177], v[48:51]
	v_mfma_f32_16x16x32_bf16 v[44:47], v[162:165], v[174:177], v[44:47]
	v_mfma_f32_16x16x32_bf16 v[32:35], v[148:151], v[182:185], v[32:35]
	v_mfma_f32_16x16x32_bf16 v[28:31], v[162:165], v[182:185], v[28:31]
	v_mfma_f32_16x16x32_bf16 v[16:19], v[148:151], v[196:199], v[16:19]
	v_mfma_f32_16x16x32_bf16 v[12:15], v[162:165], v[196:199], v[12:15]
	v_mfma_f32_16x16x32_bf16 v[4:7], v[148:151], v[204:207], v[4:7]
	v_mfma_f32_16x16x32_bf16 v[0:3], v[162:165], v[204:207], v[0:3]
	v_mfma_f32_16x16x32_bf16 v[48:51], v[158:161], v[178:181], v[48:51]
	v_mfma_f32_16x16x32_bf16 v[44:47], v[166:169], v[178:181], v[44:47]
	v_mfma_f32_16x16x32_bf16 v[32:35], v[158:161], v[192:195], v[32:35]
	v_mfma_f32_16x16x32_bf16 v[28:31], v[166:169], v[192:195], v[28:31]
	v_mfma_f32_16x16x32_bf16 v[16:19], v[158:161], v[200:203], v[16:19]
	v_mfma_f32_16x16x32_bf16 v[12:15], v[166:169], v[200:203], v[12:15]
	v_mfma_f32_16x16x32_bf16 v[4:7], v[158:161], v[208:211], v[4:7]
	v_mfma_f32_16x16x32_bf16 v[0:3], v[166:169], v[208:211], v[0:3]
	s_setprio 0
	s_barrier
	v_add_u32_e32 v124, s63, v154
	v_add_u32_e32 v166, s62, v154
	ds_read_b128 v[112:115], v124
	ds_read_b128 v[116:119], v124 offset:1024
	ds_read_b128 v[120:123], v124 offset:2048
	ds_read_b128 v[124:127], v124 offset:3072
	ds_read_b128 v[148:151], v166
	ds_read_b128 v[158:161], v166 offset:1024
	ds_read_b128 v[162:165], v166 offset:2048
	ds_read_b128 v[166:169], v166 offset:3072
	s_mov_b32 m0, s53
	v_lshl_add_u64 v[214:215], s[34:35], 0, v[146:147]
	ds_read_b128 v[174:177], v157 offset:32768
	ds_read_b128 v[178:181], v157 offset:33792
	ds_read_b128 v[182:185], v157 offset:34816
	ds_read_b128 v[192:195], v157 offset:35840
	ds_read_b128 v[196:199], v157 offset:36864
	ds_read_b128 v[200:203], v157 offset:37888
	ds_read_b128 v[204:207], v157 offset:38912
	ds_read_b128 v[208:211], v157 offset:39936
	global_load_lds_dwordx4 v[214:215], off
	v_lshl_add_u64 v[214:215], s[34:35], 0, v[144:145]
	s_mov_b32 m0, s56
	s_nop 0
	global_load_lds_dwordx4 v[214:215], off
	s_waitcnt vmcnt(8)
	s_waitcnt lgkmcnt(0)
	s_barrier
	s_setprio 1
	v_mfma_f32_16x16x32_bf16 v[140:143], v[112:115], v[174:177], v[140:143]
	v_mfma_f32_16x16x32_bf16 v[136:139], v[120:123], v[174:177], v[136:139]
	v_mfma_f32_16x16x32_bf16 v[108:111], v[112:115], v[182:185], v[108:111]
	v_mfma_f32_16x16x32_bf16 v[104:107], v[120:123], v[182:185], v[104:107]
	v_mfma_f32_16x16x32_bf16 v[92:95], v[112:115], v[196:199], v[92:95]
	v_mfma_f32_16x16x32_bf16 v[88:91], v[120:123], v[196:199], v[88:91]
	v_mfma_f32_16x16x32_bf16 v[76:79], v[112:115], v[204:207], v[76:79]
	v_mfma_f32_16x16x32_bf16 v[72:75], v[120:123], v[204:207], v[72:75]
	v_mfma_f32_16x16x32_bf16 v[140:143], v[116:119], v[178:181], v[140:143]
	v_mfma_f32_16x16x32_bf16 v[136:139], v[124:127], v[178:181], v[136:139]
	v_mfma_f32_16x16x32_bf16 v[108:111], v[116:119], v[192:195], v[108:111]
	v_mfma_f32_16x16x32_bf16 v[104:107], v[124:127], v[192:195], v[104:107]
	v_mfma_f32_16x16x32_bf16 v[92:95], v[116:119], v[200:203], v[92:95]
	v_mfma_f32_16x16x32_bf16 v[88:91], v[124:127], v[200:203], v[88:91]
	v_mfma_f32_16x16x32_bf16 v[76:79], v[116:119], v[208:211], v[76:79]
	v_mfma_f32_16x16x32_bf16 v[72:75], v[124:127], v[208:211], v[72:75]
	s_setprio 0
	s_setprio 1
	v_mfma_f32_16x16x32_bf16 v[132:135], v[148:151], v[174:177], v[132:135]
	v_mfma_f32_16x16x32_bf16 v[128:131], v[162:165], v[174:177], v[128:131]
	v_mfma_f32_16x16x32_bf16 v[100:103], v[148:151], v[182:185], v[100:103]
	v_mfma_f32_16x16x32_bf16 v[96:99], v[162:165], v[182:185], v[96:99]
	v_mfma_f32_16x16x32_bf16 v[84:87], v[148:151], v[196:199], v[84:87]
	v_mfma_f32_16x16x32_bf16 v[80:83], v[162:165], v[196:199], v[80:83]
	v_mfma_f32_16x16x32_bf16 v[68:71], v[148:151], v[204:207], v[68:71]
	v_mfma_f32_16x16x32_bf16 v[64:67], v[162:165], v[204:207], v[64:67]
	v_mfma_f32_16x16x32_bf16 v[132:135], v[158:161], v[178:181], v[132:135]
	v_mfma_f32_16x16x32_bf16 v[128:131], v[166:169], v[178:181], v[128:131]
	v_mfma_f32_16x16x32_bf16 v[100:103], v[158:161], v[192:195], v[100:103]
	v_mfma_f32_16x16x32_bf16 v[96:99], v[166:169], v[192:195], v[96:99]
	v_mfma_f32_16x16x32_bf16 v[84:87], v[158:161], v[200:203], v[84:87]
	v_mfma_f32_16x16x32_bf16 v[80:83], v[166:169], v[200:203], v[80:83]
	v_mfma_f32_16x16x32_bf16 v[68:71], v[158:161], v[208:211], v[68:71]
	v_mfma_f32_16x16x32_bf16 v[64:67], v[166:169], v[208:211], v[64:67]
	s_setprio 0
	s_barrier
; #define PG8_STAGE(bufoff, gbase, voff) do { _Pragma("unroll") for (int _i = 0; _i < 2; ++_i) \
;         __builtin_amdgcn_global_load_lds((const unsigned*)((const char*)(gbase) + (voff)[_i]), (PG8_LAS unsigned*)(lds + (bufoff) + ldsw + _i * 8192), 16, 0, 0); } while (0)
; #define PG8_LDA(dst, b, h) do { _Pragma("unroll") for (int m = 0; m < 4; ++m) _Pragma("unroll") for (int k = 0; k < 2; ++k) dst[m][k] = *(const PG8_LAS bf16x8*)(lds + PG8_SA(b, h) + aoff + m * 2048 + k * 1024); } while (0)
; #define PG8_MMA(ai, bj, At, Bt) do { __builtin_amdgcn_s_setprio(1); _Pragma("unroll") for (int m = 0; m < 4; ++m) _Pragma("unroll") for (int n = 0; n < 2; ++n) _Pragma("unroll") for (int k = 0; k < 2; ++k) \
;         acc[ai][bj][m][n] = __builtin_amdgcn_mfma_f32_16x16x32_bf16(Bt[n][k], At[m][k], acc[ai][bj][m][n], 0, 0, 0); __builtin_amdgcn_s_setprio(0); } while (0)
; #define PG8_WAIT_V(n) asm volatile("s_waitcnt vmcnt(" #n ")" ::: "memory")
; #define PG8_WAIT_L(n) asm volatile("s_waitcnt lgkmcnt(" #n ")" ::: "memory")
; #define PG8_BAR __builtin_amdgcn_s_barrier()
; #define PG8_SCHED __builtin_amdgcn_sched_barrier(0)
; template <class Epi, class Sched, bool ALIGN_EPI = false, bool SP2 = false>
; __device__ __forceinline__ void gemm_phase(PG8_LAS unsigned char* lds, const Gemm g, const Sched& S, const Epi& E) {
;     ...
;             PG8_LDA(At, 1, 1); PG8_STAGE(PG8_SB(1, 0), b3, voffB); PG8_STAGE(PG8_SB(1, 1), b3 + hstepB, voffB); PG8_STAGE(PG8_SA(1, 0), a3, voffA);
;             PG8_WAIT_V(8); PG8_WAIT_L(0); PG8_BAR; PG8_MMA(1, 0, At, B0); PG8_MMA(1, 1, At, B1); PG8_BAR; PG8_SCHED;
;     ...
;         if constexpr (ALIGN_EPI) { if (wr == 0) PG8_BAR; }
	s_mov_b32 m0, s23
	v_lshl_add_u64 v[152:153], v[152:153], 0, s[80:81]
	ds_read_b128 v[174:177], v157 offset:49152
	ds_read_b128 v[178:181], v157 offset:50176
	ds_read_b128 v[182:185], v157 offset:51200
	ds_read_b128 v[192:195], v157 offset:52224
	ds_read_b128 v[196:199], v157 offset:53248
	ds_read_b128 v[200:203], v157 offset:54272
	ds_read_b128 v[204:207], v157 offset:55296
	ds_read_b128 v[208:211], v157 offset:56320
	global_load_lds_dwordx4 v[152:153], off
	v_lshl_add_u64 v[152:153], v[170:171], 0, s[80:81]
	s_mov_b32 m0, s19
	s_nop 0
	global_load_lds_dwordx4 v[152:153], off
	v_lshl_add_u64 v[152:153], s[30:31], 0, v[146:147]
	s_mov_b32 m0, s70
	s_nop 0
	global_load_lds_dwordx4 v[152:153], off
	v_lshl_add_u64 v[152:153], s[30:31], 0, v[144:145]
	s_mov_b32 m0, s68
	s_nop 0
	global_load_lds_dwordx4 v[152:153], off
	v_lshl_add_u64 v[152:153], v[186:187], 0, s[80:81]
	s_mov_b32 m0, s57
	s_nop 0
	global_load_lds_dwordx4 v[152:153], off
	v_lshl_add_u64 v[152:153], v[212:213], 0, s[80:81]
	s_mov_b32 m0, s58
	s_nop 0
	global_load_lds_dwordx4 v[152:153], off
	s_waitcnt vmcnt(8)
	s_waitcnt lgkmcnt(0)
	s_barrier
	s_setprio 1
	v_mfma_f32_16x16x32_bf16 v[60:63], v[112:115], v[174:177], v[60:63]
	v_mfma_f32_16x16x32_bf16 v[56:59], v[120:123], v[174:177], v[56:59]
	v_mfma_f32_16x16x32_bf16 v[52:55], v[112:115], v[182:185], v[52:55]
	v_mfma_f32_16x16x32_bf16 v[40:43], v[120:123], v[182:185], v[40:43]
	v_mfma_f32_16x16x32_bf16 v[36:39], v[112:115], v[196:199], v[36:39]
	v_mfma_f32_16x16x32_bf16 v[24:27], v[120:123], v[196:199], v[24:27]
	v_mfma_f32_16x16x32_bf16 v[20:23], v[112:115], v[204:207], v[20:23]
	v_mfma_f32_16x16x32_bf16 v[8:11], v[120:123], v[204:207], v[8:11]
	v_mfma_f32_16x16x32_bf16 v[60:63], v[116:119], v[178:181], v[60:63]
	v_mfma_f32_16x16x32_bf16 v[56:59], v[124:127], v[178:181], v[56:59]
	v_mfma_f32_16x16x32_bf16 v[52:55], v[116:119], v[192:195], v[52:55]
	v_mfma_f32_16x16x32_bf16 v[40:43], v[124:127], v[192:195], v[40:43]
	v_mfma_f32_16x16x32_bf16 v[36:39], v[116:119], v[200:203], v[36:39]
	v_mfma_f32_16x16x32_bf16 v[24:27], v[124:127], v[200:203], v[24:27]
	v_mfma_f32_16x16x32_bf16 v[20:23], v[116:119], v[208:211], v[20:23]
	v_mfma_f32_16x16x32_bf16 v[8:11], v[124:127], v[208:211], v[8:11]
	s_setprio 0
	s_setprio 1
	v_mfma_f32_16x16x32_bf16 v[48:51], v[148:151], v[174:177], v[48:51]
	v_mfma_f32_16x16x32_bf16 v[44:47], v[162:165], v[174:177], v[44:47]
	v_mfma_f32_16x16x32_bf16 v[32:35], v[148:151], v[182:185], v[32:35]
	v_mfma_f32_16x16x32_bf16 v[28:31], v[162:165], v[182:185], v[28:31]
	v_mfma_f32_16x16x32_bf16 v[16:19], v[148:151], v[196:199], v[16:19]
	v_mfma_f32_16x16x32_bf16 v[12:15], v[162:165], v[196:199], v[12:15]
	v_mfma_f32_16x16x32_bf16 v[4:7], v[148:151], v[204:207], v[4:7]
	v_mfma_f32_16x16x32_bf16 v[0:3], v[162:165], v[204:207], v[0:3]
	v_mfma_f32_16x16x32_bf16 v[48:51], v[158:161], v[178:181], v[48:51]
	v_mfma_f32_16x16x32_bf16 v[44:47], v[166:169], v[178:181], v[44:47]
	v_mfma_f32_16x16x32_bf16 v[32:35], v[158:161], v[192:195], v[32:35]
	v_mfma_f32_16x16x32_bf16 v[28:31], v[166:169], v[192:195], v[28:31]
	v_mfma_f32_16x16x32_bf16 v[16:19], v[158:161], v[200:203], v[16:19]
	v_mfma_f32_16x16x32_bf16 v[12:15], v[166:169], v[200:203], v[12:15]
	v_mfma_f32_16x16x32_bf16 v[4:7], v[158:161], v[208:211], v[4:7]
	v_mfma_f32_16x16x32_bf16 v[0:3], v[166:169], v[208:211], v[0:3]
	s_setprio 0
	s_barrier
	s_movk_i32 s19, 0x100
	s_andn2_b64 vcc, exec, s[28:29]
	s_mov_b64 s[30:31], -1
	s_mov_b64 s[28:29], 0
	s_cbranch_vccz .LBB0_570
	s_and_b64 vcc, exec, s[10:11]
	s_cbranch_vccz .LBB0_573
	s_barrier

;     __device__ __forceinline__ bool next(int i, Unit& u) const { const int L = i * G + c; if (L >= nsub) return false; u.pk = L >> 4; u.pm = MLAT / BM + (L & 3); u.pn = (L >> 2) & 3; return true; }
; #define PG8_STAGE(bufoff, gbase, voff) do { _Pragma("unroll") for (int _i = 0; _i < 2; ++_i) \
;         __builtin_amdgcn_global_load_lds((const unsigned*)((const char*)(gbase) + (voff)[_i]), (PG8_LAS unsigned*)(lds + (bufoff) + ldsw + _i * 8192), 16, 0, 0); } while (0)
; #define PG8_LDA(dst, b, h) do { _Pragma("unroll") for (int m = 0; m < 4; ++m) _Pragma("unroll") for (int k = 0; k < 2; ++k) dst[m][k] = *(const PG8_LAS bf16x8*)(lds + PG8_SA(b, h) + aoff + m * 2048 + k * 1024); } while (0)
; #define PG8_LDB(dst, b, h) do { _Pragma("unroll") for (int n = 0; n < 2; ++n) _Pragma("unroll") for (int k = 0; k < 2; ++k) dst[n][k] = *(const PG8_LAS bf16x8*)(lds + PG8_SB(b, h) + boff + n * 2048 + k * 1024); } while (0)
; #define PG8_WAIT_V(n) asm volatile("s_waitcnt vmcnt(" #n ")" ::: "memory")
; #define PG8_WAIT_L(n) asm volatile("s_waitcnt lgkmcnt(" #n ")" ::: "memory")
; template <class Epi, class Sched, bool ALIGN_EPI = false, bool SP2 = false>
; __device__ __forceinline__ void gemm_phase(PG8_LAS unsigned char* lds, const Gemm g, const Sched& S, const Epi& E) {
;     ...
;         const bool has_next = S.next(ui + 1, nxt);
;         const char* nA = has_next ? g.a_of(nxt) : cA; const char* nB = has_next ? g.b_of(nxt) : cB;
;         for (int t = 0; t < nt; t += 2) {
;             const bool last = (t == nt - 2);
;             const char* a1 = cA + (size_t)(t + 1) * kstep;
;             const char* a2 = last ? nA : cA + (size_t)(t + 2) * kstep; const char* b2 = last ? nB : cB + (size_t)(t + 2) * kstep;
;             const char* a3 = a2 + kstep; const char* b3 = b2 + kstep;
;             if (last && has_next) S.a_ready(nxt);
;             if constexpr (SP2) {
;             PG8_LDB(B0, 0, 0); PG8_LDB(B1, 0, 1); PG8_SCHED; PG8_LDA(At, 0, 0); PG8_STAGE(PG8_SA(1, 1), a1 + hstepA, voffA);
;             PG8_WAIT_V(8); PG8_WAIT_L(0); PG8_BAR; PG8_MMA(0, 0, At, B0); PG8_MMA(0, 1, At, B1); PG8_BAR; PG8_SCHED;
;             PG8_LDA(At, 0, 1); PG8_STAGE(PG8_SB(0, 0), b2, voffB); PG8_STAGE(PG8_SB(0, 1), b2 + hstepB, voffB); PG8_STAGE(PG8_SA(0, 0), a2, voffA);
;             PG8_WAIT_V(8); PG8_WAIT_L(0); PG8_BAR; PG8_MMA(1, 0, At, B0); PG8_MMA(1, 1, At, B1); PG8_BAR; PG8_SCHED;
.LBB0_780:
	s_add_u32 s12, s10, 0xfffc0080
	s_addc_u32 s13, s11, -1
	s_add_i32 s61, 0, 0x10000
	s_cmp_eq_u32 s21, 12
	s_cselect_b32 s15, s5, s13
	s_cselect_b32 s14, s16, s12
	s_cselect_b32 s13, s17, s20
	s_cselect_b32 s12, s18, s19
	s_add_i32 s63, 0, 0x14000
	v_add_u32_e32 v44, s61, v197
	v_add_u32_e32 v60, s63, v197
	ds_read_b128 v[32:35], v44
	ds_read_b128 v[36:39], v44 offset:1024
	ds_read_b128 v[40:43], v44 offset:2048
	ds_read_b128 v[44:47], v44 offset:3072
	ds_read_b128 v[48:51], v60
	ds_read_b128 v[52:55], v60 offset:1024
	ds_read_b128 v[56:59], v60 offset:2048
	ds_read_b128 v[60:63], v60 offset:3072
	s_add_i32 m0, s27, 0xc000
	ds_read_b128 v[168:171], v201
	ds_read_b128 v[178:181], v201 offset:1024
	ds_read_b128 v[182:185], v201 offset:2048
	ds_read_b128 v[202:205], v201 offset:3072
	ds_read_b128 v[206:209], v201 offset:4096
	ds_read_b128 v[210:213], v201 offset:5120
	ds_read_b128 v[214:217], v201 offset:6144
	ds_read_b128 v[218:221], v201 offset:7168
	global_load_lds_dwordx4 v164, s[10:11]
	s_add_i32 m0, s27, 0xe000
	s_nop 0
	global_load_lds_dwordx4 v166, s[10:11]
	s_waitcnt vmcnt(8)
	s_waitcnt lgkmcnt(0)
	s_barrier
	s_setprio 1
	v_mfma_f32_16x16x32_bf16 v[156:159], v[32:35], v[168:171], v[156:159]
	v_mfma_f32_16x16x32_bf16 v[152:155], v[40:43], v[168:171], v[152:155]
	v_mfma_f32_16x16x32_bf16 v[140:143], v[32:35], v[182:185], v[140:143]
	v_mfma_f32_16x16x32_bf16 v[136:139], v[40:43], v[182:185], v[136:139]
	v_mfma_f32_16x16x32_bf16 v[124:127], v[32:35], v[206:209], v[124:127]
	v_mfma_f32_16x16x32_bf16 v[120:123], v[40:43], v[206:209], v[120:123]
	v_mfma_f32_16x16x32_bf16 v[108:111], v[32:35], v[214:217], v[108:111]
	v_mfma_f32_16x16x32_bf16 v[104:107], v[40:43], v[214:217], v[104:107]
	v_mfma_f32_16x16x32_bf16 v[156:159], v[36:39], v[178:181], v[156:159]
	v_mfma_f32_16x16x32_bf16 v[152:155], v[44:47], v[178:181], v[152:155]
	v_mfma_f32_16x16x32_bf16 v[140:143], v[36:39], v[202:205], v[140:143]
	v_mfma_f32_16x16x32_bf16 v[136:139], v[44:47], v[202:205], v[136:139]
	v_mfma_f32_16x16x32_bf16 v[124:127], v[36:39], v[210:213], v[124:127]
	v_mfma_f32_16x16x32_bf16 v[120:123], v[44:47], v[210:213], v[120:123]
	v_mfma_f32_16x16x32_bf16 v[108:111], v[36:39], v[218:221], v[108:111]
	v_mfma_f32_16x16x32_bf16 v[104:107], v[44:47], v[218:221], v[104:107]
	s_setprio 0
	s_setprio 1
	v_mfma_f32_16x16x32_bf16 v[148:151], v[48:51], v[168:171], v[148:151]
	v_mfma_f32_16x16x32_bf16 v[144:147], v[56:59], v[168:171], v[144:147]
	v_mfma_f32_16x16x32_bf16 v[132:135], v[48:51], v[182:185], v[132:135]
	v_mfma_f32_16x16x32_bf16 v[128:131], v[56:59], v[182:185], v[128:131]
	v_mfma_f32_16x16x32_bf16 v[116:119], v[48:51], v[206:209], v[116:119]
	v_mfma_f32_16x16x32_bf16 v[112:115], v[56:59], v[206:209], v[112:115]
	v_mfma_f32_16x16x32_bf16 v[100:103], v[48:51], v[214:217], v[100:103]
	v_mfma_f32_16x16x32_bf16 v[96:99], v[56:59], v[214:217], v[96:99]
	v_mfma_f32_16x16x32_bf16 v[148:151], v[52:55], v[178:181], v[148:151]
	v_mfma_f32_16x16x32_bf16 v[144:147], v[60:63], v[178:181], v[144:147]
	v_mfma_f32_16x16x32_bf16 v[132:135], v[52:55], v[202:205], v[132:135]
	v_mfma_f32_16x16x32_bf16 v[128:131], v[60:63], v[202:205], v[128:131]
	v_mfma_f32_16x16x32_bf16 v[116:119], v[52:55], v[210:213], v[116:119]
	v_mfma_f32_16x16x32_bf16 v[112:115], v[60:63], v[210:213], v[112:115]
	v_mfma_f32_16x16x32_bf16 v[100:103], v[52:55], v[218:221], v[100:103]
	v_mfma_f32_16x16x32_bf16 v[96:99], v[60:63], v[218:221], v[96:99]
	s_setprio 0
	s_barrier
	s_add_i32 s61, s61, s91
	v_lshl_add_u64 v[174:175], s[12:13], 0, v[160:161]
	s_mov_b32 m0, s61
	ds_read_b128 v[168:171], v201 offset:16384
	ds_read_b128 v[178:181], v201 offset:17408
	ds_read_b128 v[182:185], v201 offset:18432
	ds_read_b128 v[202:205], v201 offset:19456
	ds_read_b128 v[206:209], v201 offset:20480
	ds_read_b128 v[210:213], v201 offset:21504
	ds_read_b128 v[214:217], v201 offset:22528
	ds_read_b128 v[218:221], v201 offset:23552
	global_load_lds_dwordx4 v[174:175], off
	s_add_i32 m0, s61, 0x2000
	s_add_u32 s70, s12, 0x40000
	v_lshl_add_u64 v[176:177], s[12:13], 0, v[162:163]
	s_addc_u32 s71, s13, 0
	s_add_i32 s61, s63, s91
	global_load_lds_dwordx4 v[176:177], off
	s_mov_b32 m0, s61
	v_lshl_add_u64 v[192:193], s[14:15], 0, v[162:163]
	global_load_lds_dwordx4 v160, s[70:71]
	s_add_i32 m0, s61, 0x2000
	s_nop 0
	global_load_lds_dwordx4 v162, s[70:71]
	v_lshl_add_u64 v[186:187], s[14:15], 0, v[160:161]
	s_mov_b32 m0, s27
	s_nop 0
	global_load_lds_dwordx4 v[186:187], off
	s_mov_b32 m0, s93
	s_nop 0
	global_load_lds_dwordx4 v[192:193], off
	s_waitcnt vmcnt(8)
	s_waitcnt lgkmcnt(0)
	s_barrier
; #define PG8_STAGE(bufoff, gbase, voff) do { _Pragma("unroll") for (int _i = 0; _i < 2; ++_i) \
;         __builtin_amdgcn_global_load_lds((const unsigned*)((const char*)(gbase) + (voff)[_i]), (PG8_LAS unsigned*)(lds + (bufoff) + ldsw + _i * 8192), 16, 0, 0); } while (0)
; #define PG8_LDA(dst, b, h) do { _Pragma("unroll") for (int m = 0; m < 4; ++m) _Pragma("unroll") for (int k = 0; k < 2; ++k) dst[m][k] = *(const PG8_LAS bf16x8*)(lds + PG8_SA(b, h) + aoff + m * 2048 + k * 1024); } while (0)
; #define PG8_LDB(dst, b, h) do { _Pragma("unroll") for (int n = 0; n < 2; ++n) _Pragma("unroll") for (int k = 0; k < 2; ++k) dst[n][k] = *(const PG8_LAS bf16x8*)(lds + PG8_SB(b, h) + boff + n * 2048 + k * 1024); } while (0)
; #define PG8_MMA(ai, bj, At, Bt) do { __builtin_amdgcn_s_setprio(1); _Pragma("unroll") for (int m = 0; m < 4; ++m) _Pragma("unroll") for (int n = 0; n < 2; ++n) _Pragma("unroll") for (int k = 0; k < 2; ++k) \
;         acc[ai][bj][m][n] = __builtin_amdgcn_mfma_f32_16x16x32_bf16(Bt[n][k], At[m][k], acc[ai][bj][m][n], 0, 0, 0); __builtin_amdgcn_s_setprio(0); } while (0)
; #define PG8_WAIT_V(n) asm volatile("s_waitcnt vmcnt(" #n ")" ::: "memory")
; #define PG8_WAIT_L(n) asm volatile("s_waitcnt lgkmcnt(" #n ")" ::: "memory")
; #define PG8_BAR __builtin_amdgcn_s_barrier()
; #define PG8_SCHED __builtin_amdgcn_sched_barrier(0)
; template <class Epi, class Sched, bool ALIGN_EPI = false, bool SP2 = false>
; __device__ __forceinline__ void gemm_phase(PG8_LAS unsigned char* lds, const Gemm g, const Sched& S, const Epi& E) {
;     ...
;             if constexpr (SP2) {
;             PG8_LDB(B0, 0, 0); PG8_LDB(B1, 0, 1); PG8_SCHED; PG8_LDA(At, 0, 0); PG8_STAGE(PG8_SA(1, 1), a1 + hstepA, voffA);
;             PG8_WAIT_V(8); PG8_WAIT_L(0); PG8_BAR; PG8_MMA(0, 0, At, B0); PG8_MMA(0, 1, At, B1); PG8_BAR; PG8_SCHED;
;             PG8_LDA(At, 0, 1); PG8_STAGE(PG8_SB(0, 0), b2, voffB); PG8_STAGE(PG8_SB(0, 1), b2 + hstepB, voffB); PG8_STAGE(PG8_SA(0, 0), a2, voffA);
;             PG8_WAIT_V(8); PG8_WAIT_L(0); PG8_BAR; PG8_MMA(1, 0, At, B0); PG8_MMA(1, 1, At, B1); PG8_BAR; PG8_SCHED;
;             PG8_LDB(B0, 1, 0); PG8_LDB(B1, 1, 1); PG8_SCHED; PG8_LDA(At, 1, 0); PG8_STAGE(PG8_SA(0, 1), a2 + hstepA, voffA);
;             PG8_WAIT_V(8); PG8_WAIT_L(0); PG8_BAR; PG8_MMA(0, 0, At, B0); PG8_MMA(0, 1, At, B1); PG8_BAR; PG8_SCHED;
	s_setprio 1
	v_mfma_f32_16x16x32_bf16 v[92:95], v[32:35], v[168:171], v[92:95]
	v_mfma_f32_16x16x32_bf16 v[88:91], v[40:43], v[168:171], v[88:91]
	v_mfma_f32_16x16x32_bf16 v[76:79], v[32:35], v[182:185], v[76:79]
	v_mfma_f32_16x16x32_bf16 v[72:75], v[40:43], v[182:185], v[72:75]
	v_mfma_f32_16x16x32_bf16 v[28:31], v[32:35], v[206:209], v[28:31]
	v_mfma_f32_16x16x32_bf16 v[24:27], v[40:43], v[206:209], v[24:27]
	v_mfma_f32_16x16x32_bf16 v[12:15], v[32:35], v[214:217], v[12:15]
	v_mfma_f32_16x16x32_bf16 v[8:11], v[40:43], v[214:217], v[8:11]
	v_mfma_f32_16x16x32_bf16 v[92:95], v[36:39], v[178:181], v[92:95]
	v_mfma_f32_16x16x32_bf16 v[88:91], v[44:47], v[178:181], v[88:91]
	v_mfma_f32_16x16x32_bf16 v[76:79], v[36:39], v[202:205], v[76:79]
	v_mfma_f32_16x16x32_bf16 v[72:75], v[44:47], v[202:205], v[72:75]
	v_mfma_f32_16x16x32_bf16 v[28:31], v[36:39], v[210:213], v[28:31]
	v_mfma_f32_16x16x32_bf16 v[24:27], v[44:47], v[210:213], v[24:27]
	v_mfma_f32_16x16x32_bf16 v[12:15], v[36:39], v[218:221], v[12:15]
	v_mfma_f32_16x16x32_bf16 v[8:11], v[44:47], v[218:221], v[8:11]
	s_setprio 0
	s_setprio 1
	v_mfma_f32_16x16x32_bf16 v[20:23], v[48:51], v[206:209], v[20:23]
	v_mfma_f32_16x16x32_bf16 v[16:19], v[56:59], v[206:209], v[16:19]
	v_mfma_f32_16x16x32_bf16 v[4:7], v[48:51], v[214:217], v[4:7]
	v_mfma_f32_16x16x32_bf16 v[0:3], v[56:59], v[214:217], v[0:3]
	v_mfma_f32_16x16x32_bf16 v[32:35], v[48:51], v[168:171], v[84:87]
	v_mfma_f32_16x16x32_bf16 v[36:39], v[56:59], v[168:171], v[80:83]
	v_mfma_f32_16x16x32_bf16 v[40:43], v[48:51], v[182:185], v[68:71]
	v_mfma_f32_16x16x32_bf16 v[44:47], v[56:59], v[182:185], v[64:67]
	v_mfma_f32_16x16x32_bf16 v[20:23], v[52:55], v[210:213], v[20:23]
	v_mfma_f32_16x16x32_bf16 v[16:19], v[60:63], v[210:213], v[16:19]
	v_mfma_f32_16x16x32_bf16 v[4:7], v[52:55], v[218:221], v[4:7]
	v_mfma_f32_16x16x32_bf16 v[0:3], v[60:63], v[218:221], v[0:3]
	v_mfma_f32_16x16x32_bf16 v[32:35], v[52:55], v[178:181], v[32:35]
	v_mfma_f32_16x16x32_bf16 v[36:39], v[60:63], v[178:181], v[36:39]
	v_mfma_f32_16x16x32_bf16 v[40:43], v[52:55], v[202:205], v[40:43]
	v_mfma_f32_16x16x32_bf16 v[44:47], v[60:63], v[202:205], v[44:47]
	s_setprio 0
	s_barrier
	s_add_i32 s61, 0, 0x18000
	s_add_i32 s63, 0, 0x1c000
	v_add_u32_e32 v60, s61, v197
	v_add_u32_e32 v64, s63, v197
	ds_read_b128 v[48:51], v60
	ds_read_b128 v[52:55], v60 offset:1024
	ds_read_b128 v[56:59], v60 offset:2048
	ds_read_b128 v[60:63], v60 offset:3072
	ds_read_b128 v[168:171], v64
	ds_read_b128 v[178:181], v64 offset:1024
	ds_read_b128 v[182:185], v64 offset:2048
	ds_read_b128 v[202:205], v64 offset:3072
	s_add_u32 s14, s14, 0x40000
	s_addc_u32 s15, s15, 0
	s_mov_b32 m0, s95
	ds_read_b128 v[64:67], v201 offset:32768
	ds_read_b128 v[68:71], v201 offset:33792
	ds_read_b128 v[80:83], v201 offset:34816
	ds_read_b128 v[84:87], v201 offset:35840
	ds_read_b128 v[206:209], v201 offset:36864
	ds_read_b128 v[210:213], v201 offset:37888
	ds_read_b128 v[214:217], v201 offset:38912
	ds_read_b128 v[218:221], v201 offset:39936
	global_load_lds_dwordx4 v160, s[14:15]
	v_lshl_add_u64 v[194:195], s[14:15], 0, v[162:163]
	s_mov_b32 m0, s96
	s_nop 0
	global_load_lds_dwordx4 v[194:195], off
	s_waitcnt vmcnt(8)
	s_waitcnt lgkmcnt(0)
	s_barrier
	s_setprio 1
	v_mfma_f32_16x16x32_bf16 v[156:159], v[48:51], v[64:67], v[156:159]
	v_mfma_f32_16x16x32_bf16 v[152:155], v[56:59], v[64:67], v[152:155]
	v_mfma_f32_16x16x32_bf16 v[140:143], v[48:51], v[80:83], v[140:143]
	v_mfma_f32_16x16x32_bf16 v[136:139], v[56:59], v[80:83], v[136:139]
	v_mfma_f32_16x16x32_bf16 v[124:127], v[48:51], v[206:209], v[124:127]
	v_mfma_f32_16x16x32_bf16 v[120:123], v[56:59], v[206:209], v[120:123]
	v_mfma_f32_16x16x32_bf16 v[108:111], v[48:51], v[214:217], v[108:111]
	v_mfma_f32_16x16x32_bf16 v[104:107], v[56:59], v[214:217], v[104:107]
	v_mfma_f32_16x16x32_bf16 v[156:159], v[52:55], v[68:71], v[156:159]
	v_mfma_f32_16x16x32_bf16 v[152:155], v[60:63], v[68:71], v[152:155]
	v_mfma_f32_16x16x32_bf16 v[140:143], v[52:55], v[84:87], v[140:143]
	v_mfma_f32_16x16x32_bf16 v[136:139], v[60:63], v[84:87], v[136:139]
	v_mfma_f32_16x16x32_bf16 v[124:127], v[52:55], v[210:213], v[124:127]
	v_mfma_f32_16x16x32_bf16 v[120:123], v[60:63], v[210:213], v[120:123]
	v_mfma_f32_16x16x32_bf16 v[108:111], v[52:55], v[218:221], v[108:111]
	v_mfma_f32_16x16x32_bf16 v[104:107], v[60:63], v[218:221], v[104:107]
	s_setprio 0
	s_setprio 1
	v_mfma_f32_16x16x32_bf16 v[148:151], v[168:171], v[64:67], v[148:151]
	v_mfma_f32_16x16x32_bf16 v[64:67], v[182:185], v[64:67], v[144:147]
	v_mfma_f32_16x16x32_bf16 v[144:147], v[202:205], v[68:71], v[64:67]
	v_mfma_f32_16x16x32_bf16 v[64:67], v[168:171], v[80:83], v[132:135]
	v_mfma_f32_16x16x32_bf16 v[132:135], v[178:181], v[84:87], v[64:67]
	v_mfma_f32_16x16x32_bf16 v[64:67], v[182:185], v[80:83], v[128:131]
	v_mfma_f32_16x16x32_bf16 v[128:131], v[202:205], v[84:87], v[64:67]
	v_mfma_f32_16x16x32_bf16 v[64:67], v[168:171], v[206:209], v[116:119]
	v_mfma_f32_16x16x32_bf16 v[116:119], v[178:181], v[210:213], v[64:67]
	v_mfma_f32_16x16x32_bf16 v[64:67], v[182:185], v[206:209], v[112:115]
	v_mfma_f32_16x16x32_bf16 v[112:115], v[202:205], v[210:213], v[64:67]
	v_mfma_f32_16x16x32_bf16 v[64:67], v[168:171], v[214:217], v[100:103]
	v_mfma_f32_16x16x32_bf16 v[100:103], v[178:181], v[218:221], v[64:67]
	v_mfma_f32_16x16x32_bf16 v[64:67], v[182:185], v[214:217], v[96:99]
	v_mfma_f32_16x16x32_bf16 v[148:151], v[178:181], v[68:71], v[148:151]
	v_mfma_f32_16x16x32_bf16 v[96:99], v[202:205], v[218:221], v[64:67]
	s_setprio 0
	s_barrier
; #define PG8_STAGE(bufoff, gbase, voff) do { _Pragma("unroll") for (int _i = 0; _i < 2; ++_i) \
;         __builtin_amdgcn_global_load_lds((const unsigned*)((const char*)(gbase) + (voff)[_i]), (PG8_LAS unsigned*)(lds + (bufoff) + ldsw + _i * 8192), 16, 0, 0); } while (0)
; #define PG8_LDA(dst, b, h) do { _Pragma("unroll") for (int m = 0; m < 4; ++m) _Pragma("unroll") for (int k = 0; k < 2; ++k) dst[m][k] = *(const PG8_LAS bf16x8*)(lds + PG8_SA(b, h) + aoff + m * 2048 + k * 1024); } while (0)
; #define PG8_MMA(ai, bj, At, Bt) do { __builtin_amdgcn_s_setprio(1); _Pragma("unroll") for (int m = 0; m < 4; ++m) _Pragma("unroll") for (int n = 0; n < 2; ++n) _Pragma("unroll") for (int k = 0; k < 2; ++k) \
;         acc[ai][bj][m][n] = __builtin_amdgcn_mfma_f32_16x16x32_bf16(Bt[n][k], At[m][k], acc[ai][bj][m][n], 0, 0, 0); __builtin_amdgcn_s_setprio(0); } while (0)
; #define PG8_WAIT_V(n) asm volatile("s_waitcnt vmcnt(" #n ")" ::: "memory")
; #define PG8_WAIT_L(n) asm volatile("s_waitcnt lgkmcnt(" #n ")" ::: "memory")
; #define PG8_BAR __builtin_amdgcn_s_barrier()
; #define PG8_SCHED __builtin_amdgcn_sched_barrier(0)
; template <class Epi, class Sched, bool ALIGN_EPI = false, bool SP2 = false>
; __device__ __forceinline__ void gemm_phase(PG8_LAS unsigned char* lds, const Gemm g, const Sched& S, const Epi& E) {
;     ...
;             PG8_LDA(At, 1, 1); PG8_STAGE(PG8_SB(1, 0), b3, voffB); PG8_STAGE(PG8_SB(1, 1), b3 + hstepB, voffB); PG8_STAGE(PG8_SA(1, 0), a3, voffA);
;             PG8_WAIT_V(8); PG8_WAIT_L(0); PG8_BAR; PG8_MMA(1, 0, At, B0); PG8_MMA(1, 1, At, B1); PG8_BAR; PG8_SCHED;
;     ...
;         if constexpr (ALIGN_EPI) { if (wr == 0) PG8_BAR; }
	s_add_i32 s14, s61, s91
	v_lshl_add_u64 v[80:81], v[174:175], 0, s[80:81]
	s_mov_b32 m0, s14
	s_nop 0
	ds_read_b128 v[64:67], v201 offset:49152
	ds_read_b128 v[68:71], v201 offset:50176
	ds_read_b128 v[206:209], v201 offset:51200
	ds_read_b128 v[210:213], v201 offset:52224
	ds_read_b128 v[214:217], v201 offset:53248
	ds_read_b128 v[218:221], v201 offset:54272
	ds_read_b128 v[222:225], v201 offset:55296
	ds_read_b128 v[226:229], v201 offset:56320
	global_load_lds_dwordx4 v[80:81], off
	s_add_i32 m0, s14, 0x2000
	s_add_u32 s12, s12, 0x40080
	v_lshl_add_u64 v[80:81], v[176:177], 0, s[80:81]
	s_addc_u32 s13, s13, 0
	s_add_i32 s14, s63, s91
	global_load_lds_dwordx4 v[80:81], off
	s_mov_b32 m0, s14
	s_nop 0
	global_load_lds_dwordx4 v160, s[12:13]
	s_add_i32 m0, s14, 0x2000
	s_nop 0
	global_load_lds_dwordx4 v162, s[12:13]
	v_lshl_add_u64 v[80:81], v[186:187], 0, s[80:81]
	s_mov_b32 m0, s77
	s_nop 0
	global_load_lds_dwordx4 v[80:81], off
	v_lshl_add_u64 v[80:81], v[192:193], 0, s[80:81]
	s_mov_b32 m0, s1
	s_nop 0
	global_load_lds_dwordx4 v[80:81], off
	s_waitcnt vmcnt(8)
	s_waitcnt lgkmcnt(0)
	s_barrier
	s_setprio 1
	v_mfma_f32_16x16x32_bf16 v[80:83], v[48:51], v[64:67], v[92:95]
	v_mfma_f32_16x16x32_bf16 v[92:95], v[52:55], v[68:71], v[80:83]
	v_mfma_f32_16x16x32_bf16 v[80:83], v[56:59], v[64:67], v[88:91]
	v_mfma_f32_16x16x32_bf16 v[76:79], v[48:51], v[206:209], v[76:79]
	v_mfma_f32_16x16x32_bf16 v[72:75], v[56:59], v[206:209], v[72:75]
	v_mfma_f32_16x16x32_bf16 v[28:31], v[48:51], v[214:217], v[28:31]
	v_mfma_f32_16x16x32_bf16 v[24:27], v[56:59], v[214:217], v[24:27]
	v_mfma_f32_16x16x32_bf16 v[12:15], v[48:51], v[222:225], v[12:15]
	v_mfma_f32_16x16x32_bf16 v[8:11], v[56:59], v[222:225], v[8:11]
	v_mfma_f32_16x16x32_bf16 v[88:91], v[60:63], v[68:71], v[80:83]
	v_mfma_f32_16x16x32_bf16 v[76:79], v[52:55], v[210:213], v[76:79]
	v_mfma_f32_16x16x32_bf16 v[72:75], v[60:63], v[210:213], v[72:75]
	v_mfma_f32_16x16x32_bf16 v[28:31], v[52:55], v[218:221], v[28:31]
	v_mfma_f32_16x16x32_bf16 v[24:27], v[60:63], v[218:221], v[24:27]
	v_mfma_f32_16x16x32_bf16 v[12:15], v[52:55], v[226:229], v[12:15]
	v_mfma_f32_16x16x32_bf16 v[8:11], v[60:63], v[226:229], v[8:11]
	s_setprio 0
	s_setprio 1
	v_mfma_f32_16x16x32_bf16 v[32:35], v[168:171], v[64:67], v[32:35]
	v_mfma_f32_16x16x32_bf16 v[84:87], v[178:181], v[68:71], v[32:35]
	v_mfma_f32_16x16x32_bf16 v[32:35], v[182:185], v[64:67], v[36:39]
	v_mfma_f32_16x16x32_bf16 v[80:83], v[202:205], v[68:71], v[32:35]
	v_mfma_f32_16x16x32_bf16 v[32:35], v[168:171], v[206:209], v[40:43]
	v_mfma_f32_16x16x32_bf16 v[68:71], v[178:181], v[210:213], v[32:35]
	v_mfma_f32_16x16x32_bf16 v[32:35], v[182:185], v[206:209], v[44:47]
	v_mfma_f32_16x16x32_bf16 v[20:23], v[168:171], v[214:217], v[20:23]
	v_mfma_f32_16x16x32_bf16 v[16:19], v[182:185], v[214:217], v[16:19]
	v_mfma_f32_16x16x32_bf16 v[4:7], v[168:171], v[222:225], v[4:7]
	v_mfma_f32_16x16x32_bf16 v[0:3], v[182:185], v[222:225], v[0:3]
	v_mfma_f32_16x16x32_bf16 v[64:67], v[202:205], v[210:213], v[32:35]
	v_mfma_f32_16x16x32_bf16 v[20:23], v[178:181], v[218:221], v[20:23]
	v_mfma_f32_16x16x32_bf16 v[16:19], v[202:205], v[218:221], v[16:19]
	v_mfma_f32_16x16x32_bf16 v[4:7], v[178:181], v[226:229], v[4:7]
	v_mfma_f32_16x16x32_bf16 v[0:3], v[202:205], v[226:229], v[0:3]
	s_setprio 0
	s_barrier
	s_add_i32 s21, s21, 2
	s_add_u32 s10, s10, 0x100
	s_addc_u32 s11, s11, 0
	s_add_u32 s19, s19, 0x100
	s_addc_u32 s20, s20, 0
	s_cmp_gt_u32 s21, 13
	s_cbranch_scc0 .LBB0_780
	s_and_b64 vcc, exec, s[56:57]
	s_cbranch_vccz .LBB0_783
	s_barrier

;     __device__ __forceinline__ bool next(int i, Unit& u) const { const int L = i * G + c; if (L >= nsub) return false; u.pk = L >> 4; u.pm = MLAT / BM + (L & 3); u.pn = (L >> 2) & 3; return true; }
; #define PG8_STAGE(bufoff, gbase, voff) do { _Pragma("unroll") for (int _i = 0; _i < 2; ++_i) \
;         __builtin_amdgcn_global_load_lds((const unsigned*)((const char*)(gbase) + (voff)[_i]), (PG8_LAS unsigned*)(lds + (bufoff) + ldsw + _i * 8192), 16, 0, 0); } while (0)
; #define PG8_LDA(dst, b, h) do { _Pragma("unroll") for (int m = 0; m < 4; ++m) _Pragma("unroll") for (int k = 0; k < 2; ++k) dst[m][k] = *(const PG8_LAS bf16x8*)(lds + PG8_SA(b, h) + aoff + m * 2048 + k * 1024); } while (0)
; #define PG8_LDB(dst, b, h) do { _Pragma("unroll") for (int n = 0; n < 2; ++n) _Pragma("unroll") for (int k = 0; k < 2; ++k) dst[n][k] = *(const PG8_LAS bf16x8*)(lds + PG8_SB(b, h) + boff + n * 2048 + k * 1024); } while (0)
; #define PG8_WAIT_V(n) asm volatile("s_waitcnt vmcnt(" #n ")" ::: "memory")
; #define PG8_WAIT_L(n) asm volatile("s_waitcnt lgkmcnt(" #n ")" ::: "memory")
; template <class Epi, class Sched, bool ALIGN_EPI = false, bool SP2 = false>
; __device__ __forceinline__ void gemm_phase(PG8_LAS unsigned char* lds, const Gemm g, const Sched& S, const Epi& E) {
;     ...
;         const bool has_next = S.next(ui + 1, nxt);
;         const char* nA = has_next ? g.a_of(nxt) : cA; const char* nB = has_next ? g.b_of(nxt) : cB;
;         for (int t = 0; t < nt; t += 2) {
;             const bool last = (t == nt - 2);
;             const char* a1 = cA + (size_t)(t + 1) * kstep;
;             const char* a2 = last ? nA : cA + (size_t)(t + 2) * kstep; const char* b2 = last ? nB : cB + (size_t)(t + 2) * kstep;
;             const char* a3 = a2 + kstep; const char* b3 = b2 + kstep;
;             if (last && has_next) S.a_ready(nxt);
;             if constexpr (SP2) {
;             PG8_LDB(B0, 0, 0); PG8_LDB(B1, 0, 1); PG8_SCHED; PG8_LDA(At, 0, 0); PG8_STAGE(PG8_SA(1, 1), a1 + hstepA, voffA);
;             PG8_WAIT_V(8); PG8_WAIT_L(0); PG8_BAR; PG8_MMA(0, 0, At, B0); PG8_MMA(0, 1, At, B1); PG8_BAR; PG8_SCHED;
;             PG8_LDA(At, 0, 1); PG8_STAGE(PG8_SB(0, 0), b2, voffB); PG8_STAGE(PG8_SB(0, 1), b2 + hstepB, voffB); PG8_STAGE(PG8_SA(0, 0), a2, voffA);
;             PG8_WAIT_V(8); PG8_WAIT_L(0); PG8_BAR; PG8_MMA(1, 0, At, B0); PG8_MMA(1, 1, At, B1); PG8_BAR; PG8_SCHED;
.LBB0_1303:
	s_add_u32 s8, s28, 0x100
	s_addc_u32 s9, s29, 0
	s_add_i32 s63, 0, 0x10000
	s_cmp_eq_u32 s62, 2
	s_cselect_b32 s35, s25, s9
	s_cselect_b32 s34, s24, s8
	v_add_u32_e32 v142, s63, v147
	s_cselect_b32 s31, s27, s61
	s_cselect_b32 s30, s26, s59
	s_add_i32 s64, 0, 0x14000
	ds_read_b128 v[138:141], v142
	ds_read_b128 v[150:153], v142 offset:1024
	ds_read_b128 v[154:157], v142 offset:2048
	ds_read_b128 v[158:161], v142 offset:3072
	v_add_u32_e32 v142, s64, v147
	ds_read_b128 v[162:165], v142
	ds_read_b128 v[166:169], v142 offset:1024
	ds_read_b128 v[178:181], v142 offset:2048
	ds_read_b128 v[182:185], v142 offset:3072
	v_lshl_add_u64 v[142:143], s[28:29], 0, v[134:135]
	s_add_i32 m0, s46, 0xc000
	ds_read_b128 v[196:199], v149
	ds_read_b128 v[200:203], v149 offset:1024
	ds_read_b128 v[204:207], v149 offset:2048
	ds_read_b128 v[208:211], v149 offset:3072
	ds_read_b128 v[212:215], v149 offset:4096
	ds_read_b128 v[216:219], v149 offset:5120
	ds_read_b128 v[220:223], v149 offset:6144
	ds_read_b128 v[224:227], v149 offset:7168
	global_load_lds_dwordx4 v[142:143], off
	v_lshl_add_u64 v[142:143], s[28:29], 0, v[136:137]
	s_add_i32 m0, s46, 0xe000
	s_nop 0
	global_load_lds_dwordx4 v[142:143], off
	s_waitcnt vmcnt(8)
	s_waitcnt lgkmcnt(0)
	s_barrier
	s_setprio 1
	v_mfma_f32_16x16x32_bf16 v[124:127], v[138:141], v[196:199], v[124:127]
	v_mfma_f32_16x16x32_bf16 v[120:123], v[154:157], v[196:199], v[120:123]
	v_mfma_f32_16x16x32_bf16 v[108:111], v[138:141], v[204:207], v[108:111]
	v_mfma_f32_16x16x32_bf16 v[104:107], v[154:157], v[204:207], v[104:107]
	v_mfma_f32_16x16x32_bf16 v[92:95], v[138:141], v[212:215], v[92:95]
	v_mfma_f32_16x16x32_bf16 v[88:91], v[154:157], v[212:215], v[88:91]
	v_mfma_f32_16x16x32_bf16 v[76:79], v[138:141], v[220:223], v[76:79]
	v_mfma_f32_16x16x32_bf16 v[72:75], v[154:157], v[220:223], v[72:75]
	v_mfma_f32_16x16x32_bf16 v[124:127], v[150:153], v[200:203], v[124:127]
	v_mfma_f32_16x16x32_bf16 v[120:123], v[158:161], v[200:203], v[120:123]
	v_mfma_f32_16x16x32_bf16 v[108:111], v[150:153], v[208:211], v[108:111]
	v_mfma_f32_16x16x32_bf16 v[104:107], v[158:161], v[208:211], v[104:107]
	v_mfma_f32_16x16x32_bf16 v[92:95], v[150:153], v[216:219], v[92:95]
	v_mfma_f32_16x16x32_bf16 v[88:91], v[158:161], v[216:219], v[88:91]
	v_mfma_f32_16x16x32_bf16 v[76:79], v[150:153], v[224:227], v[76:79]
	v_mfma_f32_16x16x32_bf16 v[72:75], v[158:161], v[224:227], v[72:75]
	s_setprio 0
	s_setprio 1
	v_mfma_f32_16x16x32_bf16 v[116:119], v[162:165], v[196:199], v[116:119]
	v_mfma_f32_16x16x32_bf16 v[112:115], v[178:181], v[196:199], v[112:115]
	v_mfma_f32_16x16x32_bf16 v[100:103], v[162:165], v[204:207], v[100:103]
	v_mfma_f32_16x16x32_bf16 v[96:99], v[178:181], v[204:207], v[96:99]
	v_mfma_f32_16x16x32_bf16 v[84:87], v[162:165], v[212:215], v[84:87]
	v_mfma_f32_16x16x32_bf16 v[80:83], v[178:181], v[212:215], v[80:83]
	v_mfma_f32_16x16x32_bf16 v[68:71], v[162:165], v[220:223], v[68:71]
	v_mfma_f32_16x16x32_bf16 v[64:67], v[178:181], v[220:223], v[64:67]
	v_mfma_f32_16x16x32_bf16 v[116:119], v[166:169], v[200:203], v[116:119]
	v_mfma_f32_16x16x32_bf16 v[112:115], v[182:185], v[200:203], v[112:115]
	v_mfma_f32_16x16x32_bf16 v[100:103], v[166:169], v[208:211], v[100:103]
	v_mfma_f32_16x16x32_bf16 v[96:99], v[182:185], v[208:211], v[96:99]
	v_mfma_f32_16x16x32_bf16 v[84:87], v[166:169], v[216:219], v[84:87]
	v_mfma_f32_16x16x32_bf16 v[80:83], v[182:185], v[216:219], v[80:83]
	v_mfma_f32_16x16x32_bf16 v[68:71], v[166:169], v[224:227], v[68:71]
	v_mfma_f32_16x16x32_bf16 v[64:67], v[182:185], v[224:227], v[64:67]
	s_setprio 0
	s_barrier
	s_add_i32 s28, s63, s43
	v_lshl_add_u64 v[142:143], s[30:31], 0, v[172:173]
	s_mov_b32 m0, s28
	ds_read_b128 v[196:199], v149 offset:16384
	ds_read_b128 v[200:203], v149 offset:17408
	ds_read_b128 v[204:207], v149 offset:18432
	ds_read_b128 v[208:211], v149 offset:19456
	ds_read_b128 v[212:215], v149 offset:20480
	ds_read_b128 v[216:219], v149 offset:21504
	ds_read_b128 v[220:223], v149 offset:22528
	ds_read_b128 v[224:227], v149 offset:23552
	global_load_lds_dwordx4 v[142:143], off
	s_add_i32 m0, s28, 0x2000
	s_add_u32 s28, s30, 0x6000
	v_lshl_add_u64 v[170:171], s[30:31], 0, v[132:133]
	s_addc_u32 s29, s31, 0
	s_add_i32 s63, s64, s43
	global_load_lds_dwordx4 v[170:171], off
	s_mov_b32 m0, s63
	v_lshl_add_u64 v[176:177], s[34:35], 0, v[130:131]
	global_load_lds_dwordx4 v172, s[28:29]
	s_add_i32 m0, s63, 0x2000
	s_nop 0
	global_load_lds_dwordx4 v132, s[28:29]
	v_lshl_add_u64 v[174:175], s[34:35], 0, v[128:129]
	s_mov_b32 m0, s46
	s_nop 0
	global_load_lds_dwordx4 v[174:175], off
	s_mov_b32 m0, s47
	s_nop 0
	global_load_lds_dwordx4 v[176:177], off
	s_waitcnt vmcnt(8)
	s_waitcnt lgkmcnt(0)
	s_barrier
; #define PG8_STAGE(bufoff, gbase, voff) do { _Pragma("unroll") for (int _i = 0; _i < 2; ++_i) \
;         __builtin_amdgcn_global_load_lds((const unsigned*)((const char*)(gbase) + (voff)[_i]), (PG8_LAS unsigned*)(lds + (bufoff) + ldsw + _i * 8192), 16, 0, 0); } while (0)
; #define PG8_LDA(dst, b, h) do { _Pragma("unroll") for (int m = 0; m < 4; ++m) _Pragma("unroll") for (int k = 0; k < 2; ++k) dst[m][k] = *(const PG8_LAS bf16x8*)(lds + PG8_SA(b, h) + aoff + m * 2048 + k * 1024); } while (0)
; #define PG8_LDB(dst, b, h) do { _Pragma("unroll") for (int n = 0; n < 2; ++n) _Pragma("unroll") for (int k = 0; k < 2; ++k) dst[n][k] = *(const PG8_LAS bf16x8*)(lds + PG8_SB(b, h) + boff + n * 2048 + k * 1024); } while (0)
; #define PG8_MMA(ai, bj, At, Bt) do { __builtin_amdgcn_s_setprio(1); _Pragma("unroll") for (int m = 0; m < 4; ++m) _Pragma("unroll") for (int n = 0; n < 2; ++n) _Pragma("unroll") for (int k = 0; k < 2; ++k) \
;         acc[ai][bj][m][n] = __builtin_amdgcn_mfma_f32_16x16x32_bf16(Bt[n][k], At[m][k], acc[ai][bj][m][n], 0, 0, 0); __builtin_amdgcn_s_setprio(0); } while (0)
; #define PG8_WAIT_V(n) asm volatile("s_waitcnt vmcnt(" #n ")" ::: "memory")
; #define PG8_WAIT_L(n) asm volatile("s_waitcnt lgkmcnt(" #n ")" ::: "memory")
; #define PG8_BAR __builtin_amdgcn_s_barrier()
; #define PG8_SCHED __builtin_amdgcn_sched_barrier(0)
; template <class Epi, class Sched, bool ALIGN_EPI = false, bool SP2 = false>
; __device__ __forceinline__ void gemm_phase(PG8_LAS unsigned char* lds, const Gemm g, const Sched& S, const Epi& E) {
;     ...
;             if constexpr (SP2) {
;             PG8_LDB(B0, 0, 0); PG8_LDB(B1, 0, 1); PG8_SCHED; PG8_LDA(At, 0, 0); PG8_STAGE(PG8_SA(1, 1), a1 + hstepA, voffA);
;             PG8_WAIT_V(8); PG8_WAIT_L(0); PG8_BAR; PG8_MMA(0, 0, At, B0); PG8_MMA(0, 1, At, B1); PG8_BAR; PG8_SCHED;
;             PG8_LDA(At, 0, 1); PG8_STAGE(PG8_SB(0, 0), b2, voffB); PG8_STAGE(PG8_SB(0, 1), b2 + hstepB, voffB); PG8_STAGE(PG8_SA(0, 0), a2, voffA);
;             PG8_WAIT_V(8); PG8_WAIT_L(0); PG8_BAR; PG8_MMA(1, 0, At, B0); PG8_MMA(1, 1, At, B1); PG8_BAR; PG8_SCHED;
;             PG8_LDB(B0, 1, 0); PG8_LDB(B1, 1, 1); PG8_SCHED; PG8_LDA(At, 1, 0); PG8_STAGE(PG8_SA(0, 1), a2 + hstepA, voffA);
;             PG8_WAIT_V(8); PG8_WAIT_L(0); PG8_BAR; PG8_MMA(0, 0, At, B0); PG8_MMA(0, 1, At, B1); PG8_BAR; PG8_SCHED;
	s_setprio 1
	v_mfma_f32_16x16x32_bf16 v[60:63], v[138:141], v[196:199], v[60:63]
	v_mfma_f32_16x16x32_bf16 v[56:59], v[154:157], v[196:199], v[56:59]
	v_mfma_f32_16x16x32_bf16 v[44:47], v[138:141], v[204:207], v[44:47]
	v_mfma_f32_16x16x32_bf16 v[40:43], v[154:157], v[204:207], v[40:43]
	v_mfma_f32_16x16x32_bf16 v[28:31], v[138:141], v[212:215], v[28:31]
	v_mfma_f32_16x16x32_bf16 v[24:27], v[154:157], v[212:215], v[24:27]
	v_mfma_f32_16x16x32_bf16 v[12:15], v[138:141], v[220:223], v[12:15]
	v_mfma_f32_16x16x32_bf16 v[8:11], v[154:157], v[220:223], v[8:11]
	v_mfma_f32_16x16x32_bf16 v[60:63], v[150:153], v[200:203], v[60:63]
	v_mfma_f32_16x16x32_bf16 v[56:59], v[158:161], v[200:203], v[56:59]
	v_mfma_f32_16x16x32_bf16 v[44:47], v[150:153], v[208:211], v[44:47]
	v_mfma_f32_16x16x32_bf16 v[40:43], v[158:161], v[208:211], v[40:43]
	v_mfma_f32_16x16x32_bf16 v[28:31], v[150:153], v[216:219], v[28:31]
	v_mfma_f32_16x16x32_bf16 v[24:27], v[158:161], v[216:219], v[24:27]
	v_mfma_f32_16x16x32_bf16 v[12:15], v[150:153], v[224:227], v[12:15]
	v_mfma_f32_16x16x32_bf16 v[8:11], v[158:161], v[224:227], v[8:11]
	s_setprio 0
	s_setprio 1
	v_mfma_f32_16x16x32_bf16 v[52:55], v[162:165], v[196:199], v[52:55]
	v_mfma_f32_16x16x32_bf16 v[48:51], v[178:181], v[196:199], v[48:51]
	v_mfma_f32_16x16x32_bf16 v[36:39], v[162:165], v[204:207], v[36:39]
	v_mfma_f32_16x16x32_bf16 v[32:35], v[178:181], v[204:207], v[32:35]
	v_mfma_f32_16x16x32_bf16 v[20:23], v[162:165], v[212:215], v[20:23]
	v_mfma_f32_16x16x32_bf16 v[16:19], v[178:181], v[212:215], v[16:19]
	v_mfma_f32_16x16x32_bf16 v[4:7], v[162:165], v[220:223], v[4:7]
	v_mfma_f32_16x16x32_bf16 v[0:3], v[178:181], v[220:223], v[0:3]
	v_mfma_f32_16x16x32_bf16 v[52:55], v[166:169], v[200:203], v[52:55]
	v_mfma_f32_16x16x32_bf16 v[48:51], v[182:185], v[200:203], v[48:51]
	v_mfma_f32_16x16x32_bf16 v[36:39], v[166:169], v[208:211], v[36:39]
	v_mfma_f32_16x16x32_bf16 v[32:35], v[182:185], v[208:211], v[32:35]
	v_mfma_f32_16x16x32_bf16 v[20:23], v[166:169], v[216:219], v[20:23]
	v_mfma_f32_16x16x32_bf16 v[16:19], v[182:185], v[216:219], v[16:19]
	v_mfma_f32_16x16x32_bf16 v[4:7], v[166:169], v[224:227], v[4:7]
	v_mfma_f32_16x16x32_bf16 v[0:3], v[182:185], v[224:227], v[0:3]
	s_setprio 0
	s_barrier
	s_add_i32 s63, 0, 0x18000
	v_add_u32_e32 v144, s63, v147
	s_add_i32 s64, 0, 0x1c000
	ds_read_b128 v[138:141], v144
	ds_read_b128 v[150:153], v144 offset:1024
	ds_read_b128 v[154:157], v144 offset:2048
	ds_read_b128 v[158:161], v144 offset:3072
	v_add_u32_e32 v144, s64, v147
	ds_read_b128 v[162:165], v144
	ds_read_b128 v[166:169], v144 offset:1024
	ds_read_b128 v[178:181], v144 offset:2048
	ds_read_b128 v[182:185], v144 offset:3072
	s_add_u32 s28, s34, 0x18000
	s_addc_u32 s29, s35, 0
	s_mov_b32 m0, s50
	ds_read_b128 v[196:199], v149 offset:32768
	ds_read_b128 v[200:203], v149 offset:33792
	ds_read_b128 v[204:207], v149 offset:34816
	ds_read_b128 v[208:211], v149 offset:35840
	ds_read_b128 v[212:215], v149 offset:36864
	ds_read_b128 v[216:219], v149 offset:37888
	ds_read_b128 v[220:223], v149 offset:38912
	ds_read_b128 v[224:227], v149 offset:39936
	global_load_lds_dwordx4 v128, s[28:29]
	v_lshl_add_u64 v[186:187], s[28:29], 0, v[130:131]
	s_mov_b32 m0, s51
	s_nop 0
	global_load_lds_dwordx4 v[186:187], off
	s_waitcnt vmcnt(8)
	s_waitcnt lgkmcnt(0)
	s_barrier
	s_setprio 1
	v_mfma_f32_16x16x32_bf16 v[124:127], v[138:141], v[196:199], v[124:127]
	v_mfma_f32_16x16x32_bf16 v[120:123], v[154:157], v[196:199], v[120:123]
	v_mfma_f32_16x16x32_bf16 v[108:111], v[138:141], v[204:207], v[108:111]
	v_mfma_f32_16x16x32_bf16 v[104:107], v[154:157], v[204:207], v[104:107]
	v_mfma_f32_16x16x32_bf16 v[92:95], v[138:141], v[212:215], v[92:95]
	v_mfma_f32_16x16x32_bf16 v[88:91], v[154:157], v[212:215], v[88:91]
	v_mfma_f32_16x16x32_bf16 v[76:79], v[138:141], v[220:223], v[76:79]
	v_mfma_f32_16x16x32_bf16 v[72:75], v[154:157], v[220:223], v[72:75]
	v_mfma_f32_16x16x32_bf16 v[124:127], v[150:153], v[200:203], v[124:127]
	v_mfma_f32_16x16x32_bf16 v[120:123], v[158:161], v[200:203], v[120:123]
	v_mfma_f32_16x16x32_bf16 v[108:111], v[150:153], v[208:211], v[108:111]
	v_mfma_f32_16x16x32_bf16 v[104:107], v[158:161], v[208:211], v[104:107]
	v_mfma_f32_16x16x32_bf16 v[92:95], v[150:153], v[216:219], v[92:95]
	v_mfma_f32_16x16x32_bf16 v[88:91], v[158:161], v[216:219], v[88:91]
	v_mfma_f32_16x16x32_bf16 v[76:79], v[150:153], v[224:227], v[76:79]
	v_mfma_f32_16x16x32_bf16 v[72:75], v[158:161], v[224:227], v[72:75]
	s_setprio 0
	s_setprio 1
	v_mfma_f32_16x16x32_bf16 v[116:119], v[162:165], v[196:199], v[116:119]
	v_mfma_f32_16x16x32_bf16 v[112:115], v[178:181], v[196:199], v[112:115]
	v_mfma_f32_16x16x32_bf16 v[100:103], v[162:165], v[204:207], v[100:103]
	v_mfma_f32_16x16x32_bf16 v[96:99], v[178:181], v[204:207], v[96:99]
	v_mfma_f32_16x16x32_bf16 v[84:87], v[162:165], v[212:215], v[84:87]
	v_mfma_f32_16x16x32_bf16 v[80:83], v[178:181], v[212:215], v[80:83]
	v_mfma_f32_16x16x32_bf16 v[68:71], v[162:165], v[220:223], v[68:71]
	v_mfma_f32_16x16x32_bf16 v[64:67], v[178:181], v[220:223], v[64:67]
	v_mfma_f32_16x16x32_bf16 v[116:119], v[166:169], v[200:203], v[116:119]
	v_mfma_f32_16x16x32_bf16 v[112:115], v[182:185], v[200:203], v[112:115]
	v_mfma_f32_16x16x32_bf16 v[100:103], v[166:169], v[208:211], v[100:103]
	v_mfma_f32_16x16x32_bf16 v[96:99], v[182:185], v[208:211], v[96:99]
	v_mfma_f32_16x16x32_bf16 v[84:87], v[166:169], v[216:219], v[84:87]
	v_mfma_f32_16x16x32_bf16 v[80:83], v[182:185], v[216:219], v[80:83]
	v_mfma_f32_16x16x32_bf16 v[68:71], v[166:169], v[224:227], v[68:71]
	v_mfma_f32_16x16x32_bf16 v[64:67], v[182:185], v[224:227], v[64:67]
	s_setprio 0
	s_barrier
; #define PG8_STAGE(bufoff, gbase, voff) do { _Pragma("unroll") for (int _i = 0; _i < 2; ++_i) \
;         __builtin_amdgcn_global_load_lds((const unsigned*)((const char*)(gbase) + (voff)[_i]), (PG8_LAS unsigned*)(lds + (bufoff) + ldsw + _i * 8192), 16, 0, 0); } while (0)
; #define PG8_LDA(dst, b, h) do { _Pragma("unroll") for (int m = 0; m < 4; ++m) _Pragma("unroll") for (int k = 0; k < 2; ++k) dst[m][k] = *(const PG8_LAS bf16x8*)(lds + PG8_SA(b, h) + aoff + m * 2048 + k * 1024); } while (0)
; #define PG8_MMA(ai, bj, At, Bt) do { __builtin_amdgcn_s_setprio(1); _Pragma("unroll") for (int m = 0; m < 4; ++m) _Pragma("unroll") for (int n = 0; n < 2; ++n) _Pragma("unroll") for (int k = 0; k < 2; ++k) \
;         acc[ai][bj][m][n] = __builtin_amdgcn_mfma_f32_16x16x32_bf16(Bt[n][k], At[m][k], acc[ai][bj][m][n], 0, 0, 0); __builtin_amdgcn_s_setprio(0); } while (0)
; #define PG8_WAIT_V(n) asm volatile("s_waitcnt vmcnt(" #n ")" ::: "memory")
; #define PG8_WAIT_L(n) asm volatile("s_waitcnt lgkmcnt(" #n ")" ::: "memory")
; #define PG8_BAR __builtin_amdgcn_s_barrier()
; #define PG8_SCHED __builtin_amdgcn_sched_barrier(0)
; template <class Epi, class Sched, bool ALIGN_EPI = false, bool SP2 = false>
; __device__ __forceinline__ void gemm_phase(PG8_LAS unsigned char* lds, const Gemm g, const Sched& S, const Epi& E) {
;     ...
;             PG8_LDA(At, 1, 1); PG8_STAGE(PG8_SB(1, 0), b3, voffB); PG8_STAGE(PG8_SB(1, 1), b3 + hstepB, voffB); PG8_STAGE(PG8_SA(1, 0), a3, voffA);
;             PG8_WAIT_V(8); PG8_WAIT_L(0); PG8_BAR; PG8_MMA(1, 0, At, B0); PG8_MMA(1, 1, At, B1); PG8_BAR; PG8_SCHED;
;     ...
;         if constexpr (ALIGN_EPI) { if (wr == 0) PG8_BAR; }
	s_add_i32 s28, s63, s43
	v_lshl_add_u64 v[142:143], v[142:143], 0, s[80:81]
	s_mov_b32 m0, s28
	ds_read_b128 v[196:199], v149 offset:49152
	ds_read_b128 v[200:203], v149 offset:50176
	ds_read_b128 v[204:207], v149 offset:51200
	ds_read_b128 v[208:211], v149 offset:52224
	ds_read_b128 v[212:215], v149 offset:53248
	ds_read_b128 v[216:219], v149 offset:54272
	ds_read_b128 v[220:223], v149 offset:55296
	ds_read_b128 v[224:227], v149 offset:56320
	global_load_lds_dwordx4 v[142:143], off
	s_add_i32 m0, s28, 0x2000
	s_add_u32 s28, s30, 0x6080
	v_lshl_add_u64 v[142:143], v[170:171], 0, s[80:81]
	s_addc_u32 s29, s31, 0
	s_add_i32 s30, s64, s43
	global_load_lds_dwordx4 v[142:143], off
	s_mov_b32 m0, s30
	s_nop 0
	global_load_lds_dwordx4 v172, s[28:29]
	s_add_i32 m0, s30, 0x2000
	s_nop 0
	global_load_lds_dwordx4 v132, s[28:29]
	v_lshl_add_u64 v[142:143], v[174:175], 0, s[80:81]
	s_mov_b32 m0, s52
	s_nop 0
	global_load_lds_dwordx4 v[142:143], off
	v_lshl_add_u64 v[142:143], v[176:177], 0, s[80:81]
	s_mov_b32 m0, s53
	s_nop 0
	global_load_lds_dwordx4 v[142:143], off
	s_waitcnt vmcnt(8)
	s_waitcnt lgkmcnt(0)
	s_barrier
	s_setprio 1
	v_mfma_f32_16x16x32_bf16 v[60:63], v[138:141], v[196:199], v[60:63]
	v_mfma_f32_16x16x32_bf16 v[56:59], v[154:157], v[196:199], v[56:59]
	v_mfma_f32_16x16x32_bf16 v[44:47], v[138:141], v[204:207], v[44:47]
	v_mfma_f32_16x16x32_bf16 v[40:43], v[154:157], v[204:207], v[40:43]
	v_mfma_f32_16x16x32_bf16 v[28:31], v[138:141], v[212:215], v[28:31]
	v_mfma_f32_16x16x32_bf16 v[24:27], v[154:157], v[212:215], v[24:27]
	v_mfma_f32_16x16x32_bf16 v[12:15], v[138:141], v[220:223], v[12:15]
	v_mfma_f32_16x16x32_bf16 v[8:11], v[154:157], v[220:223], v[8:11]
	v_mfma_f32_16x16x32_bf16 v[60:63], v[150:153], v[200:203], v[60:63]
	v_mfma_f32_16x16x32_bf16 v[56:59], v[158:161], v[200:203], v[56:59]
	v_mfma_f32_16x16x32_bf16 v[44:47], v[150:153], v[208:211], v[44:47]
	v_mfma_f32_16x16x32_bf16 v[40:43], v[158:161], v[208:211], v[40:43]
	v_mfma_f32_16x16x32_bf16 v[28:31], v[150:153], v[216:219], v[28:31]
	v_mfma_f32_16x16x32_bf16 v[24:27], v[158:161], v[216:219], v[24:27]
	v_mfma_f32_16x16x32_bf16 v[12:15], v[150:153], v[224:227], v[12:15]
	v_mfma_f32_16x16x32_bf16 v[8:11], v[158:161], v[224:227], v[8:11]
	s_setprio 0
	s_setprio 1
	v_mfma_f32_16x16x32_bf16 v[52:55], v[162:165], v[196:199], v[52:55]
	v_mfma_f32_16x16x32_bf16 v[48:51], v[178:181], v[196:199], v[48:51]
	v_mfma_f32_16x16x32_bf16 v[36:39], v[162:165], v[204:207], v[36:39]
	v_mfma_f32_16x16x32_bf16 v[32:35], v[178:181], v[204:207], v[32:35]
	v_mfma_f32_16x16x32_bf16 v[20:23], v[162:165], v[212:215], v[20:23]
	v_mfma_f32_16x16x32_bf16 v[16:19], v[178:181], v[212:215], v[16:19]
	v_mfma_f32_16x16x32_bf16 v[4:7], v[162:165], v[220:223], v[4:7]
	v_mfma_f32_16x16x32_bf16 v[0:3], v[178:181], v[220:223], v[0:3]
	v_mfma_f32_16x16x32_bf16 v[52:55], v[166:169], v[200:203], v[52:55]
	v_mfma_f32_16x16x32_bf16 v[48:51], v[182:185], v[200:203], v[48:51]
	v_mfma_f32_16x16x32_bf16 v[36:39], v[166:169], v[208:211], v[36:39]
	v_mfma_f32_16x16x32_bf16 v[32:35], v[182:185], v[208:211], v[32:35]
	v_mfma_f32_16x16x32_bf16 v[20:23], v[166:169], v[216:219], v[20:23]
	v_mfma_f32_16x16x32_bf16 v[16:19], v[182:185], v[216:219], v[16:19]
	v_mfma_f32_16x16x32_bf16 v[4:7], v[166:169], v[224:227], v[4:7]
	v_mfma_f32_16x16x32_bf16 v[0:3], v[182:185], v[224:227], v[0:3]
	s_setprio 0
	s_barrier
	s_add_i32 s62, s62, 2
	s_add_u32 s59, s59, 0x100
	s_addc_u32 s61, s61, 0
	s_cmp_gt_u32 s62, 3
	s_mov_b64 s[28:29], s[8:9]
	s_cbranch_scc0 .LBB0_1303
	s_and_b64 vcc, exec, s[20:21]
	s_cbranch_vccz .LBB0_1306
	s_barrier

;     __device__ __forceinline__ bool next(int i, Unit& u) const { const int L = i * G + c; if (L >= nsub) return false; u.pk = L >> 4; u.pm = MLAT / BM + (L & 3); u.pn = (L >> 2) & 3; return true; }
; #define PG8_STAGE(bufoff, gbase, voff) do { _Pragma("unroll") for (int _i = 0; _i < 2; ++_i) \
;         __builtin_amdgcn_global_load_lds((const unsigned*)((const char*)(gbase) + (voff)[_i]), (PG8_LAS unsigned*)(lds + (bufoff) + ldsw + _i * 8192), 16, 0, 0); } while (0)
; #define PG8_LDA(dst, b, h) do { _Pragma("unroll") for (int m = 0; m < 4; ++m) _Pragma("unroll") for (int k = 0; k < 2; ++k) dst[m][k] = *(const PG8_LAS bf16x8*)(lds + PG8_SA(b, h) + aoff + m * 2048 + k * 1024); } while (0)
; #define PG8_LDB(dst, b, h) do { _Pragma("unroll") for (int n = 0; n < 2; ++n) _Pragma("unroll") for (int k = 0; k < 2; ++k) dst[n][k] = *(const PG8_LAS bf16x8*)(lds + PG8_SB(b, h) + boff + n * 2048 + k * 1024); } while (0)
; #define PG8_WAIT_V(n) asm volatile("s_waitcnt vmcnt(" #n ")" ::: "memory")
; #define PG8_WAIT_L(n) asm volatile("s_waitcnt lgkmcnt(" #n ")" ::: "memory")
; template <class Epi, class Sched, bool ALIGN_EPI = false, bool SP2 = false>
; __device__ __forceinline__ void gemm_phase(PG8_LAS unsigned char* lds, const Gemm g, const Sched& S, const Epi& E) {
;     ...
;         const bool has_next = S.next(ui + 1, nxt);
;         const char* nA = has_next ? g.a_of(nxt) : cA; const char* nB = has_next ? g.b_of(nxt) : cB;
;         for (int t = 0; t < nt; t += 2) {
;             const bool last = (t == nt - 2);
;             const char* a1 = cA + (size_t)(t + 1) * kstep;
;             const char* a2 = last ? nA : cA + (size_t)(t + 2) * kstep; const char* b2 = last ? nB : cB + (size_t)(t + 2) * kstep;
;             const char* a3 = a2 + kstep; const char* b3 = b2 + kstep;
;             if (last && has_next) S.a_ready(nxt);
;             if constexpr (SP2) {
;             PG8_LDB(B0, 0, 0); PG8_LDB(B1, 0, 1); PG8_SCHED; PG8_LDA(At, 0, 0); PG8_STAGE(PG8_SA(1, 1), a1 + hstepA, voffA);
;             PG8_WAIT_V(8); PG8_WAIT_L(0); PG8_BAR; PG8_MMA(0, 0, At, B0); PG8_MMA(0, 1, At, B1); PG8_BAR; PG8_SCHED;
;             PG8_LDA(At, 0, 1); PG8_STAGE(PG8_SB(0, 0), b2, voffB); PG8_STAGE(PG8_SB(0, 1), b2 + hstepB, voffB); PG8_STAGE(PG8_SA(0, 0), a2, voffA);
;             PG8_WAIT_V(8); PG8_WAIT_L(0); PG8_BAR; PG8_MMA(1, 0, At, B0); PG8_MMA(1, 1, At, B1); PG8_BAR; PG8_SCHED;
.LBB0_1337:
	s_add_u32 s51, s42, s50
	s_addc_u32 s56, s43, 0
	s_add_u32 s54, s51, 0x100
	s_addc_u32 s55, s56, 0
	s_and_b64 s[52:53], s[46:47], exec
	s_cselect_b32 s53, s29, s55
	s_cselect_b32 s52, s37, s54
	s_add_u32 s50, s40, s50
	s_addc_u32 s54, s41, 0
	s_add_u32 s50, s50, 0x100
	s_addc_u32 s54, s54, 0
	s_add_i32 s89, 0, 0x10000
	s_and_b64 s[46:47], s[46:47], exec
	s_cselect_b32 s55, s27, s54
	s_cselect_b32 s54, s39, s50
	s_add_i32 s47, 0, 0x14000
	s_add_u32 s58, s51, 0x10080
	s_addc_u32 s59, s56, 0
	s_add_i32 s87, s89, s3
	s_add_i32 m0, s65, 0xc000
	s_add_i32 s93, s65, 0xe000
	s_add_i32 s83, s87, 0x2000
	s_add_u32 s56, s54, 0x10000
	v_add_u32_e32 v160, s89, v196
	v_add_u32_e32 v174, s47, v196
	s_addc_u32 s57, s55, 0
	s_add_i32 s86, s47, s3
	ds_read_b128 v[64:67], v160
	ds_read_b128 v[68:71], v160 offset:1024
	ds_read_b128 v[156:159], v160 offset:2048
	ds_read_b128 v[160:163], v160 offset:3072
	ds_read_b128 v[164:167], v174
	ds_read_b128 v[168:171], v174 offset:1024
	ds_read_b128 v[178:181], v174 offset:2048
	ds_read_b128 v[182:185], v174 offset:3072
	s_add_i32 s85, s86, 0x2000
	s_add_i32 s79, 0, 0x18000
	s_add_i32 s78, 0, 0x1c000
	s_add_u32 s50, s52, 0x10000
	s_addc_u32 s51, s53, 0
	s_add_i32 s77, s79, s3
	s_add_i32 s76, s77, 0x2000
	s_add_u32 s46, s54, 0x10080
	s_addc_u32 s47, s55, 0
	s_add_i32 s91, s78, s3
	s_add_i32 s89, s91, 0x2000
	v_lshl_add_u64 v[174:175], s[58:59], 0, v[136:137]
	ds_read_b128 v[202:205], v200
	ds_read_b128 v[206:209], v200 offset:1024
	ds_read_b128 v[210:213], v200 offset:2048
	ds_read_b128 v[214:217], v200 offset:3072
	ds_read_b128 v[218:221], v200 offset:4096
	ds_read_b128 v[222:225], v200 offset:5120
	ds_read_b128 v[226:229], v200 offset:6144
	ds_read_b128 v[230:233], v200 offset:7168
	global_load_lds_dwordx4 v[174:175], off
	v_lshl_add_u64 v[174:175], s[58:59], 0, v[140:141]
	s_mov_b32 m0, s93
	s_nop 0
	global_load_lds_dwordx4 v[174:175], off
	s_waitcnt vmcnt(8)
	s_waitcnt lgkmcnt(0)
	s_barrier
	s_setprio 1
	v_mfma_f32_16x16x32_bf16 v[132:135], v[64:67], v[202:205], v[132:135]
	v_mfma_f32_16x16x32_bf16 v[128:131], v[156:159], v[202:205], v[128:131]
	v_mfma_f32_16x16x32_bf16 v[116:119], v[64:67], v[210:213], v[116:119]
	v_mfma_f32_16x16x32_bf16 v[112:115], v[156:159], v[210:213], v[112:115]
	v_mfma_f32_16x16x32_bf16 v[100:103], v[64:67], v[218:221], v[100:103]
	v_mfma_f32_16x16x32_bf16 v[96:99], v[156:159], v[218:221], v[96:99]
	v_mfma_f32_16x16x32_bf16 v[84:87], v[64:67], v[226:229], v[84:87]
	v_mfma_f32_16x16x32_bf16 v[80:83], v[156:159], v[226:229], v[80:83]
	v_mfma_f32_16x16x32_bf16 v[132:135], v[68:71], v[206:209], v[132:135]
	v_mfma_f32_16x16x32_bf16 v[128:131], v[160:163], v[206:209], v[128:131]
	v_mfma_f32_16x16x32_bf16 v[116:119], v[68:71], v[214:217], v[116:119]
	v_mfma_f32_16x16x32_bf16 v[112:115], v[160:163], v[214:217], v[112:115]
	v_mfma_f32_16x16x32_bf16 v[100:103], v[68:71], v[222:225], v[100:103]
	v_mfma_f32_16x16x32_bf16 v[96:99], v[160:163], v[222:225], v[96:99]
	v_mfma_f32_16x16x32_bf16 v[84:87], v[68:71], v[230:233], v[84:87]
	v_mfma_f32_16x16x32_bf16 v[80:83], v[160:163], v[230:233], v[80:83]
	s_setprio 0
	s_setprio 1
	v_mfma_f32_16x16x32_bf16 v[124:127], v[164:167], v[202:205], v[124:127]
	v_mfma_f32_16x16x32_bf16 v[120:123], v[178:181], v[202:205], v[120:123]
	v_mfma_f32_16x16x32_bf16 v[108:111], v[164:167], v[210:213], v[108:111]
	v_mfma_f32_16x16x32_bf16 v[104:107], v[178:181], v[210:213], v[104:107]
	v_mfma_f32_16x16x32_bf16 v[92:95], v[164:167], v[218:221], v[92:95]
	v_mfma_f32_16x16x32_bf16 v[88:91], v[178:181], v[218:221], v[88:91]
	v_mfma_f32_16x16x32_bf16 v[76:79], v[164:167], v[226:229], v[76:79]
	v_mfma_f32_16x16x32_bf16 v[72:75], v[178:181], v[226:229], v[72:75]
	v_mfma_f32_16x16x32_bf16 v[124:127], v[168:171], v[206:209], v[124:127]
	v_mfma_f32_16x16x32_bf16 v[120:123], v[182:185], v[206:209], v[120:123]
	v_mfma_f32_16x16x32_bf16 v[108:111], v[168:171], v[214:217], v[108:111]
	v_mfma_f32_16x16x32_bf16 v[104:107], v[182:185], v[214:217], v[104:107]
	v_mfma_f32_16x16x32_bf16 v[92:95], v[168:171], v[222:225], v[92:95]
	v_mfma_f32_16x16x32_bf16 v[88:91], v[182:185], v[222:225], v[88:91]
	v_mfma_f32_16x16x32_bf16 v[76:79], v[168:171], v[230:233], v[76:79]
	v_mfma_f32_16x16x32_bf16 v[72:75], v[182:185], v[230:233], v[72:75]
	s_setprio 0
	s_barrier
	s_mov_b32 m0, s87
	v_lshl_add_u64 v[174:175], s[54:55], 0, v[138:139]
	ds_read_b128 v[202:205], v200 offset:16384
	ds_read_b128 v[206:209], v200 offset:17408
	ds_read_b128 v[210:213], v200 offset:18432
	ds_read_b128 v[214:217], v200 offset:19456
	ds_read_b128 v[218:221], v200 offset:20480
	ds_read_b128 v[222:225], v200 offset:21504
	ds_read_b128 v[226:229], v200 offset:22528
	ds_read_b128 v[230:233], v200 offset:23552
	global_load_lds_dwordx4 v[174:175], off
	v_lshl_add_u64 v[176:177], s[54:55], 0, v[142:143]
	s_mov_b32 m0, s83
	v_lshl_add_u64 v[192:193], s[56:57], 0, v[138:139]
	global_load_lds_dwordx4 v[176:177], off
	s_mov_b32 m0, s86
	v_lshl_add_u64 v[194:195], s[52:53], 0, v[140:141]
	global_load_lds_dwordx4 v[192:193], off
	v_lshl_add_u64 v[192:193], s[56:57], 0, v[142:143]
	s_mov_b32 m0, s85
	s_nop 0
	global_load_lds_dwordx4 v[192:193], off
	v_lshl_add_u64 v[192:193], s[52:53], 0, v[136:137]
	s_mov_b32 m0, s65
	s_nop 0
	global_load_lds_dwordx4 v[192:193], off
	s_mov_b32 m0, s66
	s_nop 0
	global_load_lds_dwordx4 v[194:195], off
	s_waitcnt vmcnt(8)
	s_waitcnt lgkmcnt(0)
	s_barrier
; #define PG8_STAGE(bufoff, gbase, voff) do { _Pragma("unroll") for (int _i = 0; _i < 2; ++_i) \
;         __builtin_amdgcn_global_load_lds((const unsigned*)((const char*)(gbase) + (voff)[_i]), (PG8_LAS unsigned*)(lds + (bufoff) + ldsw + _i * 8192), 16, 0, 0); } while (0)
; #define PG8_LDA(dst, b, h) do { _Pragma("unroll") for (int m = 0; m < 4; ++m) _Pragma("unroll") for (int k = 0; k < 2; ++k) dst[m][k] = *(const PG8_LAS bf16x8*)(lds + PG8_SA(b, h) + aoff + m * 2048 + k * 1024); } while (0)
; #define PG8_LDB(dst, b, h) do { _Pragma("unroll") for (int n = 0; n < 2; ++n) _Pragma("unroll") for (int k = 0; k < 2; ++k) dst[n][k] = *(const PG8_LAS bf16x8*)(lds + PG8_SB(b, h) + boff + n * 2048 + k * 1024); } while (0)
; #define PG8_MMA(ai, bj, At, Bt) do { __builtin_amdgcn_s_setprio(1); _Pragma("unroll") for (int m = 0; m < 4; ++m) _Pragma("unroll") for (int n = 0; n < 2; ++n) _Pragma("unroll") for (int k = 0; k < 2; ++k) \
;         acc[ai][bj][m][n] = __builtin_amdgcn_mfma_f32_16x16x32_bf16(Bt[n][k], At[m][k], acc[ai][bj][m][n], 0, 0, 0); __builtin_amdgcn_s_setprio(0); } while (0)
; #define PG8_WAIT_V(n) asm volatile("s_waitcnt vmcnt(" #n ")" ::: "memory")
; #define PG8_WAIT_L(n) asm volatile("s_waitcnt lgkmcnt(" #n ")" ::: "memory")
; #define PG8_BAR __builtin_amdgcn_s_barrier()
; #define PG8_SCHED __builtin_amdgcn_sched_barrier(0)
; template <class Epi, class Sched, bool ALIGN_EPI = false, bool SP2 = false>
; __device__ __forceinline__ void gemm_phase(PG8_LAS unsigned char* lds, const Gemm g, const Sched& S, const Epi& E) {
;     ...
;             if constexpr (SP2) {
;             PG8_LDB(B0, 0, 0); PG8_LDB(B1, 0, 1); PG8_SCHED; PG8_LDA(At, 0, 0); PG8_STAGE(PG8_SA(1, 1), a1 + hstepA, voffA);
;             PG8_WAIT_V(8); PG8_WAIT_L(0); PG8_BAR; PG8_MMA(0, 0, At, B0); PG8_MMA(0, 1, At, B1); PG8_BAR; PG8_SCHED;
;             PG8_LDA(At, 0, 1); PG8_STAGE(PG8_SB(0, 0), b2, voffB); PG8_STAGE(PG8_SB(0, 1), b2 + hstepB, voffB); PG8_STAGE(PG8_SA(0, 0), a2, voffA);
;             PG8_WAIT_V(8); PG8_WAIT_L(0); PG8_BAR; PG8_MMA(1, 0, At, B0); PG8_MMA(1, 1, At, B1); PG8_BAR; PG8_SCHED;
;             PG8_LDB(B0, 1, 0); PG8_LDB(B1, 1, 1); PG8_SCHED; PG8_LDA(At, 1, 0); PG8_STAGE(PG8_SA(0, 1), a2 + hstepA, voffA);
;             PG8_WAIT_V(8); PG8_WAIT_L(0); PG8_BAR; PG8_MMA(0, 0, At, B0); PG8_MMA(0, 1, At, B1); PG8_BAR; PG8_SCHED;
	s_setprio 1
	v_mfma_f32_16x16x32_bf16 v[56:59], v[64:67], v[202:205], v[56:59]
	v_mfma_f32_16x16x32_bf16 v[48:51], v[156:159], v[202:205], v[48:51]
	v_mfma_f32_16x16x32_bf16 v[44:47], v[64:67], v[210:213], v[44:47]
	v_mfma_f32_16x16x32_bf16 v[40:43], v[156:159], v[210:213], v[40:43]
	v_mfma_f32_16x16x32_bf16 v[28:31], v[64:67], v[218:221], v[28:31]
	v_mfma_f32_16x16x32_bf16 v[24:27], v[156:159], v[218:221], v[24:27]
	v_mfma_f32_16x16x32_bf16 v[12:15], v[64:67], v[226:229], v[12:15]
	v_mfma_f32_16x16x32_bf16 v[8:11], v[156:159], v[226:229], v[8:11]
	v_mfma_f32_16x16x32_bf16 v[56:59], v[68:71], v[206:209], v[56:59]
	v_mfma_f32_16x16x32_bf16 v[48:51], v[160:163], v[206:209], v[48:51]
	v_mfma_f32_16x16x32_bf16 v[44:47], v[68:71], v[214:217], v[44:47]
	v_mfma_f32_16x16x32_bf16 v[40:43], v[160:163], v[214:217], v[40:43]
	v_mfma_f32_16x16x32_bf16 v[28:31], v[68:71], v[222:225], v[28:31]
	v_mfma_f32_16x16x32_bf16 v[24:27], v[160:163], v[222:225], v[24:27]
	v_mfma_f32_16x16x32_bf16 v[12:15], v[68:71], v[230:233], v[12:15]
	v_mfma_f32_16x16x32_bf16 v[8:11], v[160:163], v[230:233], v[8:11]
	s_setprio 0
	s_setprio 1
	v_mfma_f32_16x16x32_bf16 v[60:63], v[164:167], v[202:205], v[60:63]
	v_mfma_f32_16x16x32_bf16 v[52:55], v[178:181], v[202:205], v[52:55]
	v_mfma_f32_16x16x32_bf16 v[36:39], v[164:167], v[210:213], v[36:39]
	v_mfma_f32_16x16x32_bf16 v[32:35], v[178:181], v[210:213], v[32:35]
	v_mfma_f32_16x16x32_bf16 v[20:23], v[164:167], v[218:221], v[20:23]
	v_mfma_f32_16x16x32_bf16 v[16:19], v[178:181], v[218:221], v[16:19]
	v_mfma_f32_16x16x32_bf16 v[4:7], v[164:167], v[226:229], v[4:7]
	v_mfma_f32_16x16x32_bf16 v[0:3], v[178:181], v[226:229], v[0:3]
	v_mfma_f32_16x16x32_bf16 v[60:63], v[168:171], v[206:209], v[60:63]
	v_mfma_f32_16x16x32_bf16 v[52:55], v[182:185], v[206:209], v[52:55]
	v_mfma_f32_16x16x32_bf16 v[36:39], v[168:171], v[214:217], v[36:39]
	v_mfma_f32_16x16x32_bf16 v[32:35], v[182:185], v[214:217], v[32:35]
	v_mfma_f32_16x16x32_bf16 v[20:23], v[168:171], v[222:225], v[20:23]
	v_mfma_f32_16x16x32_bf16 v[16:19], v[182:185], v[222:225], v[16:19]
	v_mfma_f32_16x16x32_bf16 v[4:7], v[168:171], v[230:233], v[4:7]
	v_mfma_f32_16x16x32_bf16 v[0:3], v[182:185], v[230:233], v[0:3]
	s_setprio 0
	s_barrier
	v_add_u32_e32 v160, s79, v196
	v_add_u32_e32 v182, s78, v196
	ds_read_b128 v[64:67], v160
	ds_read_b128 v[68:71], v160 offset:1024
	ds_read_b128 v[156:159], v160 offset:2048
	ds_read_b128 v[160:163], v160 offset:3072
	ds_read_b128 v[164:167], v182
	ds_read_b128 v[168:171], v182 offset:1024
	ds_read_b128 v[178:181], v182 offset:2048
	ds_read_b128 v[182:185], v182 offset:3072
	s_mov_b32 m0, s67
	v_lshl_add_u64 v[234:235], s[50:51], 0, v[136:137]
	ds_read_b128 v[202:205], v200 offset:32768
	ds_read_b128 v[206:209], v200 offset:33792
	ds_read_b128 v[210:213], v200 offset:34816
	ds_read_b128 v[214:217], v200 offset:35840
	ds_read_b128 v[218:221], v200 offset:36864
	ds_read_b128 v[222:225], v200 offset:37888
	ds_read_b128 v[226:229], v200 offset:38912
	ds_read_b128 v[230:233], v200 offset:39936
	global_load_lds_dwordx4 v[234:235], off
	v_lshl_add_u64 v[234:235], s[50:51], 0, v[140:141]
	s_mov_b32 m0, s70
	s_nop 0
	global_load_lds_dwordx4 v[234:235], off
	s_waitcnt vmcnt(8)
	s_waitcnt lgkmcnt(0)
	s_barrier
	s_setprio 1
	v_mfma_f32_16x16x32_bf16 v[132:135], v[64:67], v[202:205], v[132:135]
	v_mfma_f32_16x16x32_bf16 v[128:131], v[156:159], v[202:205], v[128:131]
	v_mfma_f32_16x16x32_bf16 v[116:119], v[64:67], v[210:213], v[116:119]
	v_mfma_f32_16x16x32_bf16 v[112:115], v[156:159], v[210:213], v[112:115]
	v_mfma_f32_16x16x32_bf16 v[100:103], v[64:67], v[218:221], v[100:103]
	v_mfma_f32_16x16x32_bf16 v[96:99], v[156:159], v[218:221], v[96:99]
	v_mfma_f32_16x16x32_bf16 v[84:87], v[64:67], v[226:229], v[84:87]
	v_mfma_f32_16x16x32_bf16 v[80:83], v[156:159], v[226:229], v[80:83]
	v_mfma_f32_16x16x32_bf16 v[132:135], v[68:71], v[206:209], v[132:135]
	v_mfma_f32_16x16x32_bf16 v[128:131], v[160:163], v[206:209], v[128:131]
	v_mfma_f32_16x16x32_bf16 v[116:119], v[68:71], v[214:217], v[116:119]
	v_mfma_f32_16x16x32_bf16 v[112:115], v[160:163], v[214:217], v[112:115]
	v_mfma_f32_16x16x32_bf16 v[100:103], v[68:71], v[222:225], v[100:103]
	v_mfma_f32_16x16x32_bf16 v[96:99], v[160:163], v[222:225], v[96:99]
	v_mfma_f32_16x16x32_bf16 v[84:87], v[68:71], v[230:233], v[84:87]
	v_mfma_f32_16x16x32_bf16 v[80:83], v[160:163], v[230:233], v[80:83]
	s_setprio 0
	s_setprio 1
	v_mfma_f32_16x16x32_bf16 v[124:127], v[164:167], v[202:205], v[124:127]
	v_mfma_f32_16x16x32_bf16 v[120:123], v[178:181], v[202:205], v[120:123]
	v_mfma_f32_16x16x32_bf16 v[108:111], v[164:167], v[210:213], v[108:111]
	v_mfma_f32_16x16x32_bf16 v[104:107], v[178:181], v[210:213], v[104:107]
	v_mfma_f32_16x16x32_bf16 v[92:95], v[164:167], v[218:221], v[92:95]
	v_mfma_f32_16x16x32_bf16 v[88:91], v[178:181], v[218:221], v[88:91]
	v_mfma_f32_16x16x32_bf16 v[76:79], v[164:167], v[226:229], v[76:79]
	v_mfma_f32_16x16x32_bf16 v[72:75], v[178:181], v[226:229], v[72:75]
	v_mfma_f32_16x16x32_bf16 v[124:127], v[168:171], v[206:209], v[124:127]
	v_mfma_f32_16x16x32_bf16 v[120:123], v[182:185], v[206:209], v[120:123]
	v_mfma_f32_16x16x32_bf16 v[108:111], v[168:171], v[214:217], v[108:111]
	v_mfma_f32_16x16x32_bf16 v[104:107], v[182:185], v[214:217], v[104:107]
	v_mfma_f32_16x16x32_bf16 v[92:95], v[168:171], v[222:225], v[92:95]
	v_mfma_f32_16x16x32_bf16 v[88:91], v[182:185], v[222:225], v[88:91]
	v_mfma_f32_16x16x32_bf16 v[76:79], v[168:171], v[230:233], v[76:79]
	v_mfma_f32_16x16x32_bf16 v[72:75], v[182:185], v[230:233], v[72:75]
	s_setprio 0
	s_barrier
; #define PG8_STAGE(bufoff, gbase, voff) do { _Pragma("unroll") for (int _i = 0; _i < 2; ++_i) \
;         __builtin_amdgcn_global_load_lds((const unsigned*)((const char*)(gbase) + (voff)[_i]), (PG8_LAS unsigned*)(lds + (bufoff) + ldsw + _i * 8192), 16, 0, 0); } while (0)
; #define PG8_LDA(dst, b, h) do { _Pragma("unroll") for (int m = 0; m < 4; ++m) _Pragma("unroll") for (int k = 0; k < 2; ++k) dst[m][k] = *(const PG8_LAS bf16x8*)(lds + PG8_SA(b, h) + aoff + m * 2048 + k * 1024); } while (0)
; #define PG8_MMA(ai, bj, At, Bt) do { __builtin_amdgcn_s_setprio(1); _Pragma("unroll") for (int m = 0; m < 4; ++m) _Pragma("unroll") for (int n = 0; n < 2; ++n) _Pragma("unroll") for (int k = 0; k < 2; ++k) \
;         acc[ai][bj][m][n] = __builtin_amdgcn_mfma_f32_16x16x32_bf16(Bt[n][k], At[m][k], acc[ai][bj][m][n], 0, 0, 0); __builtin_amdgcn_s_setprio(0); } while (0)
; #define PG8_WAIT_V(n) asm volatile("s_waitcnt vmcnt(" #n ")" ::: "memory")
; #define PG8_WAIT_L(n) asm volatile("s_waitcnt lgkmcnt(" #n ")" ::: "memory")
; #define PG8_BAR __builtin_amdgcn_s_barrier()
; #define PG8_SCHED __builtin_amdgcn_sched_barrier(0)
; template <class Epi, class Sched, bool ALIGN_EPI = false, bool SP2 = false>
; __device__ __forceinline__ void gemm_phase(PG8_LAS unsigned char* lds, const Gemm g, const Sched& S, const Epi& E) {
;     ...
;             PG8_LDA(At, 1, 1); PG8_STAGE(PG8_SB(1, 0), b3, voffB); PG8_STAGE(PG8_SB(1, 1), b3 + hstepB, voffB); PG8_STAGE(PG8_SA(1, 0), a3, voffA);
;             PG8_WAIT_V(8); PG8_WAIT_L(0); PG8_BAR; PG8_MMA(1, 0, At, B0); PG8_MMA(1, 1, At, B1); PG8_BAR; PG8_SCHED;
;     ...
;         if constexpr (ALIGN_EPI) { if (wr == 0) PG8_BAR; }
	s_mov_b32 m0, s77
	v_lshl_add_u64 v[174:175], v[174:175], 0, s[80:81]
	ds_read_b128 v[202:205], v200 offset:49152
	ds_read_b128 v[206:209], v200 offset:50176
	ds_read_b128 v[210:213], v200 offset:51200
	ds_read_b128 v[214:217], v200 offset:52224
	ds_read_b128 v[218:221], v200 offset:53248
	ds_read_b128 v[222:225], v200 offset:54272
	ds_read_b128 v[226:229], v200 offset:55296
	ds_read_b128 v[230:233], v200 offset:56320
	global_load_lds_dwordx4 v[174:175], off
	v_lshl_add_u64 v[174:175], v[176:177], 0, s[80:81]
	s_mov_b32 m0, s76
	s_nop 0
	global_load_lds_dwordx4 v[174:175], off
	v_lshl_add_u64 v[174:175], s[46:47], 0, v[138:139]
	s_mov_b32 m0, s91
	s_nop 0
	global_load_lds_dwordx4 v[174:175], off
	v_lshl_add_u64 v[174:175], s[46:47], 0, v[142:143]
	s_mov_b32 m0, s89
	s_nop 0
	global_load_lds_dwordx4 v[174:175], off
	v_lshl_add_u64 v[174:175], v[192:193], 0, s[80:81]
	s_mov_b32 m0, s72
	s_nop 0
	global_load_lds_dwordx4 v[174:175], off
	v_lshl_add_u64 v[174:175], v[194:195], 0, s[80:81]
	s_mov_b32 m0, s73
	s_nop 0
	global_load_lds_dwordx4 v[174:175], off
	s_waitcnt vmcnt(8)
	s_waitcnt lgkmcnt(0)
	s_barrier
	s_setprio 1
	v_mfma_f32_16x16x32_bf16 v[56:59], v[64:67], v[202:205], v[56:59]
	v_mfma_f32_16x16x32_bf16 v[48:51], v[156:159], v[202:205], v[48:51]
	v_mfma_f32_16x16x32_bf16 v[44:47], v[64:67], v[210:213], v[44:47]
	v_mfma_f32_16x16x32_bf16 v[40:43], v[156:159], v[210:213], v[40:43]
	v_mfma_f32_16x16x32_bf16 v[28:31], v[64:67], v[218:221], v[28:31]
	v_mfma_f32_16x16x32_bf16 v[24:27], v[156:159], v[218:221], v[24:27]
	v_mfma_f32_16x16x32_bf16 v[12:15], v[64:67], v[226:229], v[12:15]
	v_mfma_f32_16x16x32_bf16 v[8:11], v[156:159], v[226:229], v[8:11]
	v_mfma_f32_16x16x32_bf16 v[56:59], v[68:71], v[206:209], v[56:59]
	v_mfma_f32_16x16x32_bf16 v[48:51], v[160:163], v[206:209], v[48:51]
	v_mfma_f32_16x16x32_bf16 v[44:47], v[68:71], v[214:217], v[44:47]
	v_mfma_f32_16x16x32_bf16 v[40:43], v[160:163], v[214:217], v[40:43]
	v_mfma_f32_16x16x32_bf16 v[28:31], v[68:71], v[222:225], v[28:31]
	v_mfma_f32_16x16x32_bf16 v[24:27], v[160:163], v[222:225], v[24:27]
	v_mfma_f32_16x16x32_bf16 v[12:15], v[68:71], v[230:233], v[12:15]
	v_mfma_f32_16x16x32_bf16 v[8:11], v[160:163], v[230:233], v[8:11]
	s_setprio 0
	s_setprio 1
	v_mfma_f32_16x16x32_bf16 v[60:63], v[164:167], v[202:205], v[60:63]
	v_mfma_f32_16x16x32_bf16 v[52:55], v[178:181], v[202:205], v[52:55]
	v_mfma_f32_16x16x32_bf16 v[36:39], v[164:167], v[210:213], v[36:39]
	v_mfma_f32_16x16x32_bf16 v[32:35], v[178:181], v[210:213], v[32:35]
	v_mfma_f32_16x16x32_bf16 v[20:23], v[164:167], v[218:221], v[20:23]
	v_mfma_f32_16x16x32_bf16 v[16:19], v[178:181], v[218:221], v[16:19]
	v_mfma_f32_16x16x32_bf16 v[4:7], v[164:167], v[226:229], v[4:7]
	v_mfma_f32_16x16x32_bf16 v[0:3], v[178:181], v[226:229], v[0:3]
	v_mfma_f32_16x16x32_bf16 v[60:63], v[168:171], v[206:209], v[60:63]
	v_mfma_f32_16x16x32_bf16 v[52:55], v[182:185], v[206:209], v[52:55]
	v_mfma_f32_16x16x32_bf16 v[36:39], v[168:171], v[214:217], v[36:39]
	v_mfma_f32_16x16x32_bf16 v[32:35], v[182:185], v[214:217], v[32:35]
	v_mfma_f32_16x16x32_bf16 v[20:23], v[168:171], v[222:225], v[20:23]
	v_mfma_f32_16x16x32_bf16 v[16:19], v[182:185], v[222:225], v[16:19]
	v_mfma_f32_16x16x32_bf16 v[4:7], v[168:171], v[230:233], v[4:7]
	v_mfma_f32_16x16x32_bf16 v[0:3], v[182:185], v[230:233], v[0:3]
	s_setprio 0
	s_barrier
	s_movk_i32 s50, 0x100
	s_andn2_b64 vcc, exec, s[44:45]
	s_mov_b64 s[46:47], -1
	s_mov_b64 s[44:45], 0
	s_cbranch_vccz .LBB0_1337
	s_and_b64 vcc, exec, s[24:25]
	s_cbranch_vccz .LBB0_1340
	s_barrier

;     __device__ __forceinline__ bool next(int i, Unit& u) const { const int L = i * G + c; if (L >= nsub) return false; u.pk = L >> 4; u.pm = MLAT / BM + (L & 3); u.pn = (L >> 2) & 3; return true; }
; #define PG8_STAGE(bufoff, gbase, voff) do { _Pragma("unroll") for (int _i = 0; _i < 2; ++_i) \
;         __builtin_amdgcn_global_load_lds((const unsigned*)((const char*)(gbase) + (voff)[_i]), (PG8_LAS unsigned*)(lds + (bufoff) + ldsw + _i * 8192), 16, 0, 0); } while (0)
; #define PG8_LDA(dst, b, h) do { _Pragma("unroll") for (int m = 0; m < 4; ++m) _Pragma("unroll") for (int k = 0; k < 2; ++k) dst[m][k] = *(const PG8_LAS bf16x8*)(lds + PG8_SA(b, h) + aoff + m * 2048 + k * 1024); } while (0)
; #define PG8_LDB(dst, b, h) do { _Pragma("unroll") for (int n = 0; n < 2; ++n) _Pragma("unroll") for (int k = 0; k < 2; ++k) dst[n][k] = *(const PG8_LAS bf16x8*)(lds + PG8_SB(b, h) + boff + n * 2048 + k * 1024); } while (0)
; #define PG8_WAIT_V(n) asm volatile("s_waitcnt vmcnt(" #n ")" ::: "memory")
; #define PG8_WAIT_L(n) asm volatile("s_waitcnt lgkmcnt(" #n ")" ::: "memory")
; template <class Epi, class Sched, bool ALIGN_EPI = false, bool SP2 = false>
; __device__ __forceinline__ void gemm_phase(PG8_LAS unsigned char* lds, const Gemm g, const Sched& S, const Epi& E) {
;     ...
;         const bool has_next = S.next(ui + 1, nxt);
;         const char* nA = has_next ? g.a_of(nxt) : cA; const char* nB = has_next ? g.b_of(nxt) : cB;
;         for (int t = 0; t < nt; t += 2) {
;             const bool last = (t == nt - 2);
;             const char* a1 = cA + (size_t)(t + 1) * kstep;
;             const char* a2 = last ? nA : cA + (size_t)(t + 2) * kstep; const char* b2 = last ? nB : cB + (size_t)(t + 2) * kstep;
;             const char* a3 = a2 + kstep; const char* b3 = b2 + kstep;
;             if (last && has_next) S.a_ready(nxt);
;             if constexpr (SP2) {
;             PG8_LDB(B0, 0, 0); PG8_LDB(B1, 0, 1); PG8_SCHED; PG8_LDA(At, 0, 0); PG8_STAGE(PG8_SA(1, 1), a1 + hstepA, voffA);
;             PG8_WAIT_V(8); PG8_WAIT_L(0); PG8_BAR; PG8_MMA(0, 0, At, B0); PG8_MMA(0, 1, At, B1); PG8_BAR; PG8_SCHED;
;             PG8_LDA(At, 0, 1); PG8_STAGE(PG8_SB(0, 0), b2, voffB); PG8_STAGE(PG8_SB(0, 1), b2 + hstepB, voffB); PG8_STAGE(PG8_SA(0, 0), a2, voffA);
;             PG8_WAIT_V(8); PG8_WAIT_L(0); PG8_BAR; PG8_MMA(1, 0, At, B0); PG8_MMA(1, 1, At, B1); PG8_BAR; PG8_SCHED;
.LBB0_1575:
	s_add_u32 s40, s38, 0xfffc0080
	s_addc_u32 s41, s39, -1
	s_add_i32 s67, 0, 0x10000
	s_cmp_eq_u32 s66, 12
	s_cselect_b32 s43, s27, s41
	s_cselect_b32 s42, s35, s40
	s_cselect_b32 s41, s25, s65
	s_cselect_b32 s40, s37, s64
	s_add_i32 s68, 0, 0x14000
	v_add_u32_e32 v92, s67, v181
	v_add_u32_e32 v164, s68, v181
	ds_read_b128 v[72:75], v92
	ds_read_b128 v[76:79], v92 offset:1024
	ds_read_b128 v[88:91], v92 offset:2048
	ds_read_b128 v[92:95], v92 offset:3072
	ds_read_b128 v[152:155], v164
	ds_read_b128 v[156:159], v164 offset:1024
	ds_read_b128 v[160:163], v164 offset:2048
	ds_read_b128 v[164:167], v164 offset:3072
	s_add_i32 m0, s51, 0xc000
	ds_read_b128 v[168:171], v186
	ds_read_b128 v[174:177], v186 offset:1024
	ds_read_b128 v[192:195], v186 offset:2048
	ds_read_b128 v[196:199], v186 offset:3072
	ds_read_b128 v[200:203], v186 offset:4096
	ds_read_b128 v[204:207], v186 offset:5120
	ds_read_b128 v[208:211], v186 offset:6144
	ds_read_b128 v[212:215], v186 offset:7168
	global_load_lds_dwordx4 v148, s[38:39]
	s_add_i32 m0, s51, 0xe000
	s_nop 0
	global_load_lds_dwordx4 v150, s[38:39]
	s_waitcnt vmcnt(8)
	s_waitcnt lgkmcnt(0)
	s_barrier
	s_setprio 1
	v_mfma_f32_16x16x32_bf16 v[140:143], v[72:75], v[168:171], v[140:143]
	v_mfma_f32_16x16x32_bf16 v[136:139], v[88:91], v[168:171], v[136:139]
	v_mfma_f32_16x16x32_bf16 v[124:127], v[72:75], v[192:195], v[124:127]
	v_mfma_f32_16x16x32_bf16 v[120:123], v[88:91], v[192:195], v[120:123]
	v_mfma_f32_16x16x32_bf16 v[108:111], v[72:75], v[200:203], v[108:111]
	v_mfma_f32_16x16x32_bf16 v[104:107], v[88:91], v[200:203], v[104:107]
	v_mfma_f32_16x16x32_bf16 v[84:87], v[72:75], v[208:211], v[84:87]
	v_mfma_f32_16x16x32_bf16 v[80:83], v[88:91], v[208:211], v[80:83]
	v_mfma_f32_16x16x32_bf16 v[140:143], v[76:79], v[174:177], v[140:143]
	v_mfma_f32_16x16x32_bf16 v[136:139], v[92:95], v[174:177], v[136:139]
	v_mfma_f32_16x16x32_bf16 v[124:127], v[76:79], v[196:199], v[124:127]
	v_mfma_f32_16x16x32_bf16 v[120:123], v[92:95], v[196:199], v[120:123]
	v_mfma_f32_16x16x32_bf16 v[108:111], v[76:79], v[204:207], v[108:111]
	v_mfma_f32_16x16x32_bf16 v[104:107], v[92:95], v[204:207], v[104:107]
	v_mfma_f32_16x16x32_bf16 v[84:87], v[76:79], v[212:215], v[84:87]
	v_mfma_f32_16x16x32_bf16 v[80:83], v[92:95], v[212:215], v[80:83]
	s_setprio 0
	s_setprio 1
	v_mfma_f32_16x16x32_bf16 v[132:135], v[152:155], v[168:171], v[132:135]
	v_mfma_f32_16x16x32_bf16 v[128:131], v[160:163], v[168:171], v[128:131]
	v_mfma_f32_16x16x32_bf16 v[116:119], v[152:155], v[192:195], v[116:119]
	v_mfma_f32_16x16x32_bf16 v[112:115], v[160:163], v[192:195], v[112:115]
	v_mfma_f32_16x16x32_bf16 v[100:103], v[152:155], v[200:203], v[100:103]
	v_mfma_f32_16x16x32_bf16 v[96:99], v[160:163], v[200:203], v[96:99]
	v_mfma_f32_16x16x32_bf16 v[68:71], v[152:155], v[208:211], v[68:71]
	v_mfma_f32_16x16x32_bf16 v[64:67], v[160:163], v[208:211], v[64:67]
	v_mfma_f32_16x16x32_bf16 v[132:135], v[156:159], v[174:177], v[132:135]
	v_mfma_f32_16x16x32_bf16 v[128:131], v[164:167], v[174:177], v[128:131]
	v_mfma_f32_16x16x32_bf16 v[116:119], v[156:159], v[196:199], v[116:119]
	v_mfma_f32_16x16x32_bf16 v[112:115], v[164:167], v[196:199], v[112:115]
	v_mfma_f32_16x16x32_bf16 v[100:103], v[156:159], v[204:207], v[100:103]
	v_mfma_f32_16x16x32_bf16 v[96:99], v[164:167], v[204:207], v[96:99]
	v_mfma_f32_16x16x32_bf16 v[68:71], v[156:159], v[212:215], v[68:71]
	v_mfma_f32_16x16x32_bf16 v[64:67], v[164:167], v[212:215], v[64:67]
	s_setprio 0
	s_barrier
	s_add_i32 s67, s67, s50
	v_lshl_add_u64 v[178:179], s[40:41], 0, v[172:173]
	s_mov_b32 m0, s67
	ds_read_b128 v[168:171], v186 offset:16384
	ds_read_b128 v[174:177], v186 offset:17408
	ds_read_b128 v[192:195], v186 offset:18432
	ds_read_b128 v[196:199], v186 offset:19456
	ds_read_b128 v[200:203], v186 offset:20480
	ds_read_b128 v[204:207], v186 offset:21504
	ds_read_b128 v[208:211], v186 offset:22528
	ds_read_b128 v[212:215], v186 offset:23552
	global_load_lds_dwordx4 v[178:179], off
	s_add_i32 m0, s67, 0x2000
	s_add_u32 s70, s40, 0x40000
	v_lshl_add_u64 v[216:217], s[40:41], 0, v[144:145]
	s_addc_u32 s71, s41, 0
	s_add_i32 s67, s68, s50
	global_load_lds_dwordx4 v[216:217], off
	s_mov_b32 m0, s67
	v_lshl_add_u64 v[220:221], s[42:43], 0, v[144:145]
	global_load_lds_dwordx4 v172, s[70:71]
	s_add_i32 m0, s67, 0x2000
	s_nop 0
	global_load_lds_dwordx4 v144, s[70:71]
	v_lshl_add_u64 v[218:219], s[42:43], 0, v[172:173]
	s_mov_b32 m0, s51
	s_nop 0
	global_load_lds_dwordx4 v[218:219], off
	s_mov_b32 m0, s52
	s_nop 0
	global_load_lds_dwordx4 v[220:221], off
	s_waitcnt vmcnt(8)
	s_waitcnt lgkmcnt(0)
	s_barrier
; #define PG8_STAGE(bufoff, gbase, voff) do { _Pragma("unroll") for (int _i = 0; _i < 2; ++_i) \
;         __builtin_amdgcn_global_load_lds((const unsigned*)((const char*)(gbase) + (voff)[_i]), (PG8_LAS unsigned*)(lds + (bufoff) + ldsw + _i * 8192), 16, 0, 0); } while (0)
; #define PG8_LDA(dst, b, h) do { _Pragma("unroll") for (int m = 0; m < 4; ++m) _Pragma("unroll") for (int k = 0; k < 2; ++k) dst[m][k] = *(const PG8_LAS bf16x8*)(lds + PG8_SA(b, h) + aoff + m * 2048 + k * 1024); } while (0)
; #define PG8_LDB(dst, b, h) do { _Pragma("unroll") for (int n = 0; n < 2; ++n) _Pragma("unroll") for (int k = 0; k < 2; ++k) dst[n][k] = *(const PG8_LAS bf16x8*)(lds + PG8_SB(b, h) + boff + n * 2048 + k * 1024); } while (0)
; #define PG8_MMA(ai, bj, At, Bt) do { __builtin_amdgcn_s_setprio(1); _Pragma("unroll") for (int m = 0; m < 4; ++m) _Pragma("unroll") for (int n = 0; n < 2; ++n) _Pragma("unroll") for (int k = 0; k < 2; ++k) \
;         acc[ai][bj][m][n] = __builtin_amdgcn_mfma_f32_16x16x32_bf16(Bt[n][k], At[m][k], acc[ai][bj][m][n], 0, 0, 0); __builtin_amdgcn_s_setprio(0); } while (0)
; #define PG8_WAIT_V(n) asm volatile("s_waitcnt vmcnt(" #n ")" ::: "memory")
; #define PG8_WAIT_L(n) asm volatile("s_waitcnt lgkmcnt(" #n ")" ::: "memory")
; #define PG8_BAR __builtin_amdgcn_s_barrier()
; #define PG8_SCHED __builtin_amdgcn_sched_barrier(0)
; template <class Epi, class Sched, bool ALIGN_EPI = false, bool SP2 = false>
; __device__ __forceinline__ void gemm_phase(PG8_LAS unsigned char* lds, const Gemm g, const Sched& S, const Epi& E) {
;     ...
;             if constexpr (SP2) {
;             PG8_LDB(B0, 0, 0); PG8_LDB(B1, 0, 1); PG8_SCHED; PG8_LDA(At, 0, 0); PG8_STAGE(PG8_SA(1, 1), a1 + hstepA, voffA);
;             PG8_WAIT_V(8); PG8_WAIT_L(0); PG8_BAR; PG8_MMA(0, 0, At, B0); PG8_MMA(0, 1, At, B1); PG8_BAR; PG8_SCHED;
;             PG8_LDA(At, 0, 1); PG8_STAGE(PG8_SB(0, 0), b2, voffB); PG8_STAGE(PG8_SB(0, 1), b2 + hstepB, voffB); PG8_STAGE(PG8_SA(0, 0), a2, voffA);
;             PG8_WAIT_V(8); PG8_WAIT_L(0); PG8_BAR; PG8_MMA(1, 0, At, B0); PG8_MMA(1, 1, At, B1); PG8_BAR; PG8_SCHED;
;             PG8_LDB(B0, 1, 0); PG8_LDB(B1, 1, 1); PG8_SCHED; PG8_LDA(At, 1, 0); PG8_STAGE(PG8_SA(0, 1), a2 + hstepA, voffA);
;             PG8_WAIT_V(8); PG8_WAIT_L(0); PG8_BAR; PG8_MMA(0, 0, At, B0); PG8_MMA(0, 1, At, B1); PG8_BAR; PG8_SCHED;
	s_setprio 1
	v_mfma_f32_16x16x32_bf16 v[60:63], v[72:75], v[168:171], v[60:63]
	v_mfma_f32_16x16x32_bf16 v[56:59], v[88:91], v[168:171], v[56:59]
	v_mfma_f32_16x16x32_bf16 v[44:47], v[72:75], v[192:195], v[44:47]
	v_mfma_f32_16x16x32_bf16 v[40:43], v[88:91], v[192:195], v[40:43]
	v_mfma_f32_16x16x32_bf16 v[28:31], v[72:75], v[200:203], v[28:31]
	v_mfma_f32_16x16x32_bf16 v[24:27], v[88:91], v[200:203], v[24:27]
	v_mfma_f32_16x16x32_bf16 v[12:15], v[72:75], v[208:211], v[12:15]
	v_mfma_f32_16x16x32_bf16 v[8:11], v[88:91], v[208:211], v[8:11]
	v_mfma_f32_16x16x32_bf16 v[60:63], v[76:79], v[174:177], v[60:63]
	v_mfma_f32_16x16x32_bf16 v[56:59], v[92:95], v[174:177], v[56:59]
	v_mfma_f32_16x16x32_bf16 v[44:47], v[76:79], v[196:199], v[44:47]
	v_mfma_f32_16x16x32_bf16 v[40:43], v[92:95], v[196:199], v[40:43]
	v_mfma_f32_16x16x32_bf16 v[28:31], v[76:79], v[204:207], v[28:31]
	v_mfma_f32_16x16x32_bf16 v[24:27], v[92:95], v[204:207], v[24:27]
	v_mfma_f32_16x16x32_bf16 v[12:15], v[76:79], v[212:215], v[12:15]
	v_mfma_f32_16x16x32_bf16 v[8:11], v[92:95], v[212:215], v[8:11]
	s_setprio 0
	s_setprio 1
	v_mfma_f32_16x16x32_bf16 v[52:55], v[152:155], v[168:171], v[52:55]
	v_mfma_f32_16x16x32_bf16 v[48:51], v[160:163], v[168:171], v[48:51]
	v_mfma_f32_16x16x32_bf16 v[36:39], v[152:155], v[192:195], v[36:39]
	v_mfma_f32_16x16x32_bf16 v[32:35], v[160:163], v[192:195], v[32:35]
	v_mfma_f32_16x16x32_bf16 v[20:23], v[152:155], v[200:203], v[20:23]
	v_mfma_f32_16x16x32_bf16 v[16:19], v[160:163], v[200:203], v[16:19]
	v_mfma_f32_16x16x32_bf16 v[4:7], v[152:155], v[208:211], v[4:7]
	v_mfma_f32_16x16x32_bf16 v[0:3], v[160:163], v[208:211], v[0:3]
	v_mfma_f32_16x16x32_bf16 v[52:55], v[156:159], v[174:177], v[52:55]
	v_mfma_f32_16x16x32_bf16 v[48:51], v[164:167], v[174:177], v[48:51]
	v_mfma_f32_16x16x32_bf16 v[36:39], v[156:159], v[196:199], v[36:39]
	v_mfma_f32_16x16x32_bf16 v[32:35], v[164:167], v[196:199], v[32:35]
	v_mfma_f32_16x16x32_bf16 v[20:23], v[156:159], v[204:207], v[20:23]
	v_mfma_f32_16x16x32_bf16 v[16:19], v[164:167], v[204:207], v[16:19]
	v_mfma_f32_16x16x32_bf16 v[4:7], v[156:159], v[212:215], v[4:7]
	v_mfma_f32_16x16x32_bf16 v[0:3], v[164:167], v[212:215], v[0:3]
	s_setprio 0
	s_barrier
	s_add_i32 s67, 0, 0x18000
	s_add_i32 s68, 0, 0x1c000
	v_add_u32_e32 v92, s67, v181
	v_add_u32_e32 v164, s68, v181
	ds_read_b128 v[72:75], v92
	ds_read_b128 v[76:79], v92 offset:1024
	ds_read_b128 v[88:91], v92 offset:2048
	ds_read_b128 v[92:95], v92 offset:3072
	ds_read_b128 v[152:155], v164
	ds_read_b128 v[156:159], v164 offset:1024
	ds_read_b128 v[160:163], v164 offset:2048
	ds_read_b128 v[164:167], v164 offset:3072
	s_add_u32 s42, s42, 0x40000
	s_addc_u32 s43, s43, 0
	s_mov_b32 m0, s53
	ds_read_b128 v[168:171], v186 offset:32768
	ds_read_b128 v[174:177], v186 offset:33792
	ds_read_b128 v[192:195], v186 offset:34816
	ds_read_b128 v[196:199], v186 offset:35840
	ds_read_b128 v[200:203], v186 offset:36864
	ds_read_b128 v[204:207], v186 offset:37888
	ds_read_b128 v[208:211], v186 offset:38912
	ds_read_b128 v[212:215], v186 offset:39936
	global_load_lds_dwordx4 v172, s[42:43]
	v_lshl_add_u64 v[222:223], s[42:43], 0, v[144:145]
	s_mov_b32 m0, s54
	s_nop 0
	global_load_lds_dwordx4 v[222:223], off
	s_waitcnt vmcnt(8)
	s_waitcnt lgkmcnt(0)
	s_barrier
	s_setprio 1
	v_mfma_f32_16x16x32_bf16 v[140:143], v[72:75], v[168:171], v[140:143]
	v_mfma_f32_16x16x32_bf16 v[136:139], v[88:91], v[168:171], v[136:139]
	v_mfma_f32_16x16x32_bf16 v[124:127], v[72:75], v[192:195], v[124:127]
	v_mfma_f32_16x16x32_bf16 v[120:123], v[88:91], v[192:195], v[120:123]
	v_mfma_f32_16x16x32_bf16 v[108:111], v[72:75], v[200:203], v[108:111]
	v_mfma_f32_16x16x32_bf16 v[104:107], v[88:91], v[200:203], v[104:107]
	v_mfma_f32_16x16x32_bf16 v[84:87], v[72:75], v[208:211], v[84:87]
	v_mfma_f32_16x16x32_bf16 v[80:83], v[88:91], v[208:211], v[80:83]
	v_mfma_f32_16x16x32_bf16 v[140:143], v[76:79], v[174:177], v[140:143]
	v_mfma_f32_16x16x32_bf16 v[136:139], v[92:95], v[174:177], v[136:139]
	v_mfma_f32_16x16x32_bf16 v[124:127], v[76:79], v[196:199], v[124:127]
	v_mfma_f32_16x16x32_bf16 v[120:123], v[92:95], v[196:199], v[120:123]
	v_mfma_f32_16x16x32_bf16 v[108:111], v[76:79], v[204:207], v[108:111]
	v_mfma_f32_16x16x32_bf16 v[104:107], v[92:95], v[204:207], v[104:107]
	v_mfma_f32_16x16x32_bf16 v[84:87], v[76:79], v[212:215], v[84:87]
	v_mfma_f32_16x16x32_bf16 v[80:83], v[92:95], v[212:215], v[80:83]
	s_setprio 0
	s_setprio 1
	v_mfma_f32_16x16x32_bf16 v[132:135], v[152:155], v[168:171], v[132:135]
	v_mfma_f32_16x16x32_bf16 v[128:131], v[160:163], v[168:171], v[128:131]
	v_mfma_f32_16x16x32_bf16 v[116:119], v[152:155], v[192:195], v[116:119]
	v_mfma_f32_16x16x32_bf16 v[112:115], v[160:163], v[192:195], v[112:115]
	v_mfma_f32_16x16x32_bf16 v[100:103], v[152:155], v[200:203], v[100:103]
	v_mfma_f32_16x16x32_bf16 v[96:99], v[160:163], v[200:203], v[96:99]
	v_mfma_f32_16x16x32_bf16 v[68:71], v[152:155], v[208:211], v[68:71]
	v_mfma_f32_16x16x32_bf16 v[64:67], v[160:163], v[208:211], v[64:67]
	v_mfma_f32_16x16x32_bf16 v[132:135], v[156:159], v[174:177], v[132:135]
	v_mfma_f32_16x16x32_bf16 v[128:131], v[164:167], v[174:177], v[128:131]
	v_mfma_f32_16x16x32_bf16 v[116:119], v[156:159], v[196:199], v[116:119]
	v_mfma_f32_16x16x32_bf16 v[112:115], v[164:167], v[196:199], v[112:115]
	v_mfma_f32_16x16x32_bf16 v[100:103], v[156:159], v[204:207], v[100:103]
	v_mfma_f32_16x16x32_bf16 v[96:99], v[164:167], v[204:207], v[96:99]
	v_mfma_f32_16x16x32_bf16 v[68:71], v[156:159], v[212:215], v[68:71]
	v_mfma_f32_16x16x32_bf16 v[64:67], v[164:167], v[212:215], v[64:67]
	s_setprio 0
	s_barrier
; #define PG8_STAGE(bufoff, gbase, voff) do { _Pragma("unroll") for (int _i = 0; _i < 2; ++_i) \
;         __builtin_amdgcn_global_load_lds((const unsigned*)((const char*)(gbase) + (voff)[_i]), (PG8_LAS unsigned*)(lds + (bufoff) + ldsw + _i * 8192), 16, 0, 0); } while (0)
; #define PG8_LDA(dst, b, h) do { _Pragma("unroll") for (int m = 0; m < 4; ++m) _Pragma("unroll") for (int k = 0; k < 2; ++k) dst[m][k] = *(const PG8_LAS bf16x8*)(lds + PG8_SA(b, h) + aoff + m * 2048 + k * 1024); } while (0)
; #define PG8_MMA(ai, bj, At, Bt) do { __builtin_amdgcn_s_setprio(1); _Pragma("unroll") for (int m = 0; m < 4; ++m) _Pragma("unroll") for (int n = 0; n < 2; ++n) _Pragma("unroll") for (int k = 0; k < 2; ++k) \
;         acc[ai][bj][m][n] = __builtin_amdgcn_mfma_f32_16x16x32_bf16(Bt[n][k], At[m][k], acc[ai][bj][m][n], 0, 0, 0); __builtin_amdgcn_s_setprio(0); } while (0)
; #define PG8_WAIT_V(n) asm volatile("s_waitcnt vmcnt(" #n ")" ::: "memory")
; #define PG8_WAIT_L(n) asm volatile("s_waitcnt lgkmcnt(" #n ")" ::: "memory")
; #define PG8_BAR __builtin_amdgcn_s_barrier()
; #define PG8_SCHED __builtin_amdgcn_sched_barrier(0)
; template <class Epi, class Sched, bool ALIGN_EPI = false, bool SP2 = false>
; __device__ __forceinline__ void gemm_phase(PG8_LAS unsigned char* lds, const Gemm g, const Sched& S, const Epi& E) {
;     ...
;             PG8_LDA(At, 1, 1); PG8_STAGE(PG8_SB(1, 0), b3, voffB); PG8_STAGE(PG8_SB(1, 1), b3 + hstepB, voffB); PG8_STAGE(PG8_SA(1, 0), a3, voffA);
;             PG8_WAIT_V(8); PG8_WAIT_L(0); PG8_BAR; PG8_MMA(1, 0, At, B0); PG8_MMA(1, 1, At, B1); PG8_BAR; PG8_SCHED;
;     ...
;         if constexpr (ALIGN_EPI) { if (wr == 0) PG8_BAR; }
	s_add_i32 s42, s67, s50
	v_lshl_add_u64 v[178:179], v[178:179], 0, s[80:81]
	s_mov_b32 m0, s42
	ds_read_b128 v[168:171], v186 offset:49152
	ds_read_b128 v[174:177], v186 offset:50176
	ds_read_b128 v[192:195], v186 offset:51200
	ds_read_b128 v[196:199], v186 offset:52224
	ds_read_b128 v[200:203], v186 offset:53248
	ds_read_b128 v[204:207], v186 offset:54272
	ds_read_b128 v[208:211], v186 offset:55296
	ds_read_b128 v[212:215], v186 offset:56320
	global_load_lds_dwordx4 v[178:179], off
	s_add_i32 m0, s42, 0x2000
	s_add_u32 s40, s40, 0x40080
	v_lshl_add_u64 v[178:179], v[216:217], 0, s[80:81]
	s_addc_u32 s41, s41, 0
	s_add_i32 s42, s68, s50
	global_load_lds_dwordx4 v[178:179], off
	s_mov_b32 m0, s42
	s_nop 0
	global_load_lds_dwordx4 v172, s[40:41]
	s_add_i32 m0, s42, 0x2000
	s_nop 0
	global_load_lds_dwordx4 v144, s[40:41]
	v_lshl_add_u64 v[178:179], v[218:219], 0, s[80:81]
	s_mov_b32 m0, s59
	s_nop 0
	global_load_lds_dwordx4 v[178:179], off
	v_lshl_add_u64 v[178:179], v[220:221], 0, s[80:81]
	s_mov_b32 m0, s60
	s_nop 0
	global_load_lds_dwordx4 v[178:179], off
	s_waitcnt vmcnt(8)
	s_waitcnt lgkmcnt(0)
	s_barrier
	s_setprio 1
	v_mfma_f32_16x16x32_bf16 v[60:63], v[72:75], v[168:171], v[60:63]
	v_mfma_f32_16x16x32_bf16 v[56:59], v[88:91], v[168:171], v[56:59]
	v_mfma_f32_16x16x32_bf16 v[44:47], v[72:75], v[192:195], v[44:47]
	v_mfma_f32_16x16x32_bf16 v[40:43], v[88:91], v[192:195], v[40:43]
	v_mfma_f32_16x16x32_bf16 v[28:31], v[72:75], v[200:203], v[28:31]
	v_mfma_f32_16x16x32_bf16 v[24:27], v[88:91], v[200:203], v[24:27]
	v_mfma_f32_16x16x32_bf16 v[12:15], v[72:75], v[208:211], v[12:15]
	v_mfma_f32_16x16x32_bf16 v[8:11], v[88:91], v[208:211], v[8:11]
	v_mfma_f32_16x16x32_bf16 v[60:63], v[76:79], v[174:177], v[60:63]
	v_mfma_f32_16x16x32_bf16 v[56:59], v[92:95], v[174:177], v[56:59]
	v_mfma_f32_16x16x32_bf16 v[44:47], v[76:79], v[196:199], v[44:47]
	v_mfma_f32_16x16x32_bf16 v[40:43], v[92:95], v[196:199], v[40:43]
	v_mfma_f32_16x16x32_bf16 v[28:31], v[76:79], v[204:207], v[28:31]
	v_mfma_f32_16x16x32_bf16 v[24:27], v[92:95], v[204:207], v[24:27]
	v_mfma_f32_16x16x32_bf16 v[12:15], v[76:79], v[212:215], v[12:15]
	v_mfma_f32_16x16x32_bf16 v[8:11], v[92:95], v[212:215], v[8:11]
	s_setprio 0
	s_setprio 1
	v_mfma_f32_16x16x32_bf16 v[52:55], v[152:155], v[168:171], v[52:55]
	v_mfma_f32_16x16x32_bf16 v[48:51], v[160:163], v[168:171], v[48:51]
	v_mfma_f32_16x16x32_bf16 v[36:39], v[152:155], v[192:195], v[36:39]
	v_mfma_f32_16x16x32_bf16 v[32:35], v[160:163], v[192:195], v[32:35]
	v_mfma_f32_16x16x32_bf16 v[20:23], v[152:155], v[200:203], v[20:23]
	v_mfma_f32_16x16x32_bf16 v[16:19], v[160:163], v[200:203], v[16:19]
	v_mfma_f32_16x16x32_bf16 v[4:7], v[152:155], v[208:211], v[4:7]
	v_mfma_f32_16x16x32_bf16 v[0:3], v[160:163], v[208:211], v[0:3]
	v_mfma_f32_16x16x32_bf16 v[52:55], v[156:159], v[174:177], v[52:55]
	v_mfma_f32_16x16x32_bf16 v[48:51], v[164:167], v[174:177], v[48:51]
	v_mfma_f32_16x16x32_bf16 v[36:39], v[156:159], v[196:199], v[36:39]
	v_mfma_f32_16x16x32_bf16 v[32:35], v[164:167], v[196:199], v[32:35]
	v_mfma_f32_16x16x32_bf16 v[20:23], v[156:159], v[204:207], v[20:23]
	v_mfma_f32_16x16x32_bf16 v[16:19], v[164:167], v[204:207], v[16:19]
	v_mfma_f32_16x16x32_bf16 v[4:7], v[156:159], v[212:215], v[4:7]
	v_mfma_f32_16x16x32_bf16 v[0:3], v[164:167], v[212:215], v[0:3]
	s_setprio 0
	s_barrier
	s_add_i32 s66, s66, 2
	s_add_u32 s38, s38, 0x100
	s_addc_u32 s39, s39, 0
	s_add_u32 s64, s64, 0x100
	s_addc_u32 s65, s65, 0
	s_cmp_gt_u32 s66, 13
	s_cbranch_scc0 .LBB0_1575
	s_and_b64 vcc, exec, s[22:23]
	s_cbranch_vccz .LBB0_1578
	s_barrier

;     __device__ __forceinline__ bool next(int i, Unit& u) const { const int L = i * G + c; if (L >= nsub) return false; u.pk = L >> 4; u.pm = MLAT / BM + (L & 3); u.pn = (L >> 2) & 3; return true; }
; #define PG8_STAGE(bufoff, gbase, voff) do { _Pragma("unroll") for (int _i = 0; _i < 2; ++_i) \
;         __builtin_amdgcn_global_load_lds((const unsigned*)((const char*)(gbase) + (voff)[_i]), (PG8_LAS unsigned*)(lds + (bufoff) + ldsw + _i * 8192), 16, 0, 0); } while (0)
; #define PG8_LDA(dst, b, h) do { _Pragma("unroll") for (int m = 0; m < 4; ++m) _Pragma("unroll") for (int k = 0; k < 2; ++k) dst[m][k] = *(const PG8_LAS bf16x8*)(lds + PG8_SA(b, h) + aoff + m * 2048 + k * 1024); } while (0)
; #define PG8_LDB(dst, b, h) do { _Pragma("unroll") for (int n = 0; n < 2; ++n) _Pragma("unroll") for (int k = 0; k < 2; ++k) dst[n][k] = *(const PG8_LAS bf16x8*)(lds + PG8_SB(b, h) + boff + n * 2048 + k * 1024); } while (0)
; #define PG8_WAIT_V(n) asm volatile("s_waitcnt vmcnt(" #n ")" ::: "memory")
; #define PG8_WAIT_L(n) asm volatile("s_waitcnt lgkmcnt(" #n ")" ::: "memory")
; template <class Epi, class Sched, bool ALIGN_EPI = false, bool SP2 = false>
; __device__ __forceinline__ void gemm_phase(PG8_LAS unsigned char* lds, const Gemm g, const Sched& S, const Epi& E) {
;     ...
;         const bool has_next = S.next(ui + 1, nxt);
;         const char* nA = has_next ? g.a_of(nxt) : cA; const char* nB = has_next ? g.b_of(nxt) : cB;
;         for (int t = 0; t < nt; t += 2) {
;             const bool last = (t == nt - 2);
;             const char* a1 = cA + (size_t)(t + 1) * kstep;
;             const char* a2 = last ? nA : cA + (size_t)(t + 2) * kstep; const char* b2 = last ? nB : cB + (size_t)(t + 2) * kstep;
;             const char* a3 = a2 + kstep; const char* b3 = b2 + kstep;
;             if (last && has_next) S.a_ready(nxt);
;             if constexpr (SP2) {
;             PG8_LDB(B0, 0, 0); PG8_LDB(B1, 0, 1); PG8_SCHED; PG8_LDA(At, 0, 0); PG8_STAGE(PG8_SA(1, 1), a1 + hstepA, voffA);
;             PG8_WAIT_V(8); PG8_WAIT_L(0); PG8_BAR; PG8_MMA(0, 0, At, B0); PG8_MMA(0, 1, At, B1); PG8_BAR; PG8_SCHED;
;             PG8_LDA(At, 0, 1); PG8_STAGE(PG8_SB(0, 0), b2, voffB); PG8_STAGE(PG8_SB(0, 1), b2 + hstepB, voffB); PG8_STAGE(PG8_SA(0, 0), a2, voffA);
;             PG8_WAIT_V(8); PG8_WAIT_L(0); PG8_BAR; PG8_MMA(1, 0, At, B0); PG8_MMA(1, 1, At, B1); PG8_BAR; PG8_SCHED;
.LBB0_1612:
	s_add_u32 s23, s26, s19
	s_addc_u32 s40, s27, 0
	s_add_u32 s36, s23, 0x100
	s_addc_u32 s37, s40, 0
	s_and_b64 s[34:35], s[30:31], exec
	s_cselect_b32 s37, s17, s37
	s_cselect_b32 s36, s16, s36
	s_add_u32 s19, s24, s19
	s_addc_u32 s34, s25, 0
	s_add_u32 s19, s19, 0x100
	s_addc_u32 s34, s34, 0
	s_add_i32 s66, 0, 0x10000
	s_and_b64 s[30:31], s[30:31], exec
	s_cselect_b32 s39, s21, s34
	s_cselect_b32 s38, s20, s19
	s_add_i32 s31, 0, 0x14000
	s_add_u32 s42, s23, 0x40080
	s_addc_u32 s43, s40, 0
	s_add_i32 s65, s66, s50
	s_add_i32 m0, s51, 0xc000
	s_add_i32 s68, s51, 0xe000
	s_add_i32 s62, s65, 0x2000
	s_add_u32 s40, s38, 0x40000
	v_add_u32_e32 v124, s66, v154
	v_add_u32_e32 v152, s31, v154
	s_addc_u32 s41, s39, 0
	s_add_i32 s64, s31, s50
	ds_read_b128 v[112:115], v124
	ds_read_b128 v[116:119], v124 offset:1024
	ds_read_b128 v[120:123], v124 offset:2048
	ds_read_b128 v[124:127], v124 offset:3072
	ds_read_b128 v[148:151], v152
	ds_read_b128 v[158:161], v152 offset:1024
	ds_read_b128 v[162:165], v152 offset:2048
	ds_read_b128 v[166:169], v152 offset:3072
	s_add_i32 s63, s64, 0x2000
	s_add_i32 s61, 0, 0x18000
	s_add_i32 s60, 0, 0x1c000
	s_add_u32 s34, s36, 0x40000
	s_addc_u32 s35, s37, 0
	s_add_i32 s23, s61, s50
	s_add_i32 s19, s23, 0x2000
	s_add_u32 s30, s38, 0x40080
	s_addc_u32 s31, s39, 0
	s_add_i32 s67, s60, s50
	s_add_i32 s66, s67, 0x2000
	v_lshl_add_u64 v[152:153], s[42:43], 0, v[146:147]
	ds_read_b128 v[174:177], v157
	ds_read_b128 v[178:181], v157 offset:1024
	ds_read_b128 v[182:185], v157 offset:2048
	ds_read_b128 v[192:195], v157 offset:3072
	ds_read_b128 v[196:199], v157 offset:4096
	ds_read_b128 v[200:203], v157 offset:5120
	ds_read_b128 v[204:207], v157 offset:6144
	ds_read_b128 v[208:211], v157 offset:7168
	global_load_lds_dwordx4 v[152:153], off
	v_lshl_add_u64 v[152:153], s[42:43], 0, v[144:145]
	s_mov_b32 m0, s68
	s_nop 0
	global_load_lds_dwordx4 v[152:153], off
	s_waitcnt vmcnt(8)
	s_waitcnt lgkmcnt(0)
	s_barrier
	s_setprio 1
	v_mfma_f32_16x16x32_bf16 v[140:143], v[112:115], v[174:177], v[140:143]
	v_mfma_f32_16x16x32_bf16 v[136:139], v[120:123], v[174:177], v[136:139]
	v_mfma_f32_16x16x32_bf16 v[108:111], v[112:115], v[182:185], v[108:111]
	v_mfma_f32_16x16x32_bf16 v[104:107], v[120:123], v[182:185], v[104:107]
	v_mfma_f32_16x16x32_bf16 v[92:95], v[112:115], v[196:199], v[92:95]
	v_mfma_f32_16x16x32_bf16 v[88:91], v[120:123], v[196:199], v[88:91]
	v_mfma_f32_16x16x32_bf16 v[76:79], v[112:115], v[204:207], v[76:79]
	v_mfma_f32_16x16x32_bf16 v[72:75], v[120:123], v[204:207], v[72:75]
	v_mfma_f32_16x16x32_bf16 v[140:143], v[116:119], v[178:181], v[140:143]
	v_mfma_f32_16x16x32_bf16 v[136:139], v[124:127], v[178:181], v[136:139]
	v_mfma_f32_16x16x32_bf16 v[108:111], v[116:119], v[192:195], v[108:111]
	v_mfma_f32_16x16x32_bf16 v[104:107], v[124:127], v[192:195], v[104:107]
	v_mfma_f32_16x16x32_bf16 v[92:95], v[116:119], v[200:203], v[92:95]
	v_mfma_f32_16x16x32_bf16 v[88:91], v[124:127], v[200:203], v[88:91]
	v_mfma_f32_16x16x32_bf16 v[76:79], v[116:119], v[208:211], v[76:79]
	v_mfma_f32_16x16x32_bf16 v[72:75], v[124:127], v[208:211], v[72:75]
	s_setprio 0
	s_setprio 1
	v_mfma_f32_16x16x32_bf16 v[132:135], v[148:151], v[174:177], v[132:135]
	v_mfma_f32_16x16x32_bf16 v[128:131], v[162:165], v[174:177], v[128:131]
	v_mfma_f32_16x16x32_bf16 v[100:103], v[148:151], v[182:185], v[100:103]
	v_mfma_f32_16x16x32_bf16 v[96:99], v[162:165], v[182:185], v[96:99]
	v_mfma_f32_16x16x32_bf16 v[84:87], v[148:151], v[196:199], v[84:87]
	v_mfma_f32_16x16x32_bf16 v[80:83], v[162:165], v[196:199], v[80:83]
	v_mfma_f32_16x16x32_bf16 v[68:71], v[148:151], v[204:207], v[68:71]
	v_mfma_f32_16x16x32_bf16 v[64:67], v[162:165], v[204:207], v[64:67]
	v_mfma_f32_16x16x32_bf16 v[132:135], v[158:161], v[178:181], v[132:135]
	v_mfma_f32_16x16x32_bf16 v[128:131], v[166:169], v[178:181], v[128:131]
	v_mfma_f32_16x16x32_bf16 v[100:103], v[158:161], v[192:195], v[100:103]
	v_mfma_f32_16x16x32_bf16 v[96:99], v[166:169], v[192:195], v[96:99]
	v_mfma_f32_16x16x32_bf16 v[84:87], v[158:161], v[200:203], v[84:87]
	v_mfma_f32_16x16x32_bf16 v[80:83], v[166:169], v[200:203], v[80:83]
	v_mfma_f32_16x16x32_bf16 v[68:71], v[158:161], v[208:211], v[68:71]
	v_mfma_f32_16x16x32_bf16 v[64:67], v[166:169], v[208:211], v[64:67]
	s_setprio 0
	s_barrier
	s_mov_b32 m0, s65
	v_lshl_add_u64 v[152:153], s[38:39], 0, v[146:147]
	ds_read_b128 v[174:177], v157 offset:16384
	ds_read_b128 v[178:181], v157 offset:17408
	ds_read_b128 v[182:185], v157 offset:18432
	ds_read_b128 v[192:195], v157 offset:19456
	ds_read_b128 v[196:199], v157 offset:20480
	ds_read_b128 v[200:203], v157 offset:21504
	ds_read_b128 v[204:207], v157 offset:22528
	ds_read_b128 v[208:211], v157 offset:23552
	global_load_lds_dwordx4 v[152:153], off
	v_lshl_add_u64 v[170:171], s[38:39], 0, v[144:145]
	s_mov_b32 m0, s62
	v_lshl_add_u64 v[186:187], s[40:41], 0, v[146:147]
	global_load_lds_dwordx4 v[170:171], off
	s_mov_b32 m0, s64
	v_lshl_add_u64 v[212:213], s[36:37], 0, v[144:145]
	global_load_lds_dwordx4 v[186:187], off
	v_lshl_add_u64 v[186:187], s[40:41], 0, v[144:145]
	s_mov_b32 m0, s63
	s_nop 0
	global_load_lds_dwordx4 v[186:187], off
	v_lshl_add_u64 v[186:187], s[36:37], 0, v[146:147]
	s_mov_b32 m0, s51
	s_nop 0
	global_load_lds_dwordx4 v[186:187], off
	s_mov_b32 m0, s52
	s_nop 0
	global_load_lds_dwordx4 v[212:213], off
	s_waitcnt vmcnt(8)
	s_waitcnt lgkmcnt(0)
	s_barrier
; #define PG8_STAGE(bufoff, gbase, voff) do { _Pragma("unroll") for (int _i = 0; _i < 2; ++_i) \
;         __builtin_amdgcn_global_load_lds((const unsigned*)((const char*)(gbase) + (voff)[_i]), (PG8_LAS unsigned*)(lds + (bufoff) + ldsw + _i * 8192), 16, 0, 0); } while (0)
; #define PG8_LDA(dst, b, h) do { _Pragma("unroll") for (int m = 0; m < 4; ++m) _Pragma("unroll") for (int k = 0; k < 2; ++k) dst[m][k] = *(const PG8_LAS bf16x8*)(lds + PG8_SA(b, h) + aoff + m * 2048 + k * 1024); } while (0)
; #define PG8_LDB(dst, b, h) do { _Pragma("unroll") for (int n = 0; n < 2; ++n) _Pragma("unroll") for (int k = 0; k < 2; ++k) dst[n][k] = *(const PG8_LAS bf16x8*)(lds + PG8_SB(b, h) + boff + n * 2048 + k * 1024); } while (0)
; #define PG8_MMA(ai, bj, At, Bt) do { __builtin_amdgcn_s_setprio(1); _Pragma("unroll") for (int m = 0; m < 4; ++m) _Pragma("unroll") for (int n = 0; n < 2; ++n) _Pragma("unroll") for (int k = 0; k < 2; ++k) \
;         acc[ai][bj][m][n] = __builtin_amdgcn_mfma_f32_16x16x32_bf16(Bt[n][k], At[m][k], acc[ai][bj][m][n], 0, 0, 0); __builtin_amdgcn_s_setprio(0); } while (0)
; #define PG8_WAIT_V(n) asm volatile("s_waitcnt vmcnt(" #n ")" ::: "memory")
; #define PG8_WAIT_L(n) asm volatile("s_waitcnt lgkmcnt(" #n ")" ::: "memory")
; #define PG8_BAR __builtin_amdgcn_s_barrier()
; #define PG8_SCHED __builtin_amdgcn_sched_barrier(0)
; template <class Epi, class Sched, bool ALIGN_EPI = false, bool SP2 = false>
; __device__ __forceinline__ void gemm_phase(PG8_LAS unsigned char* lds, const Gemm g, const Sched& S, const Epi& E) {
;     ...
;             if constexpr (SP2) {
;             PG8_LDB(B0, 0, 0); PG8_LDB(B1, 0, 1); PG8_SCHED; PG8_LDA(At, 0, 0); PG8_STAGE(PG8_SA(1, 1), a1 + hstepA, voffA);
;             PG8_WAIT_V(8); PG8_WAIT_L(0); PG8_BAR; PG8_MMA(0, 0, At, B0); PG8_MMA(0, 1, At, B1); PG8_BAR; PG8_SCHED;
;             PG8_LDA(At, 0, 1); PG8_STAGE(PG8_SB(0, 0), b2, voffB); PG8_STAGE(PG8_SB(0, 1), b2 + hstepB, voffB); PG8_STAGE(PG8_SA(0, 0), a2, voffA);
;             PG8_WAIT_V(8); PG8_WAIT_L(0); PG8_BAR; PG8_MMA(1, 0, At, B0); PG8_MMA(1, 1, At, B1); PG8_BAR; PG8_SCHED;
;             PG8_LDB(B0, 1, 0); PG8_LDB(B1, 1, 1); PG8_SCHED; PG8_LDA(At, 1, 0); PG8_STAGE(PG8_SA(0, 1), a2 + hstepA, voffA);
;             PG8_WAIT_V(8); PG8_WAIT_L(0); PG8_BAR; PG8_MMA(0, 0, At, B0); PG8_MMA(0, 1, At, B1); PG8_BAR; PG8_SCHED;
	s_setprio 1
	v_mfma_f32_16x16x32_bf16 v[60:63], v[112:115], v[174:177], v[60:63]
	v_mfma_f32_16x16x32_bf16 v[56:59], v[120:123], v[174:177], v[56:59]
	v_mfma_f32_16x16x32_bf16 v[52:55], v[112:115], v[182:185], v[52:55]
	v_mfma_f32_16x16x32_bf16 v[40:43], v[120:123], v[182:185], v[40:43]
	v_mfma_f32_16x16x32_bf16 v[36:39], v[112:115], v[196:199], v[36:39]
	v_mfma_f32_16x16x32_bf16 v[24:27], v[120:123], v[196:199], v[24:27]
	v_mfma_f32_16x16x32_bf16 v[20:23], v[112:115], v[204:207], v[20:23]
	v_mfma_f32_16x16x32_bf16 v[8:11], v[120:123], v[204:207], v[8:11]
	v_mfma_f32_16x16x32_bf16 v[60:63], v[116:119], v[178:181], v[60:63]
	v_mfma_f32_16x16x32_bf16 v[56:59], v[124:127], v[178:181], v[56:59]
	v_mfma_f32_16x16x32_bf16 v[52:55], v[116:119], v[192:195], v[52:55]
	v_mfma_f32_16x16x32_bf16 v[40:43], v[124:127], v[192:195], v[40:43]
	v_mfma_f32_16x16x32_bf16 v[36:39], v[116:119], v[200:203], v[36:39]
	v_mfma_f32_16x16x32_bf16 v[24:27], v[124:127], v[200:203], v[24:27]
	v_mfma_f32_16x16x32_bf16 v[20:23], v[116:119], v[208:211], v[20:23]
	v_mfma_f32_16x16x32_bf16 v[8:11], v[124:127], v[208:211], v[8:11]
	s_setprio 0
	s_setprio 1
	v_mfma_f32_16x16x32_bf16 v[48:51], v[148:151], v[174:177], v[48:51]
	v_mfma_f32_16x16x32_bf16 v[44:47], v[162:165], v[174:177], v[44:47]
	v_mfma_f32_16x16x32_bf16 v[32:35], v[148:151], v[182:185], v[32:35]
	v_mfma_f32_16x16x32_bf16 v[28:31], v[162:165], v[182:185], v[28:31]
	v_mfma_f32_16x16x32_bf16 v[16:19], v[148:151], v[196:199], v[16:19]
	v_mfma_f32_16x16x32_bf16 v[12:15], v[162:165], v[196:199], v[12:15]
	v_mfma_f32_16x16x32_bf16 v[4:7], v[148:151], v[204:207], v[4:7]
	v_mfma_f32_16x16x32_bf16 v[0:3], v[162:165], v[204:207], v[0:3]
	v_mfma_f32_16x16x32_bf16 v[48:51], v[158:161], v[178:181], v[48:51]
	v_mfma_f32_16x16x32_bf16 v[44:47], v[166:169], v[178:181], v[44:47]
	v_mfma_f32_16x16x32_bf16 v[32:35], v[158:161], v[192:195], v[32:35]
	v_mfma_f32_16x16x32_bf16 v[28:31], v[166:169], v[192:195], v[28:31]
	v_mfma_f32_16x16x32_bf16 v[16:19], v[158:161], v[200:203], v[16:19]
	v_mfma_f32_16x16x32_bf16 v[12:15], v[166:169], v[200:203], v[12:15]
	v_mfma_f32_16x16x32_bf16 v[4:7], v[158:161], v[208:211], v[4:7]
	v_mfma_f32_16x16x32_bf16 v[0:3], v[166:169], v[208:211], v[0:3]
	s_setprio 0
	s_barrier
	v_add_u32_e32 v124, s61, v154
	v_add_u32_e32 v166, s60, v154
	ds_read_b128 v[112:115], v124
	ds_read_b128 v[116:119], v124 offset:1024
	ds_read_b128 v[120:123], v124 offset:2048
	ds_read_b128 v[124:127], v124 offset:3072
	ds_read_b128 v[148:151], v166
	ds_read_b128 v[158:161], v166 offset:1024
	ds_read_b128 v[162:165], v166 offset:2048
	ds_read_b128 v[166:169], v166 offset:3072
	s_mov_b32 m0, s53
	v_lshl_add_u64 v[214:215], s[34:35], 0, v[146:147]
	ds_read_b128 v[174:177], v157 offset:32768
	ds_read_b128 v[178:181], v157 offset:33792
	ds_read_b128 v[182:185], v157 offset:34816
	ds_read_b128 v[192:195], v157 offset:35840
	ds_read_b128 v[196:199], v157 offset:36864
	ds_read_b128 v[200:203], v157 offset:37888
	ds_read_b128 v[204:207], v157 offset:38912
	ds_read_b128 v[208:211], v157 offset:39936
	global_load_lds_dwordx4 v[214:215], off
	v_lshl_add_u64 v[214:215], s[34:35], 0, v[144:145]
	s_mov_b32 m0, s54
	s_nop 0
	global_load_lds_dwordx4 v[214:215], off
	s_waitcnt vmcnt(8)
	s_waitcnt lgkmcnt(0)
	s_barrier
	s_setprio 1
	v_mfma_f32_16x16x32_bf16 v[140:143], v[112:115], v[174:177], v[140:143]
	v_mfma_f32_16x16x32_bf16 v[136:139], v[120:123], v[174:177], v[136:139]
	v_mfma_f32_16x16x32_bf16 v[108:111], v[112:115], v[182:185], v[108:111]
	v_mfma_f32_16x16x32_bf16 v[104:107], v[120:123], v[182:185], v[104:107]
	v_mfma_f32_16x16x32_bf16 v[92:95], v[112:115], v[196:199], v[92:95]
	v_mfma_f32_16x16x32_bf16 v[88:91], v[120:123], v[196:199], v[88:91]
	v_mfma_f32_16x16x32_bf16 v[76:79], v[112:115], v[204:207], v[76:79]
	v_mfma_f32_16x16x32_bf16 v[72:75], v[120:123], v[204:207], v[72:75]
	v_mfma_f32_16x16x32_bf16 v[140:143], v[116:119], v[178:181], v[140:143]
	v_mfma_f32_16x16x32_bf16 v[136:139], v[124:127], v[178:181], v[136:139]
	v_mfma_f32_16x16x32_bf16 v[108:111], v[116:119], v[192:195], v[108:111]
	v_mfma_f32_16x16x32_bf16 v[104:107], v[124:127], v[192:195], v[104:107]
	v_mfma_f32_16x16x32_bf16 v[92:95], v[116:119], v[200:203], v[92:95]
	v_mfma_f32_16x16x32_bf16 v[88:91], v[124:127], v[200:203], v[88:91]
	v_mfma_f32_16x16x32_bf16 v[76:79], v[116:119], v[208:211], v[76:79]
	v_mfma_f32_16x16x32_bf16 v[72:75], v[124:127], v[208:211], v[72:75]
	s_setprio 0
	s_setprio 1
	v_mfma_f32_16x16x32_bf16 v[132:135], v[148:151], v[174:177], v[132:135]
	v_mfma_f32_16x16x32_bf16 v[128:131], v[162:165], v[174:177], v[128:131]
	v_mfma_f32_16x16x32_bf16 v[100:103], v[148:151], v[182:185], v[100:103]
	v_mfma_f32_16x16x32_bf16 v[96:99], v[162:165], v[182:185], v[96:99]
	v_mfma_f32_16x16x32_bf16 v[84:87], v[148:151], v[196:199], v[84:87]
	v_mfma_f32_16x16x32_bf16 v[80:83], v[162:165], v[196:199], v[80:83]
	v_mfma_f32_16x16x32_bf16 v[68:71], v[148:151], v[204:207], v[68:71]
	v_mfma_f32_16x16x32_bf16 v[64:67], v[162:165], v[204:207], v[64:67]
	v_mfma_f32_16x16x32_bf16 v[132:135], v[158:161], v[178:181], v[132:135]
	v_mfma_f32_16x16x32_bf16 v[128:131], v[166:169], v[178:181], v[128:131]
	v_mfma_f32_16x16x32_bf16 v[100:103], v[158:161], v[192:195], v[100:103]
	v_mfma_f32_16x16x32_bf16 v[96:99], v[166:169], v[192:195], v[96:99]
	v_mfma_f32_16x16x32_bf16 v[84:87], v[158:161], v[200:203], v[84:87]
	v_mfma_f32_16x16x32_bf16 v[80:83], v[166:169], v[200:203], v[80:83]
	v_mfma_f32_16x16x32_bf16 v[68:71], v[158:161], v[208:211], v[68:71]
	v_mfma_f32_16x16x32_bf16 v[64:67], v[166:169], v[208:211], v[64:67]
	s_setprio 0
	s_barrier
; #define PG8_STAGE(bufoff, gbase, voff) do { _Pragma("unroll") for (int _i = 0; _i < 2; ++_i) \
;         __builtin_amdgcn_global_load_lds((const unsigned*)((const char*)(gbase) + (voff)[_i]), (PG8_LAS unsigned*)(lds + (bufoff) + ldsw + _i * 8192), 16, 0, 0); } while (0)
; #define PG8_LDA(dst, b, h) do { _Pragma("unroll") for (int m = 0; m < 4; ++m) _Pragma("unroll") for (int k = 0; k < 2; ++k) dst[m][k] = *(const PG8_LAS bf16x8*)(lds + PG8_SA(b, h) + aoff + m * 2048 + k * 1024); } while (0)
; #define PG8_MMA(ai, bj, At, Bt) do { __builtin_amdgcn_s_setprio(1); _Pragma("unroll") for (int m = 0; m < 4; ++m) _Pragma("unroll") for (int n = 0; n < 2; ++n) _Pragma("unroll") for (int k = 0; k < 2; ++k) \
;         acc[ai][bj][m][n] = __builtin_amdgcn_mfma_f32_16x16x32_bf16(Bt[n][k], At[m][k], acc[ai][bj][m][n], 0, 0, 0); __builtin_amdgcn_s_setprio(0); } while (0)
; #define PG8_WAIT_V(n) asm volatile("s_waitcnt vmcnt(" #n ")" ::: "memory")
; #define PG8_WAIT_L(n) asm volatile("s_waitcnt lgkmcnt(" #n ")" ::: "memory")
; #define PG8_BAR __builtin_amdgcn_s_barrier()
; #define PG8_SCHED __builtin_amdgcn_sched_barrier(0)
; template <class Epi, class Sched, bool ALIGN_EPI = false, bool SP2 = false>
; __device__ __forceinline__ void gemm_phase(PG8_LAS unsigned char* lds, const Gemm g, const Sched& S, const Epi& E) {
;     ...
;             PG8_LDA(At, 1, 1); PG8_STAGE(PG8_SB(1, 0), b3, voffB); PG8_STAGE(PG8_SB(1, 1), b3 + hstepB, voffB); PG8_STAGE(PG8_SA(1, 0), a3, voffA);
;             PG8_WAIT_V(8); PG8_WAIT_L(0); PG8_BAR; PG8_MMA(1, 0, At, B0); PG8_MMA(1, 1, At, B1); PG8_BAR; PG8_SCHED;
;     ...
;         if constexpr (ALIGN_EPI) { if (wr == 0) PG8_BAR; }
	s_mov_b32 m0, s23
	v_lshl_add_u64 v[152:153], v[152:153], 0, s[80:81]
	ds_read_b128 v[174:177], v157 offset:49152
	ds_read_b128 v[178:181], v157 offset:50176
	ds_read_b128 v[182:185], v157 offset:51200
	ds_read_b128 v[192:195], v157 offset:52224
	ds_read_b128 v[196:199], v157 offset:53248
	ds_read_b128 v[200:203], v157 offset:54272
	ds_read_b128 v[204:207], v157 offset:55296
	ds_read_b128 v[208:211], v157 offset:56320
	global_load_lds_dwordx4 v[152:153], off
	v_lshl_add_u64 v[152:153], v[170:171], 0, s[80:81]
	s_mov_b32 m0, s19
	s_nop 0
	global_load_lds_dwordx4 v[152:153], off
	v_lshl_add_u64 v[152:153], s[30:31], 0, v[146:147]
	s_mov_b32 m0, s67
	s_nop 0
	global_load_lds_dwordx4 v[152:153], off
	v_lshl_add_u64 v[152:153], s[30:31], 0, v[144:145]
	s_mov_b32 m0, s66
	s_nop 0
	global_load_lds_dwordx4 v[152:153], off
	v_lshl_add_u64 v[152:153], v[186:187], 0, s[80:81]
	s_mov_b32 m0, s55
	s_nop 0
	global_load_lds_dwordx4 v[152:153], off
	v_lshl_add_u64 v[152:153], v[212:213], 0, s[80:81]
	s_mov_b32 m0, s56
	s_nop 0
	global_load_lds_dwordx4 v[152:153], off
	s_waitcnt vmcnt(8)
	s_waitcnt lgkmcnt(0)
	s_barrier
	s_setprio 1
	v_mfma_f32_16x16x32_bf16 v[60:63], v[112:115], v[174:177], v[60:63]
	v_mfma_f32_16x16x32_bf16 v[56:59], v[120:123], v[174:177], v[56:59]
	v_mfma_f32_16x16x32_bf16 v[52:55], v[112:115], v[182:185], v[52:55]
	v_mfma_f32_16x16x32_bf16 v[40:43], v[120:123], v[182:185], v[40:43]
	v_mfma_f32_16x16x32_bf16 v[36:39], v[112:115], v[196:199], v[36:39]
	v_mfma_f32_16x16x32_bf16 v[24:27], v[120:123], v[196:199], v[24:27]
	v_mfma_f32_16x16x32_bf16 v[20:23], v[112:115], v[204:207], v[20:23]
	v_mfma_f32_16x16x32_bf16 v[8:11], v[120:123], v[204:207], v[8:11]
	v_mfma_f32_16x16x32_bf16 v[60:63], v[116:119], v[178:181], v[60:63]
	v_mfma_f32_16x16x32_bf16 v[56:59], v[124:127], v[178:181], v[56:59]
	v_mfma_f32_16x16x32_bf16 v[52:55], v[116:119], v[192:195], v[52:55]
	v_mfma_f32_16x16x32_bf16 v[40:43], v[124:127], v[192:195], v[40:43]
	v_mfma_f32_16x16x32_bf16 v[36:39], v[116:119], v[200:203], v[36:39]
	v_mfma_f32_16x16x32_bf16 v[24:27], v[124:127], v[200:203], v[24:27]
	v_mfma_f32_16x16x32_bf16 v[20:23], v[116:119], v[208:211], v[20:23]
	v_mfma_f32_16x16x32_bf16 v[8:11], v[124:127], v[208:211], v[8:11]
	s_setprio 0
	s_setprio 1
	v_mfma_f32_16x16x32_bf16 v[48:51], v[148:151], v[174:177], v[48:51]
	v_mfma_f32_16x16x32_bf16 v[44:47], v[162:165], v[174:177], v[44:47]
	v_mfma_f32_16x16x32_bf16 v[32:35], v[148:151], v[182:185], v[32:35]
	v_mfma_f32_16x16x32_bf16 v[28:31], v[162:165], v[182:185], v[28:31]
	v_mfma_f32_16x16x32_bf16 v[16:19], v[148:151], v[196:199], v[16:19]
	v_mfma_f32_16x16x32_bf16 v[12:15], v[162:165], v[196:199], v[12:15]
	v_mfma_f32_16x16x32_bf16 v[4:7], v[148:151], v[204:207], v[4:7]
	v_mfma_f32_16x16x32_bf16 v[0:3], v[162:165], v[204:207], v[0:3]
	v_mfma_f32_16x16x32_bf16 v[48:51], v[158:161], v[178:181], v[48:51]
	v_mfma_f32_16x16x32_bf16 v[44:47], v[166:169], v[178:181], v[44:47]
	v_mfma_f32_16x16x32_bf16 v[32:35], v[158:161], v[192:195], v[32:35]
	v_mfma_f32_16x16x32_bf16 v[28:31], v[166:169], v[192:195], v[28:31]
	v_mfma_f32_16x16x32_bf16 v[16:19], v[158:161], v[200:203], v[16:19]
	v_mfma_f32_16x16x32_bf16 v[12:15], v[166:169], v[200:203], v[12:15]
	v_mfma_f32_16x16x32_bf16 v[4:7], v[158:161], v[208:211], v[4:7]
	v_mfma_f32_16x16x32_bf16 v[0:3], v[166:169], v[208:211], v[0:3]
	s_setprio 0
	s_barrier
	s_movk_i32 s19, 0x100
	s_andn2_b64 vcc, exec, s[28:29]
	s_mov_b64 s[30:31], -1
	s_mov_b64 s[28:29], 0
	s_cbranch_vccz .LBB0_1612
	s_and_b64 vcc, exec, s[10:11]
	s_cbranch_vccz .LBB0_1615
	s_barrier

;     __device__ __forceinline__ bool next(int i, Unit& u) const { const int L = i * G + c; if (L >= nsub) return false; u.pk = L >> 4; u.pm = MLAT / BM + (L & 3); u.pn = (L >> 2) & 3; return true; }
; #define PG8_STAGE(bufoff, gbase, voff) do { _Pragma("unroll") for (int _i = 0; _i < 2; ++_i) \
;         __builtin_amdgcn_global_load_lds((const unsigned*)((const char*)(gbase) + (voff)[_i]), (PG8_LAS unsigned*)(lds + (bufoff) + ldsw + _i * 8192), 16, 0, 0); } while (0)
; #define PG8_LDA(dst, b, h) do { _Pragma("unroll") for (int m = 0; m < 4; ++m) _Pragma("unroll") for (int k = 0; k < 2; ++k) dst[m][k] = *(const PG8_LAS bf16x8*)(lds + PG8_SA(b, h) + aoff + m * 2048 + k * 1024); } while (0)
; #define PG8_LDB(dst, b, h) do { _Pragma("unroll") for (int n = 0; n < 2; ++n) _Pragma("unroll") for (int k = 0; k < 2; ++k) dst[n][k] = *(const PG8_LAS bf16x8*)(lds + PG8_SB(b, h) + boff + n * 2048 + k * 1024); } while (0)
; #define PG8_WAIT_V(n) asm volatile("s_waitcnt vmcnt(" #n ")" ::: "memory")
; #define PG8_WAIT_L(n) asm volatile("s_waitcnt lgkmcnt(" #n ")" ::: "memory")
; template <class Epi, class Sched, bool ALIGN_EPI = false, bool SP2 = false>
; __device__ __forceinline__ void gemm_phase(PG8_LAS unsigned char* lds, const Gemm g, const Sched& S, const Epi& E) {
;     ...
;         const bool has_next = S.next(ui + 1, nxt);
;         const char* nA = has_next ? g.a_of(nxt) : cA; const char* nB = has_next ? g.b_of(nxt) : cB;
;         for (int t = 0; t < nt; t += 2) {
;             const bool last = (t == nt - 2);
;             const char* a1 = cA + (size_t)(t + 1) * kstep;
;             const char* a2 = last ? nA : cA + (size_t)(t + 2) * kstep; const char* b2 = last ? nB : cB + (size_t)(t + 2) * kstep;
;             const char* a3 = a2 + kstep; const char* b3 = b2 + kstep;
;             if (last && has_next) S.a_ready(nxt);
;             if constexpr (SP2) {
;             PG8_LDB(B0, 0, 0); PG8_LDB(B1, 0, 1); PG8_SCHED; PG8_LDA(At, 0, 0); PG8_STAGE(PG8_SA(1, 1), a1 + hstepA, voffA);
;             PG8_WAIT_V(8); PG8_WAIT_L(0); PG8_BAR; PG8_MMA(0, 0, At, B0); PG8_MMA(0, 1, At, B1); PG8_BAR; PG8_SCHED;
;             PG8_LDA(At, 0, 1); PG8_STAGE(PG8_SB(0, 0), b2, voffB); PG8_STAGE(PG8_SB(0, 1), b2 + hstepB, voffB); PG8_STAGE(PG8_SA(0, 0), a2, voffA);
;             PG8_WAIT_V(8); PG8_WAIT_L(0); PG8_BAR; PG8_MMA(1, 0, At, B0); PG8_MMA(1, 1, At, B1); PG8_BAR; PG8_SCHED;
.LBB0_1786:
	s_add_u32 s36, s34, 0xfffc0080
	s_addc_u32 s37, s35, -1
	s_add_i32 s64, 0, 0x10000
	s_cmp_eq_u32 s63, 12
	s_cselect_b32 s39, s11, s37
	s_cselect_b32 s38, s25, s36
	s_cselect_b32 s37, s23, s62
	s_cselect_b32 s36, s60, s61
	s_add_i32 s66, 0, 0x14000
	v_add_u32_e32 v140, s64, v163
	v_add_u32_e32 v158, s66, v163
	ds_read_b128 v[128:131], v140
	ds_read_b128 v[132:135], v140 offset:1024
	ds_read_b128 v[136:139], v140 offset:2048
	ds_read_b128 v[140:143], v140 offset:3072
	ds_read_b128 v[154:157], v158
	ds_read_b128 v[166:169], v158 offset:1024
	ds_read_b128 v[174:177], v158 offset:2048
	ds_read_b128 v[178:181], v158 offset:3072
	s_add_i32 m0, s31, 0xc000
	ds_read_b128 v[182:185], v165
	ds_read_b128 v[192:195], v165 offset:1024
	ds_read_b128 v[196:199], v165 offset:2048
	ds_read_b128 v[200:203], v165 offset:3072
	ds_read_b128 v[204:207], v165 offset:4096
	ds_read_b128 v[208:211], v165 offset:5120
	ds_read_b128 v[212:215], v165 offset:6144
	ds_read_b128 v[216:219], v165 offset:7168
	global_load_lds_dwordx4 v150, s[34:35]
	s_add_i32 m0, s31, 0xe000
	s_nop 0
	global_load_lds_dwordx4 v152, s[34:35]
	s_waitcnt vmcnt(8)
	s_waitcnt lgkmcnt(0)
	s_barrier
	s_setprio 1
	v_mfma_f32_16x16x32_bf16 v[124:127], v[128:131], v[182:185], v[124:127]
	v_mfma_f32_16x16x32_bf16 v[120:123], v[136:139], v[182:185], v[120:123]
	v_mfma_f32_16x16x32_bf16 v[108:111], v[128:131], v[196:199], v[108:111]
	v_mfma_f32_16x16x32_bf16 v[104:107], v[136:139], v[196:199], v[104:107]
	v_mfma_f32_16x16x32_bf16 v[92:95], v[128:131], v[204:207], v[92:95]
	v_mfma_f32_16x16x32_bf16 v[88:91], v[136:139], v[204:207], v[88:91]
	v_mfma_f32_16x16x32_bf16 v[76:79], v[128:131], v[212:215], v[76:79]
	v_mfma_f32_16x16x32_bf16 v[72:75], v[136:139], v[212:215], v[72:75]
	v_mfma_f32_16x16x32_bf16 v[124:127], v[132:135], v[192:195], v[124:127]
	v_mfma_f32_16x16x32_bf16 v[120:123], v[140:143], v[192:195], v[120:123]
	v_mfma_f32_16x16x32_bf16 v[108:111], v[132:135], v[200:203], v[108:111]
	v_mfma_f32_16x16x32_bf16 v[104:107], v[140:143], v[200:203], v[104:107]
	v_mfma_f32_16x16x32_bf16 v[92:95], v[132:135], v[208:211], v[92:95]
	v_mfma_f32_16x16x32_bf16 v[88:91], v[140:143], v[208:211], v[88:91]
	v_mfma_f32_16x16x32_bf16 v[76:79], v[132:135], v[216:219], v[76:79]
	v_mfma_f32_16x16x32_bf16 v[72:75], v[140:143], v[216:219], v[72:75]
	s_setprio 0
	s_setprio 1
	v_mfma_f32_16x16x32_bf16 v[116:119], v[154:157], v[182:185], v[116:119]
	v_mfma_f32_16x16x32_bf16 v[112:115], v[174:177], v[182:185], v[112:115]
	v_mfma_f32_16x16x32_bf16 v[100:103], v[154:157], v[196:199], v[100:103]
	v_mfma_f32_16x16x32_bf16 v[96:99], v[174:177], v[196:199], v[96:99]
	v_mfma_f32_16x16x32_bf16 v[84:87], v[154:157], v[204:207], v[84:87]
	v_mfma_f32_16x16x32_bf16 v[80:83], v[174:177], v[204:207], v[80:83]
	v_mfma_f32_16x16x32_bf16 v[68:71], v[154:157], v[212:215], v[68:71]
	v_mfma_f32_16x16x32_bf16 v[64:67], v[174:177], v[212:215], v[64:67]
	v_mfma_f32_16x16x32_bf16 v[116:119], v[166:169], v[192:195], v[116:119]
	v_mfma_f32_16x16x32_bf16 v[112:115], v[178:181], v[192:195], v[112:115]
	v_mfma_f32_16x16x32_bf16 v[100:103], v[166:169], v[200:203], v[100:103]
	v_mfma_f32_16x16x32_bf16 v[96:99], v[178:181], v[200:203], v[96:99]
	v_mfma_f32_16x16x32_bf16 v[84:87], v[166:169], v[208:211], v[84:87]
	v_mfma_f32_16x16x32_bf16 v[80:83], v[178:181], v[208:211], v[80:83]
	v_mfma_f32_16x16x32_bf16 v[68:71], v[166:169], v[216:219], v[68:71]
	v_mfma_f32_16x16x32_bf16 v[64:67], v[178:181], v[216:219], v[64:67]
	s_setprio 0
	s_barrier
	s_add_i32 s64, s64, s46
	v_lshl_add_u64 v[158:159], s[36:37], 0, v[172:173]
	s_mov_b32 m0, s64
	ds_read_b128 v[182:185], v165 offset:16384
	ds_read_b128 v[192:195], v165 offset:17408
	ds_read_b128 v[196:199], v165 offset:18432
	ds_read_b128 v[200:203], v165 offset:19456
	ds_read_b128 v[204:207], v165 offset:20480
	ds_read_b128 v[208:211], v165 offset:21504
	ds_read_b128 v[212:215], v165 offset:22528
	ds_read_b128 v[216:219], v165 offset:23552
	global_load_lds_dwordx4 v[158:159], off
	s_add_i32 m0, s64, 0x2000
	s_add_u32 s64, s36, 0x10000
	v_lshl_add_u64 v[170:171], s[36:37], 0, v[148:149]
	s_addc_u32 s65, s37, 0
	s_add_i32 s66, s66, s46
	global_load_lds_dwordx4 v[170:171], off
	s_mov_b32 m0, s66
	v_lshl_add_u64 v[220:221], s[38:39], 0, v[146:147]
	global_load_lds_dwordx4 v172, s[64:65]
	s_add_i32 m0, s66, 0x2000
	s_nop 0
	global_load_lds_dwordx4 v148, s[64:65]
	v_lshl_add_u64 v[186:187], s[38:39], 0, v[144:145]
	s_mov_b32 m0, s31
	s_nop 0
	global_load_lds_dwordx4 v[186:187], off
	s_mov_b32 m0, s47
	s_nop 0
	global_load_lds_dwordx4 v[220:221], off
	s_waitcnt vmcnt(8)
	s_waitcnt lgkmcnt(0)
	s_barrier
; #define PG8_STAGE(bufoff, gbase, voff) do { _Pragma("unroll") for (int _i = 0; _i < 2; ++_i) \
;         __builtin_amdgcn_global_load_lds((const unsigned*)((const char*)(gbase) + (voff)[_i]), (PG8_LAS unsigned*)(lds + (bufoff) + ldsw + _i * 8192), 16, 0, 0); } while (0)
; #define PG8_LDA(dst, b, h) do { _Pragma("unroll") for (int m = 0; m < 4; ++m) _Pragma("unroll") for (int k = 0; k < 2; ++k) dst[m][k] = *(const PG8_LAS bf16x8*)(lds + PG8_SA(b, h) + aoff + m * 2048 + k * 1024); } while (0)
; #define PG8_LDB(dst, b, h) do { _Pragma("unroll") for (int n = 0; n < 2; ++n) _Pragma("unroll") for (int k = 0; k < 2; ++k) dst[n][k] = *(const PG8_LAS bf16x8*)(lds + PG8_SB(b, h) + boff + n * 2048 + k * 1024); } while (0)
; #define PG8_MMA(ai, bj, At, Bt) do { __builtin_amdgcn_s_setprio(1); _Pragma("unroll") for (int m = 0; m < 4; ++m) _Pragma("unroll") for (int n = 0; n < 2; ++n) _Pragma("unroll") for (int k = 0; k < 2; ++k) \
;         acc[ai][bj][m][n] = __builtin_amdgcn_mfma_f32_16x16x32_bf16(Bt[n][k], At[m][k], acc[ai][bj][m][n], 0, 0, 0); __builtin_amdgcn_s_setprio(0); } while (0)
; #define PG8_WAIT_V(n) asm volatile("s_waitcnt vmcnt(" #n ")" ::: "memory")
; #define PG8_WAIT_L(n) asm volatile("s_waitcnt lgkmcnt(" #n ")" ::: "memory")
; #define PG8_BAR __builtin_amdgcn_s_barrier()
; #define PG8_SCHED __builtin_amdgcn_sched_barrier(0)
; template <class Epi, class Sched, bool ALIGN_EPI = false, bool SP2 = false>
; __device__ __forceinline__ void gemm_phase(PG8_LAS unsigned char* lds, const Gemm g, const Sched& S, const Epi& E) {
;     ...
;             PG8_WAIT_V(8); PG8_WAIT_L(0); PG8_BAR; PG8_MMA(0, 0, At, B0); PG8_MMA(0, 1, At, B1); PG8_BAR; PG8_SCHED;
;             PG8_LDA(At, 0, 1); PG8_STAGE(PG8_SB(0, 0), b2, voffB); PG8_STAGE(PG8_SB(0, 1), b2 + hstepB, voffB); PG8_STAGE(PG8_SA(0, 0), a2, voffA);
;             PG8_WAIT_V(8); PG8_WAIT_L(0); PG8_BAR; PG8_MMA(1, 0, At, B0); PG8_MMA(1, 1, At, B1); PG8_BAR; PG8_SCHED;
;             PG8_LDB(B0, 1, 0); PG8_LDB(B1, 1, 1); PG8_SCHED; PG8_LDA(At, 1, 0); PG8_STAGE(PG8_SA(0, 1), a2 + hstepA, voffA);
;             PG8_WAIT_V(8); PG8_WAIT_L(0); PG8_BAR; PG8_MMA(0, 0, At, B0); PG8_MMA(0, 1, At, B1); PG8_BAR; PG8_SCHED;
	s_setprio 1
	v_mfma_f32_16x16x32_bf16 v[60:63], v[128:131], v[182:185], v[60:63]
	v_mfma_f32_16x16x32_bf16 v[56:59], v[136:139], v[182:185], v[56:59]
	v_mfma_f32_16x16x32_bf16 v[44:47], v[128:131], v[196:199], v[44:47]
	v_mfma_f32_16x16x32_bf16 v[40:43], v[136:139], v[196:199], v[40:43]
	v_mfma_f32_16x16x32_bf16 v[28:31], v[128:131], v[204:207], v[28:31]
	v_mfma_f32_16x16x32_bf16 v[24:27], v[136:139], v[204:207], v[24:27]
	v_mfma_f32_16x16x32_bf16 v[12:15], v[128:131], v[212:215], v[12:15]
	v_mfma_f32_16x16x32_bf16 v[8:11], v[136:139], v[212:215], v[8:11]
	v_mfma_f32_16x16x32_bf16 v[60:63], v[132:135], v[192:195], v[60:63]
	v_mfma_f32_16x16x32_bf16 v[56:59], v[140:143], v[192:195], v[56:59]
	v_mfma_f32_16x16x32_bf16 v[44:47], v[132:135], v[200:203], v[44:47]
	v_mfma_f32_16x16x32_bf16 v[40:43], v[140:143], v[200:203], v[40:43]
	v_mfma_f32_16x16x32_bf16 v[28:31], v[132:135], v[208:211], v[28:31]
	v_mfma_f32_16x16x32_bf16 v[24:27], v[140:143], v[208:211], v[24:27]
	v_mfma_f32_16x16x32_bf16 v[12:15], v[132:135], v[216:219], v[12:15]
	v_mfma_f32_16x16x32_bf16 v[8:11], v[140:143], v[216:219], v[8:11]
	s_setprio 0
	s_setprio 1
	v_mfma_f32_16x16x32_bf16 v[52:55], v[154:157], v[182:185], v[52:55]
	v_mfma_f32_16x16x32_bf16 v[48:51], v[174:177], v[182:185], v[48:51]
	v_mfma_f32_16x16x32_bf16 v[36:39], v[154:157], v[196:199], v[36:39]
	v_mfma_f32_16x16x32_bf16 v[32:35], v[174:177], v[196:199], v[32:35]
	v_mfma_f32_16x16x32_bf16 v[20:23], v[154:157], v[204:207], v[20:23]
	v_mfma_f32_16x16x32_bf16 v[16:19], v[174:177], v[204:207], v[16:19]
	v_mfma_f32_16x16x32_bf16 v[4:7], v[154:157], v[212:215], v[4:7]
	v_mfma_f32_16x16x32_bf16 v[0:3], v[174:177], v[212:215], v[0:3]
	v_mfma_f32_16x16x32_bf16 v[52:55], v[166:169], v[192:195], v[52:55]
	v_mfma_f32_16x16x32_bf16 v[48:51], v[178:181], v[192:195], v[48:51]
	v_mfma_f32_16x16x32_bf16 v[36:39], v[166:169], v[200:203], v[36:39]
	v_mfma_f32_16x16x32_bf16 v[32:35], v[178:181], v[200:203], v[32:35]
	v_mfma_f32_16x16x32_bf16 v[20:23], v[166:169], v[208:211], v[20:23]
	v_mfma_f32_16x16x32_bf16 v[16:19], v[178:181], v[208:211], v[16:19]
	v_mfma_f32_16x16x32_bf16 v[4:7], v[166:169], v[216:219], v[4:7]
	v_mfma_f32_16x16x32_bf16 v[0:3], v[178:181], v[216:219], v[0:3]
	s_setprio 0
	s_barrier
	s_add_i32 s64, 0, 0x18000
	s_add_i32 s65, 0, 0x1c000
	v_add_u32_e32 v140, s64, v163
	v_add_u32_e32 v160, s65, v163
	ds_read_b128 v[128:131], v140
	ds_read_b128 v[132:135], v140 offset:1024
	ds_read_b128 v[136:139], v140 offset:2048
	ds_read_b128 v[140:143], v140 offset:3072
	ds_read_b128 v[154:157], v160
	ds_read_b128 v[166:169], v160 offset:1024
	ds_read_b128 v[174:177], v160 offset:2048
	ds_read_b128 v[178:181], v160 offset:3072
	s_add_u32 s38, s38, 0x40000
	s_addc_u32 s39, s39, 0
	s_mov_b32 m0, s49
	ds_read_b128 v[182:185], v165 offset:32768
	ds_read_b128 v[192:195], v165 offset:33792
	ds_read_b128 v[196:199], v165 offset:34816
	ds_read_b128 v[200:203], v165 offset:35840
	ds_read_b128 v[204:207], v165 offset:36864
	ds_read_b128 v[208:211], v165 offset:37888
	ds_read_b128 v[212:215], v165 offset:38912
	ds_read_b128 v[216:219], v165 offset:39936
	global_load_lds_dwordx4 v144, s[38:39]
	v_lshl_add_u64 v[222:223], s[38:39], 0, v[146:147]
	s_mov_b32 m0, s50
	s_nop 0
	global_load_lds_dwordx4 v[222:223], off
	s_waitcnt vmcnt(8)
	s_waitcnt lgkmcnt(0)
	s_barrier
	s_setprio 1
	v_mfma_f32_16x16x32_bf16 v[124:127], v[128:131], v[182:185], v[124:127]
	v_mfma_f32_16x16x32_bf16 v[120:123], v[136:139], v[182:185], v[120:123]
	v_mfma_f32_16x16x32_bf16 v[108:111], v[128:131], v[196:199], v[108:111]
	v_mfma_f32_16x16x32_bf16 v[104:107], v[136:139], v[196:199], v[104:107]
	v_mfma_f32_16x16x32_bf16 v[92:95], v[128:131], v[204:207], v[92:95]
	v_mfma_f32_16x16x32_bf16 v[88:91], v[136:139], v[204:207], v[88:91]
	v_mfma_f32_16x16x32_bf16 v[76:79], v[128:131], v[212:215], v[76:79]
	v_mfma_f32_16x16x32_bf16 v[72:75], v[136:139], v[212:215], v[72:75]
	v_mfma_f32_16x16x32_bf16 v[124:127], v[132:135], v[192:195], v[124:127]
	v_mfma_f32_16x16x32_bf16 v[120:123], v[140:143], v[192:195], v[120:123]
	v_mfma_f32_16x16x32_bf16 v[108:111], v[132:135], v[200:203], v[108:111]
	v_mfma_f32_16x16x32_bf16 v[104:107], v[140:143], v[200:203], v[104:107]
	v_mfma_f32_16x16x32_bf16 v[92:95], v[132:135], v[208:211], v[92:95]
	v_mfma_f32_16x16x32_bf16 v[88:91], v[140:143], v[208:211], v[88:91]
	v_mfma_f32_16x16x32_bf16 v[76:79], v[132:135], v[216:219], v[76:79]
	v_mfma_f32_16x16x32_bf16 v[72:75], v[140:143], v[216:219], v[72:75]
	s_setprio 0
	s_setprio 1
	v_mfma_f32_16x16x32_bf16 v[116:119], v[154:157], v[182:185], v[116:119]
	v_mfma_f32_16x16x32_bf16 v[112:115], v[174:177], v[182:185], v[112:115]
	v_mfma_f32_16x16x32_bf16 v[100:103], v[154:157], v[196:199], v[100:103]
	v_mfma_f32_16x16x32_bf16 v[96:99], v[174:177], v[196:199], v[96:99]
	v_mfma_f32_16x16x32_bf16 v[84:87], v[154:157], v[204:207], v[84:87]
	v_mfma_f32_16x16x32_bf16 v[80:83], v[174:177], v[204:207], v[80:83]
	v_mfma_f32_16x16x32_bf16 v[68:71], v[154:157], v[212:215], v[68:71]
	v_mfma_f32_16x16x32_bf16 v[64:67], v[174:177], v[212:215], v[64:67]
	v_mfma_f32_16x16x32_bf16 v[116:119], v[166:169], v[192:195], v[116:119]
	v_mfma_f32_16x16x32_bf16 v[112:115], v[178:181], v[192:195], v[112:115]
	v_mfma_f32_16x16x32_bf16 v[100:103], v[166:169], v[200:203], v[100:103]
	v_mfma_f32_16x16x32_bf16 v[96:99], v[178:181], v[200:203], v[96:99]
	v_mfma_f32_16x16x32_bf16 v[84:87], v[166:169], v[208:211], v[84:87]
	v_mfma_f32_16x16x32_bf16 v[80:83], v[178:181], v[208:211], v[80:83]
	v_mfma_f32_16x16x32_bf16 v[68:71], v[166:169], v[216:219], v[68:71]
	v_mfma_f32_16x16x32_bf16 v[64:67], v[178:181], v[216:219], v[64:67]
	s_setprio 0
	s_barrier
; #define PG8_STAGE(bufoff, gbase, voff) do { _Pragma("unroll") for (int _i = 0; _i < 2; ++_i) \
;         __builtin_amdgcn_global_load_lds((const unsigned*)((const char*)(gbase) + (voff)[_i]), (PG8_LAS unsigned*)(lds + (bufoff) + ldsw + _i * 8192), 16, 0, 0); } while (0)
; #define PG8_LDA(dst, b, h) do { _Pragma("unroll") for (int m = 0; m < 4; ++m) _Pragma("unroll") for (int k = 0; k < 2; ++k) dst[m][k] = *(const PG8_LAS bf16x8*)(lds + PG8_SA(b, h) + aoff + m * 2048 + k * 1024); } while (0)
; #define PG8_MMA(ai, bj, At, Bt) do { __builtin_amdgcn_s_setprio(1); _Pragma("unroll") for (int m = 0; m < 4; ++m) _Pragma("unroll") for (int n = 0; n < 2; ++n) _Pragma("unroll") for (int k = 0; k < 2; ++k) \
;         acc[ai][bj][m][n] = __builtin_amdgcn_mfma_f32_16x16x32_bf16(Bt[n][k], At[m][k], acc[ai][bj][m][n], 0, 0, 0); __builtin_amdgcn_s_setprio(0); } while (0)
; #define PG8_WAIT_V(n) asm volatile("s_waitcnt vmcnt(" #n ")" ::: "memory")
; #define PG8_WAIT_L(n) asm volatile("s_waitcnt lgkmcnt(" #n ")" ::: "memory")
; #define PG8_BAR __builtin_amdgcn_s_barrier()
; #define PG8_SCHED __builtin_amdgcn_sched_barrier(0)
; template <class Epi, class Sched, bool ALIGN_EPI = false, bool SP2 = false>
; __device__ __forceinline__ void gemm_phase(PG8_LAS unsigned char* lds, const Gemm g, const Sched& S, const Epi& E) {
;     ...
;         for (int t = 0; t < nt; t += 2) {
;     ...
;             PG8_LDA(At, 1, 1); PG8_STAGE(PG8_SB(1, 0), b3, voffB); PG8_STAGE(PG8_SB(1, 1), b3 + hstepB, voffB); PG8_STAGE(PG8_SA(1, 0), a3, voffA);
;             PG8_WAIT_V(8); PG8_WAIT_L(0); PG8_BAR; PG8_MMA(1, 0, At, B0); PG8_MMA(1, 1, At, B1); PG8_BAR; PG8_SCHED;
	s_add_i32 s38, s64, s46
	v_lshl_add_u64 v[158:159], v[158:159], 0, s[80:81]
	s_mov_b32 m0, s38
	ds_read_b128 v[182:185], v165 offset:49152
	ds_read_b128 v[192:195], v165 offset:50176
	ds_read_b128 v[196:199], v165 offset:51200
	ds_read_b128 v[200:203], v165 offset:52224
	ds_read_b128 v[204:207], v165 offset:53248
	ds_read_b128 v[208:211], v165 offset:54272
	ds_read_b128 v[212:215], v165 offset:55296
	ds_read_b128 v[216:219], v165 offset:56320
	global_load_lds_dwordx4 v[158:159], off
	s_add_i32 m0, s38, 0x2000
	s_add_u32 s36, s36, 0x10080
	v_lshl_add_u64 v[158:159], v[170:171], 0, s[80:81]
	s_addc_u32 s37, s37, 0
	s_add_i32 s38, s65, s46
	global_load_lds_dwordx4 v[158:159], off
	s_mov_b32 m0, s38
	s_nop 0
	global_load_lds_dwordx4 v172, s[36:37]
	s_add_i32 m0, s38, 0x2000
	s_nop 0
	global_load_lds_dwordx4 v148, s[36:37]
	v_lshl_add_u64 v[158:159], v[186:187], 0, s[80:81]
	s_mov_b32 m0, s57
	s_nop 0
	global_load_lds_dwordx4 v[158:159], off
	v_lshl_add_u64 v[158:159], v[220:221], 0, s[80:81]
	s_mov_b32 m0, s58
	s_nop 0
	global_load_lds_dwordx4 v[158:159], off
	s_waitcnt vmcnt(8)
	s_waitcnt lgkmcnt(0)
	s_barrier
	s_setprio 1
	v_mfma_f32_16x16x32_bf16 v[60:63], v[128:131], v[182:185], v[60:63]
	v_mfma_f32_16x16x32_bf16 v[56:59], v[136:139], v[182:185], v[56:59]
	v_mfma_f32_16x16x32_bf16 v[44:47], v[128:131], v[196:199], v[44:47]
	v_mfma_f32_16x16x32_bf16 v[40:43], v[136:139], v[196:199], v[40:43]
	v_mfma_f32_16x16x32_bf16 v[28:31], v[128:131], v[204:207], v[28:31]
	v_mfma_f32_16x16x32_bf16 v[24:27], v[136:139], v[204:207], v[24:27]
	v_mfma_f32_16x16x32_bf16 v[12:15], v[128:131], v[212:215], v[12:15]
	v_mfma_f32_16x16x32_bf16 v[8:11], v[136:139], v[212:215], v[8:11]
	v_mfma_f32_16x16x32_bf16 v[60:63], v[132:135], v[192:195], v[60:63]
	v_mfma_f32_16x16x32_bf16 v[56:59], v[140:143], v[192:195], v[56:59]
	v_mfma_f32_16x16x32_bf16 v[44:47], v[132:135], v[200:203], v[44:47]
	v_mfma_f32_16x16x32_bf16 v[40:43], v[140:143], v[200:203], v[40:43]
	v_mfma_f32_16x16x32_bf16 v[28:31], v[132:135], v[208:211], v[28:31]
	v_mfma_f32_16x16x32_bf16 v[24:27], v[140:143], v[208:211], v[24:27]
	v_mfma_f32_16x16x32_bf16 v[12:15], v[132:135], v[216:219], v[12:15]
	v_mfma_f32_16x16x32_bf16 v[8:11], v[140:143], v[216:219], v[8:11]
	s_setprio 0
	s_setprio 1
	v_mfma_f32_16x16x32_bf16 v[52:55], v[154:157], v[182:185], v[52:55]
	v_mfma_f32_16x16x32_bf16 v[48:51], v[174:177], v[182:185], v[48:51]
	v_mfma_f32_16x16x32_bf16 v[36:39], v[154:157], v[196:199], v[36:39]
	v_mfma_f32_16x16x32_bf16 v[32:35], v[174:177], v[196:199], v[32:35]
	v_mfma_f32_16x16x32_bf16 v[20:23], v[154:157], v[204:207], v[20:23]
	v_mfma_f32_16x16x32_bf16 v[16:19], v[174:177], v[204:207], v[16:19]
	v_mfma_f32_16x16x32_bf16 v[4:7], v[154:157], v[212:215], v[4:7]
	v_mfma_f32_16x16x32_bf16 v[0:3], v[174:177], v[212:215], v[0:3]
	v_mfma_f32_16x16x32_bf16 v[52:55], v[166:169], v[192:195], v[52:55]
	v_mfma_f32_16x16x32_bf16 v[48:51], v[178:181], v[192:195], v[48:51]
	v_mfma_f32_16x16x32_bf16 v[36:39], v[166:169], v[200:203], v[36:39]
	v_mfma_f32_16x16x32_bf16 v[32:35], v[178:181], v[200:203], v[32:35]
	v_mfma_f32_16x16x32_bf16 v[20:23], v[166:169], v[208:211], v[20:23]
	v_mfma_f32_16x16x32_bf16 v[16:19], v[178:181], v[208:211], v[16:19]
	v_mfma_f32_16x16x32_bf16 v[4:7], v[166:169], v[216:219], v[4:7]
	v_mfma_f32_16x16x32_bf16 v[0:3], v[178:181], v[216:219], v[0:3]
	s_setprio 0
	s_barrier
	s_add_i32 s63, s63, 2
	s_add_u32 s34, s34, 0x100
	s_addc_u32 s35, s35, 0
	s_add_u32 s61, s61, 0x100
	s_addc_u32 s62, s62, 0
	s_cmp_gt_u32 s63, 13
	s_cbranch_scc0 .LBB0_1786
	s_and_b64 vcc, exec, s[20:21]
	s_cbranch_vccz .LBB0_1789
	s_barrier

;     __device__ __forceinline__ bool next(int i, Unit& u) const { const int L = i * G + c; if (L >= nsub) return false; u.pk = L >> 4; u.pm = MLAT / BM + (L & 3); u.pn = (L >> 2) & 3; return true; }
; #define PG8_STAGE(bufoff, gbase, voff) do { _Pragma("unroll") for (int _i = 0; _i < 2; ++_i) \
;         __builtin_amdgcn_global_load_lds((const unsigned*)((const char*)(gbase) + (voff)[_i]), (PG8_LAS unsigned*)(lds + (bufoff) + ldsw + _i * 8192), 16, 0, 0); } while (0)
; #define PG8_LDA(dst, b, h) do { _Pragma("unroll") for (int m = 0; m < 4; ++m) _Pragma("unroll") for (int k = 0; k < 2; ++k) dst[m][k] = *(const PG8_LAS bf16x8*)(lds + PG8_SA(b, h) + aoff + m * 2048 + k * 1024); } while (0)
; #define PG8_LDB(dst, b, h) do { _Pragma("unroll") for (int n = 0; n < 2; ++n) _Pragma("unroll") for (int k = 0; k < 2; ++k) dst[n][k] = *(const PG8_LAS bf16x8*)(lds + PG8_SB(b, h) + boff + n * 2048 + k * 1024); } while (0)
; #define PG8_WAIT_V(n) asm volatile("s_waitcnt vmcnt(" #n ")" ::: "memory")
; #define PG8_WAIT_L(n) asm volatile("s_waitcnt lgkmcnt(" #n ")" ::: "memory")
; #define PG8_BAR __builtin_amdgcn_s_barrier()
; #define PG8_SCHED __builtin_amdgcn_sched_barrier(0)
; template <class Epi, class Sched, bool ALIGN_EPI = false, bool SP2 = false>
; __device__ __forceinline__ void gemm_phase(PG8_LAS unsigned char* lds, const Gemm g, const Sched& S, const Epi& E) {
;     ...
;         const bool has_next = S.next(ui + 1, nxt);
;         const char* nA = has_next ? g.a_of(nxt) : cA; const char* nB = has_next ? g.b_of(nxt) : cB;
;         for (int t = 0; t < nt; t += 2) {
;             const bool last = (t == nt - 2);
;             const char* a1 = cA + (size_t)(t + 1) * kstep;
;             const char* a2 = last ? nA : cA + (size_t)(t + 2) * kstep; const char* b2 = last ? nB : cB + (size_t)(t + 2) * kstep;
;             const char* a3 = a2 + kstep; const char* b3 = b2 + kstep;
;             if (last && has_next) S.a_ready(nxt);
;             if constexpr (SP2) {
;             PG8_LDB(B0, 0, 0); PG8_LDB(B1, 0, 1); PG8_SCHED; PG8_LDA(At, 0, 0); PG8_STAGE(PG8_SA(1, 1), a1 + hstepA, voffA);
;             PG8_WAIT_V(8); PG8_WAIT_L(0); PG8_BAR; PG8_MMA(0, 0, At, B0); PG8_MMA(0, 1, At, B1); PG8_BAR; PG8_SCHED;
;             PG8_LDA(At, 0, 1); PG8_STAGE(PG8_SB(0, 0), b2, voffB); PG8_STAGE(PG8_SB(0, 1), b2 + hstepB, voffB); PG8_STAGE(PG8_SA(0, 0), a2, voffA);
.LBB0_1906:
	s_add_u32 s40, s38, 0xfff00080
	s_addc_u32 s41, s39, -1
	s_add_i32 s71, 0, 0x10000
	s_cmp_eq_u32 s70, 60
	s_cselect_b32 s43, s27, s41
	s_cselect_b32 s42, s35, s40
	s_cselect_b32 s41, s25, s68
	s_cselect_b32 s40, s37, s67
	s_add_i32 s74, 0, 0x14000
	v_add_u32_e32 v92, s71, v181
	v_add_u32_e32 v164, s74, v181
	ds_read_b128 v[72:75], v92
	ds_read_b128 v[80:83], v92 offset:1024
	ds_read_b128 v[88:91], v92 offset:2048
	ds_read_b128 v[92:95], v92 offset:3072
	ds_read_b128 v[152:155], v164
	ds_read_b128 v[156:159], v164 offset:1024
	ds_read_b128 v[160:163], v164 offset:2048
	ds_read_b128 v[164:167], v164 offset:3072
	s_add_i32 m0, s51, 0xc000
	ds_read_b128 v[168:171], v186
	ds_read_b128 v[174:177], v186 offset:1024
	ds_read_b128 v[192:195], v186 offset:2048
	ds_read_b128 v[196:199], v186 offset:3072
	ds_read_b128 v[200:203], v186 offset:4096
	ds_read_b128 v[204:207], v186 offset:5120
	ds_read_b128 v[208:211], v186 offset:6144
	ds_read_b128 v[212:215], v186 offset:7168
	global_load_lds_dwordx4 v148, s[38:39]
	s_add_i32 m0, s51, 0xe000
	s_nop 0
	global_load_lds_dwordx4 v150, s[38:39]
	s_waitcnt vmcnt(8)
	s_waitcnt lgkmcnt(0)
	s_barrier
	s_setprio 1
	v_mfma_f32_16x16x32_bf16 v[140:143], v[72:75], v[168:171], v[140:143]
	v_mfma_f32_16x16x32_bf16 v[136:139], v[88:91], v[168:171], v[136:139]
	v_mfma_f32_16x16x32_bf16 v[124:127], v[72:75], v[192:195], v[124:127]
	v_mfma_f32_16x16x32_bf16 v[120:123], v[88:91], v[192:195], v[120:123]
	v_mfma_f32_16x16x32_bf16 v[108:111], v[72:75], v[200:203], v[108:111]
	v_mfma_f32_16x16x32_bf16 v[104:107], v[88:91], v[200:203], v[104:107]
	v_mfma_f32_16x16x32_bf16 v[84:87], v[72:75], v[208:211], v[84:87]
	v_mfma_f32_16x16x32_bf16 v[76:79], v[88:91], v[208:211], v[76:79]
	v_mfma_f32_16x16x32_bf16 v[140:143], v[80:83], v[174:177], v[140:143]
	v_mfma_f32_16x16x32_bf16 v[136:139], v[92:95], v[174:177], v[136:139]
	v_mfma_f32_16x16x32_bf16 v[124:127], v[80:83], v[196:199], v[124:127]
	v_mfma_f32_16x16x32_bf16 v[120:123], v[92:95], v[196:199], v[120:123]
	v_mfma_f32_16x16x32_bf16 v[108:111], v[80:83], v[204:207], v[108:111]
	v_mfma_f32_16x16x32_bf16 v[104:107], v[92:95], v[204:207], v[104:107]
	v_mfma_f32_16x16x32_bf16 v[84:87], v[80:83], v[212:215], v[84:87]
	v_mfma_f32_16x16x32_bf16 v[76:79], v[92:95], v[212:215], v[76:79]
	s_setprio 0
	s_setprio 1
	v_mfma_f32_16x16x32_bf16 v[132:135], v[152:155], v[168:171], v[132:135]
	v_mfma_f32_16x16x32_bf16 v[128:131], v[160:163], v[168:171], v[128:131]
	v_mfma_f32_16x16x32_bf16 v[116:119], v[152:155], v[192:195], v[116:119]
	v_mfma_f32_16x16x32_bf16 v[112:115], v[160:163], v[192:195], v[112:115]
	v_mfma_f32_16x16x32_bf16 v[100:103], v[152:155], v[200:203], v[100:103]
	v_mfma_f32_16x16x32_bf16 v[96:99], v[160:163], v[200:203], v[96:99]
	v_mfma_f32_16x16x32_bf16 v[68:71], v[152:155], v[208:211], v[68:71]
	v_mfma_f32_16x16x32_bf16 v[64:67], v[160:163], v[208:211], v[64:67]
	v_mfma_f32_16x16x32_bf16 v[132:135], v[156:159], v[174:177], v[132:135]
	v_mfma_f32_16x16x32_bf16 v[128:131], v[164:167], v[174:177], v[128:131]
	v_mfma_f32_16x16x32_bf16 v[116:119], v[156:159], v[196:199], v[116:119]
	v_mfma_f32_16x16x32_bf16 v[112:115], v[164:167], v[196:199], v[112:115]
	v_mfma_f32_16x16x32_bf16 v[100:103], v[156:159], v[204:207], v[100:103]
	v_mfma_f32_16x16x32_bf16 v[96:99], v[164:167], v[204:207], v[96:99]
	v_mfma_f32_16x16x32_bf16 v[68:71], v[156:159], v[212:215], v[68:71]
	v_mfma_f32_16x16x32_bf16 v[64:67], v[164:167], v[212:215], v[64:67]
	s_setprio 0
	s_barrier
	s_add_i32 s71, s71, s50
	v_lshl_add_u64 v[178:179], s[40:41], 0, v[172:173]
	s_mov_b32 m0, s71
	ds_read_b128 v[168:171], v186 offset:16384
	ds_read_b128 v[174:177], v186 offset:17408
	ds_read_b128 v[192:195], v186 offset:18432
	ds_read_b128 v[196:199], v186 offset:19456
	ds_read_b128 v[200:203], v186 offset:20480
	ds_read_b128 v[204:207], v186 offset:21504
	ds_read_b128 v[208:211], v186 offset:22528
	ds_read_b128 v[212:215], v186 offset:23552
	global_load_lds_dwordx4 v[178:179], off
	s_add_i32 m0, s71, 0x2000
	s_add_u32 s72, s40, 0x100000
	v_lshl_add_u64 v[216:217], s[40:41], 0, v[144:145]
	s_addc_u32 s73, s41, 0
	s_add_i32 s71, s74, s50
	global_load_lds_dwordx4 v[216:217], off
	s_mov_b32 m0, s71
	v_lshl_add_u64 v[220:221], s[42:43], 0, v[144:145]
	global_load_lds_dwordx4 v172, s[72:73]
	s_add_i32 m0, s71, 0x2000
	s_nop 0
	global_load_lds_dwordx4 v144, s[72:73]
	v_lshl_add_u64 v[218:219], s[42:43], 0, v[172:173]
	s_mov_b32 m0, s51
	s_nop 0
	global_load_lds_dwordx4 v[218:219], off
	s_mov_b32 m0, s52
	s_nop 0
	global_load_lds_dwordx4 v[220:221], off
	s_waitcnt vmcnt(8)
	s_waitcnt lgkmcnt(0)
	s_barrier
; #define PG8_STAGE(bufoff, gbase, voff) do { _Pragma("unroll") for (int _i = 0; _i < 2; ++_i) \
;         __builtin_amdgcn_global_load_lds((const unsigned*)((const char*)(gbase) + (voff)[_i]), (PG8_LAS unsigned*)(lds + (bufoff) + ldsw + _i * 8192), 16, 0, 0); } while (0)
; #define PG8_LDA(dst, b, h) do { _Pragma("unroll") for (int m = 0; m < 4; ++m) _Pragma("unroll") for (int k = 0; k < 2; ++k) dst[m][k] = *(const PG8_LAS bf16x8*)(lds + PG8_SA(b, h) + aoff + m * 2048 + k * 1024); } while (0)
; #define PG8_LDB(dst, b, h) do { _Pragma("unroll") for (int n = 0; n < 2; ++n) _Pragma("unroll") for (int k = 0; k < 2; ++k) dst[n][k] = *(const PG8_LAS bf16x8*)(lds + PG8_SB(b, h) + boff + n * 2048 + k * 1024); } while (0)
; #define PG8_MMA(ai, bj, At, Bt) do { __builtin_amdgcn_s_setprio(1); _Pragma("unroll") for (int m = 0; m < 4; ++m) _Pragma("unroll") for (int n = 0; n < 2; ++n) _Pragma("unroll") for (int k = 0; k < 2; ++k) \
;         acc[ai][bj][m][n] = __builtin_amdgcn_mfma_f32_16x16x32_bf16(Bt[n][k], At[m][k], acc[ai][bj][m][n], 0, 0, 0); __builtin_amdgcn_s_setprio(0); } while (0)
; #define PG8_WAIT_V(n) asm volatile("s_waitcnt vmcnt(" #n ")" ::: "memory")
; #define PG8_WAIT_L(n) asm volatile("s_waitcnt lgkmcnt(" #n ")" ::: "memory")
; #define PG8_BAR __builtin_amdgcn_s_barrier()
; #define PG8_SCHED __builtin_amdgcn_sched_barrier(0)
; template <class Epi, class Sched, bool ALIGN_EPI = false, bool SP2 = false>
; __device__ __forceinline__ void gemm_phase(PG8_LAS unsigned char* lds, const Gemm g, const Sched& S, const Epi& E) {
;     ...
;             PG8_WAIT_V(8); PG8_WAIT_L(0); PG8_BAR; PG8_MMA(1, 0, At, B0); PG8_MMA(1, 1, At, B1); PG8_BAR; PG8_SCHED;
;             PG8_LDB(B0, 1, 0); PG8_LDB(B1, 1, 1); PG8_SCHED; PG8_LDA(At, 1, 0); PG8_STAGE(PG8_SA(0, 1), a2 + hstepA, voffA);
;             PG8_WAIT_V(8); PG8_WAIT_L(0); PG8_BAR; PG8_MMA(0, 0, At, B0); PG8_MMA(0, 1, At, B1); PG8_BAR; PG8_SCHED;
	s_setprio 1
	v_mfma_f32_16x16x32_bf16 v[60:63], v[72:75], v[168:171], v[60:63]
	v_mfma_f32_16x16x32_bf16 v[56:59], v[88:91], v[168:171], v[56:59]
	v_mfma_f32_16x16x32_bf16 v[44:47], v[72:75], v[192:195], v[44:47]
	v_mfma_f32_16x16x32_bf16 v[40:43], v[88:91], v[192:195], v[40:43]
	v_mfma_f32_16x16x32_bf16 v[28:31], v[72:75], v[200:203], v[28:31]
	v_mfma_f32_16x16x32_bf16 v[24:27], v[88:91], v[200:203], v[24:27]
	v_mfma_f32_16x16x32_bf16 v[12:15], v[72:75], v[208:211], v[12:15]
	v_mfma_f32_16x16x32_bf16 v[8:11], v[88:91], v[208:211], v[8:11]
	v_mfma_f32_16x16x32_bf16 v[60:63], v[80:83], v[174:177], v[60:63]
	v_mfma_f32_16x16x32_bf16 v[56:59], v[92:95], v[174:177], v[56:59]
	v_mfma_f32_16x16x32_bf16 v[44:47], v[80:83], v[196:199], v[44:47]
	v_mfma_f32_16x16x32_bf16 v[40:43], v[92:95], v[196:199], v[40:43]
	v_mfma_f32_16x16x32_bf16 v[28:31], v[80:83], v[204:207], v[28:31]
	v_mfma_f32_16x16x32_bf16 v[24:27], v[92:95], v[204:207], v[24:27]
	v_mfma_f32_16x16x32_bf16 v[12:15], v[80:83], v[212:215], v[12:15]
	v_mfma_f32_16x16x32_bf16 v[8:11], v[92:95], v[212:215], v[8:11]
	s_setprio 0
	s_setprio 1
	v_mfma_f32_16x16x32_bf16 v[52:55], v[152:155], v[168:171], v[52:55]
	v_mfma_f32_16x16x32_bf16 v[48:51], v[160:163], v[168:171], v[48:51]
	v_mfma_f32_16x16x32_bf16 v[36:39], v[152:155], v[192:195], v[36:39]
	v_mfma_f32_16x16x32_bf16 v[32:35], v[160:163], v[192:195], v[32:35]
	v_mfma_f32_16x16x32_bf16 v[20:23], v[152:155], v[200:203], v[20:23]
	v_mfma_f32_16x16x32_bf16 v[16:19], v[160:163], v[200:203], v[16:19]
	v_mfma_f32_16x16x32_bf16 v[4:7], v[152:155], v[208:211], v[4:7]
	v_mfma_f32_16x16x32_bf16 v[0:3], v[160:163], v[208:211], v[0:3]
	v_mfma_f32_16x16x32_bf16 v[52:55], v[156:159], v[174:177], v[52:55]
	v_mfma_f32_16x16x32_bf16 v[48:51], v[164:167], v[174:177], v[48:51]
	v_mfma_f32_16x16x32_bf16 v[36:39], v[156:159], v[196:199], v[36:39]
	v_mfma_f32_16x16x32_bf16 v[32:35], v[164:167], v[196:199], v[32:35]
	v_mfma_f32_16x16x32_bf16 v[20:23], v[156:159], v[204:207], v[20:23]
	v_mfma_f32_16x16x32_bf16 v[16:19], v[164:167], v[204:207], v[16:19]
	v_mfma_f32_16x16x32_bf16 v[4:7], v[156:159], v[212:215], v[4:7]
	v_mfma_f32_16x16x32_bf16 v[0:3], v[164:167], v[212:215], v[0:3]
	s_setprio 0
	s_barrier
	s_add_i32 s71, 0, 0x18000
	s_add_i32 s72, 0, 0x1c000
	v_add_u32_e32 v92, s71, v181
	v_add_u32_e32 v164, s72, v181
	ds_read_b128 v[72:75], v92
	ds_read_b128 v[80:83], v92 offset:1024
	ds_read_b128 v[88:91], v92 offset:2048
	ds_read_b128 v[92:95], v92 offset:3072
	ds_read_b128 v[152:155], v164
	ds_read_b128 v[156:159], v164 offset:1024
	ds_read_b128 v[160:163], v164 offset:2048
	ds_read_b128 v[164:167], v164 offset:3072
	s_add_u32 s42, s42, 0x100000
	s_addc_u32 s43, s43, 0
	s_mov_b32 m0, s53
	ds_read_b128 v[168:171], v186 offset:32768
	ds_read_b128 v[174:177], v186 offset:33792
	ds_read_b128 v[192:195], v186 offset:34816
	ds_read_b128 v[196:199], v186 offset:35840
	ds_read_b128 v[200:203], v186 offset:36864
	ds_read_b128 v[204:207], v186 offset:37888
	ds_read_b128 v[208:211], v186 offset:38912
	ds_read_b128 v[212:215], v186 offset:39936
	global_load_lds_dwordx4 v172, s[42:43]
	v_lshl_add_u64 v[222:223], s[42:43], 0, v[144:145]
	s_mov_b32 m0, s57
	s_nop 0
	global_load_lds_dwordx4 v[222:223], off
	s_waitcnt vmcnt(8)
	s_waitcnt lgkmcnt(0)
	s_barrier
	s_setprio 1
	v_mfma_f32_16x16x32_bf16 v[140:143], v[72:75], v[168:171], v[140:143]
	v_mfma_f32_16x16x32_bf16 v[136:139], v[88:91], v[168:171], v[136:139]
	v_mfma_f32_16x16x32_bf16 v[124:127], v[72:75], v[192:195], v[124:127]
	v_mfma_f32_16x16x32_bf16 v[120:123], v[88:91], v[192:195], v[120:123]
	v_mfma_f32_16x16x32_bf16 v[108:111], v[72:75], v[200:203], v[108:111]
	v_mfma_f32_16x16x32_bf16 v[104:107], v[88:91], v[200:203], v[104:107]
	v_mfma_f32_16x16x32_bf16 v[84:87], v[72:75], v[208:211], v[84:87]
	v_mfma_f32_16x16x32_bf16 v[76:79], v[88:91], v[208:211], v[76:79]
	v_mfma_f32_16x16x32_bf16 v[140:143], v[80:83], v[174:177], v[140:143]
	v_mfma_f32_16x16x32_bf16 v[136:139], v[92:95], v[174:177], v[136:139]
	v_mfma_f32_16x16x32_bf16 v[124:127], v[80:83], v[196:199], v[124:127]
	v_mfma_f32_16x16x32_bf16 v[120:123], v[92:95], v[196:199], v[120:123]
	v_mfma_f32_16x16x32_bf16 v[108:111], v[80:83], v[204:207], v[108:111]
	v_mfma_f32_16x16x32_bf16 v[104:107], v[92:95], v[204:207], v[104:107]
	v_mfma_f32_16x16x32_bf16 v[84:87], v[80:83], v[212:215], v[84:87]
	v_mfma_f32_16x16x32_bf16 v[76:79], v[92:95], v[212:215], v[76:79]
	s_setprio 0
	s_setprio 1
	v_mfma_f32_16x16x32_bf16 v[132:135], v[152:155], v[168:171], v[132:135]
	v_mfma_f32_16x16x32_bf16 v[128:131], v[160:163], v[168:171], v[128:131]
	v_mfma_f32_16x16x32_bf16 v[116:119], v[152:155], v[192:195], v[116:119]
	v_mfma_f32_16x16x32_bf16 v[112:115], v[160:163], v[192:195], v[112:115]
	v_mfma_f32_16x16x32_bf16 v[100:103], v[152:155], v[200:203], v[100:103]
	v_mfma_f32_16x16x32_bf16 v[96:99], v[160:163], v[200:203], v[96:99]
	v_mfma_f32_16x16x32_bf16 v[68:71], v[152:155], v[208:211], v[68:71]
	v_mfma_f32_16x16x32_bf16 v[64:67], v[160:163], v[208:211], v[64:67]
	v_mfma_f32_16x16x32_bf16 v[132:135], v[156:159], v[174:177], v[132:135]
	v_mfma_f32_16x16x32_bf16 v[128:131], v[164:167], v[174:177], v[128:131]
	v_mfma_f32_16x16x32_bf16 v[116:119], v[156:159], v[196:199], v[116:119]
	v_mfma_f32_16x16x32_bf16 v[112:115], v[164:167], v[196:199], v[112:115]
	v_mfma_f32_16x16x32_bf16 v[100:103], v[156:159], v[204:207], v[100:103]
	v_mfma_f32_16x16x32_bf16 v[96:99], v[164:167], v[204:207], v[96:99]
	v_mfma_f32_16x16x32_bf16 v[68:71], v[156:159], v[212:215], v[68:71]
	v_mfma_f32_16x16x32_bf16 v[64:67], v[164:167], v[212:215], v[64:67]
	s_setprio 0
	s_barrier
; #define PG8_STAGE(bufoff, gbase, voff) do { _Pragma("unroll") for (int _i = 0; _i < 2; ++_i) \
;         __builtin_amdgcn_global_load_lds((const unsigned*)((const char*)(gbase) + (voff)[_i]), (PG8_LAS unsigned*)(lds + (bufoff) + ldsw + _i * 8192), 16, 0, 0); } while (0)
; #define PG8_LDA(dst, b, h) do { _Pragma("unroll") for (int m = 0; m < 4; ++m) _Pragma("unroll") for (int k = 0; k < 2; ++k) dst[m][k] = *(const PG8_LAS bf16x8*)(lds + PG8_SA(b, h) + aoff + m * 2048 + k * 1024); } while (0)
; #define PG8_MMA(ai, bj, At, Bt) do { __builtin_amdgcn_s_setprio(1); _Pragma("unroll") for (int m = 0; m < 4; ++m) _Pragma("unroll") for (int n = 0; n < 2; ++n) _Pragma("unroll") for (int k = 0; k < 2; ++k) \
;         acc[ai][bj][m][n] = __builtin_amdgcn_mfma_f32_16x16x32_bf16(Bt[n][k], At[m][k], acc[ai][bj][m][n], 0, 0, 0); __builtin_amdgcn_s_setprio(0); } while (0)
; #define PG8_WAIT_V(n) asm volatile("s_waitcnt vmcnt(" #n ")" ::: "memory")
; #define PG8_WAIT_L(n) asm volatile("s_waitcnt lgkmcnt(" #n ")" ::: "memory")
; #define PG8_BAR __builtin_amdgcn_s_barrier()
; #define PG8_SCHED __builtin_amdgcn_sched_barrier(0)
; template <class Epi, class Sched, bool ALIGN_EPI = false, bool SP2 = false>
; __device__ __forceinline__ void gemm_phase(PG8_LAS unsigned char* lds, const Gemm g, const Sched& S, const Epi& E) {
;     ...
;         for (int t = 0; t < nt; t += 2) {
;     ...
;             PG8_LDA(At, 1, 1); PG8_STAGE(PG8_SB(1, 0), b3, voffB); PG8_STAGE(PG8_SB(1, 1), b3 + hstepB, voffB); PG8_STAGE(PG8_SA(1, 0), a3, voffA);
;             PG8_WAIT_V(8); PG8_WAIT_L(0); PG8_BAR; PG8_MMA(1, 0, At, B0); PG8_MMA(1, 1, At, B1); PG8_BAR; PG8_SCHED;
	s_add_i32 s42, s71, s50
	v_lshl_add_u64 v[178:179], v[178:179], 0, s[80:81]
	s_mov_b32 m0, s42
	ds_read_b128 v[168:171], v186 offset:49152
	ds_read_b128 v[174:177], v186 offset:50176
	ds_read_b128 v[192:195], v186 offset:51200
	ds_read_b128 v[196:199], v186 offset:52224
	ds_read_b128 v[200:203], v186 offset:53248
	ds_read_b128 v[204:207], v186 offset:54272
	ds_read_b128 v[208:211], v186 offset:55296
	ds_read_b128 v[212:215], v186 offset:56320
	global_load_lds_dwordx4 v[178:179], off
	s_add_i32 m0, s42, 0x2000
	s_add_u32 s40, s40, 0x100080
	v_lshl_add_u64 v[178:179], v[216:217], 0, s[80:81]
	s_addc_u32 s41, s41, 0
	s_add_i32 s42, s72, s50
	global_load_lds_dwordx4 v[178:179], off
	s_mov_b32 m0, s42
	s_nop 0
	global_load_lds_dwordx4 v172, s[40:41]
	s_add_i32 m0, s42, 0x2000
	s_nop 0
	global_load_lds_dwordx4 v144, s[40:41]
	v_lshl_add_u64 v[178:179], v[218:219], 0, s[80:81]
	s_mov_b32 m0, s62
	s_nop 0
	global_load_lds_dwordx4 v[178:179], off
	v_lshl_add_u64 v[178:179], v[220:221], 0, s[80:81]
	s_mov_b32 m0, s63
	s_nop 0
	global_load_lds_dwordx4 v[178:179], off
	s_waitcnt vmcnt(8)
	s_waitcnt lgkmcnt(0)
	s_barrier
	s_setprio 1
	v_mfma_f32_16x16x32_bf16 v[60:63], v[72:75], v[168:171], v[60:63]
	v_mfma_f32_16x16x32_bf16 v[56:59], v[88:91], v[168:171], v[56:59]
	v_mfma_f32_16x16x32_bf16 v[44:47], v[72:75], v[192:195], v[44:47]
	v_mfma_f32_16x16x32_bf16 v[40:43], v[88:91], v[192:195], v[40:43]
	v_mfma_f32_16x16x32_bf16 v[28:31], v[72:75], v[200:203], v[28:31]
	v_mfma_f32_16x16x32_bf16 v[24:27], v[88:91], v[200:203], v[24:27]
	v_mfma_f32_16x16x32_bf16 v[12:15], v[72:75], v[208:211], v[12:15]
	v_mfma_f32_16x16x32_bf16 v[8:11], v[88:91], v[208:211], v[8:11]
	v_mfma_f32_16x16x32_bf16 v[60:63], v[80:83], v[174:177], v[60:63]
	v_mfma_f32_16x16x32_bf16 v[56:59], v[92:95], v[174:177], v[56:59]
	v_mfma_f32_16x16x32_bf16 v[44:47], v[80:83], v[196:199], v[44:47]
	v_mfma_f32_16x16x32_bf16 v[40:43], v[92:95], v[196:199], v[40:43]
	v_mfma_f32_16x16x32_bf16 v[28:31], v[80:83], v[204:207], v[28:31]
	v_mfma_f32_16x16x32_bf16 v[24:27], v[92:95], v[204:207], v[24:27]
	v_mfma_f32_16x16x32_bf16 v[12:15], v[80:83], v[212:215], v[12:15]
	v_mfma_f32_16x16x32_bf16 v[8:11], v[92:95], v[212:215], v[8:11]
	s_setprio 0
	s_setprio 1
	v_mfma_f32_16x16x32_bf16 v[52:55], v[152:155], v[168:171], v[52:55]
	v_mfma_f32_16x16x32_bf16 v[48:51], v[160:163], v[168:171], v[48:51]
	v_mfma_f32_16x16x32_bf16 v[36:39], v[152:155], v[192:195], v[36:39]
	v_mfma_f32_16x16x32_bf16 v[32:35], v[160:163], v[192:195], v[32:35]
	v_mfma_f32_16x16x32_bf16 v[20:23], v[152:155], v[200:203], v[20:23]
	v_mfma_f32_16x16x32_bf16 v[16:19], v[160:163], v[200:203], v[16:19]
	v_mfma_f32_16x16x32_bf16 v[4:7], v[152:155], v[208:211], v[4:7]
	v_mfma_f32_16x16x32_bf16 v[0:3], v[160:163], v[208:211], v[0:3]
	v_mfma_f32_16x16x32_bf16 v[52:55], v[156:159], v[174:177], v[52:55]
	v_mfma_f32_16x16x32_bf16 v[48:51], v[164:167], v[174:177], v[48:51]
	v_mfma_f32_16x16x32_bf16 v[36:39], v[156:159], v[196:199], v[36:39]
	v_mfma_f32_16x16x32_bf16 v[32:35], v[164:167], v[196:199], v[32:35]
	v_mfma_f32_16x16x32_bf16 v[20:23], v[156:159], v[204:207], v[20:23]
	v_mfma_f32_16x16x32_bf16 v[16:19], v[164:167], v[204:207], v[16:19]
	v_mfma_f32_16x16x32_bf16 v[4:7], v[156:159], v[212:215], v[4:7]
	v_mfma_f32_16x16x32_bf16 v[0:3], v[164:167], v[212:215], v[0:3]
	s_setprio 0
	s_barrier
	s_add_i32 s70, s70, 2
	s_add_u32 s38, s38, 0x100
	s_addc_u32 s39, s39, 0
	s_add_u32 s67, s67, 0x100
	s_addc_u32 s68, s68, 0
	s_cmp_gt_u32 s70, 61
	s_cbranch_scc0 .LBB0_1906
	s_and_b64 vcc, exec, s[22:23]
	s_cbranch_vccz .LBB0_1909
	s_barrier

;     __device__ __forceinline__ bool next(int i, Unit& u) const { const int L = i * G + c; if (L >= nsub) return false; u.pk = L >> 4; u.pm = MLAT / BM + (L & 3); u.pn = (L >> 2) & 3; return true; }
; #define PG8_STAGE(bufoff, gbase, voff) do { _Pragma("unroll") for (int _i = 0; _i < 2; ++_i) \
;         __builtin_amdgcn_global_load_lds((const unsigned*)((const char*)(gbase) + (voff)[_i]), (PG8_LAS unsigned*)(lds + (bufoff) + ldsw + _i * 8192), 16, 0, 0); } while (0)
; #define PG8_LDA(dst, b, h) do { _Pragma("unroll") for (int m = 0; m < 4; ++m) _Pragma("unroll") for (int k = 0; k < 2; ++k) dst[m][k] = *(const PG8_LAS bf16x8*)(lds + PG8_SA(b, h) + aoff + m * 2048 + k * 1024); } while (0)
; #define PG8_LDB(dst, b, h) do { _Pragma("unroll") for (int n = 0; n < 2; ++n) _Pragma("unroll") for (int k = 0; k < 2; ++k) dst[n][k] = *(const PG8_LAS bf16x8*)(lds + PG8_SB(b, h) + boff + n * 2048 + k * 1024); } while (0)
; #define PG8_WAIT_V(n) asm volatile("s_waitcnt vmcnt(" #n ")" ::: "memory")
; #define PG8_WAIT_L(n) asm volatile("s_waitcnt lgkmcnt(" #n ")" ::: "memory")
; #define PG8_BAR __builtin_amdgcn_s_barrier()
; #define PG8_SCHED __builtin_amdgcn_sched_barrier(0)
; template <class Epi, class Sched, bool ALIGN_EPI = false, bool SP2 = false>
; __device__ __forceinline__ void gemm_phase(PG8_LAS unsigned char* lds, const Gemm g, const Sched& S, const Epi& E) {
;     ...
;         const bool has_next = S.next(ui + 1, nxt);
;         const char* nA = has_next ? g.a_of(nxt) : cA; const char* nB = has_next ? g.b_of(nxt) : cB;
;         for (int t = 0; t < nt; t += 2) {
;             const bool last = (t == nt - 2);
;             const char* a1 = cA + (size_t)(t + 1) * kstep;
;             const char* a2 = last ? nA : cA + (size_t)(t + 2) * kstep; const char* b2 = last ? nB : cB + (size_t)(t + 2) * kstep;
;             const char* a3 = a2 + kstep; const char* b3 = b2 + kstep;
;             if (last && has_next) S.a_ready(nxt);
;             if constexpr (SP2) {
;             PG8_LDB(B0, 0, 0); PG8_LDB(B1, 0, 1); PG8_SCHED; PG8_LDA(At, 0, 0); PG8_STAGE(PG8_SA(1, 1), a1 + hstepA, voffA);
;             PG8_WAIT_V(8); PG8_WAIT_L(0); PG8_BAR; PG8_MMA(0, 0, At, B0); PG8_MMA(0, 1, At, B1); PG8_BAR; PG8_SCHED;
;             PG8_LDA(At, 0, 1); PG8_STAGE(PG8_SB(0, 0), b2, voffB); PG8_STAGE(PG8_SB(0, 1), b2 + hstepB, voffB); PG8_STAGE(PG8_SA(0, 0), a2, voffA);
.LBB0_1950:
	s_add_u32 s30, s28, 0xfff00080
	s_addc_u32 s31, s29, -1
	s_add_i32 s62, 0, 0x10000
	s_cmp_eq_u32 s61, 60
	s_cselect_b32 s35, s21, s31
	s_cselect_b32 s34, s27, s30
	s_cselect_b32 s31, s15, s60
	s_cselect_b32 s30, s58, s59
	s_add_i32 s64, 0, 0x14000
	v_add_u32_e32 v108, s62, v153
	v_add_u32_e32 v150, s64, v153
	ds_read_b128 v[52:55], v108
	ds_read_b128 v[92:95], v108 offset:1024
	ds_read_b128 v[100:103], v108 offset:2048
	ds_read_b128 v[108:111], v108 offset:3072
	ds_read_b128 v[156:159], v150
	ds_read_b128 v[160:163], v150 offset:1024
	ds_read_b128 v[164:167], v150 offset:2048
	ds_read_b128 v[168:171], v150 offset:3072
	s_add_i32 m0, s38, 0xc000
	ds_read_b128 v[174:177], v155
	ds_read_b128 v[178:181], v155 offset:1024
	ds_read_b128 v[182:185], v155 offset:2048
	ds_read_b128 v[192:195], v155 offset:3072
	ds_read_b128 v[196:199], v155 offset:4096
	ds_read_b128 v[200:203], v155 offset:5120
	ds_read_b128 v[204:207], v155 offset:6144
	ds_read_b128 v[208:211], v155 offset:7168
	global_load_lds_dwordx4 v146, s[28:29]
	s_add_i32 m0, s38, 0xe000
	s_nop 0
	global_load_lds_dwordx4 v148, s[28:29]
	s_waitcnt vmcnt(8)
	s_waitcnt lgkmcnt(0)
	s_barrier
	s_setprio 1
	v_mfma_f32_16x16x32_bf16 v[140:143], v[52:55], v[174:177], v[140:143]
	v_mfma_f32_16x16x32_bf16 v[136:139], v[100:103], v[174:177], v[136:139]
	v_mfma_f32_16x16x32_bf16 v[124:127], v[52:55], v[182:185], v[124:127]
	v_mfma_f32_16x16x32_bf16 v[120:123], v[100:103], v[182:185], v[120:123]
	v_mfma_f32_16x16x32_bf16 v[104:107], v[52:55], v[196:199], v[104:107]
	v_mfma_f32_16x16x32_bf16 v[96:99], v[100:103], v[196:199], v[96:99]
	v_mfma_f32_16x16x32_bf16 v[80:83], v[52:55], v[204:207], v[80:83]
	v_mfma_f32_16x16x32_bf16 v[76:79], v[100:103], v[204:207], v[76:79]
	v_mfma_f32_16x16x32_bf16 v[140:143], v[92:95], v[178:181], v[140:143]
	v_mfma_f32_16x16x32_bf16 v[136:139], v[108:111], v[178:181], v[136:139]
	v_mfma_f32_16x16x32_bf16 v[124:127], v[92:95], v[192:195], v[124:127]
	v_mfma_f32_16x16x32_bf16 v[120:123], v[108:111], v[192:195], v[120:123]
	v_mfma_f32_16x16x32_bf16 v[104:107], v[92:95], v[200:203], v[104:107]
	v_mfma_f32_16x16x32_bf16 v[96:99], v[108:111], v[200:203], v[96:99]
	v_mfma_f32_16x16x32_bf16 v[80:83], v[92:95], v[208:211], v[80:83]
	v_mfma_f32_16x16x32_bf16 v[76:79], v[108:111], v[208:211], v[76:79]
	s_setprio 0
	s_setprio 1
	v_mfma_f32_16x16x32_bf16 v[132:135], v[156:159], v[174:177], v[132:135]
	v_mfma_f32_16x16x32_bf16 v[128:131], v[164:167], v[174:177], v[128:131]
	v_mfma_f32_16x16x32_bf16 v[116:119], v[156:159], v[182:185], v[116:119]
	v_mfma_f32_16x16x32_bf16 v[112:115], v[164:167], v[182:185], v[112:115]
	v_mfma_f32_16x16x32_bf16 v[88:91], v[156:159], v[196:199], v[88:91]
	v_mfma_f32_16x16x32_bf16 v[84:87], v[164:167], v[196:199], v[84:87]
	v_mfma_f32_16x16x32_bf16 v[72:75], v[156:159], v[204:207], v[72:75]
	v_mfma_f32_16x16x32_bf16 v[68:71], v[164:167], v[204:207], v[68:71]
	v_mfma_f32_16x16x32_bf16 v[132:135], v[160:163], v[178:181], v[132:135]
	v_mfma_f32_16x16x32_bf16 v[128:131], v[168:171], v[178:181], v[128:131]
	v_mfma_f32_16x16x32_bf16 v[116:119], v[160:163], v[192:195], v[116:119]
	v_mfma_f32_16x16x32_bf16 v[112:115], v[168:171], v[192:195], v[112:115]
	v_mfma_f32_16x16x32_bf16 v[88:91], v[160:163], v[200:203], v[88:91]
	v_mfma_f32_16x16x32_bf16 v[84:87], v[168:171], v[200:203], v[84:87]
	v_mfma_f32_16x16x32_bf16 v[72:75], v[160:163], v[208:211], v[72:75]
	v_mfma_f32_16x16x32_bf16 v[68:71], v[168:171], v[208:211], v[68:71]
	s_setprio 0
	s_barrier
	s_add_i32 s62, s62, s37
	v_lshl_add_u64 v[150:151], s[30:31], 0, v[172:173]
	s_mov_b32 m0, s62
	ds_read_b128 v[174:177], v155 offset:16384
	ds_read_b128 v[178:181], v155 offset:17408
	ds_read_b128 v[182:185], v155 offset:18432
	ds_read_b128 v[192:195], v155 offset:19456
	ds_read_b128 v[196:199], v155 offset:20480
	ds_read_b128 v[200:203], v155 offset:21504
	ds_read_b128 v[204:207], v155 offset:22528
	ds_read_b128 v[208:211], v155 offset:23552
	global_load_lds_dwordx4 v[150:151], off
	s_add_i32 m0, s62, 0x2000
	s_add_u32 s62, s30, 0x100000
	v_lshl_add_u64 v[186:187], s[30:31], 0, v[144:145]
	s_addc_u32 s63, s31, 0
	s_add_i32 s64, s64, s37
	global_load_lds_dwordx4 v[186:187], off
	s_mov_b32 m0, s64
	v_lshl_add_u64 v[214:215], s[34:35], 0, v[144:145]
	global_load_lds_dwordx4 v172, s[62:63]
	s_add_i32 m0, s64, 0x2000
	s_nop 0
	global_load_lds_dwordx4 v144, s[62:63]
	v_lshl_add_u64 v[212:213], s[34:35], 0, v[172:173]
	s_mov_b32 m0, s38
	s_nop 0
	global_load_lds_dwordx4 v[212:213], off
	s_mov_b32 m0, s39
	s_nop 0
	global_load_lds_dwordx4 v[214:215], off
	s_waitcnt vmcnt(8)
	s_waitcnt lgkmcnt(0)
	s_barrier
; #define PG8_STAGE(bufoff, gbase, voff) do { _Pragma("unroll") for (int _i = 0; _i < 2; ++_i) \
;         __builtin_amdgcn_global_load_lds((const unsigned*)((const char*)(gbase) + (voff)[_i]), (PG8_LAS unsigned*)(lds + (bufoff) + ldsw + _i * 8192), 16, 0, 0); } while (0)
; #define PG8_LDA(dst, b, h) do { _Pragma("unroll") for (int m = 0; m < 4; ++m) _Pragma("unroll") for (int k = 0; k < 2; ++k) dst[m][k] = *(const PG8_LAS bf16x8*)(lds + PG8_SA(b, h) + aoff + m * 2048 + k * 1024); } while (0)
; #define PG8_LDB(dst, b, h) do { _Pragma("unroll") for (int n = 0; n < 2; ++n) _Pragma("unroll") for (int k = 0; k < 2; ++k) dst[n][k] = *(const PG8_LAS bf16x8*)(lds + PG8_SB(b, h) + boff + n * 2048 + k * 1024); } while (0)
; #define PG8_MMA(ai, bj, At, Bt) do { __builtin_amdgcn_s_setprio(1); _Pragma("unroll") for (int m = 0; m < 4; ++m) _Pragma("unroll") for (int n = 0; n < 2; ++n) _Pragma("unroll") for (int k = 0; k < 2; ++k) \
;         acc[ai][bj][m][n] = __builtin_amdgcn_mfma_f32_16x16x32_bf16(Bt[n][k], At[m][k], acc[ai][bj][m][n], 0, 0, 0); __builtin_amdgcn_s_setprio(0); } while (0)
; #define PG8_WAIT_V(n) asm volatile("s_waitcnt vmcnt(" #n ")" ::: "memory")
; #define PG8_WAIT_L(n) asm volatile("s_waitcnt lgkmcnt(" #n ")" ::: "memory")
; #define PG8_BAR __builtin_amdgcn_s_barrier()
; #define PG8_SCHED __builtin_amdgcn_sched_barrier(0)
; template <class Epi, class Sched, bool ALIGN_EPI = false, bool SP2 = false>
; __device__ __forceinline__ void gemm_phase(PG8_LAS unsigned char* lds, const Gemm g, const Sched& S, const Epi& E) {
;     ...
;             PG8_WAIT_V(8); PG8_WAIT_L(0); PG8_BAR; PG8_MMA(1, 0, At, B0); PG8_MMA(1, 1, At, B1); PG8_BAR; PG8_SCHED;
;             PG8_LDB(B0, 1, 0); PG8_LDB(B1, 1, 1); PG8_SCHED; PG8_LDA(At, 1, 0); PG8_STAGE(PG8_SA(0, 1), a2 + hstepA, voffA);
;             PG8_WAIT_V(8); PG8_WAIT_L(0); PG8_BAR; PG8_MMA(0, 0, At, B0); PG8_MMA(0, 1, At, B1); PG8_BAR; PG8_SCHED;
	s_setprio 1
	v_mfma_f32_16x16x32_bf16 v[64:67], v[52:55], v[174:177], v[64:67]
	v_mfma_f32_16x16x32_bf16 v[60:63], v[100:103], v[174:177], v[60:63]
	v_mfma_f32_16x16x32_bf16 v[44:47], v[52:55], v[182:185], v[44:47]
	v_mfma_f32_16x16x32_bf16 v[40:43], v[100:103], v[182:185], v[40:43]
	v_mfma_f32_16x16x32_bf16 v[28:31], v[52:55], v[196:199], v[28:31]
	v_mfma_f32_16x16x32_bf16 v[24:27], v[100:103], v[196:199], v[24:27]
	v_mfma_f32_16x16x32_bf16 v[12:15], v[52:55], v[204:207], v[12:15]
	v_mfma_f32_16x16x32_bf16 v[8:11], v[100:103], v[204:207], v[8:11]
	v_mfma_f32_16x16x32_bf16 v[64:67], v[92:95], v[178:181], v[64:67]
	v_mfma_f32_16x16x32_bf16 v[60:63], v[108:111], v[178:181], v[60:63]
	v_mfma_f32_16x16x32_bf16 v[44:47], v[92:95], v[192:195], v[44:47]
	v_mfma_f32_16x16x32_bf16 v[40:43], v[108:111], v[192:195], v[40:43]
	v_mfma_f32_16x16x32_bf16 v[28:31], v[92:95], v[200:203], v[28:31]
	v_mfma_f32_16x16x32_bf16 v[24:27], v[108:111], v[200:203], v[24:27]
	v_mfma_f32_16x16x32_bf16 v[12:15], v[92:95], v[208:211], v[12:15]
	v_mfma_f32_16x16x32_bf16 v[8:11], v[108:111], v[208:211], v[8:11]
	s_setprio 0
	s_setprio 1
	v_mfma_f32_16x16x32_bf16 v[48:51], v[164:167], v[174:177], v[48:51]
	v_mfma_f32_16x16x32_bf16 v[36:39], v[156:159], v[182:185], v[36:39]
	v_mfma_f32_16x16x32_bf16 v[32:35], v[164:167], v[182:185], v[32:35]
	v_mfma_f32_16x16x32_bf16 v[20:23], v[156:159], v[196:199], v[20:23]
	v_mfma_f32_16x16x32_bf16 v[16:19], v[164:167], v[196:199], v[16:19]
	v_mfma_f32_16x16x32_bf16 v[4:7], v[156:159], v[204:207], v[4:7]
	v_mfma_f32_16x16x32_bf16 v[0:3], v[164:167], v[204:207], v[0:3]
	v_mfma_f32_16x16x32_bf16 v[52:55], v[156:159], v[174:177], v[56:59]
	v_mfma_f32_16x16x32_bf16 v[48:51], v[168:171], v[178:181], v[48:51]
	v_mfma_f32_16x16x32_bf16 v[36:39], v[160:163], v[192:195], v[36:39]
	v_mfma_f32_16x16x32_bf16 v[32:35], v[168:171], v[192:195], v[32:35]
	v_mfma_f32_16x16x32_bf16 v[20:23], v[160:163], v[200:203], v[20:23]
	v_mfma_f32_16x16x32_bf16 v[16:19], v[168:171], v[200:203], v[16:19]
	v_mfma_f32_16x16x32_bf16 v[4:7], v[160:163], v[208:211], v[4:7]
	v_mfma_f32_16x16x32_bf16 v[0:3], v[168:171], v[208:211], v[0:3]
	v_mfma_f32_16x16x32_bf16 v[52:55], v[160:163], v[178:181], v[52:55]
	s_setprio 0
	s_barrier
	s_add_i32 s62, 0, 0x18000
	s_add_i32 s63, 0, 0x1c000
	v_add_u32_e32 v108, s62, v153
	v_add_u32_e32 v168, s63, v153
	ds_read_b128 v[56:59], v108
	ds_read_b128 v[92:95], v108 offset:1024
	ds_read_b128 v[100:103], v108 offset:2048
	ds_read_b128 v[108:111], v108 offset:3072
	ds_read_b128 v[156:159], v168
	ds_read_b128 v[160:163], v168 offset:1024
	ds_read_b128 v[164:167], v168 offset:2048
	ds_read_b128 v[168:171], v168 offset:3072
	s_add_u32 s34, s34, 0x100000
	s_addc_u32 s35, s35, 0
	s_mov_b32 m0, s40
	ds_read_b128 v[174:177], v155 offset:32768
	ds_read_b128 v[178:181], v155 offset:33792
	ds_read_b128 v[182:185], v155 offset:34816
	ds_read_b128 v[192:195], v155 offset:35840
	ds_read_b128 v[196:199], v155 offset:36864
	ds_read_b128 v[200:203], v155 offset:37888
	ds_read_b128 v[204:207], v155 offset:38912
	ds_read_b128 v[208:211], v155 offset:39936
	global_load_lds_dwordx4 v172, s[34:35]
	v_lshl_add_u64 v[216:217], s[34:35], 0, v[144:145]
	s_mov_b32 m0, s41
	s_nop 0
	global_load_lds_dwordx4 v[216:217], off
	s_waitcnt vmcnt(8)
	s_waitcnt lgkmcnt(0)
	s_barrier
	s_setprio 1
	v_mfma_f32_16x16x32_bf16 v[140:143], v[56:59], v[174:177], v[140:143]
	v_mfma_f32_16x16x32_bf16 v[136:139], v[100:103], v[174:177], v[136:139]
	v_mfma_f32_16x16x32_bf16 v[124:127], v[56:59], v[182:185], v[124:127]
	v_mfma_f32_16x16x32_bf16 v[120:123], v[100:103], v[182:185], v[120:123]
	v_mfma_f32_16x16x32_bf16 v[104:107], v[56:59], v[196:199], v[104:107]
	v_mfma_f32_16x16x32_bf16 v[96:99], v[100:103], v[196:199], v[96:99]
	v_mfma_f32_16x16x32_bf16 v[80:83], v[56:59], v[204:207], v[80:83]
	v_mfma_f32_16x16x32_bf16 v[76:79], v[100:103], v[204:207], v[76:79]
	v_mfma_f32_16x16x32_bf16 v[140:143], v[92:95], v[178:181], v[140:143]
	v_mfma_f32_16x16x32_bf16 v[136:139], v[108:111], v[178:181], v[136:139]
	v_mfma_f32_16x16x32_bf16 v[124:127], v[92:95], v[192:195], v[124:127]
	v_mfma_f32_16x16x32_bf16 v[120:123], v[108:111], v[192:195], v[120:123]
	v_mfma_f32_16x16x32_bf16 v[104:107], v[92:95], v[200:203], v[104:107]
	v_mfma_f32_16x16x32_bf16 v[96:99], v[108:111], v[200:203], v[96:99]
	v_mfma_f32_16x16x32_bf16 v[80:83], v[92:95], v[208:211], v[80:83]
	v_mfma_f32_16x16x32_bf16 v[76:79], v[108:111], v[208:211], v[76:79]
	s_setprio 0
	s_setprio 1
	v_mfma_f32_16x16x32_bf16 v[132:135], v[156:159], v[174:177], v[132:135]
	v_mfma_f32_16x16x32_bf16 v[128:131], v[164:167], v[174:177], v[128:131]
	v_mfma_f32_16x16x32_bf16 v[116:119], v[156:159], v[182:185], v[116:119]
	v_mfma_f32_16x16x32_bf16 v[112:115], v[164:167], v[182:185], v[112:115]
	v_mfma_f32_16x16x32_bf16 v[88:91], v[156:159], v[196:199], v[88:91]
	v_mfma_f32_16x16x32_bf16 v[84:87], v[164:167], v[196:199], v[84:87]
	v_mfma_f32_16x16x32_bf16 v[72:75], v[156:159], v[204:207], v[72:75]
	v_mfma_f32_16x16x32_bf16 v[68:71], v[164:167], v[204:207], v[68:71]
	v_mfma_f32_16x16x32_bf16 v[132:135], v[160:163], v[178:181], v[132:135]
	v_mfma_f32_16x16x32_bf16 v[128:131], v[168:171], v[178:181], v[128:131]
	v_mfma_f32_16x16x32_bf16 v[116:119], v[160:163], v[192:195], v[116:119]
	v_mfma_f32_16x16x32_bf16 v[112:115], v[168:171], v[192:195], v[112:115]
	v_mfma_f32_16x16x32_bf16 v[88:91], v[160:163], v[200:203], v[88:91]
	v_mfma_f32_16x16x32_bf16 v[84:87], v[168:171], v[200:203], v[84:87]
	v_mfma_f32_16x16x32_bf16 v[72:75], v[160:163], v[208:211], v[72:75]
	v_mfma_f32_16x16x32_bf16 v[68:71], v[168:171], v[208:211], v[68:71]
	s_setprio 0
	s_barrier
; #define PG8_STAGE(bufoff, gbase, voff) do { _Pragma("unroll") for (int _i = 0; _i < 2; ++_i) \
;         __builtin_amdgcn_global_load_lds((const unsigned*)((const char*)(gbase) + (voff)[_i]), (PG8_LAS unsigned*)(lds + (bufoff) + ldsw + _i * 8192), 16, 0, 0); } while (0)
; #define PG8_LDA(dst, b, h) do { _Pragma("unroll") for (int m = 0; m < 4; ++m) _Pragma("unroll") for (int k = 0; k < 2; ++k) dst[m][k] = *(const PG8_LAS bf16x8*)(lds + PG8_SA(b, h) + aoff + m * 2048 + k * 1024); } while (0)
; #define PG8_MMA(ai, bj, At, Bt) do { __builtin_amdgcn_s_setprio(1); _Pragma("unroll") for (int m = 0; m < 4; ++m) _Pragma("unroll") for (int n = 0; n < 2; ++n) _Pragma("unroll") for (int k = 0; k < 2; ++k) \
;         acc[ai][bj][m][n] = __builtin_amdgcn_mfma_f32_16x16x32_bf16(Bt[n][k], At[m][k], acc[ai][bj][m][n], 0, 0, 0); __builtin_amdgcn_s_setprio(0); } while (0)
; #define PG8_WAIT_V(n) asm volatile("s_waitcnt vmcnt(" #n ")" ::: "memory")
; #define PG8_WAIT_L(n) asm volatile("s_waitcnt lgkmcnt(" #n ")" ::: "memory")
; #define PG8_BAR __builtin_amdgcn_s_barrier()
; #define PG8_SCHED __builtin_amdgcn_sched_barrier(0)
; template <class Epi, class Sched, bool ALIGN_EPI = false, bool SP2 = false>
; __device__ __forceinline__ void gemm_phase(PG8_LAS unsigned char* lds, const Gemm g, const Sched& S, const Epi& E) {
;     ...
;         for (int t = 0; t < nt; t += 2) {
;     ...
;             PG8_LDA(At, 1, 1); PG8_STAGE(PG8_SB(1, 0), b3, voffB); PG8_STAGE(PG8_SB(1, 1), b3 + hstepB, voffB); PG8_STAGE(PG8_SA(1, 0), a3, voffA);
;             PG8_WAIT_V(8); PG8_WAIT_L(0); PG8_BAR; PG8_MMA(1, 0, At, B0); PG8_MMA(1, 1, At, B1); PG8_BAR; PG8_SCHED;
	s_add_i32 s34, s62, s37
	v_lshl_add_u64 v[150:151], v[150:151], 0, s[80:81]
	s_mov_b32 m0, s34
	ds_read_b128 v[174:177], v155 offset:49152
	ds_read_b128 v[178:181], v155 offset:50176
	ds_read_b128 v[182:185], v155 offset:51200
	ds_read_b128 v[192:195], v155 offset:52224
	ds_read_b128 v[196:199], v155 offset:53248
	ds_read_b128 v[200:203], v155 offset:54272
	ds_read_b128 v[204:207], v155 offset:55296
	ds_read_b128 v[208:211], v155 offset:56320
	global_load_lds_dwordx4 v[150:151], off
	s_add_i32 m0, s34, 0x2000
	s_add_u32 s30, s30, 0x100080
	v_lshl_add_u64 v[150:151], v[186:187], 0, s[80:81]
	s_addc_u32 s31, s31, 0
	s_add_i32 s34, s63, s37
	global_load_lds_dwordx4 v[150:151], off
	s_mov_b32 m0, s34
	s_nop 0
	global_load_lds_dwordx4 v172, s[30:31]
	s_add_i32 m0, s34, 0x2000
	s_nop 0
	global_load_lds_dwordx4 v144, s[30:31]
	v_lshl_add_u64 v[150:151], v[212:213], 0, s[80:81]
	s_mov_b32 m0, s50
	s_nop 0
	global_load_lds_dwordx4 v[150:151], off
	v_lshl_add_u64 v[150:151], v[214:215], 0, s[80:81]
	s_mov_b32 m0, s51
	s_nop 0
	global_load_lds_dwordx4 v[150:151], off
	s_waitcnt vmcnt(8)
	s_waitcnt lgkmcnt(0)
	s_barrier
	s_setprio 1
	v_mfma_f32_16x16x32_bf16 v[64:67], v[56:59], v[174:177], v[64:67]
	v_mfma_f32_16x16x32_bf16 v[60:63], v[100:103], v[174:177], v[60:63]
	v_mfma_f32_16x16x32_bf16 v[44:47], v[56:59], v[182:185], v[44:47]
	v_mfma_f32_16x16x32_bf16 v[40:43], v[100:103], v[182:185], v[40:43]
	v_mfma_f32_16x16x32_bf16 v[28:31], v[56:59], v[196:199], v[28:31]
	v_mfma_f32_16x16x32_bf16 v[24:27], v[100:103], v[196:199], v[24:27]
	v_mfma_f32_16x16x32_bf16 v[12:15], v[56:59], v[204:207], v[12:15]
	v_mfma_f32_16x16x32_bf16 v[8:11], v[100:103], v[204:207], v[8:11]
	v_mfma_f32_16x16x32_bf16 v[64:67], v[92:95], v[178:181], v[64:67]
	v_mfma_f32_16x16x32_bf16 v[60:63], v[108:111], v[178:181], v[60:63]
	v_mfma_f32_16x16x32_bf16 v[44:47], v[92:95], v[192:195], v[44:47]
	v_mfma_f32_16x16x32_bf16 v[40:43], v[108:111], v[192:195], v[40:43]
	v_mfma_f32_16x16x32_bf16 v[28:31], v[92:95], v[200:203], v[28:31]
	v_mfma_f32_16x16x32_bf16 v[24:27], v[108:111], v[200:203], v[24:27]
	v_mfma_f32_16x16x32_bf16 v[12:15], v[92:95], v[208:211], v[12:15]
	v_mfma_f32_16x16x32_bf16 v[8:11], v[108:111], v[208:211], v[8:11]
	s_setprio 0
	s_setprio 1
	v_mfma_f32_16x16x32_bf16 v[52:55], v[156:159], v[174:177], v[52:55]
	v_mfma_f32_16x16x32_bf16 v[48:51], v[164:167], v[174:177], v[48:51]
	v_mfma_f32_16x16x32_bf16 v[36:39], v[156:159], v[182:185], v[36:39]
	v_mfma_f32_16x16x32_bf16 v[32:35], v[164:167], v[182:185], v[32:35]
	v_mfma_f32_16x16x32_bf16 v[20:23], v[156:159], v[196:199], v[20:23]
	v_mfma_f32_16x16x32_bf16 v[16:19], v[164:167], v[196:199], v[16:19]
	v_mfma_f32_16x16x32_bf16 v[4:7], v[156:159], v[204:207], v[4:7]
	v_mfma_f32_16x16x32_bf16 v[0:3], v[164:167], v[204:207], v[0:3]
	v_mfma_f32_16x16x32_bf16 v[56:59], v[160:163], v[178:181], v[52:55]
	v_mfma_f32_16x16x32_bf16 v[48:51], v[168:171], v[178:181], v[48:51]
	v_mfma_f32_16x16x32_bf16 v[36:39], v[160:163], v[192:195], v[36:39]
	v_mfma_f32_16x16x32_bf16 v[32:35], v[168:171], v[192:195], v[32:35]
	v_mfma_f32_16x16x32_bf16 v[20:23], v[160:163], v[200:203], v[20:23]
	v_mfma_f32_16x16x32_bf16 v[16:19], v[168:171], v[200:203], v[16:19]
	v_mfma_f32_16x16x32_bf16 v[4:7], v[160:163], v[208:211], v[4:7]
	v_mfma_f32_16x16x32_bf16 v[0:3], v[168:171], v[208:211], v[0:3]
	s_setprio 0
	s_barrier
	s_add_i32 s61, s61, 2
	s_add_u32 s28, s28, 0x100
	s_addc_u32 s29, s29, 0
	s_add_u32 s59, s59, 0x100
	s_addc_u32 s60, s60, 0
	s_cmp_gt_u32 s61, 61
	s_cbranch_scc0 .LBB0_1950
	s_and_b64 vcc, exec, s[12:13]
	s_cbranch_vccz .LBB0_1953
	s_barrier

;     __device__ __forceinline__ bool next(int i, Unit& u) const { const int L = i * G + c; if (L >= nsub) return false; u.pk = L >> 4; u.pm = MLAT / BM + (L & 3); u.pn = (L >> 2) & 3; return true; }
; #define PG8_STAGE(bufoff, gbase, voff) do { _Pragma("unroll") for (int _i = 0; _i < 2; ++_i) \
;         __builtin_amdgcn_global_load_lds((const unsigned*)((const char*)(gbase) + (voff)[_i]), (PG8_LAS unsigned*)(lds + (bufoff) + ldsw + _i * 8192), 16, 0, 0); } while (0)
; #define PG8_LDA(dst, b, h) do { _Pragma("unroll") for (int m = 0; m < 4; ++m) _Pragma("unroll") for (int k = 0; k < 2; ++k) dst[m][k] = *(const PG8_LAS bf16x8*)(lds + PG8_SA(b, h) + aoff + m * 2048 + k * 1024); } while (0)
; #define PG8_LDB(dst, b, h) do { _Pragma("unroll") for (int n = 0; n < 2; ++n) _Pragma("unroll") for (int k = 0; k < 2; ++k) dst[n][k] = *(const PG8_LAS bf16x8*)(lds + PG8_SB(b, h) + boff + n * 2048 + k * 1024); } while (0)
; #define PG8_WAIT_V(n) asm volatile("s_waitcnt vmcnt(" #n ")" ::: "memory")
; #define PG8_WAIT_L(n) asm volatile("s_waitcnt lgkmcnt(" #n ")" ::: "memory")
; #define PG8_BAR __builtin_amdgcn_s_barrier()
; #define PG8_SCHED __builtin_amdgcn_sched_barrier(0)
; template <class Epi, class Sched, bool ALIGN_EPI = false, bool SP2 = false>
; __device__ __forceinline__ void gemm_phase(PG8_LAS unsigned char* lds, const Gemm g, const Sched& S, const Epi& E) {
;     ...
;         const bool has_next = S.next(ui + 1, nxt);
;         const char* nA = has_next ? g.a_of(nxt) : cA; const char* nB = has_next ? g.b_of(nxt) : cB;
;         for (int t = 0; t < nt; t += 2) {
;             const bool last = (t == nt - 2);
;             const char* a1 = cA + (size_t)(t + 1) * kstep;
;             const char* a2 = last ? nA : cA + (size_t)(t + 2) * kstep; const char* b2 = last ? nB : cB + (size_t)(t + 2) * kstep;
;             const char* a3 = a2 + kstep; const char* b3 = b2 + kstep;
;             if (last && has_next) S.a_ready(nxt);
;             if constexpr (SP2) {
;             PG8_LDB(B0, 0, 0); PG8_LDB(B1, 0, 1); PG8_SCHED; PG8_LDA(At, 0, 0); PG8_STAGE(PG8_SA(1, 1), a1 + hstepA, voffA);
;             PG8_WAIT_V(8); PG8_WAIT_L(0); PG8_BAR; PG8_MMA(0, 0, At, B0); PG8_MMA(0, 1, At, B1); PG8_BAR; PG8_SCHED;
;             PG8_LDA(At, 0, 1); PG8_STAGE(PG8_SB(0, 0), b2, voffB); PG8_STAGE(PG8_SB(0, 1), b2 + hstepB, voffB); PG8_STAGE(PG8_SA(0, 0), a2, voffA);
.LBB0_1972:
	s_add_u32 s26, s24, 0xfff00080
	s_addc_u32 s27, s25, -1
	s_add_i32 s49, 0, 0x10000
	s_cmp_eq_u32 s47, 4
	s_cselect_b32 s29, s15, s27
	s_cselect_b32 s28, s14, s26
	s_cselect_b32 s27, s21, s23
	s_cselect_b32 s26, s20, s17
	s_add_i32 s52, 0, 0x14000
	v_add_u32_e32 v124, s49, v158
	v_add_u32_e32 v156, s52, v158
	ds_read_b128 v[108:111], v124
	ds_read_b128 v[116:119], v124 offset:1024
	ds_read_b128 v[120:123], v124 offset:2048
	ds_read_b128 v[124:127], v124 offset:3072
	ds_read_b128 v[152:155], v156
	ds_read_b128 v[162:165], v156 offset:1024
	ds_read_b128 v[166:169], v156 offset:2048
	ds_read_b128 v[174:177], v156 offset:3072
	s_add_i32 m0, s34, 0xc000
	ds_read_b128 v[178:181], v161
	ds_read_b128 v[182:185], v161 offset:1024
	ds_read_b128 v[192:195], v161 offset:2048
	ds_read_b128 v[196:199], v161 offset:3072
	ds_read_b128 v[200:203], v161 offset:4096
	ds_read_b128 v[204:207], v161 offset:5120
	ds_read_b128 v[208:211], v161 offset:6144
	ds_read_b128 v[212:215], v161 offset:7168
	global_load_lds_dwordx4 v148, s[24:25]
	v_lshl_add_u64 v[156:157], s[24:25], 0, v[150:151]
	s_add_i32 m0, s34, 0xe000
	s_nop 0
	global_load_lds_dwordx4 v[156:157], off
	s_waitcnt vmcnt(8)
	s_waitcnt lgkmcnt(0)
	s_barrier
	s_setprio 1
	v_mfma_f32_16x16x32_bf16 v[140:143], v[108:111], v[178:181], v[140:143]
	v_mfma_f32_16x16x32_bf16 v[136:139], v[120:123], v[178:181], v[136:139]
	v_mfma_f32_16x16x32_bf16 v[112:115], v[108:111], v[192:195], v[112:115]
	v_mfma_f32_16x16x32_bf16 v[104:107], v[120:123], v[192:195], v[104:107]
	v_mfma_f32_16x16x32_bf16 v[92:95], v[108:111], v[200:203], v[92:95]
	v_mfma_f32_16x16x32_bf16 v[88:91], v[120:123], v[200:203], v[88:91]
	v_mfma_f32_16x16x32_bf16 v[76:79], v[108:111], v[208:211], v[76:79]
	v_mfma_f32_16x16x32_bf16 v[72:75], v[120:123], v[208:211], v[72:75]
	v_mfma_f32_16x16x32_bf16 v[140:143], v[116:119], v[182:185], v[140:143]
	v_mfma_f32_16x16x32_bf16 v[136:139], v[124:127], v[182:185], v[136:139]
	v_mfma_f32_16x16x32_bf16 v[112:115], v[116:119], v[196:199], v[112:115]
	v_mfma_f32_16x16x32_bf16 v[104:107], v[124:127], v[196:199], v[104:107]
	v_mfma_f32_16x16x32_bf16 v[92:95], v[116:119], v[204:207], v[92:95]
	v_mfma_f32_16x16x32_bf16 v[88:91], v[124:127], v[204:207], v[88:91]
	v_mfma_f32_16x16x32_bf16 v[76:79], v[116:119], v[212:215], v[76:79]
	v_mfma_f32_16x16x32_bf16 v[72:75], v[124:127], v[212:215], v[72:75]
	s_setprio 0
	s_setprio 1
	v_mfma_f32_16x16x32_bf16 v[132:135], v[152:155], v[178:181], v[132:135]
	v_mfma_f32_16x16x32_bf16 v[128:131], v[166:169], v[178:181], v[128:131]
	v_mfma_f32_16x16x32_bf16 v[100:103], v[152:155], v[192:195], v[100:103]
	v_mfma_f32_16x16x32_bf16 v[96:99], v[166:169], v[192:195], v[96:99]
	v_mfma_f32_16x16x32_bf16 v[84:87], v[152:155], v[200:203], v[84:87]
	v_mfma_f32_16x16x32_bf16 v[80:83], v[166:169], v[200:203], v[80:83]
	v_mfma_f32_16x16x32_bf16 v[68:71], v[152:155], v[208:211], v[68:71]
	v_mfma_f32_16x16x32_bf16 v[64:67], v[166:169], v[208:211], v[64:67]
	v_mfma_f32_16x16x32_bf16 v[132:135], v[162:165], v[182:185], v[132:135]
	v_mfma_f32_16x16x32_bf16 v[128:131], v[174:177], v[182:185], v[128:131]
	v_mfma_f32_16x16x32_bf16 v[100:103], v[162:165], v[196:199], v[100:103]
	v_mfma_f32_16x16x32_bf16 v[96:99], v[174:177], v[196:199], v[96:99]
	v_mfma_f32_16x16x32_bf16 v[84:87], v[162:165], v[204:207], v[84:87]
	v_mfma_f32_16x16x32_bf16 v[80:83], v[174:177], v[204:207], v[80:83]
	v_mfma_f32_16x16x32_bf16 v[68:71], v[162:165], v[212:215], v[68:71]
	v_mfma_f32_16x16x32_bf16 v[64:67], v[174:177], v[212:215], v[64:67]
	s_setprio 0
	s_barrier
	s_add_i32 s49, s49, s31
	v_lshl_add_u64 v[156:157], s[26:27], 0, v[146:147]
	s_mov_b32 m0, s49
	ds_read_b128 v[178:181], v161 offset:16384
	ds_read_b128 v[182:185], v161 offset:17408
	ds_read_b128 v[192:195], v161 offset:18432
	ds_read_b128 v[196:199], v161 offset:19456
	ds_read_b128 v[200:203], v161 offset:20480
	ds_read_b128 v[204:207], v161 offset:21504
	ds_read_b128 v[208:211], v161 offset:22528
	ds_read_b128 v[212:215], v161 offset:23552
	global_load_lds_dwordx4 v[156:157], off
	s_add_i32 m0, s49, 0x2000
	s_add_u32 s50, s26, 0x100000
	v_lshl_add_u64 v[170:171], s[26:27], 0, v[144:145]
	s_addc_u32 s51, s27, 0
	s_add_i32 s49, s52, s31
	global_load_lds_dwordx4 v[170:171], off
	s_mov_b32 m0, s49
	v_lshl_add_u64 v[216:217], s[28:29], 0, v[144:145]
	global_load_lds_dwordx4 v146, s[50:51]
	s_add_i32 m0, s49, 0x2000
	s_nop 0
	global_load_lds_dwordx4 v144, s[50:51]
	v_lshl_add_u64 v[186:187], s[28:29], 0, v[146:147]
	s_mov_b32 m0, s34
	s_nop 0
	global_load_lds_dwordx4 v[186:187], off
	s_mov_b32 m0, s35
	s_nop 0
	global_load_lds_dwordx4 v[216:217], off
	s_waitcnt vmcnt(8)
	s_waitcnt lgkmcnt(0)
	s_barrier
; #define PG8_STAGE(bufoff, gbase, voff) do { _Pragma("unroll") for (int _i = 0; _i < 2; ++_i) \
;         __builtin_amdgcn_global_load_lds((const unsigned*)((const char*)(gbase) + (voff)[_i]), (PG8_LAS unsigned*)(lds + (bufoff) + ldsw + _i * 8192), 16, 0, 0); } while (0)
; #define PG8_LDA(dst, b, h) do { _Pragma("unroll") for (int m = 0; m < 4; ++m) _Pragma("unroll") for (int k = 0; k < 2; ++k) dst[m][k] = *(const PG8_LAS bf16x8*)(lds + PG8_SA(b, h) + aoff + m * 2048 + k * 1024); } while (0)
; #define PG8_LDB(dst, b, h) do { _Pragma("unroll") for (int n = 0; n < 2; ++n) _Pragma("unroll") for (int k = 0; k < 2; ++k) dst[n][k] = *(const PG8_LAS bf16x8*)(lds + PG8_SB(b, h) + boff + n * 2048 + k * 1024); } while (0)
; #define PG8_MMA(ai, bj, At, Bt) do { __builtin_amdgcn_s_setprio(1); _Pragma("unroll") for (int m = 0; m < 4; ++m) _Pragma("unroll") for (int n = 0; n < 2; ++n) _Pragma("unroll") for (int k = 0; k < 2; ++k) \
;         acc[ai][bj][m][n] = __builtin_amdgcn_mfma_f32_16x16x32_bf16(Bt[n][k], At[m][k], acc[ai][bj][m][n], 0, 0, 0); __builtin_amdgcn_s_setprio(0); } while (0)
; #define PG8_WAIT_V(n) asm volatile("s_waitcnt vmcnt(" #n ")" ::: "memory")
; #define PG8_WAIT_L(n) asm volatile("s_waitcnt lgkmcnt(" #n ")" ::: "memory")
; #define PG8_BAR __builtin_amdgcn_s_barrier()
; #define PG8_SCHED __builtin_amdgcn_sched_barrier(0)
; template <class Epi, class Sched, bool ALIGN_EPI = false, bool SP2 = false>
; __device__ __forceinline__ void gemm_phase(PG8_LAS unsigned char* lds, const Gemm g, const Sched& S, const Epi& E) {
;     ...
;             PG8_WAIT_V(8); PG8_WAIT_L(0); PG8_BAR; PG8_MMA(1, 0, At, B0); PG8_MMA(1, 1, At, B1); PG8_BAR; PG8_SCHED;
;             PG8_LDB(B0, 1, 0); PG8_LDB(B1, 1, 1); PG8_SCHED; PG8_LDA(At, 1, 0); PG8_STAGE(PG8_SA(0, 1), a2 + hstepA, voffA);
;             PG8_WAIT_V(8); PG8_WAIT_L(0); PG8_BAR; PG8_MMA(0, 0, At, B0); PG8_MMA(0, 1, At, B1); PG8_BAR; PG8_SCHED;
	s_setprio 1
	v_mfma_f32_16x16x32_bf16 v[60:63], v[108:111], v[178:181], v[60:63]
	v_mfma_f32_16x16x32_bf16 v[56:59], v[120:123], v[178:181], v[56:59]
	v_mfma_f32_16x16x32_bf16 v[52:55], v[108:111], v[192:195], v[52:55]
	v_mfma_f32_16x16x32_bf16 v[40:43], v[120:123], v[192:195], v[40:43]
	v_mfma_f32_16x16x32_bf16 v[36:39], v[108:111], v[200:203], v[36:39]
	v_mfma_f32_16x16x32_bf16 v[24:27], v[120:123], v[200:203], v[24:27]
	v_mfma_f32_16x16x32_bf16 v[20:23], v[108:111], v[208:211], v[20:23]
	v_mfma_f32_16x16x32_bf16 v[8:11], v[120:123], v[208:211], v[8:11]
	v_mfma_f32_16x16x32_bf16 v[60:63], v[116:119], v[182:185], v[60:63]
	v_mfma_f32_16x16x32_bf16 v[56:59], v[124:127], v[182:185], v[56:59]
	v_mfma_f32_16x16x32_bf16 v[52:55], v[116:119], v[196:199], v[52:55]
	v_mfma_f32_16x16x32_bf16 v[40:43], v[124:127], v[196:199], v[40:43]
	v_mfma_f32_16x16x32_bf16 v[36:39], v[116:119], v[204:207], v[36:39]
	v_mfma_f32_16x16x32_bf16 v[24:27], v[124:127], v[204:207], v[24:27]
	v_mfma_f32_16x16x32_bf16 v[20:23], v[116:119], v[212:215], v[20:23]
	v_mfma_f32_16x16x32_bf16 v[8:11], v[124:127], v[212:215], v[8:11]
	s_setprio 0
	s_setprio 1
	v_mfma_f32_16x16x32_bf16 v[48:51], v[152:155], v[178:181], v[48:51]
	v_mfma_f32_16x16x32_bf16 v[44:47], v[166:169], v[178:181], v[44:47]
	v_mfma_f32_16x16x32_bf16 v[32:35], v[152:155], v[192:195], v[32:35]
	v_mfma_f32_16x16x32_bf16 v[28:31], v[166:169], v[192:195], v[28:31]
	v_mfma_f32_16x16x32_bf16 v[16:19], v[152:155], v[200:203], v[16:19]
	v_mfma_f32_16x16x32_bf16 v[12:15], v[166:169], v[200:203], v[12:15]
	v_mfma_f32_16x16x32_bf16 v[4:7], v[152:155], v[208:211], v[4:7]
	v_mfma_f32_16x16x32_bf16 v[0:3], v[166:169], v[208:211], v[0:3]
	v_mfma_f32_16x16x32_bf16 v[48:51], v[162:165], v[182:185], v[48:51]
	v_mfma_f32_16x16x32_bf16 v[44:47], v[174:177], v[182:185], v[44:47]
	v_mfma_f32_16x16x32_bf16 v[32:35], v[162:165], v[196:199], v[32:35]
	v_mfma_f32_16x16x32_bf16 v[28:31], v[174:177], v[196:199], v[28:31]
	v_mfma_f32_16x16x32_bf16 v[16:19], v[162:165], v[204:207], v[16:19]
	v_mfma_f32_16x16x32_bf16 v[12:15], v[174:177], v[204:207], v[12:15]
	v_mfma_f32_16x16x32_bf16 v[4:7], v[162:165], v[212:215], v[4:7]
	v_mfma_f32_16x16x32_bf16 v[0:3], v[174:177], v[212:215], v[0:3]
	s_setprio 0
	s_barrier
	s_add_i32 s49, 0, 0x18000
	s_add_i32 s50, 0, 0x1c000
	v_add_u32_e32 v124, s49, v158
	v_add_u32_e32 v172, s50, v158
	ds_read_b128 v[108:111], v124
	ds_read_b128 v[116:119], v124 offset:1024
	ds_read_b128 v[120:123], v124 offset:2048
	ds_read_b128 v[124:127], v124 offset:3072
	ds_read_b128 v[152:155], v172
	ds_read_b128 v[162:165], v172 offset:1024
	ds_read_b128 v[166:169], v172 offset:2048
	ds_read_b128 v[174:177], v172 offset:3072
	s_add_u32 s28, s28, 0x100000
	s_addc_u32 s29, s29, 0
	s_mov_b32 m0, s36
	ds_read_b128 v[178:181], v161 offset:32768
	ds_read_b128 v[182:185], v161 offset:33792
	ds_read_b128 v[192:195], v161 offset:34816
	ds_read_b128 v[196:199], v161 offset:35840
	ds_read_b128 v[200:203], v161 offset:36864
	ds_read_b128 v[204:207], v161 offset:37888
	ds_read_b128 v[208:211], v161 offset:38912
	ds_read_b128 v[212:215], v161 offset:39936
	global_load_lds_dwordx4 v146, s[28:29]
	v_lshl_add_u64 v[218:219], s[28:29], 0, v[144:145]
	s_mov_b32 m0, s37
	s_nop 0
	global_load_lds_dwordx4 v[218:219], off
	s_waitcnt vmcnt(8)
	s_waitcnt lgkmcnt(0)
	s_barrier
	s_setprio 1
	v_mfma_f32_16x16x32_bf16 v[140:143], v[108:111], v[178:181], v[140:143]
	v_mfma_f32_16x16x32_bf16 v[136:139], v[120:123], v[178:181], v[136:139]
	v_mfma_f32_16x16x32_bf16 v[112:115], v[108:111], v[192:195], v[112:115]
	v_mfma_f32_16x16x32_bf16 v[104:107], v[120:123], v[192:195], v[104:107]
	v_mfma_f32_16x16x32_bf16 v[92:95], v[108:111], v[200:203], v[92:95]
	v_mfma_f32_16x16x32_bf16 v[88:91], v[120:123], v[200:203], v[88:91]
	v_mfma_f32_16x16x32_bf16 v[76:79], v[108:111], v[208:211], v[76:79]
	v_mfma_f32_16x16x32_bf16 v[72:75], v[120:123], v[208:211], v[72:75]
	v_mfma_f32_16x16x32_bf16 v[140:143], v[116:119], v[182:185], v[140:143]
	v_mfma_f32_16x16x32_bf16 v[136:139], v[124:127], v[182:185], v[136:139]
	v_mfma_f32_16x16x32_bf16 v[112:115], v[116:119], v[196:199], v[112:115]
	v_mfma_f32_16x16x32_bf16 v[104:107], v[124:127], v[196:199], v[104:107]
	v_mfma_f32_16x16x32_bf16 v[92:95], v[116:119], v[204:207], v[92:95]
	v_mfma_f32_16x16x32_bf16 v[88:91], v[124:127], v[204:207], v[88:91]
	v_mfma_f32_16x16x32_bf16 v[76:79], v[116:119], v[212:215], v[76:79]
	v_mfma_f32_16x16x32_bf16 v[72:75], v[124:127], v[212:215], v[72:75]
	s_setprio 0
	s_setprio 1
	v_mfma_f32_16x16x32_bf16 v[132:135], v[152:155], v[178:181], v[132:135]
	v_mfma_f32_16x16x32_bf16 v[128:131], v[166:169], v[178:181], v[128:131]
	v_mfma_f32_16x16x32_bf16 v[100:103], v[152:155], v[192:195], v[100:103]
	v_mfma_f32_16x16x32_bf16 v[96:99], v[166:169], v[192:195], v[96:99]
	v_mfma_f32_16x16x32_bf16 v[84:87], v[152:155], v[200:203], v[84:87]
	v_mfma_f32_16x16x32_bf16 v[80:83], v[166:169], v[200:203], v[80:83]
	v_mfma_f32_16x16x32_bf16 v[68:71], v[152:155], v[208:211], v[68:71]
	v_mfma_f32_16x16x32_bf16 v[64:67], v[166:169], v[208:211], v[64:67]
	v_mfma_f32_16x16x32_bf16 v[132:135], v[162:165], v[182:185], v[132:135]
	v_mfma_f32_16x16x32_bf16 v[128:131], v[174:177], v[182:185], v[128:131]
	v_mfma_f32_16x16x32_bf16 v[100:103], v[162:165], v[196:199], v[100:103]
	v_mfma_f32_16x16x32_bf16 v[96:99], v[174:177], v[196:199], v[96:99]
	v_mfma_f32_16x16x32_bf16 v[84:87], v[162:165], v[204:207], v[84:87]
	v_mfma_f32_16x16x32_bf16 v[80:83], v[174:177], v[204:207], v[80:83]
	v_mfma_f32_16x16x32_bf16 v[68:71], v[162:165], v[212:215], v[68:71]
	v_mfma_f32_16x16x32_bf16 v[64:67], v[174:177], v[212:215], v[64:67]
	s_setprio 0
	s_barrier
; #define PG8_STAGE(bufoff, gbase, voff) do { _Pragma("unroll") for (int _i = 0; _i < 2; ++_i) \
;         __builtin_amdgcn_global_load_lds((const unsigned*)((const char*)(gbase) + (voff)[_i]), (PG8_LAS unsigned*)(lds + (bufoff) + ldsw + _i * 8192), 16, 0, 0); } while (0)
; #define PG8_LDA(dst, b, h) do { _Pragma("unroll") for (int m = 0; m < 4; ++m) _Pragma("unroll") for (int k = 0; k < 2; ++k) dst[m][k] = *(const PG8_LAS bf16x8*)(lds + PG8_SA(b, h) + aoff + m * 2048 + k * 1024); } while (0)
; #define PG8_MMA(ai, bj, At, Bt) do { __builtin_amdgcn_s_setprio(1); _Pragma("unroll") for (int m = 0; m < 4; ++m) _Pragma("unroll") for (int n = 0; n < 2; ++n) _Pragma("unroll") for (int k = 0; k < 2; ++k) \
;         acc[ai][bj][m][n] = __builtin_amdgcn_mfma_f32_16x16x32_bf16(Bt[n][k], At[m][k], acc[ai][bj][m][n], 0, 0, 0); __builtin_amdgcn_s_setprio(0); } while (0)
; #define PG8_WAIT_V(n) asm volatile("s_waitcnt vmcnt(" #n ")" ::: "memory")
; #define PG8_WAIT_L(n) asm volatile("s_waitcnt lgkmcnt(" #n ")" ::: "memory")
; #define PG8_BAR __builtin_amdgcn_s_barrier()
; #define PG8_SCHED __builtin_amdgcn_sched_barrier(0)
; template <class Epi, class Sched, bool ALIGN_EPI = false, bool SP2 = false>
; __device__ __forceinline__ void gemm_phase(PG8_LAS unsigned char* lds, const Gemm g, const Sched& S, const Epi& E) {
;     ...
;         for (int t = 0; t < nt; t += 2) {
;     ...
;             PG8_LDA(At, 1, 1); PG8_STAGE(PG8_SB(1, 0), b3, voffB); PG8_STAGE(PG8_SB(1, 1), b3 + hstepB, voffB); PG8_STAGE(PG8_SA(1, 0), a3, voffA);
;             PG8_WAIT_V(8); PG8_WAIT_L(0); PG8_BAR; PG8_MMA(1, 0, At, B0); PG8_MMA(1, 1, At, B1); PG8_BAR; PG8_SCHED;
	s_add_i32 s28, s49, s31
	v_lshl_add_u64 v[156:157], v[156:157], 0, s[80:81]
	s_mov_b32 m0, s28
	ds_read_b128 v[178:181], v161 offset:49152
	ds_read_b128 v[182:185], v161 offset:50176
	ds_read_b128 v[192:195], v161 offset:51200
	ds_read_b128 v[196:199], v161 offset:52224
	ds_read_b128 v[200:203], v161 offset:53248
	ds_read_b128 v[204:207], v161 offset:54272
	ds_read_b128 v[208:211], v161 offset:55296
	ds_read_b128 v[212:215], v161 offset:56320
	global_load_lds_dwordx4 v[156:157], off
	s_add_i32 m0, s28, 0x2000
	s_add_u32 s26, s26, 0x100080
	v_lshl_add_u64 v[156:157], v[170:171], 0, s[80:81]
	s_addc_u32 s27, s27, 0
	s_add_i32 s28, s50, s31
	global_load_lds_dwordx4 v[156:157], off
	s_mov_b32 m0, s28
	s_nop 0
	global_load_lds_dwordx4 v146, s[26:27]
	s_add_i32 m0, s28, 0x2000
	s_nop 0
	global_load_lds_dwordx4 v144, s[26:27]
	v_lshl_add_u64 v[156:157], v[186:187], 0, s[80:81]
	s_mov_b32 m0, s2
	s_nop 0
	global_load_lds_dwordx4 v[156:157], off
	v_lshl_add_u64 v[156:157], v[216:217], 0, s[80:81]
	s_mov_b32 m0, s38
	s_nop 0
	global_load_lds_dwordx4 v[156:157], off
	s_waitcnt vmcnt(8)
	s_waitcnt lgkmcnt(0)
	s_barrier
	s_setprio 1
	v_mfma_f32_16x16x32_bf16 v[60:63], v[108:111], v[178:181], v[60:63]
	v_mfma_f32_16x16x32_bf16 v[56:59], v[120:123], v[178:181], v[56:59]
	v_mfma_f32_16x16x32_bf16 v[52:55], v[108:111], v[192:195], v[52:55]
	v_mfma_f32_16x16x32_bf16 v[40:43], v[120:123], v[192:195], v[40:43]
	v_mfma_f32_16x16x32_bf16 v[36:39], v[108:111], v[200:203], v[36:39]
	v_mfma_f32_16x16x32_bf16 v[24:27], v[120:123], v[200:203], v[24:27]
	v_mfma_f32_16x16x32_bf16 v[20:23], v[108:111], v[208:211], v[20:23]
	v_mfma_f32_16x16x32_bf16 v[8:11], v[120:123], v[208:211], v[8:11]
	v_mfma_f32_16x16x32_bf16 v[60:63], v[116:119], v[182:185], v[60:63]
	v_mfma_f32_16x16x32_bf16 v[56:59], v[124:127], v[182:185], v[56:59]
	v_mfma_f32_16x16x32_bf16 v[52:55], v[116:119], v[196:199], v[52:55]
	v_mfma_f32_16x16x32_bf16 v[40:43], v[124:127], v[196:199], v[40:43]
	v_mfma_f32_16x16x32_bf16 v[36:39], v[116:119], v[204:207], v[36:39]
	v_mfma_f32_16x16x32_bf16 v[24:27], v[124:127], v[204:207], v[24:27]
	v_mfma_f32_16x16x32_bf16 v[20:23], v[116:119], v[212:215], v[20:23]
	v_mfma_f32_16x16x32_bf16 v[8:11], v[124:127], v[212:215], v[8:11]
	s_setprio 0
	s_setprio 1
	v_mfma_f32_16x16x32_bf16 v[48:51], v[152:155], v[178:181], v[48:51]
	v_mfma_f32_16x16x32_bf16 v[44:47], v[166:169], v[178:181], v[44:47]
	v_mfma_f32_16x16x32_bf16 v[32:35], v[152:155], v[192:195], v[32:35]
	v_mfma_f32_16x16x32_bf16 v[28:31], v[166:169], v[192:195], v[28:31]
	v_mfma_f32_16x16x32_bf16 v[16:19], v[152:155], v[200:203], v[16:19]
	v_mfma_f32_16x16x32_bf16 v[12:15], v[166:169], v[200:203], v[12:15]
	v_mfma_f32_16x16x32_bf16 v[4:7], v[152:155], v[208:211], v[4:7]
	v_mfma_f32_16x16x32_bf16 v[0:3], v[166:169], v[208:211], v[0:3]
	v_mfma_f32_16x16x32_bf16 v[48:51], v[162:165], v[182:185], v[48:51]
	v_mfma_f32_16x16x32_bf16 v[44:47], v[174:177], v[182:185], v[44:47]
	v_mfma_f32_16x16x32_bf16 v[32:35], v[162:165], v[196:199], v[32:35]
	v_mfma_f32_16x16x32_bf16 v[28:31], v[174:177], v[196:199], v[28:31]
	v_mfma_f32_16x16x32_bf16 v[16:19], v[162:165], v[204:207], v[16:19]
	v_mfma_f32_16x16x32_bf16 v[12:15], v[174:177], v[204:207], v[12:15]
	v_mfma_f32_16x16x32_bf16 v[4:7], v[162:165], v[212:215], v[4:7]
	v_mfma_f32_16x16x32_bf16 v[0:3], v[174:177], v[212:215], v[0:3]
	s_setprio 0
	s_barrier
	s_add_i32 s47, s47, 2
	s_add_u32 s24, s24, 0x100
	s_addc_u32 s25, s25, 0
	s_add_u32 s17, s17, 0x100
	s_addc_u32 s23, s23, 0
	s_cmp_gt_u32 s47, 5
	s_cbranch_scc0 .LBB0_1972
	s_and_b64 vcc, exec, s[10:11]
	s_cbranch_vccz .LBB0_1975
	s_barrier
